# GEMM loops: load-segment SALU (pointer/m0 setup for the first DMA) and post-MFMA SALU moved into the gaps of the preceding MFMA block
# speedup vs baseline: 1.0105x; 1.0057x over previous
.LBB0_86:
	v_mov_b64_e32 v[0:1], 0x800
	s_ashr_i32 s7, s6, 31
	v_cmp_lt_i64_e32 vcc, s[8:9], v[0:1]
	s_lshl_b64 s[8:9], s[6:7], 20
	s_add_u32 s8, s23, s8
	s_addc_u32 s9, s24, s9
	s_and_b64 s[10:11], vcc, exec
	s_cselect_b32 s7, s9, s15
	s_cselect_b32 s38, s8, s14
	s_ashr_i32 s5, s4, 31
	s_lshl_b64 s[10:11], s[4:5], 20
	s_add_u32 s10, s25, s10
	s_addc_u32 s11, s26, s11
	s_and_b64 s[18:19], vcc, exec
	s_cselect_b32 s5, s11, s17
	s_cselect_b32 s39, s10, s16
	s_add_u32 s14, s14, 0x80080
	s_addc_u32 s15, s15, 0
	s_add_u32 s40, s16, 0x100
	s_addc_u32 s41, s17, 0
	s_mov_b32 s42, -2
	s_mov_b64 s[48:49], 0x80
	v_add_u32_e32 v220, 0x10000, v183
	s_add_u32 s16, s14, 0xfff80080
	s_addc_u32 s17, s15, -1
	s_add_i32 s43, 0, 0x10000
	ds_read_b128 v[128:131], v220 offset:0
	ds_read_b128 v[132:135], v220 offset:1024
	ds_read_b128 v[136:139], v220 offset:2048
	ds_read_b128 v[140:143], v220 offset:3072
	s_cmp_eq_u32 s42, 28
	s_cselect_b32 s19, s7, s17
	s_cselect_b32 s18, s38, s16
	s_cselect_b32 s17, s5, s41
	s_cselect_b32 s16, s39, s40
	s_add_i32 m0, s28, 0xc000
	ds_read_b128 v[144:147], v185
	ds_read_b128 v[148:151], v185 offset:1024
	ds_read_b128 v[152:155], v185 offset:2048
	ds_read_b128 v[156:159], v185 offset:3072
	ds_read_b128 v[170:173], v185 offset:4096
	ds_read_b128 v[174:177], v185 offset:5120
	ds_read_b128 v[178:181], v185 offset:6144
	ds_read_b128 v[186:189], v185 offset:7168
	global_load_lds_dwordx4 v166, s[14:15]
	s_add_i32 m0, s28, 0xe000
	s_nop 0
	global_load_lds_dwordx4 v168, s[14:15]
	s_waitcnt lgkmcnt(8)
	s_barrier
	s_waitcnt lgkmcnt(0)
	v_mfma_f32_16x16x32_bf16 v[124:127], v[128:131], v[144:147], 0
	v_mfma_f32_16x16x32_bf16 v[120:123], v[136:139], v[144:147], 0
	v_mfma_f32_16x16x32_bf16 v[108:111], v[128:131], v[152:155], 0
	v_mfma_f32_16x16x32_bf16 v[104:107], v[136:139], v[152:155], 0
	s_add_i32 s46, 0, 0x14000
	s_add_i32 s43, s43, s27
	v_mfma_f32_16x16x32_bf16 v[92:95], v[128:131], v[170:173], 0
	s_mov_b32 m0, s43
	v_mfma_f32_16x16x32_bf16 v[88:91], v[136:139], v[170:173], 0
	v_mfma_f32_16x16x32_bf16 v[76:79], v[128:131], v[178:181], 0
	v_mfma_f32_16x16x32_bf16 v[72:75], v[136:139], v[178:181], 0
	v_mfma_f32_16x16x32_bf16 v[124:127], v[132:135], v[148:151], v[124:127]
	v_mfma_f32_16x16x32_bf16 v[120:123], v[140:143], v[148:151], v[120:123]
	v_mfma_f32_16x16x32_bf16 v[108:111], v[132:135], v[156:159], v[108:111]
	v_mfma_f32_16x16x32_bf16 v[104:107], v[140:143], v[156:159], v[104:107]
	v_mfma_f32_16x16x32_bf16 v[92:95], v[132:135], v[174:177], v[92:95]
	v_mfma_f32_16x16x32_bf16 v[88:91], v[140:143], v[174:177], v[88:91]
	v_mfma_f32_16x16x32_bf16 v[76:79], v[132:135], v[186:189], v[76:79]
	v_mfma_f32_16x16x32_bf16 v[72:75], v[140:143], v[186:189], v[72:75]
	s_barrier
	ds_read_b128 v[196:199], v220 offset:16384
	ds_read_b128 v[204:207], v220 offset:17408
	ds_read_b128 v[208:211], v220 offset:18432
	ds_read_b128 v[214:217], v220 offset:19456
	global_load_lds_dwordx4 v192, s[16:17]
	s_add_i32 m0, s43, 0x2000
	s_nop 0
	global_load_lds_dwordx4 v164, s[16:17]
	s_barrier
	s_waitcnt lgkmcnt(0)
	v_mfma_f32_16x16x32_bf16 v[116:119], v[196:199], v[144:147], 0
	v_mfma_f32_16x16x32_bf16 v[112:115], v[208:211], v[144:147], 0
	v_mfma_f32_16x16x32_bf16 v[100:103], v[196:199], v[152:155], 0
	v_mfma_f32_16x16x32_bf16 v[96:99], v[208:211], v[152:155], 0
	s_mov_b32 m0, s28
	v_mfma_f32_16x16x32_bf16 v[84:87], v[196:199], v[170:173], 0
	s_add_u32 s48, s18, 0x80
	s_addc_u32 s49, s19, 0
	v_mfma_f32_16x16x32_bf16 v[80:83], v[208:211], v[170:173], 0
	v_mfma_f32_16x16x32_bf16 v[68:71], v[196:199], v[178:181], 0
	v_mfma_f32_16x16x32_bf16 v[64:67], v[208:211], v[178:181], 0
	v_mfma_f32_16x16x32_bf16 v[116:119], v[204:207], v[148:151], v[116:119]
	v_mfma_f32_16x16x32_bf16 v[112:115], v[214:217], v[148:151], v[112:115]
	v_mfma_f32_16x16x32_bf16 v[100:103], v[204:207], v[156:159], v[100:103]
	v_mfma_f32_16x16x32_bf16 v[96:99], v[214:217], v[156:159], v[96:99]
	v_mfma_f32_16x16x32_bf16 v[84:87], v[204:207], v[174:177], v[84:87]
	v_mfma_f32_16x16x32_bf16 v[80:83], v[214:217], v[174:177], v[80:83]
	v_mfma_f32_16x16x32_bf16 v[68:71], v[204:207], v[186:189], v[68:71]
	v_mfma_f32_16x16x32_bf16 v[64:67], v[214:217], v[186:189], v[64:67]
	s_barrier
	ds_read_b128 v[144:147], v185 offset:16384
	ds_read_b128 v[148:151], v185 offset:17408
	ds_read_b128 v[152:155], v185 offset:18432
	ds_read_b128 v[156:159], v185 offset:19456
	ds_read_b128 v[170:173], v185 offset:20480
	ds_read_b128 v[174:177], v185 offset:21504
	ds_read_b128 v[178:181], v185 offset:22528
	ds_read_b128 v[186:189], v185 offset:23552
	global_load_lds_dwordx4 v160, s[18:19]
	s_mov_b32 m0, s29
	s_nop 0
	global_load_lds_dwordx4 v162, s[18:19]
	s_barrier
	s_waitcnt lgkmcnt(0)
	v_mfma_f32_16x16x32_bf16 v[60:63], v[128:131], v[144:147], 0
	v_mfma_f32_16x16x32_bf16 v[56:59], v[136:139], v[144:147], 0
	v_mfma_f32_16x16x32_bf16 v[44:47], v[128:131], v[152:155], 0
	v_mfma_f32_16x16x32_bf16 v[40:43], v[136:139], v[152:155], 0
	s_add_u32 s44, s16, 0x80000
	s_addc_u32 s45, s17, 0
	v_mfma_f32_16x16x32_bf16 v[28:31], v[128:131], v[170:173], 0
	s_add_i32 s43, s46, s27
	s_mov_b32 m0, s43
	v_mfma_f32_16x16x32_bf16 v[24:27], v[136:139], v[170:173], 0
	v_mfma_f32_16x16x32_bf16 v[12:15], v[128:131], v[178:181], 0
	v_mfma_f32_16x16x32_bf16 v[8:11], v[136:139], v[178:181], 0
	v_mfma_f32_16x16x32_bf16 v[60:63], v[132:135], v[148:151], v[60:63]
	v_mfma_f32_16x16x32_bf16 v[56:59], v[140:143], v[148:151], v[56:59]
	v_mfma_f32_16x16x32_bf16 v[44:47], v[132:135], v[156:159], v[44:47]
	v_mfma_f32_16x16x32_bf16 v[40:43], v[140:143], v[156:159], v[40:43]
	v_mfma_f32_16x16x32_bf16 v[28:31], v[132:135], v[174:177], v[28:31]
	v_mfma_f32_16x16x32_bf16 v[24:27], v[140:143], v[174:177], v[24:27]
	v_mfma_f32_16x16x32_bf16 v[12:15], v[132:135], v[186:189], v[12:15]
	v_mfma_f32_16x16x32_bf16 v[8:11], v[140:143], v[186:189], v[8:11]
	s_barrier
	global_load_lds_dwordx4 v192, s[44:45]
	s_add_i32 m0, s43, 0x2000
	s_nop 0
	global_load_lds_dwordx4 v164, s[44:45]
	s_waitcnt vmcnt(6)
	s_barrier
	v_mfma_f32_16x16x32_bf16 v[52:55], v[196:199], v[144:147], 0
	v_mfma_f32_16x16x32_bf16 v[48:51], v[208:211], v[144:147], 0
	v_mfma_f32_16x16x32_bf16 v[36:39], v[196:199], v[152:155], 0
	v_mfma_f32_16x16x32_bf16 v[32:35], v[208:211], v[152:155], 0
	s_add_i32 s43, 0, 0x18000
	v_mfma_f32_16x16x32_bf16 v[20:23], v[196:199], v[170:173], 0
	s_add_u32 s18, s18, 0x80000
	s_addc_u32 s19, s19, 0
	v_mfma_f32_16x16x32_bf16 v[16:19], v[208:211], v[170:173], 0
	s_mov_b32 m0, s30
	v_mfma_f32_16x16x32_bf16 v[4:7], v[196:199], v[178:181], 0
	v_mfma_f32_16x16x32_bf16 v[0:3], v[208:211], v[178:181], 0
	v_mfma_f32_16x16x32_bf16 v[52:55], v[204:207], v[148:151], v[52:55]
	v_mfma_f32_16x16x32_bf16 v[48:51], v[214:217], v[148:151], v[48:51]
	v_mfma_f32_16x16x32_bf16 v[36:39], v[204:207], v[156:159], v[36:39]
	v_mfma_f32_16x16x32_bf16 v[32:35], v[214:217], v[156:159], v[32:35]
	v_mfma_f32_16x16x32_bf16 v[20:23], v[204:207], v[174:177], v[20:23]
	v_mfma_f32_16x16x32_bf16 v[16:19], v[214:217], v[174:177], v[16:19]
	v_mfma_f32_16x16x32_bf16 v[4:7], v[204:207], v[186:189], v[4:7]
	v_mfma_f32_16x16x32_bf16 v[0:3], v[214:217], v[186:189], v[0:3]
	s_barrier
	ds_read_b128 v[128:131], v220 offset:32768
	ds_read_b128 v[132:135], v220 offset:33792
	ds_read_b128 v[136:139], v220 offset:34816
	ds_read_b128 v[140:143], v220 offset:35840
	ds_read_b128 v[144:147], v185 offset:32768
	ds_read_b128 v[148:151], v185 offset:33792
	ds_read_b128 v[152:155], v185 offset:34816
	ds_read_b128 v[156:159], v185 offset:35840
	ds_read_b128 v[170:173], v185 offset:36864
	ds_read_b128 v[174:177], v185 offset:37888
	ds_read_b128 v[178:181], v185 offset:38912
	ds_read_b128 v[186:189], v185 offset:39936
	global_load_lds_dwordx4 v160, s[18:19]
	s_mov_b32 m0, s31
	s_nop 0
	global_load_lds_dwordx4 v162, s[18:19]
	s_waitcnt lgkmcnt(8)
	s_barrier
	s_waitcnt lgkmcnt(0)
	v_mfma_f32_16x16x32_bf16 v[124:127], v[128:131], v[144:147], v[124:127]
	v_mfma_f32_16x16x32_bf16 v[120:123], v[136:139], v[144:147], v[120:123]
	v_mfma_f32_16x16x32_bf16 v[108:111], v[128:131], v[152:155], v[108:111]
	v_mfma_f32_16x16x32_bf16 v[104:107], v[136:139], v[152:155], v[104:107]
	s_add_i32 s18, 0, 0x1c000
	s_add_i32 s19, s43, s27
	v_mfma_f32_16x16x32_bf16 v[92:95], v[128:131], v[170:173], v[92:95]
	s_add_i32 m0, s19, 0xffffff80
	v_mfma_f32_16x16x32_bf16 v[88:91], v[136:139], v[170:173], v[88:91]
	v_mfma_f32_16x16x32_bf16 v[76:79], v[128:131], v[178:181], v[76:79]
	v_mfma_f32_16x16x32_bf16 v[72:75], v[136:139], v[178:181], v[72:75]
	v_mfma_f32_16x16x32_bf16 v[124:127], v[132:135], v[148:151], v[124:127]
	v_mfma_f32_16x16x32_bf16 v[120:123], v[140:143], v[148:151], v[120:123]
	v_mfma_f32_16x16x32_bf16 v[108:111], v[132:135], v[156:159], v[108:111]
	v_mfma_f32_16x16x32_bf16 v[104:107], v[140:143], v[156:159], v[104:107]
	v_mfma_f32_16x16x32_bf16 v[92:95], v[132:135], v[174:177], v[92:95]
	v_mfma_f32_16x16x32_bf16 v[88:91], v[140:143], v[174:177], v[88:91]
	v_mfma_f32_16x16x32_bf16 v[76:79], v[132:135], v[186:189], v[76:79]
	v_mfma_f32_16x16x32_bf16 v[72:75], v[140:143], v[186:189], v[72:75]
	s_barrier
	ds_read_b128 v[196:199], v220 offset:49152
	ds_read_b128 v[204:207], v220 offset:50176
	ds_read_b128 v[208:211], v220 offset:51200
	ds_read_b128 v[214:217], v220 offset:52224
	global_load_lds_dwordx4 v192, s[16:17] offset:128
	s_add_i32 m0, s19, 0x1f80
	s_nop 0
	global_load_lds_dwordx4 v164, s[16:17] offset:128
	s_barrier
	s_waitcnt lgkmcnt(0)
	v_mfma_f32_16x16x32_bf16 v[116:119], v[196:199], v[144:147], v[116:119]
	v_mfma_f32_16x16x32_bf16 v[112:115], v[208:211], v[144:147], v[112:115]
	v_mfma_f32_16x16x32_bf16 v[100:103], v[196:199], v[152:155], v[100:103]
	v_mfma_f32_16x16x32_bf16 v[96:99], v[208:211], v[152:155], v[96:99]
	s_mov_b32 m0, s35
	v_mfma_f32_16x16x32_bf16 v[84:87], v[196:199], v[170:173], v[84:87]
	v_mfma_f32_16x16x32_bf16 v[80:83], v[208:211], v[170:173], v[80:83]
	v_mfma_f32_16x16x32_bf16 v[68:71], v[196:199], v[178:181], v[68:71]
	v_mfma_f32_16x16x32_bf16 v[64:67], v[208:211], v[178:181], v[64:67]
	v_mfma_f32_16x16x32_bf16 v[116:119], v[204:207], v[148:151], v[116:119]
	v_mfma_f32_16x16x32_bf16 v[112:115], v[214:217], v[148:151], v[112:115]
	v_mfma_f32_16x16x32_bf16 v[100:103], v[204:207], v[156:159], v[100:103]
	v_mfma_f32_16x16x32_bf16 v[96:99], v[214:217], v[156:159], v[96:99]
	v_mfma_f32_16x16x32_bf16 v[84:87], v[204:207], v[174:177], v[84:87]
	v_mfma_f32_16x16x32_bf16 v[80:83], v[214:217], v[174:177], v[80:83]
	v_mfma_f32_16x16x32_bf16 v[68:71], v[204:207], v[186:189], v[68:71]
	v_mfma_f32_16x16x32_bf16 v[64:67], v[214:217], v[186:189], v[64:67]
	s_barrier
	ds_read_b128 v[144:147], v185 offset:49152
	ds_read_b128 v[148:151], v185 offset:50176
	ds_read_b128 v[152:155], v185 offset:51200
	ds_read_b128 v[156:159], v185 offset:52224
	ds_read_b128 v[170:173], v185 offset:53248
	ds_read_b128 v[174:177], v185 offset:54272
	ds_read_b128 v[178:181], v185 offset:55296
	ds_read_b128 v[186:189], v185 offset:56320
	global_load_lds_dwordx4 v160, s[48:49]
	s_mov_b32 m0, s36
	s_nop 0
	global_load_lds_dwordx4 v162, s[48:49]
	s_barrier
	s_waitcnt lgkmcnt(0)
	v_mfma_f32_16x16x32_bf16 v[60:63], v[128:131], v[144:147], v[60:63]
	v_mfma_f32_16x16x32_bf16 v[56:59], v[136:139], v[144:147], v[56:59]
	v_mfma_f32_16x16x32_bf16 v[44:47], v[128:131], v[152:155], v[44:47]
	v_mfma_f32_16x16x32_bf16 v[40:43], v[136:139], v[152:155], v[40:43]
	s_add_u32 s16, s16, 0x80080
	s_addc_u32 s17, s17, 0
	v_mfma_f32_16x16x32_bf16 v[28:31], v[128:131], v[170:173], v[28:31]
	s_add_i32 s18, s18, s27
	s_mov_b32 m0, s18
	v_mfma_f32_16x16x32_bf16 v[24:27], v[136:139], v[170:173], v[24:27]
	v_mfma_f32_16x16x32_bf16 v[12:15], v[128:131], v[178:181], v[12:15]
	v_mfma_f32_16x16x32_bf16 v[8:11], v[136:139], v[178:181], v[8:11]
	v_mfma_f32_16x16x32_bf16 v[60:63], v[132:135], v[148:151], v[60:63]
	v_mfma_f32_16x16x32_bf16 v[56:59], v[140:143], v[148:151], v[56:59]
	v_mfma_f32_16x16x32_bf16 v[44:47], v[132:135], v[156:159], v[44:47]
	v_mfma_f32_16x16x32_bf16 v[40:43], v[140:143], v[156:159], v[40:43]
	v_mfma_f32_16x16x32_bf16 v[28:31], v[132:135], v[174:177], v[28:31]
	v_mfma_f32_16x16x32_bf16 v[24:27], v[140:143], v[174:177], v[24:27]
	v_mfma_f32_16x16x32_bf16 v[12:15], v[132:135], v[186:189], v[12:15]
	v_mfma_f32_16x16x32_bf16 v[8:11], v[140:143], v[186:189], v[8:11]
	s_barrier
	global_load_lds_dwordx4 v192, s[16:17]
	s_add_i32 m0, s18, 0x2000
	s_nop 0
	global_load_lds_dwordx4 v164, s[16:17]
	s_waitcnt vmcnt(6)
	s_barrier
	v_mfma_f32_16x16x32_bf16 v[52:55], v[196:199], v[144:147], v[52:55]
	v_mfma_f32_16x16x32_bf16 v[48:51], v[208:211], v[144:147], v[48:51]
	v_mfma_f32_16x16x32_bf16 v[36:39], v[196:199], v[152:155], v[36:39]
	v_mfma_f32_16x16x32_bf16 v[32:35], v[208:211], v[152:155], v[32:35]
	s_add_i32 s42, s42, 2
	v_mfma_f32_16x16x32_bf16 v[20:23], v[196:199], v[170:173], v[20:23]
	s_add_u32 s14, s14, 0x100
	s_addc_u32 s15, s15, 0
	v_mfma_f32_16x16x32_bf16 v[16:19], v[208:211], v[170:173], v[16:19]
	s_add_u32 s40, s40, 0x100
	s_addc_u32 s41, s41, 0
	v_mfma_f32_16x16x32_bf16 v[4:7], v[196:199], v[178:181], v[4:7]
	v_mfma_f32_16x16x32_bf16 v[0:3], v[208:211], v[178:181], v[0:3]
	v_mfma_f32_16x16x32_bf16 v[52:55], v[204:207], v[148:151], v[52:55]
	v_mfma_f32_16x16x32_bf16 v[48:51], v[214:217], v[148:151], v[48:51]
	v_mfma_f32_16x16x32_bf16 v[36:39], v[204:207], v[156:159], v[36:39]
	v_mfma_f32_16x16x32_bf16 v[32:35], v[214:217], v[156:159], v[32:35]
	v_mfma_f32_16x16x32_bf16 v[20:23], v[204:207], v[174:177], v[20:23]
	v_mfma_f32_16x16x32_bf16 v[16:19], v[214:217], v[174:177], v[16:19]
	v_mfma_f32_16x16x32_bf16 v[4:7], v[204:207], v[186:189], v[4:7]
	v_mfma_f32_16x16x32_bf16 v[0:3], v[214:217], v[186:189], v[0:3]
	s_cmp_gt_u32 s42, 29
	s_barrier
.LBB0_87:
	s_add_u32 s16, s14, 0xfff80080
	s_addc_u32 s17, s15, -1
	s_add_i32 s43, 0, 0x10000
	ds_read_b128 v[128:131], v220 offset:0
	ds_read_b128 v[132:135], v220 offset:1024
	ds_read_b128 v[136:139], v220 offset:2048
	ds_read_b128 v[140:143], v220 offset:3072
	s_cmp_eq_u32 s42, 28
	s_cselect_b32 s19, s7, s17
	s_cselect_b32 s18, s38, s16
	s_cselect_b32 s17, s5, s41
	s_cselect_b32 s16, s39, s40
	s_add_i32 m0, s28, 0xc000
	ds_read_b128 v[144:147], v185
	ds_read_b128 v[148:151], v185 offset:1024
	ds_read_b128 v[152:155], v185 offset:2048
	ds_read_b128 v[156:159], v185 offset:3072
	ds_read_b128 v[170:173], v185 offset:4096
	ds_read_b128 v[174:177], v185 offset:5120
	ds_read_b128 v[178:181], v185 offset:6144
	ds_read_b128 v[186:189], v185 offset:7168
	global_load_lds_dwordx4 v166, s[14:15]
	s_add_i32 m0, s28, 0xe000
	s_nop 0
	global_load_lds_dwordx4 v168, s[14:15]
	s_waitcnt lgkmcnt(8)
	s_barrier
	s_waitcnt lgkmcnt(0)
	v_mfma_f32_16x16x32_bf16 v[124:127], v[128:131], v[144:147], v[124:127]
	v_mfma_f32_16x16x32_bf16 v[120:123], v[136:139], v[144:147], v[120:123]
	v_mfma_f32_16x16x32_bf16 v[108:111], v[128:131], v[152:155], v[108:111]
	v_mfma_f32_16x16x32_bf16 v[104:107], v[136:139], v[152:155], v[104:107]
	s_add_i32 s46, 0, 0x14000
	s_add_i32 s43, s43, s27
	v_mfma_f32_16x16x32_bf16 v[92:95], v[128:131], v[170:173], v[92:95]
	s_mov_b32 m0, s43
	v_mfma_f32_16x16x32_bf16 v[88:91], v[136:139], v[170:173], v[88:91]
	v_mfma_f32_16x16x32_bf16 v[76:79], v[128:131], v[178:181], v[76:79]
	v_mfma_f32_16x16x32_bf16 v[72:75], v[136:139], v[178:181], v[72:75]
	v_mfma_f32_16x16x32_bf16 v[124:127], v[132:135], v[148:151], v[124:127]
	v_mfma_f32_16x16x32_bf16 v[120:123], v[140:143], v[148:151], v[120:123]
	v_mfma_f32_16x16x32_bf16 v[108:111], v[132:135], v[156:159], v[108:111]
	v_mfma_f32_16x16x32_bf16 v[104:107], v[140:143], v[156:159], v[104:107]
	v_mfma_f32_16x16x32_bf16 v[92:95], v[132:135], v[174:177], v[92:95]
	v_mfma_f32_16x16x32_bf16 v[88:91], v[140:143], v[174:177], v[88:91]
	v_mfma_f32_16x16x32_bf16 v[76:79], v[132:135], v[186:189], v[76:79]
	v_mfma_f32_16x16x32_bf16 v[72:75], v[140:143], v[186:189], v[72:75]
	s_barrier
	ds_read_b128 v[196:199], v220 offset:16384
	ds_read_b128 v[204:207], v220 offset:17408
	ds_read_b128 v[208:211], v220 offset:18432
	ds_read_b128 v[214:217], v220 offset:19456
	global_load_lds_dwordx4 v192, s[16:17]
	s_add_i32 m0, s43, 0x2000
	s_nop 0
	global_load_lds_dwordx4 v164, s[16:17]
	s_barrier
	s_waitcnt lgkmcnt(0)
	v_mfma_f32_16x16x32_bf16 v[116:119], v[196:199], v[144:147], v[116:119]
	v_mfma_f32_16x16x32_bf16 v[112:115], v[208:211], v[144:147], v[112:115]
	v_mfma_f32_16x16x32_bf16 v[100:103], v[196:199], v[152:155], v[100:103]
	v_mfma_f32_16x16x32_bf16 v[96:99], v[208:211], v[152:155], v[96:99]
	s_mov_b32 m0, s28
	v_mfma_f32_16x16x32_bf16 v[84:87], v[196:199], v[170:173], v[84:87]
	s_add_u32 s48, s18, 0x80
	s_addc_u32 s49, s19, 0
	v_mfma_f32_16x16x32_bf16 v[80:83], v[208:211], v[170:173], v[80:83]
	v_mfma_f32_16x16x32_bf16 v[68:71], v[196:199], v[178:181], v[68:71]
	v_mfma_f32_16x16x32_bf16 v[64:67], v[208:211], v[178:181], v[64:67]
	v_mfma_f32_16x16x32_bf16 v[116:119], v[204:207], v[148:151], v[116:119]
	v_mfma_f32_16x16x32_bf16 v[112:115], v[214:217], v[148:151], v[112:115]
	v_mfma_f32_16x16x32_bf16 v[100:103], v[204:207], v[156:159], v[100:103]
	v_mfma_f32_16x16x32_bf16 v[96:99], v[214:217], v[156:159], v[96:99]
	v_mfma_f32_16x16x32_bf16 v[84:87], v[204:207], v[174:177], v[84:87]
	v_mfma_f32_16x16x32_bf16 v[80:83], v[214:217], v[174:177], v[80:83]
	v_mfma_f32_16x16x32_bf16 v[68:71], v[204:207], v[186:189], v[68:71]
	v_mfma_f32_16x16x32_bf16 v[64:67], v[214:217], v[186:189], v[64:67]
	s_barrier
	ds_read_b128 v[144:147], v185 offset:16384
	ds_read_b128 v[148:151], v185 offset:17408
	ds_read_b128 v[152:155], v185 offset:18432
	ds_read_b128 v[156:159], v185 offset:19456
	ds_read_b128 v[170:173], v185 offset:20480
	ds_read_b128 v[174:177], v185 offset:21504
	ds_read_b128 v[178:181], v185 offset:22528
	ds_read_b128 v[186:189], v185 offset:23552
	global_load_lds_dwordx4 v160, s[18:19]
	s_mov_b32 m0, s29
	s_nop 0
	global_load_lds_dwordx4 v162, s[18:19]
	s_barrier
	s_waitcnt lgkmcnt(0)
	v_mfma_f32_16x16x32_bf16 v[60:63], v[128:131], v[144:147], v[60:63]
	v_mfma_f32_16x16x32_bf16 v[56:59], v[136:139], v[144:147], v[56:59]
	v_mfma_f32_16x16x32_bf16 v[44:47], v[128:131], v[152:155], v[44:47]
	v_mfma_f32_16x16x32_bf16 v[40:43], v[136:139], v[152:155], v[40:43]
	s_add_u32 s44, s16, 0x80000
	s_addc_u32 s45, s17, 0
	v_mfma_f32_16x16x32_bf16 v[28:31], v[128:131], v[170:173], v[28:31]
	s_add_i32 s43, s46, s27
	s_mov_b32 m0, s43
	v_mfma_f32_16x16x32_bf16 v[24:27], v[136:139], v[170:173], v[24:27]
	v_mfma_f32_16x16x32_bf16 v[12:15], v[128:131], v[178:181], v[12:15]
	v_mfma_f32_16x16x32_bf16 v[8:11], v[136:139], v[178:181], v[8:11]
	v_mfma_f32_16x16x32_bf16 v[60:63], v[132:135], v[148:151], v[60:63]
	v_mfma_f32_16x16x32_bf16 v[56:59], v[140:143], v[148:151], v[56:59]
	v_mfma_f32_16x16x32_bf16 v[44:47], v[132:135], v[156:159], v[44:47]
	v_mfma_f32_16x16x32_bf16 v[40:43], v[140:143], v[156:159], v[40:43]
	v_mfma_f32_16x16x32_bf16 v[28:31], v[132:135], v[174:177], v[28:31]
	v_mfma_f32_16x16x32_bf16 v[24:27], v[140:143], v[174:177], v[24:27]
	v_mfma_f32_16x16x32_bf16 v[12:15], v[132:135], v[186:189], v[12:15]
	v_mfma_f32_16x16x32_bf16 v[8:11], v[140:143], v[186:189], v[8:11]
	s_barrier
	global_load_lds_dwordx4 v192, s[44:45]
	s_add_i32 m0, s43, 0x2000
	s_nop 0
	global_load_lds_dwordx4 v164, s[44:45]
	s_waitcnt vmcnt(6)
	s_barrier
	v_mfma_f32_16x16x32_bf16 v[52:55], v[196:199], v[144:147], v[52:55]
	v_mfma_f32_16x16x32_bf16 v[48:51], v[208:211], v[144:147], v[48:51]
	v_mfma_f32_16x16x32_bf16 v[36:39], v[196:199], v[152:155], v[36:39]
	v_mfma_f32_16x16x32_bf16 v[32:35], v[208:211], v[152:155], v[32:35]
	s_add_i32 s43, 0, 0x18000
	v_mfma_f32_16x16x32_bf16 v[20:23], v[196:199], v[170:173], v[20:23]
	s_add_u32 s18, s18, 0x80000
	s_addc_u32 s19, s19, 0
	v_mfma_f32_16x16x32_bf16 v[16:19], v[208:211], v[170:173], v[16:19]
	s_mov_b32 m0, s30
	v_mfma_f32_16x16x32_bf16 v[4:7], v[196:199], v[178:181], v[4:7]
	v_mfma_f32_16x16x32_bf16 v[0:3], v[208:211], v[178:181], v[0:3]
	v_mfma_f32_16x16x32_bf16 v[52:55], v[204:207], v[148:151], v[52:55]
	v_mfma_f32_16x16x32_bf16 v[48:51], v[214:217], v[148:151], v[48:51]
	v_mfma_f32_16x16x32_bf16 v[36:39], v[204:207], v[156:159], v[36:39]
	v_mfma_f32_16x16x32_bf16 v[32:35], v[214:217], v[156:159], v[32:35]
	v_mfma_f32_16x16x32_bf16 v[20:23], v[204:207], v[174:177], v[20:23]
	v_mfma_f32_16x16x32_bf16 v[16:19], v[214:217], v[174:177], v[16:19]
	v_mfma_f32_16x16x32_bf16 v[4:7], v[204:207], v[186:189], v[4:7]
	v_mfma_f32_16x16x32_bf16 v[0:3], v[214:217], v[186:189], v[0:3]
	s_barrier
	ds_read_b128 v[128:131], v220 offset:32768
	ds_read_b128 v[132:135], v220 offset:33792
	ds_read_b128 v[136:139], v220 offset:34816
	ds_read_b128 v[140:143], v220 offset:35840
	ds_read_b128 v[144:147], v185 offset:32768
	ds_read_b128 v[148:151], v185 offset:33792
	ds_read_b128 v[152:155], v185 offset:34816
	ds_read_b128 v[156:159], v185 offset:35840
	ds_read_b128 v[170:173], v185 offset:36864
	ds_read_b128 v[174:177], v185 offset:37888
	ds_read_b128 v[178:181], v185 offset:38912
	ds_read_b128 v[186:189], v185 offset:39936
	global_load_lds_dwordx4 v160, s[18:19]
	s_mov_b32 m0, s31
	s_nop 0
	global_load_lds_dwordx4 v162, s[18:19]
	s_waitcnt lgkmcnt(8)
	s_barrier
	s_waitcnt lgkmcnt(0)
	v_mfma_f32_16x16x32_bf16 v[124:127], v[128:131], v[144:147], v[124:127]
	v_mfma_f32_16x16x32_bf16 v[120:123], v[136:139], v[144:147], v[120:123]
	v_mfma_f32_16x16x32_bf16 v[108:111], v[128:131], v[152:155], v[108:111]
	v_mfma_f32_16x16x32_bf16 v[104:107], v[136:139], v[152:155], v[104:107]
	s_add_i32 s18, 0, 0x1c000
	s_add_i32 s19, s43, s27
	v_mfma_f32_16x16x32_bf16 v[92:95], v[128:131], v[170:173], v[92:95]
	s_add_i32 m0, s19, 0xffffff80
	v_mfma_f32_16x16x32_bf16 v[88:91], v[136:139], v[170:173], v[88:91]
	v_mfma_f32_16x16x32_bf16 v[76:79], v[128:131], v[178:181], v[76:79]
	v_mfma_f32_16x16x32_bf16 v[72:75], v[136:139], v[178:181], v[72:75]
	v_mfma_f32_16x16x32_bf16 v[124:127], v[132:135], v[148:151], v[124:127]
	v_mfma_f32_16x16x32_bf16 v[120:123], v[140:143], v[148:151], v[120:123]
	v_mfma_f32_16x16x32_bf16 v[108:111], v[132:135], v[156:159], v[108:111]
	v_mfma_f32_16x16x32_bf16 v[104:107], v[140:143], v[156:159], v[104:107]
	v_mfma_f32_16x16x32_bf16 v[92:95], v[132:135], v[174:177], v[92:95]
	v_mfma_f32_16x16x32_bf16 v[88:91], v[140:143], v[174:177], v[88:91]
	v_mfma_f32_16x16x32_bf16 v[76:79], v[132:135], v[186:189], v[76:79]
	v_mfma_f32_16x16x32_bf16 v[72:75], v[140:143], v[186:189], v[72:75]
	s_barrier
	ds_read_b128 v[196:199], v220 offset:49152
	ds_read_b128 v[204:207], v220 offset:50176
	ds_read_b128 v[208:211], v220 offset:51200
	ds_read_b128 v[214:217], v220 offset:52224
	global_load_lds_dwordx4 v192, s[16:17] offset:128
	s_add_i32 m0, s19, 0x1f80
	s_nop 0
	global_load_lds_dwordx4 v164, s[16:17] offset:128
	s_barrier
	s_waitcnt lgkmcnt(0)
	v_mfma_f32_16x16x32_bf16 v[116:119], v[196:199], v[144:147], v[116:119]
	v_mfma_f32_16x16x32_bf16 v[112:115], v[208:211], v[144:147], v[112:115]
	v_mfma_f32_16x16x32_bf16 v[100:103], v[196:199], v[152:155], v[100:103]
	v_mfma_f32_16x16x32_bf16 v[96:99], v[208:211], v[152:155], v[96:99]
	s_mov_b32 m0, s35
	v_mfma_f32_16x16x32_bf16 v[84:87], v[196:199], v[170:173], v[84:87]
	v_mfma_f32_16x16x32_bf16 v[80:83], v[208:211], v[170:173], v[80:83]
	v_mfma_f32_16x16x32_bf16 v[68:71], v[196:199], v[178:181], v[68:71]
	v_mfma_f32_16x16x32_bf16 v[64:67], v[208:211], v[178:181], v[64:67]
	v_mfma_f32_16x16x32_bf16 v[116:119], v[204:207], v[148:151], v[116:119]
	v_mfma_f32_16x16x32_bf16 v[112:115], v[214:217], v[148:151], v[112:115]
	v_mfma_f32_16x16x32_bf16 v[100:103], v[204:207], v[156:159], v[100:103]
	v_mfma_f32_16x16x32_bf16 v[96:99], v[214:217], v[156:159], v[96:99]
	v_mfma_f32_16x16x32_bf16 v[84:87], v[204:207], v[174:177], v[84:87]
	v_mfma_f32_16x16x32_bf16 v[80:83], v[214:217], v[174:177], v[80:83]
	v_mfma_f32_16x16x32_bf16 v[68:71], v[204:207], v[186:189], v[68:71]
	v_mfma_f32_16x16x32_bf16 v[64:67], v[214:217], v[186:189], v[64:67]
	s_barrier
	ds_read_b128 v[144:147], v185 offset:49152
	ds_read_b128 v[148:151], v185 offset:50176
	ds_read_b128 v[152:155], v185 offset:51200
	ds_read_b128 v[156:159], v185 offset:52224
	ds_read_b128 v[170:173], v185 offset:53248
	ds_read_b128 v[174:177], v185 offset:54272
	ds_read_b128 v[178:181], v185 offset:55296
	ds_read_b128 v[186:189], v185 offset:56320
	global_load_lds_dwordx4 v160, s[48:49]
	s_mov_b32 m0, s36
	s_nop 0
	global_load_lds_dwordx4 v162, s[48:49]
	s_barrier
	s_waitcnt lgkmcnt(0)
	v_mfma_f32_16x16x32_bf16 v[60:63], v[128:131], v[144:147], v[60:63]
	v_mfma_f32_16x16x32_bf16 v[56:59], v[136:139], v[144:147], v[56:59]
	v_mfma_f32_16x16x32_bf16 v[44:47], v[128:131], v[152:155], v[44:47]
	v_mfma_f32_16x16x32_bf16 v[40:43], v[136:139], v[152:155], v[40:43]
	s_add_u32 s16, s16, 0x80080
	s_addc_u32 s17, s17, 0
	v_mfma_f32_16x16x32_bf16 v[28:31], v[128:131], v[170:173], v[28:31]
	s_add_i32 s18, s18, s27
	s_mov_b32 m0, s18
	v_mfma_f32_16x16x32_bf16 v[24:27], v[136:139], v[170:173], v[24:27]
	v_mfma_f32_16x16x32_bf16 v[12:15], v[128:131], v[178:181], v[12:15]
	v_mfma_f32_16x16x32_bf16 v[8:11], v[136:139], v[178:181], v[8:11]
	v_mfma_f32_16x16x32_bf16 v[60:63], v[132:135], v[148:151], v[60:63]
	v_mfma_f32_16x16x32_bf16 v[56:59], v[140:143], v[148:151], v[56:59]
	v_mfma_f32_16x16x32_bf16 v[44:47], v[132:135], v[156:159], v[44:47]
	v_mfma_f32_16x16x32_bf16 v[40:43], v[140:143], v[156:159], v[40:43]
	v_mfma_f32_16x16x32_bf16 v[28:31], v[132:135], v[174:177], v[28:31]
	v_mfma_f32_16x16x32_bf16 v[24:27], v[140:143], v[174:177], v[24:27]
	v_mfma_f32_16x16x32_bf16 v[12:15], v[132:135], v[186:189], v[12:15]
	v_mfma_f32_16x16x32_bf16 v[8:11], v[140:143], v[186:189], v[8:11]
	s_barrier
	global_load_lds_dwordx4 v192, s[16:17]
	s_add_i32 m0, s18, 0x2000
	s_nop 0
	global_load_lds_dwordx4 v164, s[16:17]
	s_waitcnt vmcnt(6)
	s_barrier
	v_mfma_f32_16x16x32_bf16 v[52:55], v[196:199], v[144:147], v[52:55]
	v_mfma_f32_16x16x32_bf16 v[48:51], v[208:211], v[144:147], v[48:51]
	v_mfma_f32_16x16x32_bf16 v[36:39], v[196:199], v[152:155], v[36:39]
	v_mfma_f32_16x16x32_bf16 v[32:35], v[208:211], v[152:155], v[32:35]
	s_add_i32 s42, s42, 2
	v_mfma_f32_16x16x32_bf16 v[20:23], v[196:199], v[170:173], v[20:23]
	s_add_u32 s14, s14, 0x100
	s_addc_u32 s15, s15, 0
	v_mfma_f32_16x16x32_bf16 v[16:19], v[208:211], v[170:173], v[16:19]
	s_add_u32 s40, s40, 0x100
	s_addc_u32 s41, s41, 0
	v_mfma_f32_16x16x32_bf16 v[4:7], v[196:199], v[178:181], v[4:7]
	v_mfma_f32_16x16x32_bf16 v[0:3], v[208:211], v[178:181], v[0:3]
	v_mfma_f32_16x16x32_bf16 v[52:55], v[204:207], v[148:151], v[52:55]
	v_mfma_f32_16x16x32_bf16 v[48:51], v[214:217], v[148:151], v[48:51]
	v_mfma_f32_16x16x32_bf16 v[36:39], v[204:207], v[156:159], v[36:39]
	v_mfma_f32_16x16x32_bf16 v[32:35], v[214:217], v[156:159], v[32:35]
	v_mfma_f32_16x16x32_bf16 v[20:23], v[204:207], v[174:177], v[20:23]
	v_mfma_f32_16x16x32_bf16 v[16:19], v[214:217], v[174:177], v[16:19]
	v_mfma_f32_16x16x32_bf16 v[4:7], v[204:207], v[186:189], v[4:7]
	v_mfma_f32_16x16x32_bf16 v[0:3], v[214:217], v[186:189], v[0:3]
	s_cmp_gt_u32 s42, 29
	s_barrier
	s_cbranch_scc0 .LBB0_87
	v_lshl_or_b32 v128, s13, 8, v184
	v_lshl_add_u32 v172, s12, 8, v182
	v_ashrrev_i32_e32 v129, 31, v128
	v_lshlrev_b64 v[170:171], 1, v[128:129]
	v_ashrrev_i32_e32 v173, 31, v172
	v_lshl_add_u64 v[174:175], s[2:3], 0, v[170:171]
	v_lshlrev_b64 v[128:129], 13, v[172:173]
	v_lshl_add_u64 v[130:131], v[174:175], 0, v[128:129]
	global_load_dwordx4 v[186:189], v[130:131], off
	global_load_dwordx4 v[196:199], v[130:131], off offset:256
	s_lshl_b32 s5, s13, 1
	v_mul_f32_e32 v133, 0xbfb8aa3b, v124
	v_mul_f32_e32 v135, 0xbfb8aa3b, v125
	v_mul_f32_e32 v137, 0xbfb8aa3b, v126
	v_mul_f32_e32 v138, 0xbfb8aa3b, v127
	v_mul_f32_e32 v139, 0xbfb8aa3b, v120
	v_mul_f32_e32 v140, 0xbfb8aa3b, v121
	s_and_b32 s12, s5, -4
	v_or_b32_e32 v132, 16, v172
	v_or_b32_e32 v136, 48, v172
	v_exp_f32_e32 v148, v133
	v_exp_f32_e32 v149, v135
	v_exp_f32_e32 v150, v137
	v_exp_f32_e32 v151, v138
	v_exp_f32_e32 v204, v139
	v_exp_f32_e32 v205, v140
	s_ashr_i32 s13, s12, 31
	v_or_b32_e32 v134, 32, v172
	v_ashrrev_i32_e32 v133, 31, v132
	v_ashrrev_i32_e32 v137, 31, v136
	s_lshl_b64 s[12:13], s[12:13], 2
	v_mul_f32_e32 v141, 0xbfb8aa3b, v122
	v_ashrrev_i32_e32 v135, 31, v134
	v_lshlrev_b64 v[180:181], 13, v[132:133]
	v_lshlrev_b64 v[176:177], 13, v[136:137]
	s_add_u32 s12, s33, s12
	v_exp_f32_e32 v212, v141
	v_lshlrev_b64 v[138:139], 7, v[172:173]
	v_lshlrev_b64 v[140:141], 7, v[132:133]
	v_lshlrev_b64 v[142:143], 7, v[134:135]
	v_lshlrev_b64 v[178:179], 13, v[134:135]
	v_lshlrev_b64 v[144:145], 7, v[136:137]
	v_lshl_add_u64 v[128:129], s[2:3], 0, v[128:129]
	v_lshl_add_u64 v[130:131], v[174:175], 0, v[180:181]
	v_lshl_add_u64 v[136:137], v[174:175], 0, v[176:177]
	s_addc_u32 s13, s34, s13
	v_lshl_add_u64 v[146:147], v[174:175], 0, v[178:179]
	v_lshl_add_u64 v[190:191], v[128:129], 0, v[170:171]
	global_load_dwordx4 v[156:159], v[130:131], off
	global_load_dwordx4 v[152:155], v[130:131], off offset:256
	global_load_dwordx4 v[132:135], v[136:137], off
	s_nop 0
	global_load_dwordx4 v[128:131], v[136:137], off offset:256
	v_add_f32_e32 v148, 1.0, v148
	v_add_f32_e32 v149, 1.0, v149
	v_add_f32_e32 v150, 1.0, v150
	v_add_f32_e32 v151, 1.0, v151
	v_add_f32_e32 v173, 1.0, v204
	v_add_f32_e32 v204, 1.0, v205
	v_lshl_add_u64 v[136:137], s[12:13], 0, v[138:139]
	v_lshl_add_u64 v[138:139], s[12:13], 0, v[140:141]
	v_lshl_add_u64 v[140:141], s[12:13], 0, v[142:143]
	v_lshl_add_u64 v[144:145], s[12:13], 0, v[144:145]
	v_rcp_f32_e32 v214, v148
	v_rcp_f32_e32 v215, v149
	v_rcp_f32_e32 v216, v150
	v_rcp_f32_e32 v217, v151
	v_rcp_f32_e32 v218, v204
	global_load_dwordx4 v[204:207], v[136:137], off
	global_load_dwordx4 v[208:211], v[138:139], off
	s_nop 0
	global_load_dwordx4 v[136:139], v[140:141], off
	global_load_dwordx4 v[148:151], v[146:147], off
	s_nop 0
	global_load_dwordx4 v[140:143], v[146:147], off offset:256
	s_nop 0
	global_load_dwordx4 v[144:147], v[144:145], off
	v_rcp_f32_e32 v173, v173
	v_mul_f32_e32 v124, v124, v214
	v_mul_f32_e32 v125, v125, v215
	v_mul_f32_e32 v127, v127, v217
	v_mul_f32_e32 v120, v120, v173
	v_mul_f32_e32 v121, v121, v218
	s_mov_b32 s14, 0x358637bd
	s_mov_b32 s5, 0x800000
	v_mul_f32_e32 v126, v126, v216
	s_mov_b64 s[16:17], s[10:11]
	s_mov_b32 s11, 0xc000
	s_waitcnt vmcnt(0)
	v_lshlrev_b32_e32 v173, 16, v186
	v_and_b32_e32 v186, 0xffff0000, v186
	v_lshlrev_b32_e32 v214, 16, v187
	v_and_b32_e32 v187, 0xffff0000, v187
	v_mul_f32_e32 v125, v125, v186
	v_mul_f32_e32 v127, v127, v187
	v_add_f32_e32 v186, 1.0, v212
	v_mul_f32_e32 v187, 0xbfb8aa3b, v123
	v_rcp_f32_e32 v186, v186
	v_exp_f32_e32 v187, v187
	v_mul_f32_e32 v124, v124, v173
	v_and_b32_e32 v173, 0xffff0000, v188
	v_mul_f32_e32 v122, v122, v186
	v_add_f32_e32 v186, 1.0, v187
	v_mul_f32_e32 v187, 0xbfb8aa3b, v116
	v_rcp_f32_e32 v186, v186
	v_exp_f32_e32 v187, v187
	v_mul_f32_e32 v121, v121, v173
	v_lshlrev_b32_e32 v173, 16, v189
	v_mul_f32_e32 v123, v123, v186
	v_add_f32_e32 v186, 1.0, v187
	v_mul_f32_e32 v187, 0xbfb8aa3b, v117
	v_rcp_f32_e32 v186, v186
	v_exp_f32_e32 v187, v187
	v_mul_f32_e32 v122, v122, v173
	v_and_b32_e32 v173, 0xffff0000, v189
	v_mul_f32_e32 v116, v116, v186
	v_add_f32_e32 v186, 1.0, v187
	v_mul_f32_e32 v187, 0xbfb8aa3b, v118
	v_rcp_f32_e32 v186, v186
	v_exp_f32_e32 v187, v187
	v_mul_f32_e32 v123, v123, v173
	v_lshlrev_b32_e32 v173, 16, v196
	v_mul_f32_e32 v173, v116, v173
	v_mul_f32_e32 v116, v117, v186
	v_add_f32_e32 v186, 1.0, v187
	v_mul_f32_e32 v187, 0xbfb8aa3b, v119
	v_rcp_f32_e32 v186, v186
	v_exp_f32_e32 v187, v187
	v_and_b32_e32 v117, 0xffff0000, v196
	v_lshlrev_b32_e32 v215, 16, v188
	v_mul_f32_e32 v188, v116, v117
	v_mul_f32_e32 v116, v118, v186
	v_add_f32_e32 v118, 1.0, v187
	v_rcp_f32_e32 v118, v118
	v_mul_f32_e32 v186, 0xbfb8aa3b, v112
	v_exp_f32_e32 v186, v186
	v_lshlrev_b32_e32 v117, 16, v197
	v_mul_f32_e32 v187, v116, v117
	v_mul_f32_e32 v116, v119, v118
	v_mul_f32_e32 v119, 0xbfb8aa3b, v113
	v_add_f32_e32 v118, 1.0, v186
	v_exp_f32_e32 v119, v119
	v_rcp_f32_e32 v118, v118
	v_and_b32_e32 v117, 0xffff0000, v197
	v_mul_f32_e32 v186, v116, v117
	v_add_f32_e32 v117, 1.0, v119
	v_mul_f32_e32 v112, v112, v118
	v_rcp_f32_e32 v117, v117
	v_mul_f32_e32 v118, 0xbfb8aa3b, v114
	v_exp_f32_e32 v118, v118
	v_lshlrev_b32_e32 v116, 16, v198
	v_mul_f32_e32 v189, v112, v116
	v_mul_f32_e32 v112, v113, v117
	v_and_b32_e32 v113, 0xffff0000, v198
	v_add_f32_e32 v116, 1.0, v118
	v_mul_f32_e32 v196, v112, v113
	v_mul_f32_e32 v112, 0xbfb8aa3b, v115
	v_rcp_f32_e32 v116, v116
	v_exp_f32_e32 v112, v112
	v_mov_b32_e32 v117, v206
	v_mov_b32_e32 v206, v211
	v_mul_f32_e32 v113, v114, v116
	v_lshlrev_b32_e32 v114, 16, v199
	v_add_f32_e32 v112, 1.0, v112
	v_mul_f32_e32 v197, v113, v114
	v_rcp_f32_e32 v114, v112
	v_mov_b32_e32 v112, v208
	v_mov_b32_e32 v113, v204
	v_mov_b32_e32 v204, v209
	v_pk_add_f32 v[112:113], v[112:113], v[204:205]
	v_mov_b32_e32 v116, v210
	v_pk_add_f32 v[112:113], v[116:117], v[112:113]
	v_mul_f32_e32 v114, v115, v114
	v_pk_add_f32 v[116:117], v[206:207], v[112:113]
	v_mov_b64_e32 v[112:113], s[14:15]
	s_mov_b32 s14, 0x3b000000
	v_pk_fma_f32 v[118:119], v[116:117], s[14:15], v[112:113] op_sel_hi:[1,0,0]
	v_and_b32_e32 v115, 0xffff0000, v199
	v_mul_f32_e32 v116, 0x4b800000, v119
	v_cmp_gt_f32_e32 vcc, s5, v119
	v_mul_f32_e32 v126, v126, v214
	v_mul_f32_e32 v120, v120, v215
	v_cndmask_b32_e32 v116, v119, v116, vcc
	v_rsq_f32_e32 v116, v116
	v_mul_f32_e32 v119, v114, v115
	v_mul_f32_e32 v114, 0x45800000, v116
	v_cndmask_b32_e32 v198, v116, v114, vcc
	v_mul_f32_e32 v114, v124, v198
	v_mul_f32_e32 v115, v125, v198
	v_cvt_pk_bf16_f32 v114, v114, v115
	v_mul_f32_e32 v115, v126, v198
	v_mul_f32_e32 v116, v127, v198
	v_cvt_pk_bf16_f32 v115, v115, v116
	v_mul_f32_e32 v116, v120, v198
	v_mul_f32_e32 v117, v121, v198
	v_cvt_pk_bf16_f32 v116, v116, v117
	v_mul_f32_e32 v117, v122, v198
	v_mul_f32_e32 v120, v123, v198
	v_cvt_pk_bf16_f32 v117, v117, v120
	global_store_dwordx4 v[190:191], v[114:117], off
	v_mul_f32_e32 v119, v119, v198
	v_cmp_gt_f32_e32 vcc, s5, v118
	v_mul_f32_e32 v114, v173, v198
	v_mul_f32_e32 v115, v188, v198
	v_cvt_pk_bf16_f32 v114, v114, v115
	v_mul_f32_e32 v115, v187, v198
	v_mul_f32_e32 v116, v186, v198
	v_cvt_pk_bf16_f32 v115, v115, v116
	v_mul_f32_e32 v116, v189, v198
	v_mul_f32_e32 v117, v196, v198
	v_cvt_pk_bf16_f32 v116, v116, v117
	v_mul_f32_e32 v117, v197, v198
	v_cvt_pk_bf16_f32 v117, v117, v119
	v_mul_f32_e32 v119, 0x4b800000, v118
	v_cndmask_b32_e32 v118, v118, v119, vcc
	global_store_dwordx4 v[190:191], v[114:117], off offset:256
	v_rsq_f32_e32 v118, v118
	v_mul_f32_e32 v123, 0xbfb8aa3b, v61
	v_mul_f32_e32 v114, 0xbfb8aa3b, v108
	v_exp_f32_e32 v116, v114
	v_mul_f32_e32 v114, 0x45800000, v118
	v_cndmask_b32_e32 v117, v118, v114, vcc
	v_mul_f32_e32 v118, 0xbfb8aa3b, v109
	v_add_f32_e32 v116, 1.0, v116
	v_rcp_f32_e32 v116, v116
	v_exp_f32_e32 v118, v118
	v_lshl_add_u64 v[114:115], s[2:3], 0, v[180:181]
	v_lshl_add_u64 v[114:115], v[114:115], 0, v[170:171]
	v_mul_f32_e32 v108, v108, v116
	v_lshlrev_b32_e32 v116, 16, v156
	v_mul_f32_e32 v108, v108, v116
	v_add_f32_e32 v116, 1.0, v118
	v_rcp_f32_e32 v116, v116
	v_mul_f32_e32 v118, 0xbfb8aa3b, v110
	v_exp_f32_e32 v118, v118
	v_mul_f32_e32 v108, v108, v117
	v_mul_f32_e32 v109, v109, v116
	v_and_b32_e32 v116, 0xffff0000, v156
	v_mul_f32_e32 v109, v109, v116
	v_add_f32_e32 v116, 1.0, v118
	v_mul_f32_e32 v118, 0xbfb8aa3b, v111
	v_rcp_f32_e32 v116, v116
	v_exp_f32_e32 v118, v118
	v_mul_f32_e32 v109, v109, v117
	v_cvt_pk_bf16_f32 v108, v108, v109
	v_mul_f32_e32 v109, v110, v116
	v_add_f32_e32 v110, 1.0, v118
	v_rcp_f32_e32 v110, v110
	v_lshlrev_b32_e32 v116, 16, v157
	v_mul_f32_e32 v109, v109, v116
	v_and_b32_e32 v116, 0xffff0000, v157
	v_mul_f32_e32 v110, v111, v110
	v_mul_f32_e32 v111, 0xbfb8aa3b, v104
	v_exp_f32_e32 v111, v111
	v_mul_f32_e32 v110, v110, v116
	v_mul_f32_e32 v109, v109, v117
	v_mul_f32_e32 v110, v110, v117
	v_add_f32_e32 v111, 1.0, v111
	v_cvt_pk_bf16_f32 v109, v109, v110
	v_mul_f32_e32 v110, 0xbfb8aa3b, v105
	v_rcp_f32_e32 v111, v111
	v_exp_f32_e32 v110, v110
	v_exp_f32_e32 v123, v123
	v_mul_f32_e32 v124, 0xbfb8aa3b, v62
	v_mul_f32_e32 v104, v104, v111
	v_lshlrev_b32_e32 v111, 16, v158
	v_add_f32_e32 v110, 1.0, v110
	v_mul_f32_e32 v104, v104, v111
	v_rcp_f32_e32 v110, v110
	v_mul_f32_e32 v111, 0xbfb8aa3b, v106
	v_exp_f32_e32 v111, v111
	v_mul_f32_e32 v104, v104, v117
	v_mul_f32_e32 v105, v105, v110
	v_and_b32_e32 v110, 0xffff0000, v158
	v_mul_f32_e32 v105, v105, v110
	v_add_f32_e32 v110, 1.0, v111
	v_rcp_f32_e32 v111, v110
	v_mul_f32_e32 v110, 0xbfb8aa3b, v107
	v_exp_f32_e32 v116, v110
	v_mul_f32_e32 v105, v105, v117
	v_cvt_pk_bf16_f32 v110, v104, v105
	v_mul_f32_e32 v104, v106, v111
	v_add_f32_e32 v105, 1.0, v116
	v_rcp_f32_e32 v105, v105
	v_lshlrev_b32_e32 v106, 16, v159
	v_mul_f32_e32 v104, v104, v106
	v_and_b32_e32 v106, 0xffff0000, v159
	v_mul_f32_e32 v105, v107, v105
	v_mul_f32_e32 v107, 0xbfb8aa3b, v100
	v_exp_f32_e32 v107, v107
	v_mul_f32_e32 v104, v104, v117
	v_mul_f32_e32 v105, v105, v106
	v_mul_f32_e32 v105, v105, v117
	v_cvt_pk_bf16_f32 v111, v104, v105
	v_add_f32_e32 v104, 1.0, v107
	v_rcp_f32_e32 v104, v104
	v_mul_f32_e32 v105, 0xbfb8aa3b, v101
	v_exp_f32_e32 v105, v105
	global_store_dwordx4 v[114:115], v[108:111], off
	v_mul_f32_e32 v100, v100, v104
	v_lshlrev_b32_e32 v104, 16, v152
	v_mul_f32_e32 v100, v100, v104
	v_add_f32_e32 v104, 1.0, v105
	v_rcp_f32_e32 v104, v104
	v_mul_f32_e32 v105, 0xbfb8aa3b, v102
	v_exp_f32_e32 v105, v105
	v_mul_f32_e32 v100, v100, v117
	v_mul_f32_e32 v101, v101, v104
	v_and_b32_e32 v104, 0xffff0000, v152
	v_mul_f32_e32 v101, v101, v104
	v_add_f32_e32 v104, 1.0, v105
	v_mul_f32_e32 v105, 0xbfb8aa3b, v103
	v_rcp_f32_e32 v104, v104
	v_exp_f32_e32 v105, v105
	v_mul_f32_e32 v101, v101, v117
	v_cvt_pk_bf16_f32 v100, v100, v101
	v_mul_f32_e32 v101, v102, v104
	v_add_f32_e32 v102, 1.0, v105
	v_rcp_f32_e32 v102, v102
	v_lshlrev_b32_e32 v104, 16, v153
	v_mul_f32_e32 v101, v101, v104
	v_and_b32_e32 v104, 0xffff0000, v153
	v_mul_f32_e32 v102, v103, v102
	v_mul_f32_e32 v103, 0xbfb8aa3b, v96
	v_exp_f32_e32 v103, v103
	v_mul_f32_e32 v102, v102, v104
	v_mul_f32_e32 v101, v101, v117
	v_mul_f32_e32 v102, v102, v117
	v_add_f32_e32 v103, 1.0, v103
	v_cvt_pk_bf16_f32 v101, v101, v102
	v_mul_f32_e32 v102, 0xbfb8aa3b, v97
	v_rcp_f32_e32 v103, v103
	v_exp_f32_e32 v102, v102
	v_add_f32_e32 v123, 1.0, v123
	v_rcp_f32_e32 v123, v123
	v_mul_f32_e32 v96, v96, v103
	v_lshlrev_b32_e32 v103, 16, v154
	v_add_f32_e32 v102, 1.0, v102
	v_mul_f32_e32 v96, v96, v103
	v_rcp_f32_e32 v102, v102
	v_mul_f32_e32 v103, 0xbfb8aa3b, v98
	v_exp_f32_e32 v103, v103
	v_mul_f32_e32 v96, v96, v117
	v_mul_f32_e32 v97, v97, v102
	v_and_b32_e32 v102, 0xffff0000, v154
	v_mul_f32_e32 v97, v97, v102
	v_add_f32_e32 v102, 1.0, v103
	v_rcp_f32_e32 v103, v102
	v_mul_f32_e32 v102, 0xbfb8aa3b, v99
	v_exp_f32_e32 v104, v102
	v_mul_f32_e32 v97, v97, v117
	v_cvt_pk_bf16_f32 v102, v96, v97
	v_mul_f32_e32 v96, v98, v103
	v_add_f32_e32 v97, 1.0, v104
	v_rcp_f32_e32 v97, v97
	v_lshlrev_b32_e32 v98, 16, v155
	v_mul_f32_e32 v96, v96, v98
	v_and_b32_e32 v98, 0xffff0000, v155
	v_mul_f32_e32 v97, v99, v97
	v_mul_f32_e32 v99, 0xbfb8aa3b, v93
	v_exp_f32_e32 v99, v99
	v_mul_f32_e32 v97, v97, v98
	v_mul_f32_e32 v96, v96, v117
	v_mul_f32_e32 v97, v97, v117
	v_cvt_pk_bf16_f32 v103, v96, v97
	global_store_dwordx4 v[114:115], v[100:103], off offset:256
	v_add_f32_e32 v99, 1.0, v99
	v_rcp_f32_e32 v99, v99
	v_mul_f32_e32 v100, 0xbfb8aa3b, v94
	v_exp_f32_e32 v100, v100
	v_mul_f32_e32 v98, 0xbfb8aa3b, v92
	v_mul_f32_e32 v93, v93, v99
	v_exp_f32_e32 v98, v98
	v_add_f32_e32 v99, 1.0, v100
	v_mul_f32_e32 v100, 0xbfb8aa3b, v95
	v_rcp_f32_e32 v99, v99
	v_exp_f32_e32 v100, v100
	v_add_f32_e32 v98, 1.0, v98
	v_rcp_f32_e32 v98, v98
	v_mul_f32_e32 v94, v94, v99
	v_add_f32_e32 v99, 1.0, v100
	v_mul_f32_e32 v100, 0xbfb8aa3b, v88
	v_rcp_f32_e32 v99, v99
	v_exp_f32_e32 v100, v100
	v_mul_f32_e32 v92, v92, v98
	v_lshlrev_b32_e32 v98, 16, v148
	v_mul_f32_e32 v95, v95, v99
	v_add_f32_e32 v99, 1.0, v100
	v_mul_f32_e32 v100, 0xbfb8aa3b, v89
	v_rcp_f32_e32 v99, v99
	v_exp_f32_e32 v100, v100
	v_mul_f32_e32 v92, v92, v98
	v_and_b32_e32 v98, 0xffff0000, v148
	v_mul_f32_e32 v88, v88, v99
	v_add_f32_e32 v99, 1.0, v100
	v_mul_f32_e32 v100, 0xbfb8aa3b, v90
	v_rcp_f32_e32 v99, v99
	v_exp_f32_e32 v100, v100
	v_mul_f32_e32 v93, v93, v98
	v_lshlrev_b32_e32 v98, 16, v149
	v_mul_f32_e32 v89, v89, v99
	v_add_f32_e32 v99, 1.0, v100
	v_mul_f32_e32 v100, 0xbfb8aa3b, v91
	v_rcp_f32_e32 v99, v99
	v_exp_f32_e32 v100, v100
	v_mul_f32_e32 v94, v94, v98
	v_and_b32_e32 v98, 0xffff0000, v149
	v_mul_f32_e32 v90, v90, v99
	v_add_f32_e32 v99, 1.0, v100
	v_mul_f32_e32 v100, 0xbfb8aa3b, v84
	v_rcp_f32_e32 v99, v99
	v_exp_f32_e32 v100, v100
	v_mul_f32_e32 v95, v95, v98
	v_lshlrev_b32_e32 v98, 16, v150
	v_mul_f32_e32 v91, v91, v99
	v_add_f32_e32 v99, 1.0, v100
	v_mul_f32_e32 v100, 0xbfb8aa3b, v85
	v_rcp_f32_e32 v99, v99
	v_exp_f32_e32 v100, v100
	v_mul_f32_e32 v88, v88, v98
	v_and_b32_e32 v98, 0xffff0000, v150
	v_mul_f32_e32 v84, v84, v99
	v_add_f32_e32 v99, 1.0, v100
	v_mul_f32_e32 v100, 0xbfb8aa3b, v86
	v_rcp_f32_e32 v99, v99
	v_exp_f32_e32 v100, v100
	v_mul_f32_e32 v89, v89, v98
	v_lshlrev_b32_e32 v98, 16, v151
	v_mul_f32_e32 v90, v90, v98
	v_and_b32_e32 v98, 0xffff0000, v151
	v_mul_f32_e32 v91, v91, v98
	v_lshlrev_b32_e32 v98, 16, v140
	v_mul_f32_e32 v98, v84, v98
	v_mul_f32_e32 v84, v85, v99
	v_add_f32_e32 v99, 1.0, v100
	v_mul_f32_e32 v100, 0xbfb8aa3b, v87
	v_rcp_f32_e32 v99, v99
	v_exp_f32_e32 v100, v100
	v_and_b32_e32 v85, 0xffff0000, v140
	v_mul_f32_e32 v101, v84, v85
	v_mul_f32_e32 v84, v86, v99
	v_add_f32_e32 v86, 1.0, v100
	v_rcp_f32_e32 v86, v86
	v_mul_f32_e32 v99, 0xbfb8aa3b, v80
	v_exp_f32_e32 v99, v99
	v_lshlrev_b32_e32 v85, 16, v141
	v_mul_f32_e32 v100, v84, v85
	v_mul_f32_e32 v84, v87, v86
	v_mul_f32_e32 v87, 0xbfb8aa3b, v81
	v_add_f32_e32 v86, 1.0, v99
	v_exp_f32_e32 v87, v87
	v_rcp_f32_e32 v86, v86
	v_and_b32_e32 v85, 0xffff0000, v141
	v_mul_f32_e32 v99, v84, v85
	v_add_f32_e32 v85, 1.0, v87
	v_mul_f32_e32 v80, v80, v86
	v_rcp_f32_e32 v85, v85
	v_mul_f32_e32 v86, 0xbfb8aa3b, v82
	v_exp_f32_e32 v86, v86
	v_lshlrev_b32_e32 v84, 16, v142
	v_mul_f32_e32 v87, v80, v84
	v_mul_f32_e32 v80, v81, v85
	v_and_b32_e32 v81, 0xffff0000, v142
	v_add_f32_e32 v84, 1.0, v86
	v_mul_f32_e32 v86, v80, v81
	v_mul_f32_e32 v80, 0xbfb8aa3b, v83
	v_rcp_f32_e32 v84, v84
	v_exp_f32_e32 v80, v80
	v_mov_b32_e32 v85, v138
	v_mov_b32_e32 v138, v147
	v_mul_f32_e32 v81, v82, v84
	v_lshlrev_b32_e32 v82, 16, v143
	v_add_f32_e32 v80, 1.0, v80
	v_mul_f32_e32 v102, v81, v82
	v_rcp_f32_e32 v82, v80
	v_mov_b32_e32 v80, v144
	v_mov_b32_e32 v81, v136
	v_mov_b32_e32 v136, v145
	v_pk_add_f32 v[80:81], v[80:81], v[136:137]
	v_mov_b32_e32 v84, v146
	v_pk_add_f32 v[80:81], v[84:85], v[80:81]
	v_lshl_add_u64 v[96:97], s[2:3], 0, v[178:179]
	v_pk_add_f32 v[80:81], v[138:139], v[80:81]
	v_lshl_add_u64 v[96:97], v[96:97], 0, v[170:171]
	v_pk_fma_f32 v[84:85], v[80:81], s[14:15], v[112:113] op_sel_hi:[1,0,0]
	v_mul_f32_e32 v81, v83, v82
	v_mul_f32_e32 v80, 0x4b800000, v85
	v_cmp_gt_f32_e32 vcc, s5, v85
	v_and_b32_e32 v82, 0xffff0000, v143
	v_exp_f32_e32 v124, v124
	v_cndmask_b32_e32 v80, v85, v80, vcc
	v_rsq_f32_e32 v80, v80
	v_mul_f32_e32 v85, v81, v82
	v_mul_f32_e32 v61, v61, v123
	v_mul_f32_e32 v123, 0xbfb8aa3b, v63
	v_mul_f32_e32 v81, 0x45800000, v80
	v_cndmask_b32_e32 v103, v80, v81, vcc
	v_mul_f32_e32 v80, v92, v103
	v_mul_f32_e32 v81, v93, v103
	v_cvt_pk_bf16_f32 v80, v80, v81
	v_mul_f32_e32 v81, v94, v103
	v_mul_f32_e32 v82, v95, v103
	v_cvt_pk_bf16_f32 v81, v81, v82
	v_mul_f32_e32 v82, v88, v103
	v_mul_f32_e32 v83, v89, v103
	v_cvt_pk_bf16_f32 v82, v82, v83
	v_mul_f32_e32 v83, v90, v103
	v_mul_f32_e32 v88, v91, v103
	v_cvt_pk_bf16_f32 v83, v83, v88
	global_store_dwordx4 v[96:97], v[80:83], off
	v_mul_f32_e32 v85, v85, v103
	v_cmp_gt_f32_e32 vcc, s5, v84
	v_mul_f32_e32 v80, v98, v103
	v_mul_f32_e32 v81, v101, v103
	v_cvt_pk_bf16_f32 v80, v80, v81
	v_mul_f32_e32 v81, v100, v103
	v_mul_f32_e32 v82, v99, v103
	v_cvt_pk_bf16_f32 v81, v81, v82
	v_mul_f32_e32 v82, v87, v103
	v_mul_f32_e32 v83, v86, v103
	v_cvt_pk_bf16_f32 v82, v82, v83
	v_mul_f32_e32 v83, v102, v103
	v_cvt_pk_bf16_f32 v83, v83, v85
	v_mul_f32_e32 v85, 0x4b800000, v84
	v_cndmask_b32_e32 v84, v84, v85, vcc
	global_store_dwordx4 v[96:97], v[80:83], off offset:256
	v_rsq_f32_e32 v84, v84
	v_exp_f32_e32 v123, v123
	v_mul_f32_e32 v80, 0xbfb8aa3b, v76
	v_exp_f32_e32 v82, v80
	v_mul_f32_e32 v80, 0x45800000, v84
	v_cndmask_b32_e32 v83, v84, v80, vcc
	v_mul_f32_e32 v84, 0xbfb8aa3b, v77
	v_add_f32_e32 v82, 1.0, v82
	v_rcp_f32_e32 v82, v82
	v_exp_f32_e32 v84, v84
	v_lshl_add_u64 v[80:81], s[2:3], 0, v[176:177]
	v_lshl_add_u64 v[80:81], v[80:81], 0, v[170:171]
	v_mul_f32_e32 v76, v76, v82
	v_lshlrev_b32_e32 v82, 16, v132
	v_mul_f32_e32 v76, v76, v82
	v_add_f32_e32 v82, 1.0, v84
	v_rcp_f32_e32 v82, v82
	v_mul_f32_e32 v84, 0xbfb8aa3b, v78
	v_exp_f32_e32 v84, v84
	v_mul_f32_e32 v76, v76, v83
	v_mul_f32_e32 v77, v77, v82
	v_and_b32_e32 v82, 0xffff0000, v132
	v_mul_f32_e32 v77, v77, v82
	v_add_f32_e32 v82, 1.0, v84
	v_mul_f32_e32 v84, 0xbfb8aa3b, v79
	v_rcp_f32_e32 v82, v82
	v_exp_f32_e32 v84, v84
	v_mul_f32_e32 v77, v77, v83
	v_cvt_pk_bf16_f32 v76, v76, v77
	v_mul_f32_e32 v77, v78, v82
	v_add_f32_e32 v78, 1.0, v84
	v_rcp_f32_e32 v78, v78
	v_lshlrev_b32_e32 v82, 16, v133
	v_mul_f32_e32 v77, v77, v82
	v_and_b32_e32 v82, 0xffff0000, v133
	v_mul_f32_e32 v78, v79, v78
	v_mul_f32_e32 v79, 0xbfb8aa3b, v72
	v_exp_f32_e32 v79, v79
	v_mul_f32_e32 v78, v78, v82
	v_mul_f32_e32 v77, v77, v83
	v_mul_f32_e32 v78, v78, v83
	v_add_f32_e32 v79, 1.0, v79
	v_cvt_pk_bf16_f32 v77, v77, v78
	v_mul_f32_e32 v78, 0xbfb8aa3b, v73
	v_rcp_f32_e32 v79, v79
	v_exp_f32_e32 v78, v78
	v_mul_f32_e32 v72, v72, v79
	v_lshlrev_b32_e32 v79, 16, v134
	v_add_f32_e32 v78, 1.0, v78
	v_mul_f32_e32 v72, v72, v79
	v_rcp_f32_e32 v78, v78
	v_mul_f32_e32 v79, 0xbfb8aa3b, v74
	v_exp_f32_e32 v79, v79
	v_mul_f32_e32 v72, v72, v83
	v_mul_f32_e32 v73, v73, v78
	v_and_b32_e32 v78, 0xffff0000, v134
	v_mul_f32_e32 v73, v73, v78
	v_add_f32_e32 v78, 1.0, v79
	v_rcp_f32_e32 v79, v78
	v_mul_f32_e32 v78, 0xbfb8aa3b, v75
	v_exp_f32_e32 v82, v78
	v_mul_f32_e32 v73, v73, v83
	v_cvt_pk_bf16_f32 v78, v72, v73
	v_mul_f32_e32 v72, v74, v79
	v_add_f32_e32 v73, 1.0, v82
	v_rcp_f32_e32 v73, v73
	v_lshlrev_b32_e32 v74, 16, v135
	v_mul_f32_e32 v72, v72, v74
	v_and_b32_e32 v74, 0xffff0000, v135
	v_mul_f32_e32 v73, v75, v73
	v_mul_f32_e32 v75, 0xbfb8aa3b, v68
	v_exp_f32_e32 v75, v75
	v_mul_f32_e32 v72, v72, v83
	v_mul_f32_e32 v73, v73, v74
	v_mul_f32_e32 v73, v73, v83
	v_cvt_pk_bf16_f32 v79, v72, v73
	v_add_f32_e32 v72, 1.0, v75
	v_rcp_f32_e32 v72, v72
	v_mul_f32_e32 v73, 0xbfb8aa3b, v69
	v_exp_f32_e32 v73, v73
	global_store_dwordx4 v[80:81], v[76:79], off
	v_mul_f32_e32 v68, v68, v72
	v_lshlrev_b32_e32 v72, 16, v128
	v_mul_f32_e32 v68, v68, v72
	v_add_f32_e32 v72, 1.0, v73
	v_rcp_f32_e32 v72, v72
	v_mul_f32_e32 v73, 0xbfb8aa3b, v70
	v_exp_f32_e32 v73, v73
	v_mul_f32_e32 v68, v68, v83
	v_mul_f32_e32 v69, v69, v72
	v_and_b32_e32 v72, 0xffff0000, v128
	v_mul_f32_e32 v69, v69, v72
	v_add_f32_e32 v72, 1.0, v73
	v_mul_f32_e32 v73, 0xbfb8aa3b, v71
	v_rcp_f32_e32 v72, v72
	v_exp_f32_e32 v73, v73
	v_mul_f32_e32 v69, v69, v83
	v_cvt_pk_bf16_f32 v68, v68, v69
	v_mul_f32_e32 v69, v70, v72
	v_add_f32_e32 v70, 1.0, v73
	v_rcp_f32_e32 v70, v70
	v_lshlrev_b32_e32 v72, 16, v129
	v_mul_f32_e32 v69, v69, v72
	v_and_b32_e32 v72, 0xffff0000, v129
	v_mul_f32_e32 v70, v71, v70
	v_mul_f32_e32 v71, 0xbfb8aa3b, v64
	v_exp_f32_e32 v71, v71
	v_mul_f32_e32 v70, v70, v72
	v_mul_f32_e32 v69, v69, v83
	v_mul_f32_e32 v70, v70, v83
	v_add_f32_e32 v71, 1.0, v71
	v_cvt_pk_bf16_f32 v69, v69, v70
	v_mul_f32_e32 v70, 0xbfb8aa3b, v65
	v_rcp_f32_e32 v71, v71
	v_exp_f32_e32 v70, v70
	v_mul_f32_e32 v64, v64, v71
	v_lshlrev_b32_e32 v71, 16, v130
	v_add_f32_e32 v70, 1.0, v70
	v_mul_f32_e32 v64, v64, v71
	v_rcp_f32_e32 v70, v70
	v_mul_f32_e32 v71, 0xbfb8aa3b, v66
	v_exp_f32_e32 v71, v71
	v_mul_f32_e32 v64, v64, v83
	v_mul_f32_e32 v65, v65, v70
	v_and_b32_e32 v70, 0xffff0000, v130
	v_mul_f32_e32 v65, v65, v70
	v_add_f32_e32 v70, 1.0, v71
	v_rcp_f32_e32 v71, v70
	v_mul_f32_e32 v70, 0xbfb8aa3b, v67
	v_exp_f32_e32 v72, v70
	v_mul_f32_e32 v65, v65, v83
	v_cvt_pk_bf16_f32 v70, v64, v65
	v_mul_f32_e32 v64, v66, v71
	v_add_f32_e32 v65, 1.0, v72
	v_rcp_f32_e32 v65, v65
	v_lshlrev_b32_e32 v66, 16, v131
	v_mul_f32_e32 v64, v64, v66
	v_and_b32_e32 v66, 0xffff0000, v131
	v_mul_f32_e32 v65, v67, v65
	v_mul_f32_e32 v64, v64, v83
	v_mul_f32_e32 v65, v65, v66
	v_mul_f32_e32 v65, v65, v83
	v_cvt_pk_bf16_f32 v71, v64, v65
	v_add_u32_e32 v64, 0x80, v172
	v_ashrrev_i32_e32 v65, 31, v64
	v_lshlrev_b64 v[110:111], 13, v[64:65]
	v_lshl_add_u64 v[66:67], v[174:175], 0, v[110:111]
	global_load_dwordx4 v[102:105], v[66:67], off
	v_lshlrev_b64 v[64:65], 7, v[64:65]
	global_store_dwordx4 v[80:81], v[68:71], off offset:256
	v_lshl_add_u64 v[64:65], s[12:13], 0, v[64:65]
	global_load_dwordx4 v[106:109], v[64:65], off
	v_add_u32_e32 v64, 0x90, v172
	v_ashrrev_i32_e32 v65, 31, v64
	v_lshlrev_b64 v[68:69], 7, v[64:65]
	v_lshl_add_u64 v[68:69], s[12:13], 0, v[68:69]
	global_load_dwordx4 v[114:117], v[66:67], off offset:256
	global_load_dwordx4 v[118:121], v[68:69], off
	v_lshlrev_b64 v[100:101], 13, v[64:65]
	v_lshl_add_u64 v[64:65], v[174:175], 0, v[100:101]
	global_load_dwordx4 v[92:95], v[64:65], off
	global_load_dwordx4 v[88:91], v[64:65], off offset:256
	v_add_u32_e32 v64, 0xa0, v172
	v_ashrrev_i32_e32 v65, 31, v64
	v_lshlrev_b64 v[66:67], 7, v[64:65]
	v_lshl_add_u64 v[66:67], s[12:13], 0, v[66:67]
	v_lshlrev_b64 v[98:99], 13, v[64:65]
	v_lshl_add_u64 v[64:65], v[174:175], 0, v[98:99]
	global_load_dwordx4 v[72:75], v[66:67], off
	global_load_dwordx4 v[84:87], v[64:65], off
	v_add_u32_e32 v66, 0xb0, v172
	v_ashrrev_i32_e32 v67, 31, v66
	v_lshlrev_b64 v[68:69], 7, v[66:67]
	v_lshlrev_b64 v[96:97], 13, v[66:67]
	v_mul_f32_e32 v66, 0xbfb8aa3b, v60
	v_exp_f32_e32 v122, v66
	v_lshl_add_u64 v[68:69], s[12:13], 0, v[68:69]
	global_load_dwordx4 v[76:79], v[64:65], off offset:256
	global_load_dwordx4 v[80:83], v[68:69], off
	v_lshl_add_u64 v[64:65], v[174:175], 0, v[96:97]
	v_add_f32_e32 v122, 1.0, v122
	v_rcp_f32_e32 v122, v122
	global_load_dwordx4 v[68:71], v[64:65], off
	s_nop 0
	global_load_dwordx4 v[64:67], v[64:65], off offset:256
	v_lshl_add_u64 v[110:111], s[2:3], 0, v[110:111]
	v_lshl_add_u64 v[110:111], v[110:111], 0, v[170:171]
	v_mul_f32_e32 v60, v60, v122
	s_mov_b32 s13, s4
	s_mov_b32 s12, s6
	s_waitcnt vmcnt(0)
	v_lshlrev_b32_e32 v122, 16, v102
	v_mul_f32_e32 v60, v60, v122
	v_add_f32_e32 v122, 1.0, v124
	v_rcp_f32_e32 v122, v122
	v_and_b32_e32 v102, 0xffff0000, v102
	v_mul_f32_e32 v61, v61, v102
	v_lshlrev_b32_e32 v102, 16, v103
	v_mul_f32_e32 v62, v62, v122
	v_add_f32_e32 v122, 1.0, v123
	v_mul_f32_e32 v123, 0xbfb8aa3b, v56
	v_rcp_f32_e32 v122, v122
	v_exp_f32_e32 v123, v123
	v_mul_f32_e32 v62, v62, v102
	v_and_b32_e32 v102, 0xffff0000, v103
	v_mul_f32_e32 v63, v63, v122
	v_add_f32_e32 v103, 1.0, v123
	v_mul_f32_e32 v122, 0xbfb8aa3b, v57
	v_rcp_f32_e32 v103, v103
	v_exp_f32_e32 v122, v122
	v_mul_f32_e32 v63, v63, v102
	v_lshlrev_b32_e32 v102, 16, v104
	v_mul_f32_e32 v56, v56, v103
	v_add_f32_e32 v103, 1.0, v122
	v_mul_f32_e32 v122, 0xbfb8aa3b, v58
	v_rcp_f32_e32 v103, v103
	v_exp_f32_e32 v122, v122
	v_mul_f32_e32 v56, v56, v102
	v_and_b32_e32 v102, 0xffff0000, v104
	v_mul_f32_e32 v57, v57, v103
	v_add_f32_e32 v103, 1.0, v122
	v_mul_f32_e32 v104, 0xbfb8aa3b, v59
	v_rcp_f32_e32 v103, v103
	v_exp_f32_e32 v104, v104
	v_mul_f32_e32 v57, v57, v102
	v_lshlrev_b32_e32 v102, 16, v105
	v_mul_f32_e32 v58, v58, v103
	v_add_f32_e32 v103, 1.0, v104
	v_mul_f32_e32 v104, 0xbfb8aa3b, v52
	v_rcp_f32_e32 v103, v103
	v_exp_f32_e32 v104, v104
	v_mul_f32_e32 v58, v58, v102
	v_and_b32_e32 v102, 0xffff0000, v105
	v_mul_f32_e32 v59, v59, v103
	v_add_f32_e32 v103, 1.0, v104
	v_mul_f32_e32 v104, 0xbfb8aa3b, v53
	v_rcp_f32_e32 v103, v103
	v_exp_f32_e32 v104, v104
	v_mul_f32_e32 v59, v59, v102
	v_lshlrev_b32_e32 v102, 16, v114
	v_mul_f32_e32 v52, v52, v103
	v_add_f32_e32 v103, 1.0, v104
	v_mul_f32_e32 v104, 0xbfb8aa3b, v54
	v_rcp_f32_e32 v103, v103
	v_exp_f32_e32 v104, v104
	v_mul_f32_e32 v102, v52, v102
	v_mul_f32_e32 v52, v53, v103
	v_add_f32_e32 v103, 1.0, v104
	v_mul_f32_e32 v104, 0xbfb8aa3b, v55
	v_rcp_f32_e32 v103, v103
	v_exp_f32_e32 v104, v104
	v_and_b32_e32 v53, 0xffff0000, v114
	v_mul_f32_e32 v105, v52, v53
	v_mul_f32_e32 v52, v54, v103
	v_add_f32_e32 v54, 1.0, v104
	v_rcp_f32_e32 v54, v54
	v_mul_f32_e32 v103, 0xbfb8aa3b, v48
	v_exp_f32_e32 v103, v103
	v_lshlrev_b32_e32 v53, 16, v115
	v_mul_f32_e32 v104, v52, v53
	v_mul_f32_e32 v52, v55, v54
	v_mul_f32_e32 v55, 0xbfb8aa3b, v49
	v_add_f32_e32 v54, 1.0, v103
	v_exp_f32_e32 v55, v55
	v_rcp_f32_e32 v54, v54
	v_and_b32_e32 v53, 0xffff0000, v115
	v_mul_f32_e32 v103, v52, v53
	v_add_f32_e32 v53, 1.0, v55
	v_mul_f32_e32 v48, v48, v54
	v_rcp_f32_e32 v53, v53
	v_mul_f32_e32 v54, 0xbfb8aa3b, v50
	v_exp_f32_e32 v54, v54
	v_lshlrev_b32_e32 v52, 16, v116
	v_mul_f32_e32 v55, v48, v52
	v_mul_f32_e32 v48, v49, v53
	v_and_b32_e32 v49, 0xffff0000, v116
	v_add_f32_e32 v52, 1.0, v54
	v_mul_f32_e32 v54, v48, v49
	v_mul_f32_e32 v48, 0xbfb8aa3b, v51
	v_rcp_f32_e32 v52, v52
	v_exp_f32_e32 v48, v48
	v_mov_b32_e32 v53, v108
	v_mov_b32_e32 v108, v121
	v_mul_f32_e32 v49, v50, v52
	v_lshlrev_b32_e32 v50, 16, v117
	v_add_f32_e32 v48, 1.0, v48
	v_mul_f32_e32 v114, v49, v50
	v_rcp_f32_e32 v50, v48
	v_mov_b32_e32 v48, v118
	v_mov_b32_e32 v49, v106
	v_mov_b32_e32 v106, v119
	v_pk_add_f32 v[48:49], v[48:49], v[106:107]
	v_mov_b32_e32 v52, v120
	v_pk_add_f32 v[48:49], v[52:53], v[48:49]
	s_nop 0
	v_pk_add_f32 v[48:49], v[108:109], v[48:49]
	s_nop 0
	v_pk_fma_f32 v[52:53], v[48:49], s[14:15], v[112:113] op_sel_hi:[1,0,0]
	v_mul_f32_e32 v49, v51, v50
	v_mul_f32_e32 v48, 0x4b800000, v53
	v_cmp_gt_f32_e32 vcc, s5, v53
	v_and_b32_e32 v50, 0xffff0000, v117
	s_nop 0
	v_cndmask_b32_e32 v48, v53, v48, vcc
	v_rsq_f32_e32 v48, v48
	v_mul_f32_e32 v53, v49, v50
	v_mul_f32_e32 v49, 0x45800000, v48
	v_cndmask_b32_e32 v106, v48, v49, vcc
	v_mul_f32_e32 v48, v60, v106
	v_mul_f32_e32 v49, v61, v106
	v_cvt_pk_bf16_f32 v48, v48, v49
	v_mul_f32_e32 v49, v62, v106
	v_mul_f32_e32 v50, v63, v106
	v_cvt_pk_bf16_f32 v49, v49, v50
	v_mul_f32_e32 v50, v56, v106
	v_mul_f32_e32 v51, v57, v106
	v_cvt_pk_bf16_f32 v50, v50, v51
	v_mul_f32_e32 v51, v58, v106
	v_mul_f32_e32 v56, v59, v106
	v_cvt_pk_bf16_f32 v51, v51, v56
	global_store_dwordx4 v[110:111], v[48:51], off
	v_mul_f32_e32 v53, v53, v106
	v_cmp_gt_f32_e32 vcc, s5, v52
	v_mul_f32_e32 v48, v102, v106
	v_mul_f32_e32 v49, v105, v106
	v_cvt_pk_bf16_f32 v48, v48, v49
	v_mul_f32_e32 v49, v104, v106
	v_mul_f32_e32 v50, v103, v106
	v_cvt_pk_bf16_f32 v49, v49, v50
	v_mul_f32_e32 v50, v55, v106
	v_mul_f32_e32 v51, v54, v106
	v_cvt_pk_bf16_f32 v50, v50, v51
	v_mul_f32_e32 v51, v114, v106
	v_cvt_pk_bf16_f32 v51, v51, v53
	v_mul_f32_e32 v53, 0x4b800000, v52
	v_cndmask_b32_e32 v52, v52, v53, vcc
	global_store_dwordx4 v[110:111], v[48:51], off offset:256
	v_rsq_f32_e32 v52, v52
	s_nop 0
	v_mul_f32_e32 v48, 0xbfb8aa3b, v44
	v_exp_f32_e32 v50, v48
	v_mul_f32_e32 v48, 0x45800000, v52
	v_cndmask_b32_e32 v51, v52, v48, vcc
	v_mul_f32_e32 v52, 0xbfb8aa3b, v45
	v_add_f32_e32 v50, 1.0, v50
	v_rcp_f32_e32 v50, v50
	v_exp_f32_e32 v52, v52
	v_lshl_add_u64 v[48:49], s[2:3], 0, v[100:101]
	v_lshl_add_u64 v[48:49], v[48:49], 0, v[170:171]
	v_mul_f32_e32 v44, v44, v50
	v_lshlrev_b32_e32 v50, 16, v92
	v_mul_f32_e32 v44, v44, v50
	v_add_f32_e32 v50, 1.0, v52
	v_rcp_f32_e32 v50, v50
	v_mul_f32_e32 v52, 0xbfb8aa3b, v46
	v_exp_f32_e32 v52, v52
	v_mul_f32_e32 v44, v44, v51
	v_mul_f32_e32 v45, v45, v50
	v_and_b32_e32 v50, 0xffff0000, v92
	v_mul_f32_e32 v45, v45, v50
	v_add_f32_e32 v50, 1.0, v52
	v_mul_f32_e32 v52, 0xbfb8aa3b, v47
	v_rcp_f32_e32 v50, v50
	v_exp_f32_e32 v52, v52
	v_mul_f32_e32 v45, v45, v51
	v_cvt_pk_bf16_f32 v44, v44, v45
	v_mul_f32_e32 v45, v46, v50
	v_add_f32_e32 v46, 1.0, v52
	v_rcp_f32_e32 v46, v46
	v_lshlrev_b32_e32 v50, 16, v93
	v_mul_f32_e32 v45, v45, v50
	v_and_b32_e32 v50, 0xffff0000, v93
	v_mul_f32_e32 v46, v47, v46
	v_mul_f32_e32 v47, 0xbfb8aa3b, v40
	v_exp_f32_e32 v47, v47
	v_mul_f32_e32 v46, v46, v50
	v_mul_f32_e32 v45, v45, v51
	v_mul_f32_e32 v46, v46, v51
	v_add_f32_e32 v47, 1.0, v47
	v_cvt_pk_bf16_f32 v45, v45, v46
	v_mul_f32_e32 v46, 0xbfb8aa3b, v41
	v_rcp_f32_e32 v47, v47
	v_exp_f32_e32 v46, v46
	v_mul_f32_e32 v40, v40, v47
	v_lshlrev_b32_e32 v47, 16, v94
	v_add_f32_e32 v46, 1.0, v46
	v_mul_f32_e32 v40, v40, v47
	v_rcp_f32_e32 v46, v46
	v_mul_f32_e32 v47, 0xbfb8aa3b, v42
	v_exp_f32_e32 v47, v47
	v_mul_f32_e32 v40, v40, v51
	v_mul_f32_e32 v41, v41, v46
	v_and_b32_e32 v46, 0xffff0000, v94
	v_mul_f32_e32 v41, v41, v46
	v_add_f32_e32 v46, 1.0, v47
	v_rcp_f32_e32 v47, v46
	v_mul_f32_e32 v46, 0xbfb8aa3b, v43
	v_exp_f32_e32 v50, v46
	v_mul_f32_e32 v41, v41, v51
	v_cvt_pk_bf16_f32 v46, v40, v41
	v_mul_f32_e32 v40, v42, v47
	v_add_f32_e32 v41, 1.0, v50
	v_rcp_f32_e32 v41, v41
	v_lshlrev_b32_e32 v42, 16, v95
	v_mul_f32_e32 v40, v40, v42
	v_and_b32_e32 v42, 0xffff0000, v95
	v_mul_f32_e32 v41, v43, v41
	v_mul_f32_e32 v43, 0xbfb8aa3b, v36
	v_exp_f32_e32 v43, v43
	v_mul_f32_e32 v40, v40, v51
	v_mul_f32_e32 v41, v41, v42
	v_mul_f32_e32 v41, v41, v51
	v_cvt_pk_bf16_f32 v47, v40, v41
	v_add_f32_e32 v40, 1.0, v43
	v_rcp_f32_e32 v40, v40
	v_mul_f32_e32 v41, 0xbfb8aa3b, v37
	v_exp_f32_e32 v41, v41
	global_store_dwordx4 v[48:49], v[44:47], off
	v_mul_f32_e32 v36, v36, v40
	v_lshlrev_b32_e32 v40, 16, v88
	v_mul_f32_e32 v36, v36, v40
	v_add_f32_e32 v40, 1.0, v41
	v_rcp_f32_e32 v40, v40
	v_mul_f32_e32 v41, 0xbfb8aa3b, v38
	v_exp_f32_e32 v41, v41
	v_mul_f32_e32 v36, v36, v51
	v_mul_f32_e32 v37, v37, v40
	v_and_b32_e32 v40, 0xffff0000, v88
	v_mul_f32_e32 v37, v37, v40
	v_add_f32_e32 v40, 1.0, v41
	v_mul_f32_e32 v41, 0xbfb8aa3b, v39
	v_rcp_f32_e32 v40, v40
	v_exp_f32_e32 v41, v41
	v_mul_f32_e32 v37, v37, v51
	v_cvt_pk_bf16_f32 v36, v36, v37
	v_mul_f32_e32 v37, v38, v40
	v_add_f32_e32 v38, 1.0, v41
	v_rcp_f32_e32 v38, v38
	v_lshlrev_b32_e32 v40, 16, v89
	v_mul_f32_e32 v37, v37, v40
	v_and_b32_e32 v40, 0xffff0000, v89
	v_mul_f32_e32 v38, v39, v38
	v_mul_f32_e32 v39, 0xbfb8aa3b, v32
	v_exp_f32_e32 v39, v39
	v_mul_f32_e32 v38, v38, v40
	v_mul_f32_e32 v37, v37, v51
	v_mul_f32_e32 v38, v38, v51
	v_add_f32_e32 v39, 1.0, v39
	v_cvt_pk_bf16_f32 v37, v37, v38
	v_mul_f32_e32 v38, 0xbfb8aa3b, v33
	v_rcp_f32_e32 v39, v39
	v_exp_f32_e32 v38, v38
	v_mul_f32_e32 v32, v32, v39
	v_lshlrev_b32_e32 v39, 16, v90
	v_add_f32_e32 v38, 1.0, v38
	v_mul_f32_e32 v32, v32, v39
	v_rcp_f32_e32 v38, v38
	v_mul_f32_e32 v39, 0xbfb8aa3b, v34
	v_exp_f32_e32 v39, v39
	v_mul_f32_e32 v32, v32, v51
	v_mul_f32_e32 v33, v33, v38
	v_and_b32_e32 v38, 0xffff0000, v90
	v_mul_f32_e32 v33, v33, v38
	v_add_f32_e32 v38, 1.0, v39
	v_rcp_f32_e32 v39, v38
	v_mul_f32_e32 v38, 0xbfb8aa3b, v35
	v_exp_f32_e32 v40, v38
	v_mul_f32_e32 v33, v33, v51
	v_cvt_pk_bf16_f32 v38, v32, v33
	v_mul_f32_e32 v32, v34, v39
	v_add_f32_e32 v33, 1.0, v40
	v_rcp_f32_e32 v33, v33
	v_lshlrev_b32_e32 v34, 16, v91
	v_mul_f32_e32 v32, v32, v34
	v_and_b32_e32 v34, 0xffff0000, v91
	v_mul_f32_e32 v33, v35, v33
	v_mul_f32_e32 v35, 0xbfb8aa3b, v29
	v_exp_f32_e32 v35, v35
	v_mul_f32_e32 v33, v33, v34
	v_mul_f32_e32 v32, v32, v51
	v_mul_f32_e32 v33, v33, v51
	v_cvt_pk_bf16_f32 v39, v32, v33
	global_store_dwordx4 v[48:49], v[36:39], off offset:256
	v_add_f32_e32 v35, 1.0, v35
	v_rcp_f32_e32 v35, v35
	v_mul_f32_e32 v36, 0xbfb8aa3b, v30
	v_exp_f32_e32 v36, v36
	v_mul_f32_e32 v34, 0xbfb8aa3b, v28
	v_mul_f32_e32 v29, v29, v35
	v_exp_f32_e32 v34, v34
	v_add_f32_e32 v35, 1.0, v36
	v_mul_f32_e32 v36, 0xbfb8aa3b, v31
	v_rcp_f32_e32 v35, v35
	v_exp_f32_e32 v36, v36
	v_add_f32_e32 v34, 1.0, v34
	v_rcp_f32_e32 v34, v34
	v_mul_f32_e32 v30, v30, v35
	v_add_f32_e32 v35, 1.0, v36
	v_mul_f32_e32 v36, 0xbfb8aa3b, v24
	v_rcp_f32_e32 v35, v35
	v_exp_f32_e32 v36, v36
	v_mul_f32_e32 v28, v28, v34
	v_lshlrev_b32_e32 v34, 16, v84
	v_mul_f32_e32 v31, v31, v35
	v_add_f32_e32 v35, 1.0, v36
	v_mul_f32_e32 v36, 0xbfb8aa3b, v25
	v_rcp_f32_e32 v35, v35
	v_exp_f32_e32 v36, v36
	v_mul_f32_e32 v28, v28, v34
	v_and_b32_e32 v34, 0xffff0000, v84
	v_mul_f32_e32 v24, v24, v35
	v_add_f32_e32 v35, 1.0, v36
	v_mul_f32_e32 v36, 0xbfb8aa3b, v26
	v_rcp_f32_e32 v35, v35
	v_exp_f32_e32 v36, v36
	v_mul_f32_e32 v29, v29, v34
	v_lshlrev_b32_e32 v34, 16, v85
	v_mul_f32_e32 v25, v25, v35
	v_add_f32_e32 v35, 1.0, v36
	v_mul_f32_e32 v36, 0xbfb8aa3b, v27
	v_rcp_f32_e32 v35, v35
	v_exp_f32_e32 v36, v36
	v_mul_f32_e32 v30, v30, v34
	v_and_b32_e32 v34, 0xffff0000, v85
	v_mul_f32_e32 v26, v26, v35
	v_add_f32_e32 v35, 1.0, v36
	v_mul_f32_e32 v36, 0xbfb8aa3b, v20
	v_rcp_f32_e32 v35, v35
	v_exp_f32_e32 v36, v36
	v_mul_f32_e32 v31, v31, v34
	v_lshlrev_b32_e32 v34, 16, v86
	v_mul_f32_e32 v27, v27, v35
	v_add_f32_e32 v35, 1.0, v36
	v_mul_f32_e32 v36, 0xbfb8aa3b, v21
	v_rcp_f32_e32 v35, v35
	v_exp_f32_e32 v36, v36
	v_mul_f32_e32 v24, v24, v34
	v_and_b32_e32 v34, 0xffff0000, v86
	v_mul_f32_e32 v20, v20, v35
	v_add_f32_e32 v35, 1.0, v36
	v_mul_f32_e32 v36, 0xbfb8aa3b, v22
	v_rcp_f32_e32 v35, v35
	v_exp_f32_e32 v36, v36
	v_mul_f32_e32 v25, v25, v34
	v_lshlrev_b32_e32 v34, 16, v87
	v_mul_f32_e32 v26, v26, v34
	v_and_b32_e32 v34, 0xffff0000, v87
	v_mul_f32_e32 v27, v27, v34
	v_lshlrev_b32_e32 v34, 16, v76
	v_mul_f32_e32 v34, v20, v34
	v_mul_f32_e32 v20, v21, v35
	v_add_f32_e32 v35, 1.0, v36
	v_mul_f32_e32 v36, 0xbfb8aa3b, v23
	v_rcp_f32_e32 v35, v35
	v_exp_f32_e32 v36, v36
	v_and_b32_e32 v21, 0xffff0000, v76
	v_mul_f32_e32 v37, v20, v21
	v_mul_f32_e32 v20, v22, v35
	v_add_f32_e32 v22, 1.0, v36
	v_rcp_f32_e32 v22, v22
	v_mul_f32_e32 v35, 0xbfb8aa3b, v16
	v_exp_f32_e32 v35, v35
	v_lshlrev_b32_e32 v21, 16, v77
	v_mul_f32_e32 v36, v20, v21
	v_mul_f32_e32 v20, v23, v22
	v_mul_f32_e32 v23, 0xbfb8aa3b, v17
	v_add_f32_e32 v22, 1.0, v35
	v_exp_f32_e32 v23, v23
	v_rcp_f32_e32 v22, v22
	v_and_b32_e32 v21, 0xffff0000, v77
	v_mul_f32_e32 v35, v20, v21
	v_add_f32_e32 v21, 1.0, v23
	v_mul_f32_e32 v16, v16, v22
	v_rcp_f32_e32 v21, v21
	v_mul_f32_e32 v22, 0xbfb8aa3b, v18
	v_exp_f32_e32 v22, v22
	v_lshlrev_b32_e32 v20, 16, v78
	v_mul_f32_e32 v23, v16, v20
	v_mul_f32_e32 v16, v17, v21
	v_and_b32_e32 v17, 0xffff0000, v78
	v_add_f32_e32 v20, 1.0, v22
	v_mul_f32_e32 v22, v16, v17
	v_mul_f32_e32 v16, 0xbfb8aa3b, v19
	v_rcp_f32_e32 v20, v20
	v_exp_f32_e32 v16, v16
	v_mov_b32_e32 v21, v74
	v_mov_b32_e32 v74, v83
	v_mul_f32_e32 v17, v18, v20
	v_lshlrev_b32_e32 v18, 16, v79
	v_add_f32_e32 v16, 1.0, v16
	v_mul_f32_e32 v38, v17, v18
	v_rcp_f32_e32 v18, v16
	v_mov_b32_e32 v16, v80
	v_mov_b32_e32 v17, v72
	v_mov_b32_e32 v72, v81
	v_pk_add_f32 v[16:17], v[16:17], v[72:73]
	v_mov_b32_e32 v20, v82
	v_pk_add_f32 v[16:17], v[20:21], v[16:17]
	v_lshl_add_u64 v[32:33], s[2:3], 0, v[98:99]
	v_pk_add_f32 v[16:17], v[74:75], v[16:17]
	v_lshl_add_u64 v[32:33], v[32:33], 0, v[170:171]
	v_pk_fma_f32 v[20:21], v[16:17], s[14:15], v[112:113] op_sel_hi:[1,0,0]
	v_mul_f32_e32 v17, v19, v18
	v_mul_f32_e32 v16, 0x4b800000, v21
	v_cmp_gt_f32_e32 vcc, s5, v21
	v_and_b32_e32 v18, 0xffff0000, v79
	s_mov_b64 s[14:15], s[8:9]
	v_cndmask_b32_e32 v16, v21, v16, vcc
	v_rsq_f32_e32 v16, v16
	v_mul_f32_e32 v21, v17, v18
	v_mul_f32_e32 v17, 0x45800000, v16
	v_cndmask_b32_e32 v39, v16, v17, vcc
	v_mul_f32_e32 v16, v28, v39
	v_mul_f32_e32 v17, v29, v39
	v_cvt_pk_bf16_f32 v16, v16, v17
	v_mul_f32_e32 v17, v30, v39
	v_mul_f32_e32 v18, v31, v39
	v_cvt_pk_bf16_f32 v17, v17, v18
	v_mul_f32_e32 v18, v24, v39
	v_mul_f32_e32 v19, v25, v39
	v_cvt_pk_bf16_f32 v18, v18, v19
	v_mul_f32_e32 v19, v26, v39
	v_mul_f32_e32 v24, v27, v39
	v_cvt_pk_bf16_f32 v19, v19, v24
	global_store_dwordx4 v[32:33], v[16:19], off
	v_mul_f32_e32 v21, v21, v39
	v_cmp_gt_f32_e32 vcc, s5, v20
	v_mul_f32_e32 v16, v34, v39
	v_mul_f32_e32 v17, v37, v39
	v_cvt_pk_bf16_f32 v16, v16, v17
	v_mul_f32_e32 v17, v36, v39
	v_mul_f32_e32 v18, v35, v39
	v_cvt_pk_bf16_f32 v17, v17, v18
	v_mul_f32_e32 v18, v23, v39
	v_mul_f32_e32 v19, v22, v39
	v_cvt_pk_bf16_f32 v18, v18, v19
	v_mul_f32_e32 v19, v38, v39
	v_cvt_pk_bf16_f32 v19, v19, v21
	v_mul_f32_e32 v21, 0x4b800000, v20
	v_cndmask_b32_e32 v20, v20, v21, vcc
	global_store_dwordx4 v[32:33], v[16:19], off offset:256
	v_rsq_f32_e32 v20, v20
	s_nop 0
	v_mul_f32_e32 v16, 0xbfb8aa3b, v12
	v_exp_f32_e32 v18, v16
	v_mul_f32_e32 v16, 0x45800000, v20
	v_cndmask_b32_e32 v19, v20, v16, vcc
	v_mul_f32_e32 v20, 0xbfb8aa3b, v13
	v_add_f32_e32 v18, 1.0, v18
	v_rcp_f32_e32 v18, v18
	v_exp_f32_e32 v20, v20
	v_lshl_add_u64 v[16:17], s[2:3], 0, v[96:97]
	v_lshl_add_u64 v[16:17], v[16:17], 0, v[170:171]
	v_mul_f32_e32 v12, v12, v18
	v_lshlrev_b32_e32 v18, 16, v68
	v_mul_f32_e32 v12, v12, v18
	v_add_f32_e32 v18, 1.0, v20
	v_rcp_f32_e32 v18, v18
	v_mul_f32_e32 v20, 0xbfb8aa3b, v14
	v_exp_f32_e32 v20, v20
	v_mul_f32_e32 v12, v12, v19
	v_mul_f32_e32 v13, v13, v18
	v_and_b32_e32 v18, 0xffff0000, v68
	v_mul_f32_e32 v13, v13, v18
	v_add_f32_e32 v18, 1.0, v20
	v_mul_f32_e32 v20, 0xbfb8aa3b, v15
	v_rcp_f32_e32 v18, v18
	v_exp_f32_e32 v20, v20
	v_mul_f32_e32 v13, v13, v19
	v_cvt_pk_bf16_f32 v12, v12, v13
	v_mul_f32_e32 v13, v14, v18
	v_add_f32_e32 v14, 1.0, v20
	v_rcp_f32_e32 v14, v14
	v_lshlrev_b32_e32 v18, 16, v69
	v_mul_f32_e32 v13, v13, v18
	v_and_b32_e32 v18, 0xffff0000, v69
	v_mul_f32_e32 v14, v15, v14
	v_mul_f32_e32 v15, 0xbfb8aa3b, v8
	v_exp_f32_e32 v15, v15
	v_mul_f32_e32 v14, v14, v18
	v_mul_f32_e32 v13, v13, v19
	v_mul_f32_e32 v14, v14, v19
	v_add_f32_e32 v15, 1.0, v15
	v_cvt_pk_bf16_f32 v13, v13, v14
	v_mul_f32_e32 v14, 0xbfb8aa3b, v9
	v_rcp_f32_e32 v15, v15
	v_exp_f32_e32 v14, v14
	s_and_b64 vcc, exec, s[0:1]
	v_mul_f32_e32 v8, v8, v15
	v_lshlrev_b32_e32 v15, 16, v70
	v_add_f32_e32 v14, 1.0, v14
	v_mul_f32_e32 v8, v8, v15
	v_rcp_f32_e32 v14, v14
	v_mul_f32_e32 v15, 0xbfb8aa3b, v10
	v_exp_f32_e32 v15, v15
	v_mul_f32_e32 v8, v8, v19
	v_mul_f32_e32 v9, v9, v14
	v_and_b32_e32 v14, 0xffff0000, v70
	v_mul_f32_e32 v9, v9, v14
	v_add_f32_e32 v14, 1.0, v15
	v_rcp_f32_e32 v15, v14
	v_mul_f32_e32 v14, 0xbfb8aa3b, v11
	v_exp_f32_e32 v18, v14
	v_mul_f32_e32 v9, v9, v19
	v_cvt_pk_bf16_f32 v14, v8, v9
	v_mul_f32_e32 v8, v10, v15
	v_add_f32_e32 v9, 1.0, v18
	v_rcp_f32_e32 v9, v9
	v_lshlrev_b32_e32 v10, 16, v71
	v_mul_f32_e32 v8, v8, v10
	v_and_b32_e32 v10, 0xffff0000, v71
	v_mul_f32_e32 v9, v11, v9
	v_mul_f32_e32 v11, 0xbfb8aa3b, v4
	v_exp_f32_e32 v11, v11
	v_mul_f32_e32 v8, v8, v19
	v_mul_f32_e32 v9, v9, v10
	v_mul_f32_e32 v9, v9, v19
	v_cvt_pk_bf16_f32 v15, v8, v9
	v_add_f32_e32 v8, 1.0, v11
	v_rcp_f32_e32 v8, v8
	v_mul_f32_e32 v9, 0xbfb8aa3b, v5
	v_exp_f32_e32 v9, v9
	global_store_dwordx4 v[16:17], v[12:15], off
	v_mul_f32_e32 v4, v4, v8
	v_lshlrev_b32_e32 v8, 16, v64
	v_mul_f32_e32 v4, v4, v8
	v_add_f32_e32 v8, 1.0, v9
	v_rcp_f32_e32 v8, v8
	v_mul_f32_e32 v9, 0xbfb8aa3b, v6
	v_exp_f32_e32 v9, v9
	v_mul_f32_e32 v4, v4, v19
	v_mul_f32_e32 v5, v5, v8
	v_and_b32_e32 v8, 0xffff0000, v64
	v_mul_f32_e32 v5, v5, v8
	v_add_f32_e32 v8, 1.0, v9
	v_mul_f32_e32 v9, 0xbfb8aa3b, v7
	v_rcp_f32_e32 v8, v8
	v_exp_f32_e32 v9, v9
	v_mul_f32_e32 v5, v5, v19
	v_cvt_pk_bf16_f32 v4, v4, v5
	v_mul_f32_e32 v5, v6, v8
	v_add_f32_e32 v6, 1.0, v9
	v_rcp_f32_e32 v6, v6
	v_lshlrev_b32_e32 v8, 16, v65
	v_mul_f32_e32 v5, v5, v8
	v_and_b32_e32 v8, 0xffff0000, v65
	v_mul_f32_e32 v6, v7, v6
	v_mul_f32_e32 v7, 0xbfb8aa3b, v0
	v_exp_f32_e32 v7, v7
	v_mul_f32_e32 v6, v6, v8
	v_mul_f32_e32 v5, v5, v19
	v_mul_f32_e32 v6, v6, v19
	v_add_f32_e32 v7, 1.0, v7
	v_cvt_pk_bf16_f32 v5, v5, v6
	v_mul_f32_e32 v6, 0xbfb8aa3b, v1
	v_rcp_f32_e32 v7, v7
	v_exp_f32_e32 v6, v6
	v_mul_f32_e32 v0, v0, v7
	v_lshlrev_b32_e32 v7, 16, v66
	v_add_f32_e32 v6, 1.0, v6
	v_mul_f32_e32 v0, v0, v7
	v_rcp_f32_e32 v6, v6
	v_mul_f32_e32 v7, 0xbfb8aa3b, v2
	v_exp_f32_e32 v7, v7
	v_mul_f32_e32 v0, v0, v19
	v_mul_f32_e32 v1, v1, v6
	v_and_b32_e32 v6, 0xffff0000, v66
	v_mul_f32_e32 v1, v1, v6
	v_add_f32_e32 v6, 1.0, v7
	v_rcp_f32_e32 v7, v6
	v_mul_f32_e32 v6, 0xbfb8aa3b, v3
	v_exp_f32_e32 v8, v6
	v_mul_f32_e32 v1, v1, v19
	v_cvt_pk_bf16_f32 v6, v0, v1
	v_mul_f32_e32 v0, v2, v7
	v_add_f32_e32 v1, 1.0, v8
	v_rcp_f32_e32 v1, v1
	v_lshlrev_b32_e32 v2, 16, v67
	v_mul_f32_e32 v0, v0, v2
	v_and_b32_e32 v2, 0xffff0000, v67
	v_mul_f32_e32 v1, v3, v1
	v_mul_f32_e32 v1, v1, v2
	v_mul_f32_e32 v0, v0, v19
	v_mul_f32_e32 v1, v1, v19
	v_cvt_pk_bf16_f32 v7, v0, v1
	global_store_dwordx4 v[16:17], v[4:7], off offset:256
	s_cbranch_vccz .LBB0_80
	s_waitcnt vmcnt(0)
	s_cmpk_gt_u32 s21, 0xff
	s_cbranch_scc1 .LBB0_91
	s_barrier

.LBB0_199:
	v_mov_b64_e32 v[0:1], 0x1000
	s_ashr_i32 s9, s8, 31
	v_cmp_lt_i64_e32 vcc, s[10:11], v[0:1]
	s_lshl_b64 s[10:11], s[8:9], 20
	s_add_u32 s10, s23, s10
	s_addc_u32 s11, s24, s11
	s_and_b64 s[12:13], vcc, exec
	s_cselect_b32 s5, s11, s15
	s_cselect_b32 s9, s10, s14
	s_ashr_i32 s7, s6, 31
	s_lshl_b64 s[12:13], s[6:7], 20
	s_add_u32 s12, s25, s12
	s_addc_u32 s13, s26, s13
	s_and_b64 s[18:19], vcc, exec
	s_cselect_b32 s7, s13, s17
	s_cselect_b32 s37, s12, s16
	s_add_u32 s14, s14, 0x80080
	s_addc_u32 s15, s15, 0
	s_add_u32 s38, s16, 0x100
	s_addc_u32 s39, s17, 0
	s_mov_b32 s40, -2
	s_mov_b64 s[48:49], 0x80
	v_add_u32_e32 v222, 0x10000, v238
	s_add_u32 s16, s14, 0xfff80080
	s_addc_u32 s17, s15, -1
	s_add_i32 s41, 0, 0x10000
	ds_read_b128 v[128:131], v222 offset:0
	ds_read_b128 v[132:135], v222 offset:1024
	ds_read_b128 v[136:139], v222 offset:2048
	ds_read_b128 v[140:143], v222 offset:3072
	s_cmp_eq_u32 s40, 28
	s_cselect_b32 s19, s5, s17
	s_cselect_b32 s18, s9, s16
	s_cselect_b32 s17, s7, s39
	s_cselect_b32 s16, s37, s38
	s_add_i32 m0, s28, 0xc000
	ds_read_b128 v[144:147], v240
	ds_read_b128 v[148:151], v240 offset:1024
	ds_read_b128 v[152:155], v240 offset:2048
	ds_read_b128 v[156:159], v240 offset:3072
	ds_read_b128 v[160:163], v240 offset:4096
	ds_read_b128 v[164:167], v240 offset:5120
	ds_read_b128 v[168:171], v240 offset:6144
	ds_read_b128 v[172:175], v240 offset:7168
	global_load_lds_dwordx4 v218, s[14:15]
	s_add_i32 m0, s28, 0xe000
	s_nop 0
	global_load_lds_dwordx4 v220, s[14:15]
	s_waitcnt lgkmcnt(8)
	s_barrier
	s_waitcnt lgkmcnt(0)
	v_mfma_f32_16x16x32_bf16 v[124:127], v[128:131], v[144:147], 0
	v_mfma_f32_16x16x32_bf16 v[120:123], v[136:139], v[144:147], 0
	v_mfma_f32_16x16x32_bf16 v[116:119], v[128:131], v[152:155], 0
	v_mfma_f32_16x16x32_bf16 v[108:111], v[136:139], v[152:155], 0
	s_add_i32 s44, 0, 0x14000
	s_add_i32 s41, s41, s27
	v_mfma_f32_16x16x32_bf16 v[100:103], v[128:131], v[160:163], 0
	s_mov_b32 m0, s41
	v_mfma_f32_16x16x32_bf16 v[92:95], v[136:139], v[160:163], 0
	v_mfma_f32_16x16x32_bf16 v[84:87], v[128:131], v[168:171], 0
	v_mfma_f32_16x16x32_bf16 v[76:79], v[136:139], v[168:171], 0
	v_mfma_f32_16x16x32_bf16 v[124:127], v[132:135], v[148:151], v[124:127]
	v_mfma_f32_16x16x32_bf16 v[120:123], v[140:143], v[148:151], v[120:123]
	v_mfma_f32_16x16x32_bf16 v[116:119], v[132:135], v[156:159], v[116:119]
	v_mfma_f32_16x16x32_bf16 v[108:111], v[140:143], v[156:159], v[108:111]
	v_mfma_f32_16x16x32_bf16 v[100:103], v[132:135], v[164:167], v[100:103]
	v_mfma_f32_16x16x32_bf16 v[92:95], v[140:143], v[164:167], v[92:95]
	v_mfma_f32_16x16x32_bf16 v[84:87], v[132:135], v[172:175], v[84:87]
	v_mfma_f32_16x16x32_bf16 v[76:79], v[140:143], v[172:175], v[76:79]
	s_barrier
	ds_read_b128 v[176:179], v222 offset:16384
	ds_read_b128 v[180:183], v222 offset:17408
	ds_read_b128 v[184:187], v222 offset:18432
	ds_read_b128 v[188:191], v222 offset:19456
	global_load_lds_dwordx4 v206, s[16:17]
	s_add_i32 m0, s41, 0x2000
	s_nop 0
	global_load_lds_dwordx4 v210, s[16:17]
	s_barrier
	s_waitcnt lgkmcnt(0)
	v_mfma_f32_16x16x32_bf16 v[112:115], v[176:179], v[144:147], 0
	v_mfma_f32_16x16x32_bf16 v[104:107], v[184:187], v[144:147], 0
	v_mfma_f32_16x16x32_bf16 v[96:99], v[176:179], v[152:155], 0
	v_mfma_f32_16x16x32_bf16 v[88:91], v[184:187], v[152:155], 0
	s_mov_b32 m0, s28
	v_mfma_f32_16x16x32_bf16 v[80:83], v[176:179], v[160:163], 0
	s_add_u32 s48, s18, 0x80
	s_addc_u32 s49, s19, 0
	v_mfma_f32_16x16x32_bf16 v[72:75], v[184:187], v[160:163], 0
	v_mfma_f32_16x16x32_bf16 v[68:71], v[176:179], v[168:171], 0
	v_mfma_f32_16x16x32_bf16 v[64:67], v[184:187], v[168:171], 0
	v_mfma_f32_16x16x32_bf16 v[112:115], v[180:183], v[148:151], v[112:115]
	v_mfma_f32_16x16x32_bf16 v[104:107], v[188:191], v[148:151], v[104:107]
	v_mfma_f32_16x16x32_bf16 v[96:99], v[180:183], v[156:159], v[96:99]
	v_mfma_f32_16x16x32_bf16 v[88:91], v[188:191], v[156:159], v[88:91]
	v_mfma_f32_16x16x32_bf16 v[80:83], v[180:183], v[164:167], v[80:83]
	v_mfma_f32_16x16x32_bf16 v[72:75], v[188:191], v[164:167], v[72:75]
	v_mfma_f32_16x16x32_bf16 v[68:71], v[180:183], v[172:175], v[68:71]
	v_mfma_f32_16x16x32_bf16 v[64:67], v[188:191], v[172:175], v[64:67]
	s_barrier
	ds_read_b128 v[144:147], v240 offset:16384
	ds_read_b128 v[148:151], v240 offset:17408
	ds_read_b128 v[152:155], v240 offset:18432
	ds_read_b128 v[156:159], v240 offset:19456
	ds_read_b128 v[160:163], v240 offset:20480
	ds_read_b128 v[164:167], v240 offset:21504
	ds_read_b128 v[168:171], v240 offset:22528
	ds_read_b128 v[172:175], v240 offset:23552
	global_load_lds_dwordx4 v204, s[18:19]
	s_mov_b32 m0, s29
	s_nop 0
	global_load_lds_dwordx4 v208, s[18:19]
	s_barrier
	s_waitcnt lgkmcnt(0)
	v_mfma_f32_16x16x32_bf16 v[60:63], v[128:131], v[144:147], 0
	v_mfma_f32_16x16x32_bf16 v[56:59], v[136:139], v[144:147], 0
	v_mfma_f32_16x16x32_bf16 v[52:55], v[128:131], v[152:155], 0
	v_mfma_f32_16x16x32_bf16 v[44:47], v[136:139], v[152:155], 0
	s_add_u32 s42, s16, 0x80000
	s_addc_u32 s43, s17, 0
	v_mfma_f32_16x16x32_bf16 v[36:39], v[128:131], v[160:163], 0
	s_add_i32 s41, s44, s27
	s_mov_b32 m0, s41
	v_mfma_f32_16x16x32_bf16 v[28:31], v[136:139], v[160:163], 0
	v_mfma_f32_16x16x32_bf16 v[20:23], v[128:131], v[168:171], 0
	v_mfma_f32_16x16x32_bf16 v[12:15], v[136:139], v[168:171], 0
	v_mfma_f32_16x16x32_bf16 v[60:63], v[132:135], v[148:151], v[60:63]
	v_mfma_f32_16x16x32_bf16 v[56:59], v[140:143], v[148:151], v[56:59]
	v_mfma_f32_16x16x32_bf16 v[52:55], v[132:135], v[156:159], v[52:55]
	v_mfma_f32_16x16x32_bf16 v[44:47], v[140:143], v[156:159], v[44:47]
	v_mfma_f32_16x16x32_bf16 v[36:39], v[132:135], v[164:167], v[36:39]
	v_mfma_f32_16x16x32_bf16 v[28:31], v[140:143], v[164:167], v[28:31]
	v_mfma_f32_16x16x32_bf16 v[20:23], v[132:135], v[172:175], v[20:23]
	v_mfma_f32_16x16x32_bf16 v[12:15], v[140:143], v[172:175], v[12:15]
	s_barrier
	global_load_lds_dwordx4 v206, s[42:43]
	s_add_i32 m0, s41, 0x2000
	s_nop 0
	global_load_lds_dwordx4 v210, s[42:43]
	s_waitcnt vmcnt(6)
	s_barrier
	v_mfma_f32_16x16x32_bf16 v[48:51], v[176:179], v[144:147], 0
	v_mfma_f32_16x16x32_bf16 v[40:43], v[184:187], v[144:147], 0
	v_mfma_f32_16x16x32_bf16 v[32:35], v[176:179], v[152:155], 0
	v_mfma_f32_16x16x32_bf16 v[24:27], v[184:187], v[152:155], 0
	s_add_i32 s41, 0, 0x18000
	v_mfma_f32_16x16x32_bf16 v[16:19], v[176:179], v[160:163], 0
	s_add_u32 s18, s18, 0x80000
	s_addc_u32 s19, s19, 0
	v_mfma_f32_16x16x32_bf16 v[8:11], v[184:187], v[160:163], 0
	s_mov_b32 m0, s30
	v_mfma_f32_16x16x32_bf16 v[4:7], v[176:179], v[168:171], 0
	v_mfma_f32_16x16x32_bf16 v[0:3], v[184:187], v[168:171], 0
	v_mfma_f32_16x16x32_bf16 v[48:51], v[180:183], v[148:151], v[48:51]
	v_mfma_f32_16x16x32_bf16 v[40:43], v[188:191], v[148:151], v[40:43]
	v_mfma_f32_16x16x32_bf16 v[32:35], v[180:183], v[156:159], v[32:35]
	v_mfma_f32_16x16x32_bf16 v[24:27], v[188:191], v[156:159], v[24:27]
	v_mfma_f32_16x16x32_bf16 v[16:19], v[180:183], v[164:167], v[16:19]
	v_mfma_f32_16x16x32_bf16 v[8:11], v[188:191], v[164:167], v[8:11]
	v_mfma_f32_16x16x32_bf16 v[4:7], v[180:183], v[172:175], v[4:7]
	v_mfma_f32_16x16x32_bf16 v[0:3], v[188:191], v[172:175], v[0:3]
	s_barrier
	ds_read_b128 v[128:131], v222 offset:32768
	ds_read_b128 v[132:135], v222 offset:33792
	ds_read_b128 v[136:139], v222 offset:34816
	ds_read_b128 v[140:143], v222 offset:35840
	ds_read_b128 v[144:147], v240 offset:32768
	ds_read_b128 v[148:151], v240 offset:33792
	ds_read_b128 v[152:155], v240 offset:34816
	ds_read_b128 v[156:159], v240 offset:35840
	ds_read_b128 v[160:163], v240 offset:36864
	ds_read_b128 v[164:167], v240 offset:37888
	ds_read_b128 v[168:171], v240 offset:38912
	ds_read_b128 v[172:175], v240 offset:39936
	global_load_lds_dwordx4 v204, s[18:19]
	s_mov_b32 m0, s31
	s_nop 0
	global_load_lds_dwordx4 v208, s[18:19]
	s_waitcnt lgkmcnt(8)
	s_barrier
	s_waitcnt lgkmcnt(0)
	v_mfma_f32_16x16x32_bf16 v[124:127], v[128:131], v[144:147], v[124:127]
	v_mfma_f32_16x16x32_bf16 v[120:123], v[136:139], v[144:147], v[120:123]
	v_mfma_f32_16x16x32_bf16 v[116:119], v[128:131], v[152:155], v[116:119]
	v_mfma_f32_16x16x32_bf16 v[108:111], v[136:139], v[152:155], v[108:111]
	s_add_i32 s18, 0, 0x1c000
	s_add_i32 s19, s41, s27
	v_mfma_f32_16x16x32_bf16 v[100:103], v[128:131], v[160:163], v[100:103]
	s_add_i32 m0, s19, 0xffffff80
	v_mfma_f32_16x16x32_bf16 v[92:95], v[136:139], v[160:163], v[92:95]
	v_mfma_f32_16x16x32_bf16 v[84:87], v[128:131], v[168:171], v[84:87]
	v_mfma_f32_16x16x32_bf16 v[76:79], v[136:139], v[168:171], v[76:79]
	v_mfma_f32_16x16x32_bf16 v[124:127], v[132:135], v[148:151], v[124:127]
	v_mfma_f32_16x16x32_bf16 v[120:123], v[140:143], v[148:151], v[120:123]
	v_mfma_f32_16x16x32_bf16 v[116:119], v[132:135], v[156:159], v[116:119]
	v_mfma_f32_16x16x32_bf16 v[108:111], v[140:143], v[156:159], v[108:111]
	v_mfma_f32_16x16x32_bf16 v[100:103], v[132:135], v[164:167], v[100:103]
	v_mfma_f32_16x16x32_bf16 v[92:95], v[140:143], v[164:167], v[92:95]
	v_mfma_f32_16x16x32_bf16 v[84:87], v[132:135], v[172:175], v[84:87]
	v_mfma_f32_16x16x32_bf16 v[76:79], v[140:143], v[172:175], v[76:79]
	s_barrier
	ds_read_b128 v[176:179], v222 offset:49152
	ds_read_b128 v[180:183], v222 offset:50176
	ds_read_b128 v[184:187], v222 offset:51200
	ds_read_b128 v[188:191], v222 offset:52224
	global_load_lds_dwordx4 v206, s[16:17] offset:128
	s_add_i32 m0, s19, 0x1f80
	s_nop 0
	global_load_lds_dwordx4 v210, s[16:17] offset:128
	s_barrier
	s_waitcnt lgkmcnt(0)
	v_mfma_f32_16x16x32_bf16 v[112:115], v[176:179], v[144:147], v[112:115]
	v_mfma_f32_16x16x32_bf16 v[104:107], v[184:187], v[144:147], v[104:107]
	v_mfma_f32_16x16x32_bf16 v[96:99], v[176:179], v[152:155], v[96:99]
	v_mfma_f32_16x16x32_bf16 v[88:91], v[184:187], v[152:155], v[88:91]
	s_mov_b32 m0, s33
	v_mfma_f32_16x16x32_bf16 v[80:83], v[176:179], v[160:163], v[80:83]
	v_mfma_f32_16x16x32_bf16 v[72:75], v[184:187], v[160:163], v[72:75]
	v_mfma_f32_16x16x32_bf16 v[68:71], v[176:179], v[168:171], v[68:71]
	v_mfma_f32_16x16x32_bf16 v[64:67], v[184:187], v[168:171], v[64:67]
	v_mfma_f32_16x16x32_bf16 v[112:115], v[180:183], v[148:151], v[112:115]
	v_mfma_f32_16x16x32_bf16 v[104:107], v[188:191], v[148:151], v[104:107]
	v_mfma_f32_16x16x32_bf16 v[96:99], v[180:183], v[156:159], v[96:99]
	v_mfma_f32_16x16x32_bf16 v[88:91], v[188:191], v[156:159], v[88:91]
	v_mfma_f32_16x16x32_bf16 v[80:83], v[180:183], v[164:167], v[80:83]
	v_mfma_f32_16x16x32_bf16 v[72:75], v[188:191], v[164:167], v[72:75]
	v_mfma_f32_16x16x32_bf16 v[68:71], v[180:183], v[172:175], v[68:71]
	v_mfma_f32_16x16x32_bf16 v[64:67], v[188:191], v[172:175], v[64:67]
	s_barrier
	ds_read_b128 v[144:147], v240 offset:49152
	ds_read_b128 v[148:151], v240 offset:50176
	ds_read_b128 v[152:155], v240 offset:51200
	ds_read_b128 v[156:159], v240 offset:52224
	ds_read_b128 v[160:163], v240 offset:53248
	ds_read_b128 v[164:167], v240 offset:54272
	ds_read_b128 v[168:171], v240 offset:55296
	ds_read_b128 v[172:175], v240 offset:56320
	global_load_lds_dwordx4 v204, s[48:49]
	s_mov_b32 m0, s34
	s_nop 0
	global_load_lds_dwordx4 v208, s[48:49]
	s_barrier
	s_waitcnt lgkmcnt(0)
	v_mfma_f32_16x16x32_bf16 v[60:63], v[128:131], v[144:147], v[60:63]
	v_mfma_f32_16x16x32_bf16 v[56:59], v[136:139], v[144:147], v[56:59]
	v_mfma_f32_16x16x32_bf16 v[52:55], v[128:131], v[152:155], v[52:55]
	v_mfma_f32_16x16x32_bf16 v[44:47], v[136:139], v[152:155], v[44:47]
	s_add_u32 s16, s16, 0x80080
	s_addc_u32 s17, s17, 0
	v_mfma_f32_16x16x32_bf16 v[36:39], v[128:131], v[160:163], v[36:39]
	s_add_i32 s18, s18, s27
	s_mov_b32 m0, s18
	v_mfma_f32_16x16x32_bf16 v[28:31], v[136:139], v[160:163], v[28:31]
	v_mfma_f32_16x16x32_bf16 v[20:23], v[128:131], v[168:171], v[20:23]
	v_mfma_f32_16x16x32_bf16 v[12:15], v[136:139], v[168:171], v[12:15]
	v_mfma_f32_16x16x32_bf16 v[60:63], v[132:135], v[148:151], v[60:63]
	v_mfma_f32_16x16x32_bf16 v[56:59], v[140:143], v[148:151], v[56:59]
	v_mfma_f32_16x16x32_bf16 v[52:55], v[132:135], v[156:159], v[52:55]
	v_mfma_f32_16x16x32_bf16 v[44:47], v[140:143], v[156:159], v[44:47]
	v_mfma_f32_16x16x32_bf16 v[36:39], v[132:135], v[164:167], v[36:39]
	v_mfma_f32_16x16x32_bf16 v[28:31], v[140:143], v[164:167], v[28:31]
	v_mfma_f32_16x16x32_bf16 v[20:23], v[132:135], v[172:175], v[20:23]
	v_mfma_f32_16x16x32_bf16 v[12:15], v[140:143], v[172:175], v[12:15]
	s_barrier
	global_load_lds_dwordx4 v206, s[16:17]
	s_add_i32 m0, s18, 0x2000
	s_nop 0
	global_load_lds_dwordx4 v210, s[16:17]
	s_waitcnt vmcnt(6)
	s_barrier
	v_mfma_f32_16x16x32_bf16 v[48:51], v[176:179], v[144:147], v[48:51]
	v_mfma_f32_16x16x32_bf16 v[40:43], v[184:187], v[144:147], v[40:43]
	v_mfma_f32_16x16x32_bf16 v[32:35], v[176:179], v[152:155], v[32:35]
	v_mfma_f32_16x16x32_bf16 v[24:27], v[184:187], v[152:155], v[24:27]
	s_add_i32 s40, s40, 2
	v_mfma_f32_16x16x32_bf16 v[16:19], v[176:179], v[160:163], v[16:19]
	s_add_u32 s14, s14, 0x100
	s_addc_u32 s15, s15, 0
	v_mfma_f32_16x16x32_bf16 v[8:11], v[184:187], v[160:163], v[8:11]
	s_add_u32 s38, s38, 0x100
	s_addc_u32 s39, s39, 0
	v_mfma_f32_16x16x32_bf16 v[4:7], v[176:179], v[168:171], v[4:7]
	v_mfma_f32_16x16x32_bf16 v[0:3], v[184:187], v[168:171], v[0:3]
	v_mfma_f32_16x16x32_bf16 v[48:51], v[180:183], v[148:151], v[48:51]
	v_mfma_f32_16x16x32_bf16 v[40:43], v[188:191], v[148:151], v[40:43]
	v_mfma_f32_16x16x32_bf16 v[32:35], v[180:183], v[156:159], v[32:35]
	v_mfma_f32_16x16x32_bf16 v[24:27], v[188:191], v[156:159], v[24:27]
	v_mfma_f32_16x16x32_bf16 v[16:19], v[180:183], v[164:167], v[16:19]
	v_mfma_f32_16x16x32_bf16 v[8:11], v[188:191], v[164:167], v[8:11]
	v_mfma_f32_16x16x32_bf16 v[4:7], v[180:183], v[172:175], v[4:7]
	v_mfma_f32_16x16x32_bf16 v[0:3], v[188:191], v[172:175], v[0:3]
	s_cmp_gt_u32 s40, 29
	s_barrier
.LBB0_200:
	s_add_u32 s16, s14, 0xfff80080
	s_addc_u32 s17, s15, -1
	s_add_i32 s41, 0, 0x10000
	ds_read_b128 v[128:131], v222 offset:0
	ds_read_b128 v[132:135], v222 offset:1024
	ds_read_b128 v[136:139], v222 offset:2048
	ds_read_b128 v[140:143], v222 offset:3072
	s_cmp_eq_u32 s40, 28
	s_cselect_b32 s19, s5, s17
	s_cselect_b32 s18, s9, s16
	s_cselect_b32 s17, s7, s39
	s_cselect_b32 s16, s37, s38
	s_add_i32 m0, s28, 0xc000
	ds_read_b128 v[144:147], v240
	ds_read_b128 v[148:151], v240 offset:1024
	ds_read_b128 v[152:155], v240 offset:2048
	ds_read_b128 v[156:159], v240 offset:3072
	ds_read_b128 v[160:163], v240 offset:4096
	ds_read_b128 v[164:167], v240 offset:5120
	ds_read_b128 v[168:171], v240 offset:6144
	ds_read_b128 v[172:175], v240 offset:7168
	global_load_lds_dwordx4 v218, s[14:15]
	s_add_i32 m0, s28, 0xe000
	s_nop 0
	global_load_lds_dwordx4 v220, s[14:15]
	s_waitcnt lgkmcnt(8)
	s_barrier
	s_waitcnt lgkmcnt(0)
	v_mfma_f32_16x16x32_bf16 v[124:127], v[128:131], v[144:147], v[124:127]
	v_mfma_f32_16x16x32_bf16 v[120:123], v[136:139], v[144:147], v[120:123]
	v_mfma_f32_16x16x32_bf16 v[116:119], v[128:131], v[152:155], v[116:119]
	v_mfma_f32_16x16x32_bf16 v[108:111], v[136:139], v[152:155], v[108:111]
	s_add_i32 s44, 0, 0x14000
	s_add_i32 s41, s41, s27
	v_mfma_f32_16x16x32_bf16 v[100:103], v[128:131], v[160:163], v[100:103]
	s_mov_b32 m0, s41
	v_mfma_f32_16x16x32_bf16 v[92:95], v[136:139], v[160:163], v[92:95]
	v_mfma_f32_16x16x32_bf16 v[84:87], v[128:131], v[168:171], v[84:87]
	v_mfma_f32_16x16x32_bf16 v[76:79], v[136:139], v[168:171], v[76:79]
	v_mfma_f32_16x16x32_bf16 v[124:127], v[132:135], v[148:151], v[124:127]
	v_mfma_f32_16x16x32_bf16 v[120:123], v[140:143], v[148:151], v[120:123]
	v_mfma_f32_16x16x32_bf16 v[116:119], v[132:135], v[156:159], v[116:119]
	v_mfma_f32_16x16x32_bf16 v[108:111], v[140:143], v[156:159], v[108:111]
	v_mfma_f32_16x16x32_bf16 v[100:103], v[132:135], v[164:167], v[100:103]
	v_mfma_f32_16x16x32_bf16 v[92:95], v[140:143], v[164:167], v[92:95]
	v_mfma_f32_16x16x32_bf16 v[84:87], v[132:135], v[172:175], v[84:87]
	v_mfma_f32_16x16x32_bf16 v[76:79], v[140:143], v[172:175], v[76:79]
	s_barrier
	ds_read_b128 v[176:179], v222 offset:16384
	ds_read_b128 v[180:183], v222 offset:17408
	ds_read_b128 v[184:187], v222 offset:18432
	ds_read_b128 v[188:191], v222 offset:19456
	global_load_lds_dwordx4 v206, s[16:17]
	s_add_i32 m0, s41, 0x2000
	s_nop 0
	global_load_lds_dwordx4 v210, s[16:17]
	s_barrier
	s_waitcnt lgkmcnt(0)
	v_mfma_f32_16x16x32_bf16 v[112:115], v[176:179], v[144:147], v[112:115]
	v_mfma_f32_16x16x32_bf16 v[104:107], v[184:187], v[144:147], v[104:107]
	v_mfma_f32_16x16x32_bf16 v[96:99], v[176:179], v[152:155], v[96:99]
	v_mfma_f32_16x16x32_bf16 v[88:91], v[184:187], v[152:155], v[88:91]
	s_mov_b32 m0, s28
	v_mfma_f32_16x16x32_bf16 v[80:83], v[176:179], v[160:163], v[80:83]
	s_add_u32 s48, s18, 0x80
	s_addc_u32 s49, s19, 0
	v_mfma_f32_16x16x32_bf16 v[72:75], v[184:187], v[160:163], v[72:75]
	v_mfma_f32_16x16x32_bf16 v[68:71], v[176:179], v[168:171], v[68:71]
	v_mfma_f32_16x16x32_bf16 v[64:67], v[184:187], v[168:171], v[64:67]
	v_mfma_f32_16x16x32_bf16 v[112:115], v[180:183], v[148:151], v[112:115]
	v_mfma_f32_16x16x32_bf16 v[104:107], v[188:191], v[148:151], v[104:107]
	v_mfma_f32_16x16x32_bf16 v[96:99], v[180:183], v[156:159], v[96:99]
	v_mfma_f32_16x16x32_bf16 v[88:91], v[188:191], v[156:159], v[88:91]
	v_mfma_f32_16x16x32_bf16 v[80:83], v[180:183], v[164:167], v[80:83]
	v_mfma_f32_16x16x32_bf16 v[72:75], v[188:191], v[164:167], v[72:75]
	v_mfma_f32_16x16x32_bf16 v[68:71], v[180:183], v[172:175], v[68:71]
	v_mfma_f32_16x16x32_bf16 v[64:67], v[188:191], v[172:175], v[64:67]
	s_barrier
	ds_read_b128 v[144:147], v240 offset:16384
	ds_read_b128 v[148:151], v240 offset:17408
	ds_read_b128 v[152:155], v240 offset:18432
	ds_read_b128 v[156:159], v240 offset:19456
	ds_read_b128 v[160:163], v240 offset:20480
	ds_read_b128 v[164:167], v240 offset:21504
	ds_read_b128 v[168:171], v240 offset:22528
	ds_read_b128 v[172:175], v240 offset:23552
	global_load_lds_dwordx4 v204, s[18:19]
	s_mov_b32 m0, s29
	s_nop 0
	global_load_lds_dwordx4 v208, s[18:19]
	s_barrier
	s_waitcnt lgkmcnt(0)
	v_mfma_f32_16x16x32_bf16 v[60:63], v[128:131], v[144:147], v[60:63]
	v_mfma_f32_16x16x32_bf16 v[56:59], v[136:139], v[144:147], v[56:59]
	v_mfma_f32_16x16x32_bf16 v[52:55], v[128:131], v[152:155], v[52:55]
	v_mfma_f32_16x16x32_bf16 v[44:47], v[136:139], v[152:155], v[44:47]
	s_add_u32 s42, s16, 0x80000
	s_addc_u32 s43, s17, 0
	v_mfma_f32_16x16x32_bf16 v[36:39], v[128:131], v[160:163], v[36:39]
	s_add_i32 s41, s44, s27
	s_mov_b32 m0, s41
	v_mfma_f32_16x16x32_bf16 v[28:31], v[136:139], v[160:163], v[28:31]
	v_mfma_f32_16x16x32_bf16 v[20:23], v[128:131], v[168:171], v[20:23]
	v_mfma_f32_16x16x32_bf16 v[12:15], v[136:139], v[168:171], v[12:15]
	v_mfma_f32_16x16x32_bf16 v[60:63], v[132:135], v[148:151], v[60:63]
	v_mfma_f32_16x16x32_bf16 v[56:59], v[140:143], v[148:151], v[56:59]
	v_mfma_f32_16x16x32_bf16 v[52:55], v[132:135], v[156:159], v[52:55]
	v_mfma_f32_16x16x32_bf16 v[44:47], v[140:143], v[156:159], v[44:47]
	v_mfma_f32_16x16x32_bf16 v[36:39], v[132:135], v[164:167], v[36:39]
	v_mfma_f32_16x16x32_bf16 v[28:31], v[140:143], v[164:167], v[28:31]
	v_mfma_f32_16x16x32_bf16 v[20:23], v[132:135], v[172:175], v[20:23]
	v_mfma_f32_16x16x32_bf16 v[12:15], v[140:143], v[172:175], v[12:15]
	s_barrier
	global_load_lds_dwordx4 v206, s[42:43]
	s_add_i32 m0, s41, 0x2000
	s_nop 0
	global_load_lds_dwordx4 v210, s[42:43]
	s_waitcnt vmcnt(6)
	s_barrier
	v_mfma_f32_16x16x32_bf16 v[48:51], v[176:179], v[144:147], v[48:51]
	v_mfma_f32_16x16x32_bf16 v[40:43], v[184:187], v[144:147], v[40:43]
	v_mfma_f32_16x16x32_bf16 v[32:35], v[176:179], v[152:155], v[32:35]
	v_mfma_f32_16x16x32_bf16 v[24:27], v[184:187], v[152:155], v[24:27]
	s_add_i32 s41, 0, 0x18000
	v_mfma_f32_16x16x32_bf16 v[16:19], v[176:179], v[160:163], v[16:19]
	s_add_u32 s18, s18, 0x80000
	s_addc_u32 s19, s19, 0
	v_mfma_f32_16x16x32_bf16 v[8:11], v[184:187], v[160:163], v[8:11]
	s_mov_b32 m0, s30
	v_mfma_f32_16x16x32_bf16 v[4:7], v[176:179], v[168:171], v[4:7]
	v_mfma_f32_16x16x32_bf16 v[0:3], v[184:187], v[168:171], v[0:3]
	v_mfma_f32_16x16x32_bf16 v[48:51], v[180:183], v[148:151], v[48:51]
	v_mfma_f32_16x16x32_bf16 v[40:43], v[188:191], v[148:151], v[40:43]
	v_mfma_f32_16x16x32_bf16 v[32:35], v[180:183], v[156:159], v[32:35]
	v_mfma_f32_16x16x32_bf16 v[24:27], v[188:191], v[156:159], v[24:27]
	v_mfma_f32_16x16x32_bf16 v[16:19], v[180:183], v[164:167], v[16:19]
	v_mfma_f32_16x16x32_bf16 v[8:11], v[188:191], v[164:167], v[8:11]
	v_mfma_f32_16x16x32_bf16 v[4:7], v[180:183], v[172:175], v[4:7]
	v_mfma_f32_16x16x32_bf16 v[0:3], v[188:191], v[172:175], v[0:3]
	s_barrier
	ds_read_b128 v[128:131], v222 offset:32768
	ds_read_b128 v[132:135], v222 offset:33792
	ds_read_b128 v[136:139], v222 offset:34816
	ds_read_b128 v[140:143], v222 offset:35840
	ds_read_b128 v[144:147], v240 offset:32768
	ds_read_b128 v[148:151], v240 offset:33792
	ds_read_b128 v[152:155], v240 offset:34816
	ds_read_b128 v[156:159], v240 offset:35840
	ds_read_b128 v[160:163], v240 offset:36864
	ds_read_b128 v[164:167], v240 offset:37888
	ds_read_b128 v[168:171], v240 offset:38912
	ds_read_b128 v[172:175], v240 offset:39936
	global_load_lds_dwordx4 v204, s[18:19]
	s_mov_b32 m0, s31
	s_nop 0
	global_load_lds_dwordx4 v208, s[18:19]
	s_waitcnt lgkmcnt(8)
	s_barrier
	s_waitcnt lgkmcnt(0)
	v_mfma_f32_16x16x32_bf16 v[124:127], v[128:131], v[144:147], v[124:127]
	v_mfma_f32_16x16x32_bf16 v[120:123], v[136:139], v[144:147], v[120:123]
	v_mfma_f32_16x16x32_bf16 v[116:119], v[128:131], v[152:155], v[116:119]
	v_mfma_f32_16x16x32_bf16 v[108:111], v[136:139], v[152:155], v[108:111]
	s_add_i32 s18, 0, 0x1c000
	s_add_i32 s19, s41, s27
	v_mfma_f32_16x16x32_bf16 v[100:103], v[128:131], v[160:163], v[100:103]
	s_add_i32 m0, s19, 0xffffff80
	v_mfma_f32_16x16x32_bf16 v[92:95], v[136:139], v[160:163], v[92:95]
	v_mfma_f32_16x16x32_bf16 v[84:87], v[128:131], v[168:171], v[84:87]
	v_mfma_f32_16x16x32_bf16 v[76:79], v[136:139], v[168:171], v[76:79]
	v_mfma_f32_16x16x32_bf16 v[124:127], v[132:135], v[148:151], v[124:127]
	v_mfma_f32_16x16x32_bf16 v[120:123], v[140:143], v[148:151], v[120:123]
	v_mfma_f32_16x16x32_bf16 v[116:119], v[132:135], v[156:159], v[116:119]
	v_mfma_f32_16x16x32_bf16 v[108:111], v[140:143], v[156:159], v[108:111]
	v_mfma_f32_16x16x32_bf16 v[100:103], v[132:135], v[164:167], v[100:103]
	v_mfma_f32_16x16x32_bf16 v[92:95], v[140:143], v[164:167], v[92:95]
	v_mfma_f32_16x16x32_bf16 v[84:87], v[132:135], v[172:175], v[84:87]
	v_mfma_f32_16x16x32_bf16 v[76:79], v[140:143], v[172:175], v[76:79]
	s_barrier
	ds_read_b128 v[176:179], v222 offset:49152
	ds_read_b128 v[180:183], v222 offset:50176
	ds_read_b128 v[184:187], v222 offset:51200
	ds_read_b128 v[188:191], v222 offset:52224
	global_load_lds_dwordx4 v206, s[16:17] offset:128
	s_add_i32 m0, s19, 0x1f80
	s_nop 0
	global_load_lds_dwordx4 v210, s[16:17] offset:128
	s_barrier
	s_waitcnt lgkmcnt(0)
	v_mfma_f32_16x16x32_bf16 v[112:115], v[176:179], v[144:147], v[112:115]
	v_mfma_f32_16x16x32_bf16 v[104:107], v[184:187], v[144:147], v[104:107]
	v_mfma_f32_16x16x32_bf16 v[96:99], v[176:179], v[152:155], v[96:99]
	v_mfma_f32_16x16x32_bf16 v[88:91], v[184:187], v[152:155], v[88:91]
	s_mov_b32 m0, s33
	v_mfma_f32_16x16x32_bf16 v[80:83], v[176:179], v[160:163], v[80:83]
	v_mfma_f32_16x16x32_bf16 v[72:75], v[184:187], v[160:163], v[72:75]
	v_mfma_f32_16x16x32_bf16 v[68:71], v[176:179], v[168:171], v[68:71]
	v_mfma_f32_16x16x32_bf16 v[64:67], v[184:187], v[168:171], v[64:67]
	v_mfma_f32_16x16x32_bf16 v[112:115], v[180:183], v[148:151], v[112:115]
	v_mfma_f32_16x16x32_bf16 v[104:107], v[188:191], v[148:151], v[104:107]
	v_mfma_f32_16x16x32_bf16 v[96:99], v[180:183], v[156:159], v[96:99]
	v_mfma_f32_16x16x32_bf16 v[88:91], v[188:191], v[156:159], v[88:91]
	v_mfma_f32_16x16x32_bf16 v[80:83], v[180:183], v[164:167], v[80:83]
	v_mfma_f32_16x16x32_bf16 v[72:75], v[188:191], v[164:167], v[72:75]
	v_mfma_f32_16x16x32_bf16 v[68:71], v[180:183], v[172:175], v[68:71]
	v_mfma_f32_16x16x32_bf16 v[64:67], v[188:191], v[172:175], v[64:67]
	s_barrier
	ds_read_b128 v[144:147], v240 offset:49152
	ds_read_b128 v[148:151], v240 offset:50176
	ds_read_b128 v[152:155], v240 offset:51200
	ds_read_b128 v[156:159], v240 offset:52224
	ds_read_b128 v[160:163], v240 offset:53248
	ds_read_b128 v[164:167], v240 offset:54272
	ds_read_b128 v[168:171], v240 offset:55296
	ds_read_b128 v[172:175], v240 offset:56320
	global_load_lds_dwordx4 v204, s[48:49]
	s_mov_b32 m0, s34
	s_nop 0
	global_load_lds_dwordx4 v208, s[48:49]
	s_barrier
	s_waitcnt lgkmcnt(0)
	v_mfma_f32_16x16x32_bf16 v[60:63], v[128:131], v[144:147], v[60:63]
	v_mfma_f32_16x16x32_bf16 v[56:59], v[136:139], v[144:147], v[56:59]
	v_mfma_f32_16x16x32_bf16 v[52:55], v[128:131], v[152:155], v[52:55]
	v_mfma_f32_16x16x32_bf16 v[44:47], v[136:139], v[152:155], v[44:47]
	s_add_u32 s16, s16, 0x80080
	s_addc_u32 s17, s17, 0
	v_mfma_f32_16x16x32_bf16 v[36:39], v[128:131], v[160:163], v[36:39]
	s_add_i32 s18, s18, s27
	s_mov_b32 m0, s18
	v_mfma_f32_16x16x32_bf16 v[28:31], v[136:139], v[160:163], v[28:31]
	v_mfma_f32_16x16x32_bf16 v[20:23], v[128:131], v[168:171], v[20:23]
	v_mfma_f32_16x16x32_bf16 v[12:15], v[136:139], v[168:171], v[12:15]
	v_mfma_f32_16x16x32_bf16 v[60:63], v[132:135], v[148:151], v[60:63]
	v_mfma_f32_16x16x32_bf16 v[56:59], v[140:143], v[148:151], v[56:59]
	v_mfma_f32_16x16x32_bf16 v[52:55], v[132:135], v[156:159], v[52:55]
	v_mfma_f32_16x16x32_bf16 v[44:47], v[140:143], v[156:159], v[44:47]
	v_mfma_f32_16x16x32_bf16 v[36:39], v[132:135], v[164:167], v[36:39]
	v_mfma_f32_16x16x32_bf16 v[28:31], v[140:143], v[164:167], v[28:31]
	v_mfma_f32_16x16x32_bf16 v[20:23], v[132:135], v[172:175], v[20:23]
	v_mfma_f32_16x16x32_bf16 v[12:15], v[140:143], v[172:175], v[12:15]
	s_barrier
	global_load_lds_dwordx4 v206, s[16:17]
	s_add_i32 m0, s18, 0x2000
	s_nop 0
	global_load_lds_dwordx4 v210, s[16:17]
	s_waitcnt vmcnt(6)
	s_barrier
	v_mfma_f32_16x16x32_bf16 v[48:51], v[176:179], v[144:147], v[48:51]
	v_mfma_f32_16x16x32_bf16 v[40:43], v[184:187], v[144:147], v[40:43]
	v_mfma_f32_16x16x32_bf16 v[32:35], v[176:179], v[152:155], v[32:35]
	v_mfma_f32_16x16x32_bf16 v[24:27], v[184:187], v[152:155], v[24:27]
	s_add_i32 s40, s40, 2
	v_mfma_f32_16x16x32_bf16 v[16:19], v[176:179], v[160:163], v[16:19]
	s_add_u32 s14, s14, 0x100
	s_addc_u32 s15, s15, 0
	v_mfma_f32_16x16x32_bf16 v[8:11], v[184:187], v[160:163], v[8:11]
	s_add_u32 s38, s38, 0x100
	s_addc_u32 s39, s39, 0
	v_mfma_f32_16x16x32_bf16 v[4:7], v[176:179], v[168:171], v[4:7]
	v_mfma_f32_16x16x32_bf16 v[0:3], v[184:187], v[168:171], v[0:3]
	v_mfma_f32_16x16x32_bf16 v[48:51], v[180:183], v[148:151], v[48:51]
	v_mfma_f32_16x16x32_bf16 v[40:43], v[188:191], v[148:151], v[40:43]
	v_mfma_f32_16x16x32_bf16 v[32:35], v[180:183], v[156:159], v[32:35]
	v_mfma_f32_16x16x32_bf16 v[24:27], v[188:191], v[156:159], v[24:27]
	v_mfma_f32_16x16x32_bf16 v[16:19], v[180:183], v[164:167], v[16:19]
	v_mfma_f32_16x16x32_bf16 v[8:11], v[188:191], v[164:167], v[8:11]
	v_mfma_f32_16x16x32_bf16 v[4:7], v[180:183], v[172:175], v[4:7]
	v_mfma_f32_16x16x32_bf16 v[0:3], v[188:191], v[172:175], v[0:3]
	s_cmp_gt_u32 s40, 29
	s_barrier
	s_cbranch_scc0 .LBB0_200
	v_lshl_add_u32 v228, s4, 8, v237
	v_or_b32_e32 v226, 16, v228
	s_mov_b64 s[4:5], -1
	s_cmp_lt_i32 s36, 16
	v_ashrrev_i32_e32 v229, 31, v228
	v_lshlrev_b32_e32 v192, 1, v212
	v_ashrrev_i32_e32 v227, 31, v226
	v_or_b32_e32 v224, 32, v228
	v_or_b32_e32 v222, 48, v228
	s_cbranch_scc0 .LBB0_203
	s_and_b32 s7, s36, 7
	s_cmp_gt_i32 s36, 7
	s_cselect_b64 vcc, -1, 0
	s_and_b64 s[4:5], vcc, exec
	s_mov_b32 s4, 0x15000000
	s_cselect_b32 s4, s4, 0xd000000
	s_add_u32 s4, s50, s4
	s_addc_u32 s5, s51, 0
	s_lshl_b32 s9, s7, 9
	s_add_u32 s4, s4, s9
	v_cvt_f32_ubyte0_e32 v128, s7
	s_addc_u32 s5, s5, 0
	v_sub_f32_e32 v128, 0xc0a00000, v128
	s_mov_b32 s7, 0xc2fc0000
	v_lshl_add_u64 v[230:231], s[4:5], 0, v[192:193]
	v_cmp_gt_f32_e64 s[4:5], s7, v128
	v_ashrrev_i32_e32 v225, 31, v224
	s_nop 0
	v_cndmask_b32_e64 v129, 0, v234, s[4:5]
	v_add_f32_e32 v128, v128, v129
	v_exp_f32_e32 v128, v128
	s_and_b64 s[4:5], s[4:5], exec
	s_cselect_b32 s4, 0xffffffc0, 0
	v_mov_b32_e32 v129, v193
	v_ldexp_f32 v128, v128, s4
	v_sub_f32_e32 v128, 1.0, v128
	v_log_f32_e32 v241, v128
	v_lshlrev_b32_e32 v128, 9, v228
	v_and_b32_e32 v128, 0x1f9e00, v128
	v_lshl_add_u64 v[130:131], v[214:215], 0, v[128:129]
	v_lshl_add_u64 v[132:133], v[216:217], 0, v[128:129]
	global_load_dwordx4 v[180:183], v[130:131], off offset:16
	global_load_dwordx4 v[188:191], v[130:131], off
	global_load_dwordx4 v[176:179], v[132:133], off offset:16
	global_load_dwordx4 v[184:187], v[132:133], off
	v_or_b32_e32 v130, 0x2000, v128
	v_mov_b32_e32 v131, v193
	v_lshl_add_u64 v[132:133], v[214:215], 0, v[130:131]
	v_lshl_add_u64 v[130:131], v[216:217], 0, v[130:131]
	global_load_dwordx4 v[164:167], v[132:133], off offset:16
	global_load_dwordx4 v[172:175], v[132:133], off
	global_load_dwordx4 v[160:163], v[130:131], off offset:16
	global_load_dwordx4 v[168:171], v[130:131], off
	v_mul_f32_e64 v196, v241, -v239
	v_cmp_gt_f32_e64 s[4:5], s7, v196
	v_or_b32_e32 v130, 0x4000, v128
	v_mov_b32_e32 v131, v193
	v_cndmask_b32_e64 v196, 0, v234, s[4:5]
	v_fma_f32 v196, v241, -v239, v196
	v_exp_f32_e32 v196, v196
	v_cndmask_b32_e64 v197, 0, v235, s[4:5]
	v_lshl_add_u64 v[132:133], v[214:215], 0, v[130:131]
	v_lshl_add_u64 v[130:131], v[216:217], 0, v[130:131]
	v_ldexp_f32 v196, v196, v197
	v_mul_f32_e32 v196, 0x3d800000, v196
	v_cndmask_b32_e32 v242, 1.0, v196, vcc
	v_mov_b32_e32 v196, v124
	v_mov_b32_e32 v197, v112
	global_load_dwordx4 v[148:151], v[132:133], off offset:16
	global_load_dwordx4 v[156:159], v[132:133], off
	global_load_dwordx4 v[144:147], v[130:131], off offset:16
	global_load_dwordx4 v[152:155], v[130:131], off
	v_or_b32_e32 v128, 0x6000, v128
	v_lshl_add_u64 v[130:131], v[214:215], 0, v[128:129]
	v_lshl_add_u64 v[136:137], v[216:217], 0, v[128:129]
	global_load_dwordx4 v[132:135], v[130:131], off offset:16
	global_load_dwordx4 v[140:143], v[130:131], off
	s_nop 0
	global_load_dwordx4 v[128:131], v[136:137], off offset:16
	s_nop 0
	global_load_dwordx4 v[136:139], v[136:137], off
	s_movk_i32 s4, 0x5f
	s_waitcnt vmcnt(0)
	v_mov_b32_e32 v198, v188
	v_mov_b32_e32 v199, v184
	v_pk_mul_f32 v[196:197], v[196:197], v[198:199]
	s_nop 0
	v_sub_f32_e32 v184, v196, v197
	v_mov_b32_e32 v196, v112
	v_mov_b32_e32 v197, v124
	v_pk_mul_f32 v[196:197], v[196:197], v[198:199]
	v_mul_f32_e32 v223, v242, v184
	v_add_f32_e32 v184, v196, v197
	v_mul_f32_e32 v198, v242, v184
	v_mov_b32_e32 v196, v125
	v_mov_b32_e32 v197, v113
	v_mov_b32_e32 v184, v189
	v_pk_mul_f32 v[188:189], v[196:197], v[184:185]
	s_nop 0
	v_sub_f32_e32 v188, v188, v189
	v_mul_f32_e32 v196, v242, v188
	v_mov_b32_e32 v188, v113
	v_mov_b32_e32 v189, v125
	v_pk_mul_f32 v[184:185], v[188:189], v[184:185]
	v_mov_b32_e32 v188, v190
	v_add_f32_e32 v184, v184, v185
	v_mul_f32_e32 v197, v242, v184
	v_mov_b32_e32 v184, v126
	v_mov_b32_e32 v185, v114
	v_mov_b32_e32 v189, v186
	v_pk_mul_f32 v[184:185], v[184:185], v[188:189]
	v_mov_b32_e32 v186, v191
	v_sub_f32_e32 v184, v184, v185
	v_mul_f32_e32 v190, v242, v184
	v_mov_b32_e32 v184, v114
	v_mov_b32_e32 v185, v126
	v_pk_mul_f32 v[184:185], v[184:185], v[188:189]
	s_nop 0
	v_add_f32_e32 v184, v184, v185
	v_mul_f32_e32 v188, v242, v184
	v_mov_b32_e32 v184, v127
	v_mov_b32_e32 v185, v115
	v_pk_mul_f32 v[184:185], v[184:185], v[186:187]
	s_nop 0
	v_sub_f32_e32 v184, v184, v185
	v_mul_f32_e32 v189, v242, v184
	v_mov_b32_e32 v184, v115
	v_mov_b32_e32 v185, v127
	v_pk_mul_f32 v[184:185], v[184:185], v[186:187]
	v_mov_b32_e32 v186, v180
	v_add_f32_e32 v184, v184, v185
	v_mul_f32_e32 v191, v242, v184
	v_mov_b32_e32 v184, v120
	v_mov_b32_e32 v185, v104
	v_mov_b32_e32 v187, v176
	v_pk_mul_f32 v[184:185], v[184:185], v[186:187]
	s_nop 0
	v_sub_f32_e32 v176, v184, v185
	v_mov_b32_e32 v184, v104
	v_mov_b32_e32 v185, v120
	v_pk_mul_f32 v[184:185], v[184:185], v[186:187]
	v_mul_f32_e32 v199, v242, v176
	v_add_f32_e32 v176, v184, v185
	v_mul_f32_e32 v186, v242, v176
	v_mov_b32_e32 v184, v121
	v_mov_b32_e32 v185, v105
	v_mov_b32_e32 v176, v181
	v_pk_mul_f32 v[180:181], v[184:185], v[176:177]
	s_nop 0
	v_sub_f32_e32 v180, v180, v181
	v_mul_f32_e32 v184, v242, v180
	v_mov_b32_e32 v180, v105
	v_mov_b32_e32 v181, v121
	v_pk_mul_f32 v[176:177], v[180:181], v[176:177]
	v_mov_b32_e32 v180, v182
	v_add_f32_e32 v176, v176, v177
	v_mul_f32_e32 v185, v242, v176
	v_mov_b32_e32 v176, v122
	v_mov_b32_e32 v177, v106
	v_mov_b32_e32 v181, v178
	v_pk_mul_f32 v[176:177], v[176:177], v[180:181]
	v_mov_b32_e32 v178, v183
	v_sub_f32_e32 v176, v176, v177
	v_mul_f32_e32 v182, v242, v176
	v_mov_b32_e32 v176, v106
	v_mov_b32_e32 v177, v122
	v_pk_mul_f32 v[176:177], v[176:177], v[180:181]
	s_nop 0
	v_add_f32_e32 v176, v176, v177
	v_mul_f32_e32 v187, v242, v176
	v_mov_b32_e32 v176, v123
	v_mov_b32_e32 v177, v107
	v_pk_mul_f32 v[176:177], v[176:177], v[178:179]
	s_nop 0
	v_sub_f32_e32 v176, v176, v177
	v_mul_f32_e32 v181, v242, v176
	v_mov_b32_e32 v176, v107
	v_mov_b32_e32 v177, v123
	v_pk_mul_f32 v[176:177], v[176:177], v[178:179]
	v_cvt_pk_bf16_f32 v178, v223, v196
	v_cvt_pk_bf16_f32 v179, v190, v189
	v_cvt_pk_bf16_f32 v180, v199, v184
	v_cvt_pk_bf16_f32 v181, v182, v181
	v_cvt_pk_bf16_f32 v182, v198, v197
	s_nop 0
	v_add_f32_e32 v176, v176, v177
	v_mul_f32_e32 v176, v242, v176
	v_cvt_pk_bf16_f32 v183, v188, v191
	v_cvt_pk_bf16_f32 v184, v186, v185
	v_cvt_pk_bf16_f32 v185, v187, v176
	v_lshlrev_b64 v[176:177], 12, v[228:229]
	v_lshl_add_u64 v[176:177], v[230:231], 0, v[176:177]
	global_store_dwordx4 v[176:177], v[178:181], off
	global_store_dwordx4 v[176:177], v[182:185], off offset:256
	v_ashrrev_i32_e32 v223, 31, v222
	v_bitop3_b32 v178, v228, s4, 16 bitop3:0xc8
	v_add_u32_e32 v178, 1, v178
	v_cvt_f32_ubyte0_e32 v178, v178
	v_mul_f32_e64 v179, v241, -v178
	v_cmp_gt_f32_e64 s[4:5], s7, v179
	v_mov_b32_e32 v181, v168
	v_mov_b32_e32 v190, v60
	v_cndmask_b32_e64 v180, 0, v234, s[4:5]
	v_fma_f32 v178, v241, -v178, v180
	v_exp_f32_e32 v178, v178
	v_cndmask_b32_e64 v179, 0, v235, s[4:5]
	v_mov_b32_e32 v180, v172
	s_movk_i32 s4, 0x6f
	v_ldexp_f32 v178, v178, v179
	v_mul_f32_e32 v178, 0x3d800000, v178
	v_cndmask_b32_e32 v182, 1.0, v178, vcc
	v_mov_b32_e32 v178, v116
	v_mov_b32_e32 v179, v96
	v_pk_mul_f32 v[178:179], v[178:179], v[180:181]
	v_mov_b32_e32 v191, v48
	v_sub_f32_e32 v168, v178, v179
	v_mov_b32_e32 v178, v96
	v_mov_b32_e32 v179, v116
	v_pk_mul_f32 v[178:179], v[178:179], v[180:181]
	v_mul_f32_e32 v183, v182, v168
	v_add_f32_e32 v168, v178, v179
	v_mul_f32_e32 v180, v182, v168
	v_mov_b32_e32 v178, v117
	v_mov_b32_e32 v179, v97
	v_mov_b32_e32 v168, v173
	v_pk_mul_f32 v[172:173], v[178:179], v[168:169]
	s_nop 0
	v_sub_f32_e32 v172, v172, v173
	v_mul_f32_e32 v178, v182, v172
	v_mov_b32_e32 v172, v97
	v_mov_b32_e32 v173, v117
	v_pk_mul_f32 v[168:169], v[172:173], v[168:169]
	v_mov_b32_e32 v172, v174
	v_add_f32_e32 v168, v168, v169
	v_mul_f32_e32 v179, v182, v168
	v_mov_b32_e32 v168, v118
	v_mov_b32_e32 v169, v98
	v_mov_b32_e32 v173, v170
	v_pk_mul_f32 v[168:169], v[168:169], v[172:173]
	v_mov_b32_e32 v170, v175
	v_sub_f32_e32 v168, v168, v169
	v_mul_f32_e32 v174, v182, v168
	v_mov_b32_e32 v168, v98
	v_mov_b32_e32 v169, v118
	v_pk_mul_f32 v[168:169], v[168:169], v[172:173]
	s_nop 0
	v_add_f32_e32 v168, v168, v169
	v_mul_f32_e32 v172, v182, v168
	v_mov_b32_e32 v168, v119
	v_mov_b32_e32 v169, v99
	v_pk_mul_f32 v[168:169], v[168:169], v[170:171]
	s_nop 0
	v_sub_f32_e32 v168, v168, v169
	v_mul_f32_e32 v173, v182, v168
	v_mov_b32_e32 v168, v99
	v_mov_b32_e32 v169, v119
	v_pk_mul_f32 v[168:169], v[168:169], v[170:171]
	v_mov_b32_e32 v170, v164
	v_add_f32_e32 v168, v168, v169
	v_mul_f32_e32 v175, v182, v168
	v_mov_b32_e32 v168, v108
	v_mov_b32_e32 v169, v88
	v_mov_b32_e32 v171, v160
	v_pk_mul_f32 v[168:169], v[168:169], v[170:171]
	s_nop 0
	v_sub_f32_e32 v160, v168, v169
	v_mov_b32_e32 v168, v88
	v_mov_b32_e32 v169, v108
	v_pk_mul_f32 v[168:169], v[168:169], v[170:171]
	v_mul_f32_e32 v181, v182, v160
	v_add_f32_e32 v160, v168, v169
	v_mul_f32_e32 v170, v182, v160
	v_mov_b32_e32 v168, v109
	v_mov_b32_e32 v169, v89
	v_mov_b32_e32 v160, v165
	v_pk_mul_f32 v[164:165], v[168:169], v[160:161]
	s_nop 0
	v_sub_f32_e32 v164, v164, v165
	v_mul_f32_e32 v168, v182, v164
	v_mov_b32_e32 v164, v89
	v_mov_b32_e32 v165, v109
	v_pk_mul_f32 v[160:161], v[164:165], v[160:161]
	v_mov_b32_e32 v164, v166
	v_add_f32_e32 v160, v160, v161
	v_mul_f32_e32 v169, v182, v160
	v_mov_b32_e32 v160, v110
	v_mov_b32_e32 v161, v90
	v_mov_b32_e32 v165, v162
	v_pk_mul_f32 v[160:161], v[160:161], v[164:165]
	v_mov_b32_e32 v162, v167
	v_sub_f32_e32 v160, v160, v161
	v_mul_f32_e32 v166, v182, v160
	v_mov_b32_e32 v160, v90
	v_mov_b32_e32 v161, v110
	v_pk_mul_f32 v[160:161], v[160:161], v[164:165]
	s_nop 0
	v_add_f32_e32 v160, v160, v161
	v_mul_f32_e32 v171, v182, v160
	v_mov_b32_e32 v160, v111
	v_mov_b32_e32 v161, v91
	v_pk_mul_f32 v[160:161], v[160:161], v[162:163]
	s_nop 0
	v_sub_f32_e32 v160, v160, v161
	v_mul_f32_e32 v164, v182, v160
	v_mov_b32_e32 v160, v91
	v_mov_b32_e32 v161, v111
	v_pk_mul_f32 v[160:161], v[160:161], v[162:163]
	s_nop 0
	v_add_f32_e32 v160, v160, v161
	v_mul_f32_e32 v167, v182, v160
	v_cvt_pk_bf16_f32 v160, v183, v178
	v_cvt_pk_bf16_f32 v161, v174, v173
	v_cvt_pk_bf16_f32 v162, v181, v168
	v_cvt_pk_bf16_f32 v163, v166, v164
	v_cvt_pk_bf16_f32 v164, v180, v179
	v_cvt_pk_bf16_f32 v165, v172, v175
	v_cvt_pk_bf16_f32 v166, v170, v169
	v_lshlrev_b64 v[168:169], 12, v[226:227]
	v_lshl_add_u64 v[168:169], v[230:231], 0, v[168:169]
	v_cvt_pk_bf16_f32 v167, v171, v167
	global_store_dwordx4 v[168:169], v[160:163], off
	global_store_dwordx4 v[168:169], v[164:167], off offset:256
	s_nop 0
	v_bitop3_b32 v160, v228, s4, 32 bitop3:0xc8
	v_add_u32_e32 v160, 1, v160
	v_cvt_f32_ubyte0_e32 v160, v160
	v_mul_f32_e64 v161, v241, -v160
	v_cmp_gt_f32_e64 s[4:5], s7, v161
	v_mov_b32_e32 v163, v152
	s_nop 0
	v_cndmask_b32_e64 v162, 0, v234, s[4:5]
	v_fma_f32 v160, v241, -v160, v162
	v_exp_f32_e32 v160, v160
	v_cndmask_b32_e64 v161, 0, v235, s[4:5]
	v_mov_b32_e32 v162, v156
	s_movk_i32 s4, 0x7f
	v_ldexp_f32 v160, v160, v161
	v_mul_f32_e32 v160, 0x3d800000, v160
	v_cndmask_b32_e32 v164, 1.0, v160, vcc
	v_mov_b32_e32 v160, v100
	v_mov_b32_e32 v161, v80
	v_pk_mul_f32 v[160:161], v[160:161], v[162:163]
	s_nop 0
	v_sub_f32_e32 v152, v160, v161
	v_mov_b32_e32 v160, v80
	v_mov_b32_e32 v161, v100
	v_pk_mul_f32 v[160:161], v[160:161], v[162:163]
	v_mul_f32_e32 v165, v164, v152
	v_add_f32_e32 v152, v160, v161
	v_mul_f32_e32 v162, v164, v152
	v_mov_b32_e32 v160, v101
	v_mov_b32_e32 v161, v81
	v_mov_b32_e32 v152, v157
	v_pk_mul_f32 v[156:157], v[160:161], v[152:153]
	s_nop 0
	v_sub_f32_e32 v156, v156, v157
	v_mul_f32_e32 v160, v164, v156
	v_mov_b32_e32 v156, v81
	v_mov_b32_e32 v157, v101
	v_pk_mul_f32 v[152:153], v[156:157], v[152:153]
	v_mov_b32_e32 v156, v158
	v_add_f32_e32 v152, v152, v153
	v_mul_f32_e32 v161, v164, v152
	v_mov_b32_e32 v152, v102
	v_mov_b32_e32 v153, v82
	v_mov_b32_e32 v157, v154
	v_pk_mul_f32 v[152:153], v[152:153], v[156:157]
	v_mov_b32_e32 v154, v159
	v_sub_f32_e32 v152, v152, v153
	v_mul_f32_e32 v158, v164, v152
	v_mov_b32_e32 v152, v82
	v_mov_b32_e32 v153, v102
	v_pk_mul_f32 v[152:153], v[152:153], v[156:157]
	s_nop 0
	v_add_f32_e32 v152, v152, v153
	v_mul_f32_e32 v156, v164, v152
	v_mov_b32_e32 v152, v103
	v_mov_b32_e32 v153, v83
	v_pk_mul_f32 v[152:153], v[152:153], v[154:155]
	s_nop 0
	v_sub_f32_e32 v152, v152, v153
	v_mul_f32_e32 v157, v164, v152
	v_mov_b32_e32 v152, v83
	v_mov_b32_e32 v153, v103
	v_pk_mul_f32 v[152:153], v[152:153], v[154:155]
	v_mov_b32_e32 v154, v148
	v_add_f32_e32 v152, v152, v153
	v_mul_f32_e32 v159, v164, v152
	v_mov_b32_e32 v152, v92
	v_mov_b32_e32 v153, v72
	v_mov_b32_e32 v155, v144
	v_pk_mul_f32 v[152:153], v[152:153], v[154:155]
	s_nop 0
	v_sub_f32_e32 v144, v152, v153
	v_mov_b32_e32 v152, v72
	v_mov_b32_e32 v153, v92
	v_pk_mul_f32 v[152:153], v[152:153], v[154:155]
	v_mul_f32_e32 v163, v164, v144
	v_add_f32_e32 v144, v152, v153
	v_mul_f32_e32 v154, v164, v144
	v_mov_b32_e32 v152, v93
	v_mov_b32_e32 v153, v73
	v_mov_b32_e32 v144, v149
	v_pk_mul_f32 v[148:149], v[152:153], v[144:145]
	s_nop 0
	v_sub_f32_e32 v148, v148, v149
	v_mul_f32_e32 v152, v164, v148
	v_mov_b32_e32 v148, v73
	v_mov_b32_e32 v149, v93
	v_pk_mul_f32 v[144:145], v[148:149], v[144:145]
	v_mov_b32_e32 v148, v150
	v_add_f32_e32 v144, v144, v145
	v_mul_f32_e32 v153, v164, v144
	v_mov_b32_e32 v144, v94
	v_mov_b32_e32 v145, v74
	v_mov_b32_e32 v149, v146
	v_pk_mul_f32 v[144:145], v[144:145], v[148:149]
	v_mov_b32_e32 v146, v151
	v_sub_f32_e32 v144, v144, v145
	v_mul_f32_e32 v150, v164, v144
	v_mov_b32_e32 v144, v74
	v_mov_b32_e32 v145, v94
	v_pk_mul_f32 v[144:145], v[144:145], v[148:149]
	s_nop 0
	v_add_f32_e32 v144, v144, v145
	v_mul_f32_e32 v155, v164, v144
	v_mov_b32_e32 v144, v95
	v_mov_b32_e32 v145, v75
	v_pk_mul_f32 v[144:145], v[144:145], v[146:147]
	s_nop 0
	v_sub_f32_e32 v144, v144, v145
	v_mul_f32_e32 v148, v164, v144
	v_mov_b32_e32 v144, v75
	v_mov_b32_e32 v145, v95
	v_pk_mul_f32 v[144:145], v[144:145], v[146:147]
	s_nop 0
	v_add_f32_e32 v144, v144, v145
	v_mul_f32_e32 v151, v164, v144
	v_cvt_pk_bf16_f32 v144, v165, v160
	v_cvt_pk_bf16_f32 v145, v158, v157
	v_cvt_pk_bf16_f32 v146, v163, v152
	v_cvt_pk_bf16_f32 v147, v150, v148
	v_cvt_pk_bf16_f32 v148, v162, v161
	v_cvt_pk_bf16_f32 v149, v156, v159
	v_cvt_pk_bf16_f32 v150, v154, v153
	v_lshlrev_b64 v[152:153], 12, v[224:225]
	v_lshl_add_u64 v[152:153], v[230:231], 0, v[152:153]
	v_cvt_pk_bf16_f32 v151, v155, v151
	global_store_dwordx4 v[152:153], v[144:147], off
	global_store_dwordx4 v[152:153], v[148:151], off offset:256
	s_nop 0
	v_bitop3_b32 v144, v228, s4, 48 bitop3:0xc8
	v_add_u32_e32 v144, 1, v144
	v_cvt_f32_ubyte0_e32 v144, v144
	v_mul_f32_e64 v145, v241, -v144
	v_cmp_gt_f32_e64 s[4:5], s7, v145
	v_mov_b32_e32 v147, v136
	s_nop 0
	v_cndmask_b32_e64 v146, 0, v234, s[4:5]
	v_fma_f32 v144, v241, -v144, v146
	v_exp_f32_e32 v144, v144
	v_cndmask_b32_e64 v145, 0, v235, s[4:5]
	v_mov_b32_e32 v146, v140
	s_mov_b64 s[4:5], 0x80000
	v_ldexp_f32 v144, v144, v145
	v_mul_f32_e32 v144, 0x3d800000, v144
	v_cndmask_b32_e32 v148, 1.0, v144, vcc
	v_mov_b32_e32 v144, v84
	v_mov_b32_e32 v145, v68
	v_pk_mul_f32 v[144:145], v[144:145], v[146:147]
	s_nop 0
	v_sub_f32_e32 v136, v144, v145
	v_mov_b32_e32 v144, v68
	v_mov_b32_e32 v145, v84
	v_pk_mul_f32 v[144:145], v[144:145], v[146:147]
	v_mul_f32_e32 v149, v148, v136
	v_add_f32_e32 v136, v144, v145
	v_mul_f32_e32 v146, v148, v136
	v_mov_b32_e32 v144, v85
	v_mov_b32_e32 v145, v69
	v_mov_b32_e32 v136, v141
	v_pk_mul_f32 v[140:141], v[144:145], v[136:137]
	s_nop 0
	v_sub_f32_e32 v140, v140, v141
	v_mul_f32_e32 v144, v148, v140
	v_mov_b32_e32 v140, v69
	v_mov_b32_e32 v141, v85
	v_pk_mul_f32 v[136:137], v[140:141], v[136:137]
	v_mov_b32_e32 v140, v142
	v_add_f32_e32 v136, v136, v137
	v_mul_f32_e32 v145, v148, v136
	v_mov_b32_e32 v136, v86
	v_mov_b32_e32 v137, v70
	v_mov_b32_e32 v141, v138
	v_pk_mul_f32 v[136:137], v[136:137], v[140:141]
	v_mov_b32_e32 v138, v143
	v_sub_f32_e32 v136, v136, v137
	v_mul_f32_e32 v142, v148, v136
	v_mov_b32_e32 v136, v70
	v_mov_b32_e32 v137, v86
	v_pk_mul_f32 v[136:137], v[136:137], v[140:141]
	s_nop 0
	v_add_f32_e32 v136, v136, v137
	v_mul_f32_e32 v140, v148, v136
	v_mov_b32_e32 v136, v87
	v_mov_b32_e32 v137, v71
	v_pk_mul_f32 v[136:137], v[136:137], v[138:139]
	s_nop 0
	v_sub_f32_e32 v136, v136, v137
	v_mul_f32_e32 v141, v148, v136
	v_mov_b32_e32 v136, v71
	v_mov_b32_e32 v137, v87
	v_pk_mul_f32 v[136:137], v[136:137], v[138:139]
	v_mov_b32_e32 v138, v132
	v_add_f32_e32 v136, v136, v137
	v_mul_f32_e32 v143, v148, v136
	v_mov_b32_e32 v136, v76
	v_mov_b32_e32 v137, v64
	v_mov_b32_e32 v139, v128
	v_pk_mul_f32 v[136:137], v[136:137], v[138:139]
	s_nop 0
	v_sub_f32_e32 v128, v136, v137
	v_mov_b32_e32 v136, v64
	v_mov_b32_e32 v137, v76
	v_pk_mul_f32 v[136:137], v[136:137], v[138:139]
	v_mul_f32_e32 v147, v148, v128
	v_add_f32_e32 v128, v136, v137
	v_mul_f32_e32 v138, v148, v128
	v_mov_b32_e32 v136, v77
	v_mov_b32_e32 v137, v65
	v_mov_b32_e32 v128, v133
	v_pk_mul_f32 v[132:133], v[136:137], v[128:129]
	s_nop 0
	v_sub_f32_e32 v132, v132, v133
	v_mul_f32_e32 v136, v148, v132
	v_mov_b32_e32 v132, v65
	v_mov_b32_e32 v133, v77
	v_pk_mul_f32 v[128:129], v[132:133], v[128:129]
	v_mov_b32_e32 v132, v134
	v_add_f32_e32 v128, v128, v129
	v_mul_f32_e32 v137, v148, v128
	v_mov_b32_e32 v128, v78
	v_mov_b32_e32 v129, v66
	v_mov_b32_e32 v133, v130
	v_pk_mul_f32 v[128:129], v[128:129], v[132:133]
	v_mov_b32_e32 v130, v135
	v_sub_f32_e32 v128, v128, v129
	v_mul_f32_e32 v134, v148, v128
	v_mov_b32_e32 v128, v66
	v_mov_b32_e32 v129, v78
	v_pk_mul_f32 v[128:129], v[128:129], v[132:133]
	s_nop 0
	v_add_f32_e32 v128, v128, v129
	v_mul_f32_e32 v139, v148, v128
	v_mov_b32_e32 v128, v79
	v_mov_b32_e32 v129, v67
	v_pk_mul_f32 v[128:129], v[128:129], v[130:131]
	s_nop 0
	v_sub_f32_e32 v128, v128, v129
	v_mul_f32_e32 v132, v148, v128
	v_mov_b32_e32 v128, v67
	v_mov_b32_e32 v129, v79
	v_pk_mul_f32 v[128:129], v[128:129], v[130:131]
	s_nop 0
	v_add_f32_e32 v128, v128, v129
	v_mul_f32_e32 v135, v148, v128
	v_cvt_pk_bf16_f32 v128, v149, v144
	v_cvt_pk_bf16_f32 v129, v142, v141
	v_cvt_pk_bf16_f32 v130, v147, v136
	v_cvt_pk_bf16_f32 v131, v134, v132
	v_cvt_pk_bf16_f32 v132, v146, v145
	v_cvt_pk_bf16_f32 v133, v140, v143
	v_cvt_pk_bf16_f32 v134, v138, v137
	v_lshlrev_b64 v[136:137], 12, v[222:223]
	v_lshl_add_u64 v[136:137], v[230:231], 0, v[136:137]
	v_cvt_pk_bf16_f32 v135, v139, v135
	global_store_dwordx4 v[136:137], v[128:131], off
	global_store_dwordx4 v[136:137], v[132:135], off offset:256
	s_nop 0
	v_mov_b32_e32 v128, 0x4000
	v_lshl_add_u32 v128, v228, 7, v128
	v_and_b32_e32 v128, 0x7e780, v128
	v_lshlrev_b32_e32 v128, 2, v128
	v_mov_b32_e32 v129, v193
	v_lshl_add_u64 v[130:131], v[214:215], 0, v[128:129]
	v_lshl_add_u64 v[132:133], v[216:217], 0, v[128:129]
	global_load_dwordx4 v[168:171], v[130:131], off offset:16
	global_load_dwordx4 v[172:175], v[130:131], off
	global_load_dwordx4 v[178:181], v[132:133], off offset:16
	global_load_dwordx4 v[182:185], v[132:133], off
	v_or_b32_e32 v130, 0x2000, v128
	v_mov_b32_e32 v131, v193
	v_lshl_add_u64 v[132:133], v[214:215], 0, v[130:131]
	v_lshl_add_u64 v[130:131], v[216:217], 0, v[130:131]
	global_load_dwordx4 v[164:167], v[132:133], off offset:16
	global_load_dwordx4 v[186:189], v[132:133], off
	global_load_dwordx4 v[160:163], v[130:131], off offset:16
	global_load_dwordx4 v[196:199], v[130:131], off
	v_or_b32_e32 v130, 0x4000, v128
	v_mov_b32_e32 v131, v193
	v_lshl_add_u64 v[132:133], v[214:215], 0, v[130:131]
	v_lshl_add_u64 v[130:131], v[216:217], 0, v[130:131]
	global_load_dwordx4 v[148:151], v[132:133], off offset:16
	global_load_dwordx4 v[156:159], v[132:133], off
	global_load_dwordx4 v[144:147], v[130:131], off offset:16
	global_load_dwordx4 v[152:155], v[130:131], off
	v_or_b32_e32 v128, 0x6000, v128
	v_lshl_add_u64 v[130:131], v[214:215], 0, v[128:129]
	v_lshl_add_u64 v[136:137], v[216:217], 0, v[128:129]
	global_load_dwordx4 v[132:135], v[130:131], off offset:16
	global_load_dwordx4 v[140:143], v[130:131], off
	s_nop 0
	global_load_dwordx4 v[128:131], v[136:137], off offset:16
	s_nop 0
	global_load_dwordx4 v[136:139], v[136:137], off
	s_waitcnt vmcnt(0)
	v_mov_b32_e32 v244, v172
	v_mov_b32_e32 v245, v182
	v_pk_mul_f32 v[190:191], v[190:191], v[244:245]
	v_mov_b32_e32 v182, v173
	v_sub_f32_e32 v172, v190, v191
	v_mov_b32_e32 v190, v48
	v_mov_b32_e32 v191, v60
	v_pk_mul_f32 v[190:191], v[190:191], v[244:245]
	v_mul_f32_e32 v223, v242, v172
	v_add_f32_e32 v172, v190, v191
	v_mov_b32_e32 v190, v61
	v_mov_b32_e32 v191, v49
	v_mul_f32_e32 v225, v242, v172
	v_pk_mul_f32 v[172:173], v[190:191], v[182:183]
	s_nop 0
	v_sub_f32_e32 v172, v172, v173
	v_mul_f32_e32 v190, v242, v172
	v_mov_b32_e32 v172, v49
	v_mov_b32_e32 v173, v61
	v_pk_mul_f32 v[172:173], v[172:173], v[182:183]
	v_mov_b32_e32 v182, v174
	v_add_f32_e32 v172, v172, v173
	v_mul_f32_e32 v191, v242, v172
	v_mov_b32_e32 v172, v62
	v_mov_b32_e32 v173, v50
	v_mov_b32_e32 v183, v184
	v_pk_mul_f32 v[172:173], v[172:173], v[182:183]
	v_mov_b32_e32 v184, v175
	v_sub_f32_e32 v172, v172, v173
	v_mul_f32_e32 v243, v242, v172
	v_mov_b32_e32 v172, v50
	v_mov_b32_e32 v173, v62
	v_pk_mul_f32 v[172:173], v[172:173], v[182:183]
	v_mov_b32_e32 v174, v168
	v_add_f32_e32 v172, v172, v173
	v_mul_f32_e32 v182, v242, v172
	v_mov_b32_e32 v172, v63
	v_mov_b32_e32 v173, v51
	v_pk_mul_f32 v[172:173], v[172:173], v[184:185]
	v_mov_b32_e32 v175, v178
	v_sub_f32_e32 v172, v172, v173
	v_mul_f32_e32 v183, v242, v172
	v_mov_b32_e32 v172, v51
	v_mov_b32_e32 v173, v63
	v_pk_mul_f32 v[172:173], v[172:173], v[184:185]
	v_mov_b32_e32 v178, v169
	v_add_f32_e32 v172, v172, v173
	v_mul_f32_e32 v184, v242, v172
	v_mov_b32_e32 v172, v56
	v_mov_b32_e32 v173, v40
	v_pk_mul_f32 v[172:173], v[172:173], v[174:175]
	s_nop 0
	v_sub_f32_e32 v168, v172, v173
	v_mov_b32_e32 v172, v40
	v_mov_b32_e32 v173, v56
	v_pk_mul_f32 v[172:173], v[172:173], v[174:175]
	v_mul_f32_e32 v185, v242, v168
	v_add_f32_e32 v168, v172, v173
	v_mov_b32_e32 v172, v57
	v_mov_b32_e32 v173, v41
	v_mul_f32_e32 v174, v242, v168
	v_pk_mul_f32 v[168:169], v[172:173], v[178:179]
	v_mov_b32_e32 v172, v170
	v_sub_f32_e32 v168, v168, v169
	v_mul_f32_e32 v175, v242, v168
	v_mov_b32_e32 v168, v41
	v_mov_b32_e32 v169, v57
	v_pk_mul_f32 v[168:169], v[168:169], v[178:179]
	v_mov_b32_e32 v173, v180
	v_add_f32_e32 v168, v168, v169
	v_mul_f32_e32 v178, v242, v168
	v_mov_b32_e32 v168, v58
	v_mov_b32_e32 v169, v42
	v_pk_mul_f32 v[168:169], v[168:169], v[172:173]
	v_mov_b32_e32 v180, v171
	v_sub_f32_e32 v168, v168, v169
	v_mul_f32_e32 v179, v242, v168
	v_mov_b32_e32 v168, v42
	v_mov_b32_e32 v169, v58
	v_pk_mul_f32 v[168:169], v[168:169], v[172:173]
	s_nop 0
	v_add_f32_e32 v168, v168, v169
	v_mul_f32_e32 v244, v242, v168
	v_mov_b32_e32 v168, v59
	v_mov_b32_e32 v169, v43
	v_pk_mul_f32 v[168:169], v[168:169], v[180:181]
	s_nop 0
	v_sub_f32_e32 v168, v168, v169
	v_mul_f32_e32 v171, v242, v168
	v_mov_b32_e32 v168, v43
	v_mov_b32_e32 v169, v59
	v_pk_mul_f32 v[168:169], v[168:169], v[180:181]
	s_nop 0
	v_add_f32_e32 v168, v168, v169
	v_mul_f32_e32 v180, v242, v168
	v_cvt_pk_bf16_f32 v168, v223, v190
	v_cvt_pk_bf16_f32 v169, v243, v183
	v_cvt_pk_bf16_f32 v170, v185, v175
	v_cvt_pk_bf16_f32 v171, v179, v171
	v_cvt_pk_bf16_f32 v172, v225, v191
	v_cvt_pk_bf16_f32 v173, v182, v184
	v_cvt_pk_bf16_f32 v174, v174, v178
	v_lshl_add_u64 v[178:179], v[176:177], 0, s[4:5]
	s_mov_b32 s4, 0x80000
	v_add_co_u32_e64 v176, s[4:5], s4, v176
	v_cvt_pk_bf16_f32 v175, v244, v180
	s_nop 1
	v_addc_co_u32_e64 v177, s[4:5], 0, v177, s[4:5]
	global_store_dwordx4 v[176:177], v[168:171], off
	global_store_dwordx4 v[178:179], v[172:175], off offset:256
	s_nop 0
	v_add_u32_e32 v168, 0x90, v228
	v_and_b32_e32 v169, 0x5f, v168
	v_add_u32_e32 v169, 1, v169
	v_cvt_f32_ubyte0_e32 v169, v169
	v_mul_f32_e64 v170, v241, -v169
	v_cmp_gt_f32_e64 s[4:5], s7, v170
	v_mov_b32_e32 v171, v32
	v_mov_b32_e32 v172, v186
	v_cndmask_b32_e64 v170, 0, v234, s[4:5]
	v_fma_f32 v169, v241, -v169, v170
	v_exp_f32_e32 v169, v169
	v_cndmask_b32_e64 v170, 0, v235, s[4:5]
	v_mov_b32_e32 v173, v196
	v_mov_b32_e32 v196, v187
	v_ldexp_f32 v169, v169, v170
	v_mov_b32_e32 v170, v52
	v_mul_f32_e32 v169, 0x3d800000, v169
	v_pk_mul_f32 v[170:171], v[170:171], v[172:173]
	v_cndmask_b32_e32 v169, 1.0, v169, vcc
	v_sub_f32_e32 v170, v170, v171
	v_mul_f32_e32 v174, v169, v170
	v_mov_b32_e32 v170, v32
	v_mov_b32_e32 v171, v52
	v_pk_mul_f32 v[170:171], v[170:171], v[172:173]
	v_mov_b32_e32 v172, v188
	v_add_f32_e32 v170, v170, v171
	v_mul_f32_e32 v175, v169, v170
	v_mov_b32_e32 v170, v53
	v_mov_b32_e32 v171, v33
	v_pk_mul_f32 v[170:171], v[170:171], v[196:197]
	v_mov_b32_e32 v173, v198
	v_sub_f32_e32 v170, v170, v171
	v_mul_f32_e32 v176, v169, v170
	v_mov_b32_e32 v170, v33
	v_mov_b32_e32 v171, v53
	v_pk_mul_f32 v[170:171], v[170:171], v[196:197]
	v_mov_b32_e32 v198, v189
	v_add_f32_e32 v170, v170, v171
	v_mul_f32_e32 v177, v169, v170
	v_mov_b32_e32 v170, v54
	v_mov_b32_e32 v171, v34
	v_pk_mul_f32 v[170:171], v[170:171], v[172:173]
	s_nop 0
	v_sub_f32_e32 v170, v170, v171
	v_mul_f32_e32 v178, v169, v170
	v_mov_b32_e32 v170, v34
	v_mov_b32_e32 v171, v54
	v_pk_mul_f32 v[170:171], v[170:171], v[172:173]
	v_mov_b32_e32 v172, v164
	v_add_f32_e32 v170, v170, v171
	v_mul_f32_e32 v179, v169, v170
	v_mov_b32_e32 v170, v55
	v_mov_b32_e32 v171, v35
	v_pk_mul_f32 v[170:171], v[170:171], v[198:199]
	v_mov_b32_e32 v173, v160
	v_sub_f32_e32 v170, v170, v171
	v_mul_f32_e32 v180, v169, v170
	v_mov_b32_e32 v170, v35
	v_mov_b32_e32 v171, v55
	v_pk_mul_f32 v[170:171], v[170:171], v[198:199]
	s_nop 0
	v_add_f32_e32 v170, v170, v171
	v_mul_f32_e32 v181, v169, v170
	v_mov_b32_e32 v170, v44
	v_mov_b32_e32 v171, v24
	v_pk_mul_f32 v[170:171], v[170:171], v[172:173]
	s_nop 0
	v_sub_f32_e32 v160, v170, v171
	v_mov_b32_e32 v170, v24
	v_mov_b32_e32 v171, v44
	v_pk_mul_f32 v[170:171], v[170:171], v[172:173]
	v_mul_f32_e32 v182, v169, v160
	v_add_f32_e32 v160, v170, v171
	v_mul_f32_e32 v172, v169, v160
	v_mov_b32_e32 v170, v45
	v_mov_b32_e32 v171, v25
	v_mov_b32_e32 v160, v165
	v_pk_mul_f32 v[164:165], v[170:171], v[160:161]
	s_nop 0
	v_sub_f32_e32 v164, v164, v165
	v_mul_f32_e32 v170, v169, v164
	v_mov_b32_e32 v164, v25
	v_mov_b32_e32 v165, v45
	v_pk_mul_f32 v[160:161], v[164:165], v[160:161]
	v_mov_b32_e32 v164, v166
	v_add_f32_e32 v160, v160, v161
	v_mul_f32_e32 v171, v169, v160
	v_mov_b32_e32 v160, v46
	v_mov_b32_e32 v161, v26
	v_mov_b32_e32 v165, v162
	v_pk_mul_f32 v[160:161], v[160:161], v[164:165]
	v_mov_b32_e32 v162, v167
	v_sub_f32_e32 v160, v160, v161
	v_mul_f32_e32 v166, v169, v160
	v_mov_b32_e32 v160, v26
	v_mov_b32_e32 v161, v46
	v_pk_mul_f32 v[160:161], v[160:161], v[164:165]
	s_nop 0
	v_add_f32_e32 v160, v160, v161
	v_mul_f32_e32 v173, v169, v160
	v_mov_b32_e32 v160, v47
	v_mov_b32_e32 v161, v27
	v_pk_mul_f32 v[160:161], v[160:161], v[162:163]
	s_nop 0
	v_sub_f32_e32 v160, v160, v161
	v_mul_f32_e32 v164, v169, v160
	v_mov_b32_e32 v160, v27
	v_mov_b32_e32 v161, v47
	v_pk_mul_f32 v[160:161], v[160:161], v[162:163]
	s_nop 0
	v_add_f32_e32 v160, v160, v161
	v_mul_f32_e32 v167, v169, v160
	v_ashrrev_i32_e32 v169, 31, v168
	v_lshlrev_b64 v[168:169], 12, v[168:169]
	v_cvt_pk_bf16_f32 v160, v174, v176
	v_cvt_pk_bf16_f32 v161, v178, v180
	v_cvt_pk_bf16_f32 v162, v182, v170
	v_cvt_pk_bf16_f32 v163, v166, v164
	v_lshl_add_u64 v[168:169], v[230:231], 0, v[168:169]
	v_cvt_pk_bf16_f32 v164, v175, v177
	v_cvt_pk_bf16_f32 v165, v179, v181
	v_cvt_pk_bf16_f32 v166, v172, v171
	v_cvt_pk_bf16_f32 v167, v173, v167
	global_store_dwordx4 v[168:169], v[160:163], off
	global_store_dwordx4 v[168:169], v[164:167], off offset:256
	s_nop 0
	v_add_u32_e32 v160, 0xa0, v228
	v_and_b32_e32 v161, 0x6f, v160
	v_add_u32_e32 v161, 1, v161
	v_cvt_f32_ubyte0_e32 v161, v161
	v_mul_f32_e64 v162, v241, -v161
	v_cmp_gt_f32_e64 s[4:5], s7, v162
	v_mov_b32_e32 v163, v16
	v_mov_b32_e32 v164, v156
	v_cndmask_b32_e64 v162, 0, v234, s[4:5]
	v_fma_f32 v161, v241, -v161, v162
	v_exp_f32_e32 v161, v161
	v_cndmask_b32_e64 v162, 0, v235, s[4:5]
	v_mov_b32_e32 v165, v152
	v_ldexp_f32 v161, v161, v162
	v_mov_b32_e32 v162, v36
	v_pk_mul_f32 v[162:163], v[162:163], v[164:165]
	v_mul_f32_e32 v161, 0x3d800000, v161
	v_sub_f32_e32 v152, v162, v163
	v_mov_b32_e32 v162, v16
	v_mov_b32_e32 v163, v36
	v_cndmask_b32_e32 v161, 1.0, v161, vcc
	v_pk_mul_f32 v[162:163], v[162:163], v[164:165]
	v_mul_f32_e32 v166, v161, v152
	v_add_f32_e32 v152, v162, v163
	v_mul_f32_e32 v164, v161, v152
	v_mov_b32_e32 v162, v37
	v_mov_b32_e32 v163, v17
	v_mov_b32_e32 v152, v157
	v_pk_mul_f32 v[156:157], v[162:163], v[152:153]
	s_nop 0
	v_sub_f32_e32 v156, v156, v157
	v_mul_f32_e32 v162, v161, v156
	v_mov_b32_e32 v156, v17
	v_mov_b32_e32 v157, v37
	v_pk_mul_f32 v[152:153], v[156:157], v[152:153]
	v_mov_b32_e32 v156, v158
	v_add_f32_e32 v152, v152, v153
	v_mul_f32_e32 v163, v161, v152
	v_mov_b32_e32 v152, v38
	v_mov_b32_e32 v153, v18
	v_mov_b32_e32 v157, v154
	v_pk_mul_f32 v[152:153], v[152:153], v[156:157]
	v_mov_b32_e32 v154, v159
	v_sub_f32_e32 v152, v152, v153
	v_mul_f32_e32 v158, v161, v152
	v_mov_b32_e32 v152, v18
	v_mov_b32_e32 v153, v38
	v_pk_mul_f32 v[152:153], v[152:153], v[156:157]
	s_nop 0
	v_add_f32_e32 v152, v152, v153
	v_mul_f32_e32 v156, v161, v152
	v_mov_b32_e32 v152, v39
	v_mov_b32_e32 v153, v19
	v_pk_mul_f32 v[152:153], v[152:153], v[154:155]
	s_nop 0
	v_sub_f32_e32 v152, v152, v153
	v_mul_f32_e32 v157, v161, v152
	v_mov_b32_e32 v152, v19
	v_mov_b32_e32 v153, v39
	v_pk_mul_f32 v[152:153], v[152:153], v[154:155]
	v_mov_b32_e32 v154, v148
	v_add_f32_e32 v152, v152, v153
	v_mul_f32_e32 v159, v161, v152
	v_mov_b32_e32 v152, v28
	v_mov_b32_e32 v153, v8
	v_mov_b32_e32 v155, v144
	v_pk_mul_f32 v[152:153], v[152:153], v[154:155]
	s_nop 0
	v_sub_f32_e32 v144, v152, v153
	v_mov_b32_e32 v152, v8
	v_mov_b32_e32 v153, v28
	v_pk_mul_f32 v[152:153], v[152:153], v[154:155]
	v_mul_f32_e32 v165, v161, v144
	v_add_f32_e32 v144, v152, v153
	v_mul_f32_e32 v154, v161, v144
	v_mov_b32_e32 v152, v29
	v_mov_b32_e32 v153, v9
	v_mov_b32_e32 v144, v149
	v_pk_mul_f32 v[148:149], v[152:153], v[144:145]
	s_nop 0
	v_sub_f32_e32 v148, v148, v149
	v_mul_f32_e32 v152, v161, v148
	v_mov_b32_e32 v148, v9
	v_mov_b32_e32 v149, v29
	v_pk_mul_f32 v[144:145], v[148:149], v[144:145]
	v_mov_b32_e32 v148, v150
	v_add_f32_e32 v144, v144, v145
	v_mul_f32_e32 v153, v161, v144
	v_mov_b32_e32 v144, v30
	v_mov_b32_e32 v145, v10
	v_mov_b32_e32 v149, v146
	v_pk_mul_f32 v[144:145], v[144:145], v[148:149]
	v_mov_b32_e32 v146, v151
	v_sub_f32_e32 v144, v144, v145
	v_mul_f32_e32 v150, v161, v144
	v_mov_b32_e32 v144, v10
	v_mov_b32_e32 v145, v30
	v_pk_mul_f32 v[144:145], v[144:145], v[148:149]
	s_nop 0
	v_add_f32_e32 v144, v144, v145
	v_mul_f32_e32 v155, v161, v144
	v_mov_b32_e32 v144, v31
	v_mov_b32_e32 v145, v11
	v_pk_mul_f32 v[144:145], v[144:145], v[146:147]
	s_nop 0
	v_sub_f32_e32 v144, v144, v145
	v_mul_f32_e32 v148, v161, v144
	v_mov_b32_e32 v144, v11
	v_mov_b32_e32 v145, v31
	v_pk_mul_f32 v[144:145], v[144:145], v[146:147]
	s_nop 0
	v_add_f32_e32 v144, v144, v145
	v_mul_f32_e32 v151, v161, v144
	v_ashrrev_i32_e32 v161, 31, v160
	v_cvt_pk_bf16_f32 v144, v166, v162
	v_cvt_pk_bf16_f32 v145, v158, v157
	v_cvt_pk_bf16_f32 v146, v165, v152
	v_cvt_pk_bf16_f32 v147, v150, v148
	v_cvt_pk_bf16_f32 v148, v164, v163
	v_cvt_pk_bf16_f32 v149, v156, v159
	v_cvt_pk_bf16_f32 v150, v154, v153
	v_lshlrev_b64 v[152:153], 12, v[160:161]
	v_lshl_add_u64 v[152:153], v[230:231], 0, v[152:153]
	v_cvt_pk_bf16_f32 v151, v155, v151
	global_store_dwordx4 v[152:153], v[144:147], off
	global_store_dwordx4 v[152:153], v[148:151], off offset:256
	s_nop 0
	v_add_u32_e32 v144, 0xb0, v228
	v_and_b32_e32 v145, 0x7f, v144
	v_add_u32_e32 v145, 1, v145
	v_cvt_f32_ubyte0_e32 v145, v145
	v_mul_f32_e64 v146, v241, -v145
	v_cmp_gt_f32_e64 s[4:5], s7, v146
	v_mov_b32_e32 v147, v4
	v_mov_b32_e32 v148, v140
	v_cndmask_b32_e64 v146, 0, v234, s[4:5]
	v_fma_f32 v145, v241, -v145, v146
	v_exp_f32_e32 v145, v145
	v_cndmask_b32_e64 v146, 0, v235, s[4:5]
	v_mov_b32_e32 v149, v136
	s_mov_b64 s[4:5], 0
	v_ldexp_f32 v145, v145, v146
	v_mov_b32_e32 v146, v20
	v_pk_mul_f32 v[146:147], v[146:147], v[148:149]
	v_mul_f32_e32 v145, 0x3d800000, v145
	v_sub_f32_e32 v136, v146, v147
	v_mov_b32_e32 v146, v4
	v_mov_b32_e32 v147, v20
	v_cndmask_b32_e32 v145, 1.0, v145, vcc
	v_pk_mul_f32 v[146:147], v[146:147], v[148:149]
	v_mul_f32_e32 v150, v145, v136
	v_add_f32_e32 v136, v146, v147
	v_mul_f32_e32 v148, v145, v136
	v_mov_b32_e32 v146, v21
	v_mov_b32_e32 v147, v5
	v_mov_b32_e32 v136, v141
	v_pk_mul_f32 v[140:141], v[146:147], v[136:137]
	s_nop 0
	v_sub_f32_e32 v140, v140, v141
	v_mul_f32_e32 v146, v145, v140
	v_mov_b32_e32 v140, v5
	v_mov_b32_e32 v141, v21
	v_pk_mul_f32 v[136:137], v[140:141], v[136:137]
	v_mov_b32_e32 v140, v142
	v_add_f32_e32 v136, v136, v137
	v_mul_f32_e32 v147, v145, v136
	v_mov_b32_e32 v136, v22
	v_mov_b32_e32 v137, v6
	v_mov_b32_e32 v141, v138
	v_pk_mul_f32 v[136:137], v[136:137], v[140:141]
	v_mov_b32_e32 v138, v143
	v_sub_f32_e32 v136, v136, v137
	v_mul_f32_e32 v142, v145, v136
	v_mov_b32_e32 v136, v6
	v_mov_b32_e32 v137, v22
	v_pk_mul_f32 v[136:137], v[136:137], v[140:141]
	s_nop 0
	v_add_f32_e32 v136, v136, v137
	v_mul_f32_e32 v140, v145, v136
	v_mov_b32_e32 v136, v23
	v_mov_b32_e32 v137, v7
	v_pk_mul_f32 v[136:137], v[136:137], v[138:139]
	s_nop 0
	v_sub_f32_e32 v136, v136, v137
	v_mul_f32_e32 v141, v145, v136
	v_mov_b32_e32 v136, v7
	v_mov_b32_e32 v137, v23
	v_pk_mul_f32 v[136:137], v[136:137], v[138:139]
	v_mov_b32_e32 v138, v132
	v_add_f32_e32 v136, v136, v137
	v_mul_f32_e32 v143, v145, v136
	v_mov_b32_e32 v136, v12
	v_mov_b32_e32 v137, v0
	v_mov_b32_e32 v139, v128
	v_pk_mul_f32 v[136:137], v[136:137], v[138:139]
	s_nop 0
	v_sub_f32_e32 v128, v136, v137
	v_mov_b32_e32 v136, v0
	v_mov_b32_e32 v137, v12
	v_pk_mul_f32 v[136:137], v[136:137], v[138:139]
	v_mul_f32_e32 v149, v145, v128
	v_add_f32_e32 v128, v136, v137
	v_mul_f32_e32 v138, v145, v128
	v_mov_b32_e32 v136, v13
	v_mov_b32_e32 v137, v1
	v_mov_b32_e32 v128, v133
	v_pk_mul_f32 v[132:133], v[136:137], v[128:129]
	s_nop 0
	v_sub_f32_e32 v132, v132, v133
	v_mul_f32_e32 v136, v145, v132
	v_mov_b32_e32 v132, v1
	v_mov_b32_e32 v133, v13
	v_pk_mul_f32 v[128:129], v[132:133], v[128:129]
	v_mov_b32_e32 v132, v134
	v_add_f32_e32 v128, v128, v129
	v_mul_f32_e32 v139, v145, v128
	v_mov_b32_e32 v128, v14
	v_mov_b32_e32 v129, v2
	v_mov_b32_e32 v133, v130
	v_pk_mul_f32 v[128:129], v[128:129], v[132:133]
	v_mov_b32_e32 v130, v135
	v_sub_f32_e32 v128, v128, v129
	v_mul_f32_e32 v137, v145, v128
	v_mov_b32_e32 v128, v2
	v_mov_b32_e32 v129, v14
	v_pk_mul_f32 v[128:129], v[128:129], v[132:133]
	v_cvt_pk_bf16_f32 v134, v150, v146
	v_cvt_pk_bf16_f32 v135, v142, v141
	v_cvt_pk_bf16_f32 v136, v149, v136
	s_nop 0
	v_add_f32_e32 v128, v128, v129
	v_mul_f32_e32 v132, v145, v128
	v_mov_b32_e32 v128, v15
	v_mov_b32_e32 v129, v3
	v_pk_mul_f32 v[128:129], v[128:129], v[130:131]
	s_nop 0
	v_sub_f32_e32 v128, v128, v129
	v_mul_f32_e32 v133, v145, v128
	v_mov_b32_e32 v128, v3
	v_mov_b32_e32 v129, v15
	v_pk_mul_f32 v[128:129], v[128:129], v[130:131]
	v_cvt_pk_bf16_f32 v137, v137, v133
	s_nop 0
	v_add_f32_e32 v128, v128, v129
	v_mul_f32_e32 v131, v145, v128
	v_ashrrev_i32_e32 v145, 31, v144
	v_cvt_pk_bf16_f32 v128, v148, v147
	v_cvt_pk_bf16_f32 v129, v140, v143
	v_cvt_pk_bf16_f32 v130, v138, v139
	v_cvt_pk_bf16_f32 v131, v132, v131
	v_lshlrev_b64 v[132:133], 12, v[144:145]
	v_lshl_add_u64 v[132:133], v[230:231], 0, v[132:133]
	global_store_dwordx4 v[132:133], v[134:137], off

.LBB0_216:
	v_mov_b64_e32 v[0:1], 0x1600
	s_ashr_i32 s7, s6, 31
	v_cmp_lt_i64_e32 vcc, s[8:9], v[0:1]
	s_lshl_b64 s[8:9], s[6:7], 20
	s_add_u32 s8, s22, s8
	s_addc_u32 s9, s23, s9
	s_and_b64 s[10:11], vcc, exec
	s_cselect_b32 s7, s9, s15
	s_cselect_b32 s36, s8, s14
	s_ashr_i32 s5, s4, 31
	s_lshl_b64 s[10:11], s[4:5], 20
	s_add_u32 s10, s24, s10
	s_addc_u32 s11, s25, s11
	s_and_b64 s[18:19], vcc, exec
	s_cselect_b32 s5, s11, s17
	s_cselect_b32 s37, s10, s16
	s_add_u32 s14, s14, 0x80080
	s_addc_u32 s15, s15, 0
	s_add_u32 s38, s16, 0x100
	s_addc_u32 s39, s17, 0
	s_mov_b32 s40, -2
	s_mov_b64 s[48:49], 0x80
	v_add_u32_e32 v220, 0x10000, v141
	s_add_u32 s16, s14, 0xfff80080
	s_addc_u32 s17, s15, -1
	s_add_i32 s41, 0, 0x10000
	ds_read_b128 v[144:147], v220 offset:0
	ds_read_b128 v[148:151], v220 offset:1024
	ds_read_b128 v[152:155], v220 offset:2048
	ds_read_b128 v[156:159], v220 offset:3072
	s_cmp_eq_u32 s40, 28
	s_cselect_b32 s19, s7, s17
	s_cselect_b32 s18, s36, s16
	s_cselect_b32 s17, s5, s39
	s_cselect_b32 s16, s37, s38
	s_add_i32 m0, s13, 0xc000
	ds_read_b128 v[160:163], v143
	ds_read_b128 v[164:167], v143 offset:1024
	ds_read_b128 v[168:171], v143 offset:2048
	ds_read_b128 v[172:175], v143 offset:3072
	ds_read_b128 v[176:179], v143 offset:4096
	ds_read_b128 v[180:183], v143 offset:5120
	ds_read_b128 v[184:187], v143 offset:6144
	ds_read_b128 v[188:191], v143 offset:7168
	global_load_lds_dwordx4 v134, s[14:15]
	s_add_i32 m0, s13, 0xe000
	s_nop 0
	global_load_lds_dwordx4 v136, s[14:15]
	s_waitcnt lgkmcnt(8)
	s_barrier
	s_waitcnt lgkmcnt(0)
	v_mfma_f32_16x16x32_bf16 v[124:127], v[144:147], v[160:163], 0
	v_mfma_f32_16x16x32_bf16 v[116:119], v[152:155], v[160:163], 0
	v_mfma_f32_16x16x32_bf16 v[108:111], v[144:147], v[168:171], 0
	v_mfma_f32_16x16x32_bf16 v[100:103], v[152:155], v[168:171], 0
	s_add_i32 s44, 0, 0x14000
	s_add_i32 s41, s41, s26
	v_mfma_f32_16x16x32_bf16 v[92:95], v[144:147], v[176:179], 0
	s_mov_b32 m0, s41
	v_mfma_f32_16x16x32_bf16 v[84:87], v[152:155], v[176:179], 0
	v_mfma_f32_16x16x32_bf16 v[76:79], v[144:147], v[184:187], 0
	v_mfma_f32_16x16x32_bf16 v[68:71], v[152:155], v[184:187], 0
	v_mfma_f32_16x16x32_bf16 v[124:127], v[148:151], v[164:167], v[124:127]
	v_mfma_f32_16x16x32_bf16 v[116:119], v[156:159], v[164:167], v[116:119]
	v_mfma_f32_16x16x32_bf16 v[108:111], v[148:151], v[172:175], v[108:111]
	v_mfma_f32_16x16x32_bf16 v[100:103], v[156:159], v[172:175], v[100:103]
	v_mfma_f32_16x16x32_bf16 v[92:95], v[148:151], v[180:183], v[92:95]
	v_mfma_f32_16x16x32_bf16 v[84:87], v[156:159], v[180:183], v[84:87]
	v_mfma_f32_16x16x32_bf16 v[76:79], v[148:151], v[188:191], v[76:79]
	v_mfma_f32_16x16x32_bf16 v[68:71], v[156:159], v[188:191], v[68:71]
	s_barrier
	ds_read_b128 v[196:199], v220 offset:16384
	ds_read_b128 v[204:207], v220 offset:17408
	ds_read_b128 v[208:211], v220 offset:18432
	ds_read_b128 v[214:217], v220 offset:19456
	global_load_lds_dwordx4 v192, s[16:17]
	s_add_i32 m0, s41, 0x2000
	s_nop 0
	global_load_lds_dwordx4 v128, s[16:17]
	s_barrier
	s_waitcnt lgkmcnt(0)
	v_mfma_f32_16x16x32_bf16 v[120:123], v[196:199], v[160:163], 0
	v_mfma_f32_16x16x32_bf16 v[112:115], v[208:211], v[160:163], 0
	v_mfma_f32_16x16x32_bf16 v[104:107], v[196:199], v[168:171], 0
	v_mfma_f32_16x16x32_bf16 v[96:99], v[208:211], v[168:171], 0
	s_mov_b32 m0, s13
	v_mfma_f32_16x16x32_bf16 v[88:91], v[196:199], v[176:179], 0
	s_add_u32 s48, s18, 0x80
	s_addc_u32 s49, s19, 0
	v_mfma_f32_16x16x32_bf16 v[80:83], v[208:211], v[176:179], 0
	v_mfma_f32_16x16x32_bf16 v[72:75], v[196:199], v[184:187], 0
	v_mfma_f32_16x16x32_bf16 v[64:67], v[208:211], v[184:187], 0
	v_mfma_f32_16x16x32_bf16 v[120:123], v[204:207], v[164:167], v[120:123]
	v_mfma_f32_16x16x32_bf16 v[112:115], v[214:217], v[164:167], v[112:115]
	v_mfma_f32_16x16x32_bf16 v[104:107], v[204:207], v[172:175], v[104:107]
	v_mfma_f32_16x16x32_bf16 v[96:99], v[214:217], v[172:175], v[96:99]
	v_mfma_f32_16x16x32_bf16 v[88:91], v[204:207], v[180:183], v[88:91]
	v_mfma_f32_16x16x32_bf16 v[80:83], v[214:217], v[180:183], v[80:83]
	v_mfma_f32_16x16x32_bf16 v[72:75], v[204:207], v[188:191], v[72:75]
	v_mfma_f32_16x16x32_bf16 v[64:67], v[214:217], v[188:191], v[64:67]
	s_barrier
	ds_read_b128 v[160:163], v143 offset:16384
	ds_read_b128 v[164:167], v143 offset:17408
	ds_read_b128 v[168:171], v143 offset:18432
	ds_read_b128 v[172:175], v143 offset:19456
	ds_read_b128 v[176:179], v143 offset:20480
	ds_read_b128 v[180:183], v143 offset:21504
	ds_read_b128 v[184:187], v143 offset:22528
	ds_read_b128 v[188:191], v143 offset:23552
	global_load_lds_dwordx4 v132, s[18:19]
	s_mov_b32 m0, s28
	s_nop 0
	global_load_lds_dwordx4 v130, s[18:19]
	s_barrier
	s_waitcnt lgkmcnt(0)
	v_mfma_f32_16x16x32_bf16 v[60:63], v[144:147], v[160:163], 0
	v_mfma_f32_16x16x32_bf16 v[52:55], v[152:155], v[160:163], 0
	v_mfma_f32_16x16x32_bf16 v[44:47], v[144:147], v[168:171], 0
	v_mfma_f32_16x16x32_bf16 v[36:39], v[152:155], v[168:171], 0
	s_add_u32 s42, s16, 0x80000
	s_addc_u32 s43, s17, 0
	v_mfma_f32_16x16x32_bf16 v[28:31], v[144:147], v[176:179], 0
	s_add_i32 s41, s44, s26
	s_mov_b32 m0, s41
	v_mfma_f32_16x16x32_bf16 v[20:23], v[152:155], v[176:179], 0
	v_mfma_f32_16x16x32_bf16 v[12:15], v[144:147], v[184:187], 0
	v_mfma_f32_16x16x32_bf16 v[4:7], v[152:155], v[184:187], 0
	v_mfma_f32_16x16x32_bf16 v[60:63], v[148:151], v[164:167], v[60:63]
	v_mfma_f32_16x16x32_bf16 v[52:55], v[156:159], v[164:167], v[52:55]
	v_mfma_f32_16x16x32_bf16 v[44:47], v[148:151], v[172:175], v[44:47]
	v_mfma_f32_16x16x32_bf16 v[36:39], v[156:159], v[172:175], v[36:39]
	v_mfma_f32_16x16x32_bf16 v[28:31], v[148:151], v[180:183], v[28:31]
	v_mfma_f32_16x16x32_bf16 v[20:23], v[156:159], v[180:183], v[20:23]
	v_mfma_f32_16x16x32_bf16 v[12:15], v[148:151], v[188:191], v[12:15]
	v_mfma_f32_16x16x32_bf16 v[4:7], v[156:159], v[188:191], v[4:7]
	s_barrier
	global_load_lds_dwordx4 v192, s[42:43]
	s_add_i32 m0, s41, 0x2000
	s_nop 0
	global_load_lds_dwordx4 v128, s[42:43]
	s_waitcnt vmcnt(6)
	s_barrier
	v_mfma_f32_16x16x32_bf16 v[56:59], v[196:199], v[160:163], 0
	v_mfma_f32_16x16x32_bf16 v[48:51], v[208:211], v[160:163], 0
	v_mfma_f32_16x16x32_bf16 v[40:43], v[196:199], v[168:171], 0
	v_mfma_f32_16x16x32_bf16 v[32:35], v[208:211], v[168:171], 0
	s_add_i32 s41, 0, 0x18000
	v_mfma_f32_16x16x32_bf16 v[24:27], v[196:199], v[176:179], 0
	s_add_u32 s18, s18, 0x80000
	s_addc_u32 s19, s19, 0
	v_mfma_f32_16x16x32_bf16 v[16:19], v[208:211], v[176:179], 0
	s_mov_b32 m0, s29
	v_mfma_f32_16x16x32_bf16 v[8:11], v[196:199], v[184:187], 0
	v_mfma_f32_16x16x32_bf16 v[0:3], v[208:211], v[184:187], 0
	v_mfma_f32_16x16x32_bf16 v[56:59], v[204:207], v[164:167], v[56:59]
	v_mfma_f32_16x16x32_bf16 v[48:51], v[214:217], v[164:167], v[48:51]
	v_mfma_f32_16x16x32_bf16 v[40:43], v[204:207], v[172:175], v[40:43]
	v_mfma_f32_16x16x32_bf16 v[32:35], v[214:217], v[172:175], v[32:35]
	v_mfma_f32_16x16x32_bf16 v[24:27], v[204:207], v[180:183], v[24:27]
	v_mfma_f32_16x16x32_bf16 v[16:19], v[214:217], v[180:183], v[16:19]
	v_mfma_f32_16x16x32_bf16 v[8:11], v[204:207], v[188:191], v[8:11]
	v_mfma_f32_16x16x32_bf16 v[0:3], v[214:217], v[188:191], v[0:3]
	s_barrier
	ds_read_b128 v[144:147], v220 offset:32768
	ds_read_b128 v[148:151], v220 offset:33792
	ds_read_b128 v[152:155], v220 offset:34816
	ds_read_b128 v[156:159], v220 offset:35840
	ds_read_b128 v[160:163], v143 offset:32768
	ds_read_b128 v[164:167], v143 offset:33792
	ds_read_b128 v[168:171], v143 offset:34816
	ds_read_b128 v[172:175], v143 offset:35840
	ds_read_b128 v[176:179], v143 offset:36864
	ds_read_b128 v[180:183], v143 offset:37888
	ds_read_b128 v[184:187], v143 offset:38912
	ds_read_b128 v[188:191], v143 offset:39936
	global_load_lds_dwordx4 v132, s[18:19]
	s_mov_b32 m0, s30
	s_nop 0
	global_load_lds_dwordx4 v130, s[18:19]
	s_waitcnt lgkmcnt(8)
	s_barrier
	s_waitcnt lgkmcnt(0)
	v_mfma_f32_16x16x32_bf16 v[124:127], v[144:147], v[160:163], v[124:127]
	v_mfma_f32_16x16x32_bf16 v[116:119], v[152:155], v[160:163], v[116:119]
	v_mfma_f32_16x16x32_bf16 v[108:111], v[144:147], v[168:171], v[108:111]
	v_mfma_f32_16x16x32_bf16 v[100:103], v[152:155], v[168:171], v[100:103]
	s_add_i32 s18, 0, 0x1c000
	s_add_i32 s19, s41, s26
	v_mfma_f32_16x16x32_bf16 v[92:95], v[144:147], v[176:179], v[92:95]
	s_add_i32 m0, s19, 0xffffff80
	v_mfma_f32_16x16x32_bf16 v[84:87], v[152:155], v[176:179], v[84:87]
	v_mfma_f32_16x16x32_bf16 v[76:79], v[144:147], v[184:187], v[76:79]
	v_mfma_f32_16x16x32_bf16 v[68:71], v[152:155], v[184:187], v[68:71]
	v_mfma_f32_16x16x32_bf16 v[124:127], v[148:151], v[164:167], v[124:127]
	v_mfma_f32_16x16x32_bf16 v[116:119], v[156:159], v[164:167], v[116:119]
	v_mfma_f32_16x16x32_bf16 v[108:111], v[148:151], v[172:175], v[108:111]
	v_mfma_f32_16x16x32_bf16 v[100:103], v[156:159], v[172:175], v[100:103]
	v_mfma_f32_16x16x32_bf16 v[92:95], v[148:151], v[180:183], v[92:95]
	v_mfma_f32_16x16x32_bf16 v[84:87], v[156:159], v[180:183], v[84:87]
	v_mfma_f32_16x16x32_bf16 v[76:79], v[148:151], v[188:191], v[76:79]
	v_mfma_f32_16x16x32_bf16 v[68:71], v[156:159], v[188:191], v[68:71]
	s_barrier
	ds_read_b128 v[196:199], v220 offset:49152
	ds_read_b128 v[204:207], v220 offset:50176
	ds_read_b128 v[208:211], v220 offset:51200
	ds_read_b128 v[214:217], v220 offset:52224
	global_load_lds_dwordx4 v192, s[16:17] offset:128
	s_add_i32 m0, s19, 0x1f80
	s_nop 0
	global_load_lds_dwordx4 v128, s[16:17] offset:128
	s_barrier
	s_waitcnt lgkmcnt(0)
	v_mfma_f32_16x16x32_bf16 v[120:123], v[196:199], v[160:163], v[120:123]
	v_mfma_f32_16x16x32_bf16 v[112:115], v[208:211], v[160:163], v[112:115]
	v_mfma_f32_16x16x32_bf16 v[104:107], v[196:199], v[168:171], v[104:107]
	v_mfma_f32_16x16x32_bf16 v[96:99], v[208:211], v[168:171], v[96:99]
	s_mov_b32 m0, s33
	v_mfma_f32_16x16x32_bf16 v[88:91], v[196:199], v[176:179], v[88:91]
	v_mfma_f32_16x16x32_bf16 v[80:83], v[208:211], v[176:179], v[80:83]
	v_mfma_f32_16x16x32_bf16 v[72:75], v[196:199], v[184:187], v[72:75]
	v_mfma_f32_16x16x32_bf16 v[64:67], v[208:211], v[184:187], v[64:67]
	v_mfma_f32_16x16x32_bf16 v[120:123], v[204:207], v[164:167], v[120:123]
	v_mfma_f32_16x16x32_bf16 v[112:115], v[214:217], v[164:167], v[112:115]
	v_mfma_f32_16x16x32_bf16 v[104:107], v[204:207], v[172:175], v[104:107]
	v_mfma_f32_16x16x32_bf16 v[96:99], v[214:217], v[172:175], v[96:99]
	v_mfma_f32_16x16x32_bf16 v[88:91], v[204:207], v[180:183], v[88:91]
	v_mfma_f32_16x16x32_bf16 v[80:83], v[214:217], v[180:183], v[80:83]
	v_mfma_f32_16x16x32_bf16 v[72:75], v[204:207], v[188:191], v[72:75]
	v_mfma_f32_16x16x32_bf16 v[64:67], v[214:217], v[188:191], v[64:67]
	s_barrier
	ds_read_b128 v[160:163], v143 offset:49152
	ds_read_b128 v[164:167], v143 offset:50176
	ds_read_b128 v[168:171], v143 offset:51200
	ds_read_b128 v[172:175], v143 offset:52224
	ds_read_b128 v[176:179], v143 offset:53248
	ds_read_b128 v[180:183], v143 offset:54272
	ds_read_b128 v[184:187], v143 offset:55296
	ds_read_b128 v[188:191], v143 offset:56320
	global_load_lds_dwordx4 v132, s[48:49]
	s_mov_b32 m0, s34
	s_nop 0
	global_load_lds_dwordx4 v130, s[48:49]
	s_barrier
	s_waitcnt lgkmcnt(0)
	v_mfma_f32_16x16x32_bf16 v[60:63], v[144:147], v[160:163], v[60:63]
	v_mfma_f32_16x16x32_bf16 v[52:55], v[152:155], v[160:163], v[52:55]
	v_mfma_f32_16x16x32_bf16 v[44:47], v[144:147], v[168:171], v[44:47]
	v_mfma_f32_16x16x32_bf16 v[36:39], v[152:155], v[168:171], v[36:39]
	s_add_u32 s16, s16, 0x80080
	s_addc_u32 s17, s17, 0
	v_mfma_f32_16x16x32_bf16 v[28:31], v[144:147], v[176:179], v[28:31]
	s_add_i32 s18, s18, s26
	s_mov_b32 m0, s18
	v_mfma_f32_16x16x32_bf16 v[20:23], v[152:155], v[176:179], v[20:23]
	v_mfma_f32_16x16x32_bf16 v[12:15], v[144:147], v[184:187], v[12:15]
	v_mfma_f32_16x16x32_bf16 v[4:7], v[152:155], v[184:187], v[4:7]
	v_mfma_f32_16x16x32_bf16 v[60:63], v[148:151], v[164:167], v[60:63]
	v_mfma_f32_16x16x32_bf16 v[52:55], v[156:159], v[164:167], v[52:55]
	v_mfma_f32_16x16x32_bf16 v[44:47], v[148:151], v[172:175], v[44:47]
	v_mfma_f32_16x16x32_bf16 v[36:39], v[156:159], v[172:175], v[36:39]
	v_mfma_f32_16x16x32_bf16 v[28:31], v[148:151], v[180:183], v[28:31]
	v_mfma_f32_16x16x32_bf16 v[20:23], v[156:159], v[180:183], v[20:23]
	v_mfma_f32_16x16x32_bf16 v[12:15], v[148:151], v[188:191], v[12:15]
	v_mfma_f32_16x16x32_bf16 v[4:7], v[156:159], v[188:191], v[4:7]
	s_barrier
	global_load_lds_dwordx4 v192, s[16:17]
	s_add_i32 m0, s18, 0x2000
	s_nop 0
	global_load_lds_dwordx4 v128, s[16:17]
	s_waitcnt vmcnt(6)
	s_barrier
	v_mfma_f32_16x16x32_bf16 v[56:59], v[196:199], v[160:163], v[56:59]
	v_mfma_f32_16x16x32_bf16 v[48:51], v[208:211], v[160:163], v[48:51]
	v_mfma_f32_16x16x32_bf16 v[40:43], v[196:199], v[168:171], v[40:43]
	v_mfma_f32_16x16x32_bf16 v[32:35], v[208:211], v[168:171], v[32:35]
	s_add_i32 s40, s40, 2
	v_mfma_f32_16x16x32_bf16 v[24:27], v[196:199], v[176:179], v[24:27]
	s_add_u32 s14, s14, 0x100
	s_addc_u32 s15, s15, 0
	v_mfma_f32_16x16x32_bf16 v[16:19], v[208:211], v[176:179], v[16:19]
	s_add_u32 s38, s38, 0x100
	s_addc_u32 s39, s39, 0
	v_mfma_f32_16x16x32_bf16 v[8:11], v[196:199], v[184:187], v[8:11]
	v_mfma_f32_16x16x32_bf16 v[0:3], v[208:211], v[184:187], v[0:3]
	v_mfma_f32_16x16x32_bf16 v[56:59], v[204:207], v[164:167], v[56:59]
	v_mfma_f32_16x16x32_bf16 v[48:51], v[214:217], v[164:167], v[48:51]
	v_mfma_f32_16x16x32_bf16 v[40:43], v[204:207], v[172:175], v[40:43]
	v_mfma_f32_16x16x32_bf16 v[32:35], v[214:217], v[172:175], v[32:35]
	v_mfma_f32_16x16x32_bf16 v[24:27], v[204:207], v[180:183], v[24:27]
	v_mfma_f32_16x16x32_bf16 v[16:19], v[214:217], v[180:183], v[16:19]
	v_mfma_f32_16x16x32_bf16 v[8:11], v[204:207], v[188:191], v[8:11]
	v_mfma_f32_16x16x32_bf16 v[0:3], v[214:217], v[188:191], v[0:3]
	s_cmp_gt_u32 s40, 29
	s_barrier
.LBB0_217:
	s_add_u32 s16, s14, 0xfff80080
	s_addc_u32 s17, s15, -1
	s_add_i32 s41, 0, 0x10000
	ds_read_b128 v[144:147], v220 offset:0
	ds_read_b128 v[148:151], v220 offset:1024
	ds_read_b128 v[152:155], v220 offset:2048
	ds_read_b128 v[156:159], v220 offset:3072
	s_cmp_eq_u32 s40, 28
	s_cselect_b32 s19, s7, s17
	s_cselect_b32 s18, s36, s16
	s_cselect_b32 s17, s5, s39
	s_cselect_b32 s16, s37, s38
	s_add_i32 m0, s13, 0xc000
	ds_read_b128 v[160:163], v143
	ds_read_b128 v[164:167], v143 offset:1024
	ds_read_b128 v[168:171], v143 offset:2048
	ds_read_b128 v[172:175], v143 offset:3072
	ds_read_b128 v[176:179], v143 offset:4096
	ds_read_b128 v[180:183], v143 offset:5120
	ds_read_b128 v[184:187], v143 offset:6144
	ds_read_b128 v[188:191], v143 offset:7168
	global_load_lds_dwordx4 v134, s[14:15]
	s_add_i32 m0, s13, 0xe000
	s_nop 0
	global_load_lds_dwordx4 v136, s[14:15]
	s_waitcnt lgkmcnt(8)
	s_barrier
	s_waitcnt lgkmcnt(0)
	v_mfma_f32_16x16x32_bf16 v[124:127], v[144:147], v[160:163], v[124:127]
	v_mfma_f32_16x16x32_bf16 v[116:119], v[152:155], v[160:163], v[116:119]
	v_mfma_f32_16x16x32_bf16 v[108:111], v[144:147], v[168:171], v[108:111]
	v_mfma_f32_16x16x32_bf16 v[100:103], v[152:155], v[168:171], v[100:103]
	s_add_i32 s44, 0, 0x14000
	s_add_i32 s41, s41, s26
	v_mfma_f32_16x16x32_bf16 v[92:95], v[144:147], v[176:179], v[92:95]
	s_mov_b32 m0, s41
	v_mfma_f32_16x16x32_bf16 v[84:87], v[152:155], v[176:179], v[84:87]
	v_mfma_f32_16x16x32_bf16 v[76:79], v[144:147], v[184:187], v[76:79]
	v_mfma_f32_16x16x32_bf16 v[68:71], v[152:155], v[184:187], v[68:71]
	v_mfma_f32_16x16x32_bf16 v[124:127], v[148:151], v[164:167], v[124:127]
	v_mfma_f32_16x16x32_bf16 v[116:119], v[156:159], v[164:167], v[116:119]
	v_mfma_f32_16x16x32_bf16 v[108:111], v[148:151], v[172:175], v[108:111]
	v_mfma_f32_16x16x32_bf16 v[100:103], v[156:159], v[172:175], v[100:103]
	v_mfma_f32_16x16x32_bf16 v[92:95], v[148:151], v[180:183], v[92:95]
	v_mfma_f32_16x16x32_bf16 v[84:87], v[156:159], v[180:183], v[84:87]
	v_mfma_f32_16x16x32_bf16 v[76:79], v[148:151], v[188:191], v[76:79]
	v_mfma_f32_16x16x32_bf16 v[68:71], v[156:159], v[188:191], v[68:71]
	s_barrier
	ds_read_b128 v[196:199], v220 offset:16384
	ds_read_b128 v[204:207], v220 offset:17408
	ds_read_b128 v[208:211], v220 offset:18432
	ds_read_b128 v[214:217], v220 offset:19456
	global_load_lds_dwordx4 v192, s[16:17]
	s_add_i32 m0, s41, 0x2000
	s_nop 0
	global_load_lds_dwordx4 v128, s[16:17]
	s_barrier
	s_waitcnt lgkmcnt(0)
	v_mfma_f32_16x16x32_bf16 v[120:123], v[196:199], v[160:163], v[120:123]
	v_mfma_f32_16x16x32_bf16 v[112:115], v[208:211], v[160:163], v[112:115]
	v_mfma_f32_16x16x32_bf16 v[104:107], v[196:199], v[168:171], v[104:107]
	v_mfma_f32_16x16x32_bf16 v[96:99], v[208:211], v[168:171], v[96:99]
	s_mov_b32 m0, s13
	v_mfma_f32_16x16x32_bf16 v[88:91], v[196:199], v[176:179], v[88:91]
	s_add_u32 s48, s18, 0x80
	s_addc_u32 s49, s19, 0
	v_mfma_f32_16x16x32_bf16 v[80:83], v[208:211], v[176:179], v[80:83]
	v_mfma_f32_16x16x32_bf16 v[72:75], v[196:199], v[184:187], v[72:75]
	v_mfma_f32_16x16x32_bf16 v[64:67], v[208:211], v[184:187], v[64:67]
	v_mfma_f32_16x16x32_bf16 v[120:123], v[204:207], v[164:167], v[120:123]
	v_mfma_f32_16x16x32_bf16 v[112:115], v[214:217], v[164:167], v[112:115]
	v_mfma_f32_16x16x32_bf16 v[104:107], v[204:207], v[172:175], v[104:107]
	v_mfma_f32_16x16x32_bf16 v[96:99], v[214:217], v[172:175], v[96:99]
	v_mfma_f32_16x16x32_bf16 v[88:91], v[204:207], v[180:183], v[88:91]
	v_mfma_f32_16x16x32_bf16 v[80:83], v[214:217], v[180:183], v[80:83]
	v_mfma_f32_16x16x32_bf16 v[72:75], v[204:207], v[188:191], v[72:75]
	v_mfma_f32_16x16x32_bf16 v[64:67], v[214:217], v[188:191], v[64:67]
	s_barrier
	ds_read_b128 v[160:163], v143 offset:16384
	ds_read_b128 v[164:167], v143 offset:17408
	ds_read_b128 v[168:171], v143 offset:18432
	ds_read_b128 v[172:175], v143 offset:19456
	ds_read_b128 v[176:179], v143 offset:20480
	ds_read_b128 v[180:183], v143 offset:21504
	ds_read_b128 v[184:187], v143 offset:22528
	ds_read_b128 v[188:191], v143 offset:23552
	global_load_lds_dwordx4 v132, s[18:19]
	s_mov_b32 m0, s28
	s_nop 0
	global_load_lds_dwordx4 v130, s[18:19]
	s_barrier
	s_waitcnt lgkmcnt(0)
	v_mfma_f32_16x16x32_bf16 v[60:63], v[144:147], v[160:163], v[60:63]
	v_mfma_f32_16x16x32_bf16 v[52:55], v[152:155], v[160:163], v[52:55]
	v_mfma_f32_16x16x32_bf16 v[44:47], v[144:147], v[168:171], v[44:47]
	v_mfma_f32_16x16x32_bf16 v[36:39], v[152:155], v[168:171], v[36:39]
	s_add_u32 s42, s16, 0x80000
	s_addc_u32 s43, s17, 0
	v_mfma_f32_16x16x32_bf16 v[28:31], v[144:147], v[176:179], v[28:31]
	s_add_i32 s41, s44, s26
	s_mov_b32 m0, s41
	v_mfma_f32_16x16x32_bf16 v[20:23], v[152:155], v[176:179], v[20:23]
	v_mfma_f32_16x16x32_bf16 v[12:15], v[144:147], v[184:187], v[12:15]
	v_mfma_f32_16x16x32_bf16 v[4:7], v[152:155], v[184:187], v[4:7]
	v_mfma_f32_16x16x32_bf16 v[60:63], v[148:151], v[164:167], v[60:63]
	v_mfma_f32_16x16x32_bf16 v[52:55], v[156:159], v[164:167], v[52:55]
	v_mfma_f32_16x16x32_bf16 v[44:47], v[148:151], v[172:175], v[44:47]
	v_mfma_f32_16x16x32_bf16 v[36:39], v[156:159], v[172:175], v[36:39]
	v_mfma_f32_16x16x32_bf16 v[28:31], v[148:151], v[180:183], v[28:31]
	v_mfma_f32_16x16x32_bf16 v[20:23], v[156:159], v[180:183], v[20:23]
	v_mfma_f32_16x16x32_bf16 v[12:15], v[148:151], v[188:191], v[12:15]
	v_mfma_f32_16x16x32_bf16 v[4:7], v[156:159], v[188:191], v[4:7]
	s_barrier
	global_load_lds_dwordx4 v192, s[42:43]
	s_add_i32 m0, s41, 0x2000
	s_nop 0
	global_load_lds_dwordx4 v128, s[42:43]
	s_waitcnt vmcnt(6)
	s_barrier
	v_mfma_f32_16x16x32_bf16 v[56:59], v[196:199], v[160:163], v[56:59]
	v_mfma_f32_16x16x32_bf16 v[48:51], v[208:211], v[160:163], v[48:51]
	v_mfma_f32_16x16x32_bf16 v[40:43], v[196:199], v[168:171], v[40:43]
	v_mfma_f32_16x16x32_bf16 v[32:35], v[208:211], v[168:171], v[32:35]
	s_add_i32 s41, 0, 0x18000
	v_mfma_f32_16x16x32_bf16 v[24:27], v[196:199], v[176:179], v[24:27]
	s_add_u32 s18, s18, 0x80000
	s_addc_u32 s19, s19, 0
	v_mfma_f32_16x16x32_bf16 v[16:19], v[208:211], v[176:179], v[16:19]
	s_mov_b32 m0, s29
	v_mfma_f32_16x16x32_bf16 v[8:11], v[196:199], v[184:187], v[8:11]
	v_mfma_f32_16x16x32_bf16 v[0:3], v[208:211], v[184:187], v[0:3]
	v_mfma_f32_16x16x32_bf16 v[56:59], v[204:207], v[164:167], v[56:59]
	v_mfma_f32_16x16x32_bf16 v[48:51], v[214:217], v[164:167], v[48:51]
	v_mfma_f32_16x16x32_bf16 v[40:43], v[204:207], v[172:175], v[40:43]
	v_mfma_f32_16x16x32_bf16 v[32:35], v[214:217], v[172:175], v[32:35]
	v_mfma_f32_16x16x32_bf16 v[24:27], v[204:207], v[180:183], v[24:27]
	v_mfma_f32_16x16x32_bf16 v[16:19], v[214:217], v[180:183], v[16:19]
	v_mfma_f32_16x16x32_bf16 v[8:11], v[204:207], v[188:191], v[8:11]
	v_mfma_f32_16x16x32_bf16 v[0:3], v[214:217], v[188:191], v[0:3]
	s_barrier
	ds_read_b128 v[144:147], v220 offset:32768
	ds_read_b128 v[148:151], v220 offset:33792
	ds_read_b128 v[152:155], v220 offset:34816
	ds_read_b128 v[156:159], v220 offset:35840
	ds_read_b128 v[160:163], v143 offset:32768
	ds_read_b128 v[164:167], v143 offset:33792
	ds_read_b128 v[168:171], v143 offset:34816
	ds_read_b128 v[172:175], v143 offset:35840
	ds_read_b128 v[176:179], v143 offset:36864
	ds_read_b128 v[180:183], v143 offset:37888
	ds_read_b128 v[184:187], v143 offset:38912
	ds_read_b128 v[188:191], v143 offset:39936
	global_load_lds_dwordx4 v132, s[18:19]
	s_mov_b32 m0, s30
	s_nop 0
	global_load_lds_dwordx4 v130, s[18:19]
	s_waitcnt lgkmcnt(8)
	s_barrier
	s_waitcnt lgkmcnt(0)
	v_mfma_f32_16x16x32_bf16 v[124:127], v[144:147], v[160:163], v[124:127]
	v_mfma_f32_16x16x32_bf16 v[116:119], v[152:155], v[160:163], v[116:119]
	v_mfma_f32_16x16x32_bf16 v[108:111], v[144:147], v[168:171], v[108:111]
	v_mfma_f32_16x16x32_bf16 v[100:103], v[152:155], v[168:171], v[100:103]
	s_add_i32 s18, 0, 0x1c000
	s_add_i32 s19, s41, s26
	v_mfma_f32_16x16x32_bf16 v[92:95], v[144:147], v[176:179], v[92:95]
	s_add_i32 m0, s19, 0xffffff80
	v_mfma_f32_16x16x32_bf16 v[84:87], v[152:155], v[176:179], v[84:87]
	v_mfma_f32_16x16x32_bf16 v[76:79], v[144:147], v[184:187], v[76:79]
	v_mfma_f32_16x16x32_bf16 v[68:71], v[152:155], v[184:187], v[68:71]
	v_mfma_f32_16x16x32_bf16 v[124:127], v[148:151], v[164:167], v[124:127]
	v_mfma_f32_16x16x32_bf16 v[116:119], v[156:159], v[164:167], v[116:119]
	v_mfma_f32_16x16x32_bf16 v[108:111], v[148:151], v[172:175], v[108:111]
	v_mfma_f32_16x16x32_bf16 v[100:103], v[156:159], v[172:175], v[100:103]
	v_mfma_f32_16x16x32_bf16 v[92:95], v[148:151], v[180:183], v[92:95]
	v_mfma_f32_16x16x32_bf16 v[84:87], v[156:159], v[180:183], v[84:87]
	v_mfma_f32_16x16x32_bf16 v[76:79], v[148:151], v[188:191], v[76:79]
	v_mfma_f32_16x16x32_bf16 v[68:71], v[156:159], v[188:191], v[68:71]
	s_barrier
	ds_read_b128 v[196:199], v220 offset:49152
	ds_read_b128 v[204:207], v220 offset:50176
	ds_read_b128 v[208:211], v220 offset:51200
	ds_read_b128 v[214:217], v220 offset:52224
	global_load_lds_dwordx4 v192, s[16:17] offset:128
	s_add_i32 m0, s19, 0x1f80
	s_nop 0
	global_load_lds_dwordx4 v128, s[16:17] offset:128
	s_barrier
	s_waitcnt lgkmcnt(0)
	v_mfma_f32_16x16x32_bf16 v[120:123], v[196:199], v[160:163], v[120:123]
	v_mfma_f32_16x16x32_bf16 v[112:115], v[208:211], v[160:163], v[112:115]
	v_mfma_f32_16x16x32_bf16 v[104:107], v[196:199], v[168:171], v[104:107]
	v_mfma_f32_16x16x32_bf16 v[96:99], v[208:211], v[168:171], v[96:99]
	s_mov_b32 m0, s33
	v_mfma_f32_16x16x32_bf16 v[88:91], v[196:199], v[176:179], v[88:91]
	v_mfma_f32_16x16x32_bf16 v[80:83], v[208:211], v[176:179], v[80:83]
	v_mfma_f32_16x16x32_bf16 v[72:75], v[196:199], v[184:187], v[72:75]
	v_mfma_f32_16x16x32_bf16 v[64:67], v[208:211], v[184:187], v[64:67]
	v_mfma_f32_16x16x32_bf16 v[120:123], v[204:207], v[164:167], v[120:123]
	v_mfma_f32_16x16x32_bf16 v[112:115], v[214:217], v[164:167], v[112:115]
	v_mfma_f32_16x16x32_bf16 v[104:107], v[204:207], v[172:175], v[104:107]
	v_mfma_f32_16x16x32_bf16 v[96:99], v[214:217], v[172:175], v[96:99]
	v_mfma_f32_16x16x32_bf16 v[88:91], v[204:207], v[180:183], v[88:91]
	v_mfma_f32_16x16x32_bf16 v[80:83], v[214:217], v[180:183], v[80:83]
	v_mfma_f32_16x16x32_bf16 v[72:75], v[204:207], v[188:191], v[72:75]
	v_mfma_f32_16x16x32_bf16 v[64:67], v[214:217], v[188:191], v[64:67]
	s_barrier
	ds_read_b128 v[160:163], v143 offset:49152
	ds_read_b128 v[164:167], v143 offset:50176
	ds_read_b128 v[168:171], v143 offset:51200
	ds_read_b128 v[172:175], v143 offset:52224
	ds_read_b128 v[176:179], v143 offset:53248
	ds_read_b128 v[180:183], v143 offset:54272
	ds_read_b128 v[184:187], v143 offset:55296
	ds_read_b128 v[188:191], v143 offset:56320
	global_load_lds_dwordx4 v132, s[48:49]
	s_mov_b32 m0, s34
	s_nop 0
	global_load_lds_dwordx4 v130, s[48:49]
	s_barrier
	s_waitcnt lgkmcnt(0)
	v_mfma_f32_16x16x32_bf16 v[60:63], v[144:147], v[160:163], v[60:63]
	v_mfma_f32_16x16x32_bf16 v[52:55], v[152:155], v[160:163], v[52:55]
	v_mfma_f32_16x16x32_bf16 v[44:47], v[144:147], v[168:171], v[44:47]
	v_mfma_f32_16x16x32_bf16 v[36:39], v[152:155], v[168:171], v[36:39]
	s_add_u32 s16, s16, 0x80080
	s_addc_u32 s17, s17, 0
	v_mfma_f32_16x16x32_bf16 v[28:31], v[144:147], v[176:179], v[28:31]
	s_add_i32 s18, s18, s26
	s_mov_b32 m0, s18
	v_mfma_f32_16x16x32_bf16 v[20:23], v[152:155], v[176:179], v[20:23]
	v_mfma_f32_16x16x32_bf16 v[12:15], v[144:147], v[184:187], v[12:15]
	v_mfma_f32_16x16x32_bf16 v[4:7], v[152:155], v[184:187], v[4:7]
	v_mfma_f32_16x16x32_bf16 v[60:63], v[148:151], v[164:167], v[60:63]
	v_mfma_f32_16x16x32_bf16 v[52:55], v[156:159], v[164:167], v[52:55]
	v_mfma_f32_16x16x32_bf16 v[44:47], v[148:151], v[172:175], v[44:47]
	v_mfma_f32_16x16x32_bf16 v[36:39], v[156:159], v[172:175], v[36:39]
	v_mfma_f32_16x16x32_bf16 v[28:31], v[148:151], v[180:183], v[28:31]
	v_mfma_f32_16x16x32_bf16 v[20:23], v[156:159], v[180:183], v[20:23]
	v_mfma_f32_16x16x32_bf16 v[12:15], v[148:151], v[188:191], v[12:15]
	v_mfma_f32_16x16x32_bf16 v[4:7], v[156:159], v[188:191], v[4:7]
	s_barrier
	global_load_lds_dwordx4 v192, s[16:17]
	s_add_i32 m0, s18, 0x2000
	s_nop 0
	global_load_lds_dwordx4 v128, s[16:17]
	s_waitcnt vmcnt(6)
	s_barrier
	v_mfma_f32_16x16x32_bf16 v[56:59], v[196:199], v[160:163], v[56:59]
	v_mfma_f32_16x16x32_bf16 v[48:51], v[208:211], v[160:163], v[48:51]
	v_mfma_f32_16x16x32_bf16 v[40:43], v[196:199], v[168:171], v[40:43]
	v_mfma_f32_16x16x32_bf16 v[32:35], v[208:211], v[168:171], v[32:35]
	s_add_i32 s40, s40, 2
	v_mfma_f32_16x16x32_bf16 v[24:27], v[196:199], v[176:179], v[24:27]
	s_add_u32 s14, s14, 0x100
	s_addc_u32 s15, s15, 0
	v_mfma_f32_16x16x32_bf16 v[16:19], v[208:211], v[176:179], v[16:19]
	s_add_u32 s38, s38, 0x100
	s_addc_u32 s39, s39, 0
	v_mfma_f32_16x16x32_bf16 v[8:11], v[196:199], v[184:187], v[8:11]
	v_mfma_f32_16x16x32_bf16 v[0:3], v[208:211], v[184:187], v[0:3]
	v_mfma_f32_16x16x32_bf16 v[56:59], v[204:207], v[164:167], v[56:59]
	v_mfma_f32_16x16x32_bf16 v[48:51], v[214:217], v[164:167], v[48:51]
	v_mfma_f32_16x16x32_bf16 v[40:43], v[204:207], v[172:175], v[40:43]
	v_mfma_f32_16x16x32_bf16 v[32:35], v[214:217], v[172:175], v[32:35]
	v_mfma_f32_16x16x32_bf16 v[24:27], v[204:207], v[180:183], v[24:27]
	v_mfma_f32_16x16x32_bf16 v[16:19], v[214:217], v[180:183], v[16:19]
	v_mfma_f32_16x16x32_bf16 v[8:11], v[204:207], v[188:191], v[8:11]
	v_mfma_f32_16x16x32_bf16 v[0:3], v[214:217], v[188:191], v[0:3]
	s_cmp_gt_u32 s40, 29
	s_barrier
	s_cbranch_scc0 .LBB0_217
	v_mul_f32_e32 v145, 0xbfb8aa3b, v124
	v_exp_f32_e32 v145, v145
	v_lshl_or_b32 v146, s35, 7, v142
	v_lshl_add_u32 v144, s12, 8, v140
	v_ashrrev_i32_e32 v147, 31, v146
	v_add_f32_e32 v145, 1.0, v145
	v_rcp_f32_e32 v145, v145
	v_mov_b64_e32 v[138:139], s[2:3]
	s_movk_i32 s5, 0x2c00
	v_mad_i64_i32 v[148:149], s[14:15], v144, s5, v[138:139]
	v_mul_f32_e32 v124, v124, v145
	v_mul_f32_e32 v120, v124, v120
	v_mul_f32_e32 v124, 0xbfb8aa3b, v125
	v_exp_f32_e32 v124, v124
	s_and_b64 vcc, exec, s[0:1]
	s_mov_b32 s35, s4
	s_mov_b32 s12, s6
	v_add_f32_e32 v124, 1.0, v124
	v_rcp_f32_e32 v124, v124
	s_mov_b64 s[16:17], s[10:11]
	v_mul_f32_e32 v124, v125, v124
	v_mul_f32_e32 v121, v124, v121
	v_mul_f32_e32 v124, 0xbfb8aa3b, v126
	v_exp_f32_e32 v124, v124
	s_nop 0
	v_add_f32_e32 v124, 1.0, v124
	v_rcp_f32_e32 v124, v124
	s_nop 0
	v_mul_f32_e32 v124, v126, v124
	v_mul_f32_e32 v122, v124, v122
	v_mul_f32_e32 v124, 0xbfb8aa3b, v127
	v_exp_f32_e32 v124, v124
	s_nop 0
	v_add_f32_e32 v124, 1.0, v124
	v_rcp_f32_e32 v124, v124
	s_nop 0
	v_mul_f32_e32 v124, v127, v124
	v_mul_f32_e32 v123, v124, v123
	v_mul_f32_e32 v124, 0xbfb8aa3b, v116
	v_exp_f32_e32 v124, v124
	s_nop 0
	v_add_f32_e32 v124, 1.0, v124
	v_rcp_f32_e32 v124, v124
	s_nop 0
	v_mul_f32_e32 v116, v116, v124
	v_mul_f32_e32 v116, v116, v112
	v_mul_f32_e32 v112, 0xbfb8aa3b, v117
	v_exp_f32_e32 v112, v112
	s_nop 0
	v_add_f32_e32 v112, 1.0, v112
	v_rcp_f32_e32 v112, v112
	s_nop 0
	v_mul_f32_e32 v112, v117, v112
	v_mul_f32_e32 v117, v112, v113
	v_mul_f32_e32 v112, 0xbfb8aa3b, v118
	v_exp_f32_e32 v112, v112
	s_nop 0
	v_add_f32_e32 v112, 1.0, v112
	v_rcp_f32_e32 v112, v112
	s_nop 0
	v_mul_f32_e32 v112, v118, v112
	v_mul_f32_e32 v124, v112, v114
	v_mul_f32_e32 v112, 0xbfb8aa3b, v119
	v_exp_f32_e32 v112, v112
	v_cvt_pk_bf16_f32 v114, v120, v121
	s_nop 0
	v_add_f32_e32 v112, 1.0, v112
	v_rcp_f32_e32 v112, v112
	s_nop 0
	v_mul_f32_e32 v112, v119, v112
	v_mul_f32_e32 v125, v112, v115
	v_lshlrev_b64 v[112:113], 1, v[146:147]
	v_lshl_add_u64 v[118:119], v[148:149], 0, v[112:113]
	v_cvt_pk_bf16_f32 v115, v122, v123
	v_cvt_pk_bf16_f32 v116, v116, v117
	v_cvt_pk_bf16_f32 v117, v124, v125
	global_store_dwordx4 v[118:119], v[114:117], off
	s_nop 1
	v_mul_f32_e32 v116, 0xbfb8aa3b, v108
	v_exp_f32_e32 v116, v116
	v_or_b32_e32 v114, 16, v144
	v_mad_i64_i32 v[114:115], s[14:15], v114, s5, v[138:139]
	v_add_f32_e32 v116, 1.0, v116
	v_rcp_f32_e32 v116, v116
	s_nop 0
	v_mul_f32_e32 v108, v108, v116
	v_mul_f32_e32 v104, v108, v104
	v_mul_f32_e32 v108, 0xbfb8aa3b, v109
	v_exp_f32_e32 v108, v108
	s_nop 0
	v_add_f32_e32 v108, 1.0, v108
	v_rcp_f32_e32 v108, v108
	s_nop 0
	v_mul_f32_e32 v108, v109, v108
	v_mul_f32_e32 v105, v108, v105
	v_mul_f32_e32 v108, 0xbfb8aa3b, v110
	v_exp_f32_e32 v108, v108
	s_nop 0
	v_add_f32_e32 v108, 1.0, v108
	v_rcp_f32_e32 v108, v108
	s_nop 0
	v_mul_f32_e32 v108, v110, v108
	v_mul_f32_e32 v106, v108, v106
	v_mul_f32_e32 v108, 0xbfb8aa3b, v111
	v_exp_f32_e32 v108, v108
	s_nop 0
	v_add_f32_e32 v108, 1.0, v108
	v_rcp_f32_e32 v108, v108
	s_nop 0
	v_mul_f32_e32 v108, v111, v108
	v_mul_f32_e32 v107, v108, v107
	v_mul_f32_e32 v108, 0xbfb8aa3b, v100
	v_exp_f32_e32 v108, v108
	s_nop 0
	v_add_f32_e32 v108, 1.0, v108
	v_rcp_f32_e32 v108, v108
	s_nop 0
	v_mul_f32_e32 v100, v100, v108
	v_mul_f32_e32 v108, v100, v96
	v_mul_f32_e32 v96, 0xbfb8aa3b, v101
	v_exp_f32_e32 v96, v96
	s_nop 0
	v_add_f32_e32 v96, 1.0, v96
	v_rcp_f32_e32 v96, v96
	s_nop 0
	v_mul_f32_e32 v96, v101, v96
	v_mul_f32_e32 v109, v96, v97
	v_mul_f32_e32 v96, 0xbfb8aa3b, v102
	v_exp_f32_e32 v96, v96
	v_lshl_add_u64 v[100:101], v[114:115], 0, v[112:113]
	v_add_f32_e32 v96, 1.0, v96
	v_rcp_f32_e32 v96, v96
	s_nop 0
	v_mul_f32_e32 v96, v102, v96
	v_mul_f32_e32 v102, v96, v98
	v_mul_f32_e32 v96, 0xbfb8aa3b, v103
	v_exp_f32_e32 v96, v96
	s_nop 0
	v_add_f32_e32 v96, 1.0, v96
	v_rcp_f32_e32 v96, v96
	s_nop 0
	v_mul_f32_e32 v96, v103, v96
	v_mul_f32_e32 v99, v96, v99
	v_cvt_pk_bf16_f32 v96, v104, v105
	v_cvt_pk_bf16_f32 v97, v106, v107
	v_cvt_pk_bf16_f32 v98, v108, v109
	v_cvt_pk_bf16_f32 v99, v102, v99
	global_store_dwordx4 v[100:101], v[96:99], off
	s_nop 1
	v_mul_f32_e32 v98, 0xbfb8aa3b, v92
	v_exp_f32_e32 v98, v98
	v_or_b32_e32 v96, 32, v144
	v_mad_i64_i32 v[96:97], s[14:15], v96, s5, v[138:139]
	v_add_f32_e32 v98, 1.0, v98
	v_rcp_f32_e32 v98, v98
	s_nop 0
	v_mul_f32_e32 v92, v92, v98
	v_mul_f32_e32 v88, v92, v88
	v_mul_f32_e32 v92, 0xbfb8aa3b, v93
	v_exp_f32_e32 v92, v92
	s_nop 0
	v_add_f32_e32 v92, 1.0, v92
	v_rcp_f32_e32 v92, v92
	s_nop 0
	v_mul_f32_e32 v92, v93, v92
	v_mul_f32_e32 v89, v92, v89
	v_mul_f32_e32 v92, 0xbfb8aa3b, v94
	v_exp_f32_e32 v92, v92
	s_nop 0
	v_add_f32_e32 v92, 1.0, v92
	v_rcp_f32_e32 v92, v92
	s_nop 0
	v_mul_f32_e32 v92, v94, v92
	v_mul_f32_e32 v90, v92, v90
	v_mul_f32_e32 v92, 0xbfb8aa3b, v95
	v_exp_f32_e32 v92, v92
	s_nop 0
	v_add_f32_e32 v92, 1.0, v92
	v_rcp_f32_e32 v92, v92
	s_nop 0
	v_mul_f32_e32 v92, v95, v92
	v_mul_f32_e32 v91, v92, v91
	v_mul_f32_e32 v92, 0xbfb8aa3b, v84
	v_exp_f32_e32 v92, v92
	s_nop 0
	v_add_f32_e32 v92, 1.0, v92
	v_rcp_f32_e32 v92, v92
	s_nop 0
	v_mul_f32_e32 v84, v84, v92
	v_mul_f32_e32 v92, v84, v80
	v_mul_f32_e32 v80, 0xbfb8aa3b, v85
	v_exp_f32_e32 v80, v80
	s_nop 0
	v_add_f32_e32 v80, 1.0, v80
	v_rcp_f32_e32 v80, v80
	s_nop 0
	v_mul_f32_e32 v80, v85, v80
	v_mul_f32_e32 v93, v80, v81
	v_mul_f32_e32 v80, 0xbfb8aa3b, v86
	v_exp_f32_e32 v80, v80
	v_lshl_add_u64 v[84:85], v[96:97], 0, v[112:113]
	v_add_f32_e32 v80, 1.0, v80
	v_rcp_f32_e32 v80, v80
	s_nop 0
	v_mul_f32_e32 v80, v86, v80
	v_mul_f32_e32 v86, v80, v82
	v_mul_f32_e32 v80, 0xbfb8aa3b, v87
	v_exp_f32_e32 v80, v80
	s_nop 0
	v_add_f32_e32 v80, 1.0, v80
	v_rcp_f32_e32 v80, v80
	s_nop 0
	v_mul_f32_e32 v80, v87, v80
	v_mul_f32_e32 v83, v80, v83
	v_cvt_pk_bf16_f32 v80, v88, v89
	v_cvt_pk_bf16_f32 v81, v90, v91
	v_cvt_pk_bf16_f32 v82, v92, v93
	v_cvt_pk_bf16_f32 v83, v86, v83
	global_store_dwordx4 v[84:85], v[80:83], off
	s_nop 1
	v_mul_f32_e32 v82, 0xbfb8aa3b, v76
	v_exp_f32_e32 v82, v82
	v_or_b32_e32 v80, 48, v144
	v_mad_i64_i32 v[80:81], s[14:15], v80, s5, v[138:139]
	v_add_f32_e32 v82, 1.0, v82
	v_rcp_f32_e32 v82, v82
	s_nop 0
	v_mul_f32_e32 v76, v76, v82
	v_mul_f32_e32 v72, v76, v72
	v_mul_f32_e32 v76, 0xbfb8aa3b, v77
	v_exp_f32_e32 v76, v76
	s_nop 0
	v_add_f32_e32 v76, 1.0, v76
	v_rcp_f32_e32 v76, v76
	s_nop 0
	v_mul_f32_e32 v76, v77, v76
	v_mul_f32_e32 v73, v76, v73
	v_mul_f32_e32 v76, 0xbfb8aa3b, v78
	v_exp_f32_e32 v76, v76
	s_nop 0
	v_add_f32_e32 v76, 1.0, v76
	v_rcp_f32_e32 v76, v76
	s_nop 0
	v_mul_f32_e32 v76, v78, v76
	v_mul_f32_e32 v74, v76, v74
	v_mul_f32_e32 v76, 0xbfb8aa3b, v79
	v_exp_f32_e32 v76, v76
	s_nop 0
	v_add_f32_e32 v76, 1.0, v76
	v_rcp_f32_e32 v76, v76
	s_nop 0
	v_mul_f32_e32 v76, v79, v76
	v_mul_f32_e32 v75, v76, v75
	v_mul_f32_e32 v76, 0xbfb8aa3b, v68
	v_exp_f32_e32 v76, v76
	s_nop 0
	v_add_f32_e32 v76, 1.0, v76
	v_rcp_f32_e32 v76, v76
	s_nop 0
	v_mul_f32_e32 v68, v68, v76
	v_mul_f32_e32 v76, v68, v64
	v_mul_f32_e32 v64, 0xbfb8aa3b, v69
	v_exp_f32_e32 v64, v64
	s_nop 0
	v_add_f32_e32 v64, 1.0, v64
	v_rcp_f32_e32 v64, v64
	s_nop 0
	v_mul_f32_e32 v64, v69, v64
	v_mul_f32_e32 v77, v64, v65
	v_mul_f32_e32 v64, 0xbfb8aa3b, v70
	v_exp_f32_e32 v64, v64
	v_lshl_add_u64 v[68:69], v[80:81], 0, v[112:113]
	v_add_f32_e32 v64, 1.0, v64
	v_rcp_f32_e32 v64, v64
	s_nop 0
	v_mul_f32_e32 v64, v70, v64
	v_mul_f32_e32 v70, v64, v66
	v_mul_f32_e32 v64, 0xbfb8aa3b, v71
	v_exp_f32_e32 v64, v64
	s_nop 0
	v_add_f32_e32 v64, 1.0, v64
	v_rcp_f32_e32 v64, v64
	s_nop 0
	v_mul_f32_e32 v64, v71, v64
	v_mul_f32_e32 v67, v64, v67
	v_cvt_pk_bf16_f32 v64, v72, v73
	v_cvt_pk_bf16_f32 v65, v74, v75
	v_cvt_pk_bf16_f32 v66, v76, v77
	v_cvt_pk_bf16_f32 v67, v70, v67
	global_store_dwordx4 v[68:69], v[64:67], off
	s_nop 1
	v_mul_f32_e32 v66, 0xbfb8aa3b, v60
	v_exp_f32_e32 v66, v66
	v_add_u32_e32 v64, 0x80, v144
	v_mad_i64_i32 v[64:65], s[14:15], v64, s5, v[138:139]
	v_add_f32_e32 v66, 1.0, v66
	v_rcp_f32_e32 v66, v66
	s_nop 0
	v_mul_f32_e32 v60, v60, v66
	v_mul_f32_e32 v56, v60, v56
	v_mul_f32_e32 v60, 0xbfb8aa3b, v61
	v_exp_f32_e32 v60, v60
	s_nop 0
	v_add_f32_e32 v60, 1.0, v60
	v_rcp_f32_e32 v60, v60
	s_nop 0
	v_mul_f32_e32 v60, v61, v60
	v_mul_f32_e32 v57, v60, v57
	v_mul_f32_e32 v60, 0xbfb8aa3b, v62
	v_exp_f32_e32 v60, v60
	s_nop 0
	v_add_f32_e32 v60, 1.0, v60
	v_rcp_f32_e32 v60, v60
	s_nop 0
	v_mul_f32_e32 v60, v62, v60
	v_mul_f32_e32 v58, v60, v58
	v_mul_f32_e32 v60, 0xbfb8aa3b, v63
	v_exp_f32_e32 v60, v60
	s_nop 0
	v_add_f32_e32 v60, 1.0, v60
	v_rcp_f32_e32 v60, v60
	s_nop 0
	v_mul_f32_e32 v60, v63, v60
	v_mul_f32_e32 v59, v60, v59
	v_mul_f32_e32 v60, 0xbfb8aa3b, v52
	v_exp_f32_e32 v60, v60
	s_nop 0
	v_add_f32_e32 v60, 1.0, v60
	v_rcp_f32_e32 v60, v60
	s_nop 0
	v_mul_f32_e32 v52, v52, v60
	v_mul_f32_e32 v60, v52, v48
	v_mul_f32_e32 v48, 0xbfb8aa3b, v53
	v_exp_f32_e32 v48, v48
	s_nop 0
	v_add_f32_e32 v48, 1.0, v48
	v_rcp_f32_e32 v48, v48
	s_nop 0
	v_mul_f32_e32 v48, v53, v48
	v_mul_f32_e32 v61, v48, v49
	v_mul_f32_e32 v48, 0xbfb8aa3b, v54
	v_exp_f32_e32 v48, v48
	v_lshl_add_u64 v[52:53], v[64:65], 0, v[112:113]
	v_add_f32_e32 v48, 1.0, v48
	v_rcp_f32_e32 v48, v48
	s_nop 0
	v_mul_f32_e32 v48, v54, v48
	v_mul_f32_e32 v54, v48, v50
	v_mul_f32_e32 v48, 0xbfb8aa3b, v55
	v_exp_f32_e32 v48, v48
	s_nop 0
	v_add_f32_e32 v48, 1.0, v48
	v_rcp_f32_e32 v48, v48
	s_nop 0
	v_mul_f32_e32 v48, v55, v48
	v_mul_f32_e32 v51, v48, v51
	v_cvt_pk_bf16_f32 v48, v56, v57
	v_cvt_pk_bf16_f32 v49, v58, v59
	v_cvt_pk_bf16_f32 v50, v60, v61
	v_cvt_pk_bf16_f32 v51, v54, v51
	global_store_dwordx4 v[52:53], v[48:51], off
	s_nop 1
	v_mul_f32_e32 v50, 0xbfb8aa3b, v44
	v_exp_f32_e32 v50, v50
	v_add_u32_e32 v48, 0x90, v144
	v_mad_i64_i32 v[48:49], s[14:15], v48, s5, v[138:139]
	v_add_f32_e32 v50, 1.0, v50
	v_rcp_f32_e32 v50, v50
	s_nop 0
	v_mul_f32_e32 v44, v44, v50
	v_mul_f32_e32 v40, v44, v40
	v_mul_f32_e32 v44, 0xbfb8aa3b, v45
	v_exp_f32_e32 v44, v44
	s_nop 0
	v_add_f32_e32 v44, 1.0, v44
	v_rcp_f32_e32 v44, v44
	s_nop 0
	v_mul_f32_e32 v44, v45, v44
	v_mul_f32_e32 v41, v44, v41
	v_mul_f32_e32 v44, 0xbfb8aa3b, v46
	v_exp_f32_e32 v44, v44
	s_nop 0
	v_add_f32_e32 v44, 1.0, v44
	v_rcp_f32_e32 v44, v44
	s_nop 0
	v_mul_f32_e32 v44, v46, v44
	v_mul_f32_e32 v42, v44, v42
	v_mul_f32_e32 v44, 0xbfb8aa3b, v47
	v_exp_f32_e32 v44, v44
	s_nop 0
	v_add_f32_e32 v44, 1.0, v44
	v_rcp_f32_e32 v44, v44
	s_nop 0
	v_mul_f32_e32 v44, v47, v44
	v_mul_f32_e32 v43, v44, v43
	v_mul_f32_e32 v44, 0xbfb8aa3b, v36
	v_exp_f32_e32 v44, v44
	s_nop 0
	v_add_f32_e32 v44, 1.0, v44
	v_rcp_f32_e32 v44, v44
	s_nop 0
	v_mul_f32_e32 v36, v36, v44
	v_mul_f32_e32 v44, v36, v32
	v_mul_f32_e32 v32, 0xbfb8aa3b, v37
	v_exp_f32_e32 v32, v32
	s_nop 0
	v_add_f32_e32 v32, 1.0, v32
	v_rcp_f32_e32 v32, v32
	s_nop 0
	v_mul_f32_e32 v32, v37, v32
	v_mul_f32_e32 v45, v32, v33
	v_mul_f32_e32 v32, 0xbfb8aa3b, v38
	v_exp_f32_e32 v32, v32
	v_lshl_add_u64 v[36:37], v[48:49], 0, v[112:113]
	v_add_f32_e32 v32, 1.0, v32
	v_rcp_f32_e32 v32, v32
	s_nop 0
	v_mul_f32_e32 v32, v38, v32
	v_mul_f32_e32 v38, v32, v34
	v_mul_f32_e32 v32, 0xbfb8aa3b, v39
	v_exp_f32_e32 v32, v32
	s_nop 0
	v_add_f32_e32 v32, 1.0, v32
	v_rcp_f32_e32 v32, v32
	s_nop 0
	v_mul_f32_e32 v32, v39, v32
	v_mul_f32_e32 v35, v32, v35
	v_cvt_pk_bf16_f32 v32, v40, v41
	v_cvt_pk_bf16_f32 v33, v42, v43
	v_cvt_pk_bf16_f32 v34, v44, v45
	v_cvt_pk_bf16_f32 v35, v38, v35
	global_store_dwordx4 v[36:37], v[32:35], off
	s_nop 1
	v_mul_f32_e32 v34, 0xbfb8aa3b, v28
	v_exp_f32_e32 v34, v34
	v_add_u32_e32 v32, 0xa0, v144
	v_mad_i64_i32 v[32:33], s[14:15], v32, s5, v[138:139]
	v_add_f32_e32 v34, 1.0, v34
	v_rcp_f32_e32 v34, v34
	s_nop 0
	v_mul_f32_e32 v28, v28, v34
	v_mul_f32_e32 v24, v28, v24
	v_mul_f32_e32 v28, 0xbfb8aa3b, v29
	v_exp_f32_e32 v28, v28
	s_nop 0
	v_add_f32_e32 v28, 1.0, v28
	v_rcp_f32_e32 v28, v28
	s_nop 0
	v_mul_f32_e32 v28, v29, v28
	v_mul_f32_e32 v25, v28, v25
	v_mul_f32_e32 v28, 0xbfb8aa3b, v30
	v_exp_f32_e32 v28, v28
	s_nop 0
	v_add_f32_e32 v28, 1.0, v28
	v_rcp_f32_e32 v28, v28
	s_nop 0
	v_mul_f32_e32 v28, v30, v28
	v_mul_f32_e32 v26, v28, v26
	v_mul_f32_e32 v28, 0xbfb8aa3b, v31
	v_exp_f32_e32 v28, v28
	s_nop 0
	v_add_f32_e32 v28, 1.0, v28
	v_rcp_f32_e32 v28, v28
	s_nop 0
	v_mul_f32_e32 v28, v31, v28
	v_mul_f32_e32 v27, v28, v27
	v_mul_f32_e32 v28, 0xbfb8aa3b, v20
	v_exp_f32_e32 v28, v28
	s_nop 0
	v_add_f32_e32 v28, 1.0, v28
	v_rcp_f32_e32 v28, v28
	s_nop 0
	v_mul_f32_e32 v20, v20, v28
	v_mul_f32_e32 v28, v20, v16
	v_mul_f32_e32 v16, 0xbfb8aa3b, v21
	v_exp_f32_e32 v16, v16
	s_nop 0
	v_add_f32_e32 v16, 1.0, v16
	v_rcp_f32_e32 v16, v16
	s_nop 0
	v_mul_f32_e32 v16, v21, v16
	v_mul_f32_e32 v29, v16, v17
	v_mul_f32_e32 v16, 0xbfb8aa3b, v22
	v_exp_f32_e32 v16, v16
	v_lshl_add_u64 v[20:21], v[32:33], 0, v[112:113]
	v_add_f32_e32 v16, 1.0, v16
	v_rcp_f32_e32 v16, v16
	s_nop 0
	v_mul_f32_e32 v16, v22, v16
	v_mul_f32_e32 v22, v16, v18
	v_mul_f32_e32 v16, 0xbfb8aa3b, v23
	v_exp_f32_e32 v16, v16
	s_nop 0
	v_add_f32_e32 v16, 1.0, v16
	v_rcp_f32_e32 v16, v16
	s_nop 0
	v_mul_f32_e32 v16, v23, v16
	v_mul_f32_e32 v19, v16, v19
	v_cvt_pk_bf16_f32 v16, v24, v25
	v_cvt_pk_bf16_f32 v17, v26, v27
	v_cvt_pk_bf16_f32 v18, v28, v29
	v_cvt_pk_bf16_f32 v19, v22, v19
	global_store_dwordx4 v[20:21], v[16:19], off
	s_nop 1
	v_mul_f32_e32 v18, 0xbfb8aa3b, v12
	v_exp_f32_e32 v18, v18
	v_add_u32_e32 v16, 0xb0, v144
	v_mad_i64_i32 v[16:17], s[14:15], v16, s5, v[138:139]
	v_add_f32_e32 v18, 1.0, v18
	v_rcp_f32_e32 v18, v18
	s_mov_b64 s[14:15], s[8:9]
	v_mul_f32_e32 v12, v12, v18
	v_mul_f32_e32 v8, v12, v8
	v_mul_f32_e32 v12, 0xbfb8aa3b, v13
	v_exp_f32_e32 v12, v12
	s_nop 0
	v_add_f32_e32 v12, 1.0, v12
	v_rcp_f32_e32 v12, v12
	s_nop 0
	v_mul_f32_e32 v12, v13, v12
	v_mul_f32_e32 v9, v12, v9
	v_mul_f32_e32 v12, 0xbfb8aa3b, v14
	v_exp_f32_e32 v12, v12
	s_nop 0
	v_add_f32_e32 v12, 1.0, v12
	v_rcp_f32_e32 v12, v12
	s_nop 0
	v_mul_f32_e32 v12, v14, v12
	v_mul_f32_e32 v10, v12, v10
	v_mul_f32_e32 v12, 0xbfb8aa3b, v15
	v_exp_f32_e32 v12, v12
	s_nop 0
	v_add_f32_e32 v12, 1.0, v12
	v_rcp_f32_e32 v12, v12
	s_nop 0
	v_mul_f32_e32 v12, v15, v12
	v_mul_f32_e32 v11, v12, v11
	v_mul_f32_e32 v12, 0xbfb8aa3b, v4
	v_exp_f32_e32 v12, v12
	s_nop 0
	v_add_f32_e32 v12, 1.0, v12
	v_rcp_f32_e32 v12, v12
	s_nop 0
	v_mul_f32_e32 v4, v4, v12
	v_mul_f32_e32 v12, v4, v0
	v_mul_f32_e32 v0, 0xbfb8aa3b, v5
	v_exp_f32_e32 v0, v0
	s_nop 0
	v_add_f32_e32 v0, 1.0, v0
	v_rcp_f32_e32 v0, v0
	s_nop 0
	v_mul_f32_e32 v0, v5, v0
	v_mul_f32_e32 v13, v0, v1
	v_mul_f32_e32 v0, 0xbfb8aa3b, v6
	v_exp_f32_e32 v0, v0
	v_lshl_add_u64 v[4:5], v[16:17], 0, v[112:113]
	v_add_f32_e32 v0, 1.0, v0
	v_rcp_f32_e32 v0, v0
	s_nop 0
	v_mul_f32_e32 v0, v6, v0
	v_mul_f32_e32 v6, v0, v2
	v_mul_f32_e32 v0, 0xbfb8aa3b, v7
	v_exp_f32_e32 v0, v0
	s_nop 0
	v_add_f32_e32 v0, 1.0, v0
	v_rcp_f32_e32 v0, v0
	s_nop 0
	v_mul_f32_e32 v0, v7, v0
	v_mul_f32_e32 v3, v0, v3
	v_cvt_pk_bf16_f32 v0, v8, v9
	v_cvt_pk_bf16_f32 v1, v10, v11
	v_cvt_pk_bf16_f32 v2, v12, v13
	v_cvt_pk_bf16_f32 v3, v6, v3
	global_store_dwordx4 v[4:5], v[0:3], off
	s_cbranch_vccz .LBB0_214
	s_waitcnt vmcnt(0)
	v_readlane_b32 s34, v254, 18
	s_cmpk_gt_u32 s21, 0xff
	v_readlane_b32 s35, v254, 19
	v_readlane_b32 s31, v254, 20
	s_cbranch_scc1 .LBB0_221
	s_barrier

.LBB0_245:
	s_add_u32 s10, s10, 0x80
	s_addc_u32 s11, s11, 0
	s_add_u32 s42, s12, 0x100
	s_addc_u32 s43, s13, 0
	s_mov_b32 s12, 0
	s_mov_b64 s[48:49], 0x80
	v_readlane_b32 s52, v254, 14
	v_readlane_b32 s53, v254, 15
	v_readlane_b32 s54, v254, 16
	v_readlane_b32 s55, v254, 17
	v_add_u32_e32 v218, 0x10000, v191
	s_add_i32 s44, s12, 2
	s_add_u32 s14, s10, 0x80
	s_addc_u32 s13, s11, 0
	s_add_i32 s45, 0, 0x10000
	ds_read_b128 v[120:123], v218 offset:0
	ds_read_b128 v[124:127], v218 offset:1024
	ds_read_b128 v[128:131], v218 offset:2048
	ds_read_b128 v[132:135], v218 offset:3072
	s_cmp_eq_u32 s36, s12
	s_cselect_b32 s12, s4, s14
	s_cselect_b32 s13, s5, s13
	s_cselect_b32 s15, s7, s43
	s_cselect_b32 s14, s6, s42
	s_add_i32 m0, s26, 0xc000
	ds_read_b128 v[144:147], v205
	ds_read_b128 v[148:151], v205 offset:1024
	ds_read_b128 v[152:155], v205 offset:2048
	ds_read_b128 v[156:159], v205 offset:3072
	ds_read_b128 v[160:163], v205 offset:4096
	ds_read_b128 v[164:167], v205 offset:5120
	ds_read_b128 v[178:181], v205 offset:6144
	ds_read_b128 v[182:185], v205 offset:7168
	global_load_lds_dwordx4 v174, s[10:11]
	s_add_i32 m0, s26, 0xe000
	s_nop 0
	global_load_lds_dwordx4 v176, s[10:11]
	s_waitcnt lgkmcnt(8)
	s_barrier
	s_waitcnt lgkmcnt(0)
	v_mfma_f32_16x16x32_bf16 v[140:143], v[120:123], v[144:147], 0
	v_mfma_f32_16x16x32_bf16 v[136:139], v[128:131], v[144:147], 0
	v_mfma_f32_16x16x32_bf16 v[108:111], v[120:123], v[152:155], 0
	v_mfma_f32_16x16x32_bf16 v[104:107], v[128:131], v[152:155], 0
	s_add_i32 s46, 0, 0x14000
	s_add_i32 s45, s45, s25
	v_mfma_f32_16x16x32_bf16 v[92:95], v[120:123], v[160:163], 0
	s_add_u32 s68, s14, 0x80
	s_addc_u32 s69, s15, 0
	v_mfma_f32_16x16x32_bf16 v[88:91], v[128:131], v[160:163], 0
	s_mov_b32 m0, s45
	v_mfma_f32_16x16x32_bf16 v[76:79], v[120:123], v[178:181], 0
	v_mfma_f32_16x16x32_bf16 v[72:75], v[128:131], v[178:181], 0
	v_mfma_f32_16x16x32_bf16 v[140:143], v[124:127], v[148:151], v[140:143]
	v_mfma_f32_16x16x32_bf16 v[136:139], v[132:135], v[148:151], v[136:139]
	v_mfma_f32_16x16x32_bf16 v[108:111], v[124:127], v[156:159], v[108:111]
	v_mfma_f32_16x16x32_bf16 v[104:107], v[132:135], v[156:159], v[104:107]
	v_mfma_f32_16x16x32_bf16 v[92:95], v[124:127], v[164:167], v[92:95]
	v_mfma_f32_16x16x32_bf16 v[88:91], v[132:135], v[164:167], v[88:91]
	v_mfma_f32_16x16x32_bf16 v[76:79], v[124:127], v[182:185], v[76:79]
	v_mfma_f32_16x16x32_bf16 v[72:75], v[132:135], v[182:185], v[72:75]
	s_barrier
	ds_read_b128 v[186:189], v218 offset:16384
	ds_read_b128 v[196:199], v218 offset:17408
	ds_read_b128 v[206:209], v218 offset:18432
	ds_read_b128 v[214:217], v218 offset:19456
	global_load_lds_dwordx4 v192, s[14:15]
	s_add_i32 m0, s45, 0x2000
	s_nop 0
	global_load_lds_dwordx4 v172, s[14:15]
	s_barrier
	s_waitcnt lgkmcnt(0)
	v_mfma_f32_16x16x32_bf16 v[116:119], v[186:189], v[144:147], 0
	v_mfma_f32_16x16x32_bf16 v[112:115], v[206:209], v[144:147], 0
	v_mfma_f32_16x16x32_bf16 v[100:103], v[186:189], v[152:155], 0
	v_mfma_f32_16x16x32_bf16 v[96:99], v[206:209], v[152:155], 0
	s_mov_b32 m0, s26
	v_mfma_f32_16x16x32_bf16 v[84:87], v[186:189], v[160:163], 0
	s_add_u32 s70, s12, 0x80
	s_addc_u32 s71, s13, 0
	v_mfma_f32_16x16x32_bf16 v[80:83], v[206:209], v[160:163], 0
	v_mfma_f32_16x16x32_bf16 v[68:71], v[186:189], v[178:181], 0
	v_mfma_f32_16x16x32_bf16 v[64:67], v[206:209], v[178:181], 0
	v_mfma_f32_16x16x32_bf16 v[116:119], v[196:199], v[148:151], v[116:119]
	v_mfma_f32_16x16x32_bf16 v[112:115], v[214:217], v[148:151], v[112:115]
	v_mfma_f32_16x16x32_bf16 v[100:103], v[196:199], v[156:159], v[100:103]
	v_mfma_f32_16x16x32_bf16 v[96:99], v[214:217], v[156:159], v[96:99]
	v_mfma_f32_16x16x32_bf16 v[84:87], v[196:199], v[164:167], v[84:87]
	v_mfma_f32_16x16x32_bf16 v[80:83], v[214:217], v[164:167], v[80:83]
	v_mfma_f32_16x16x32_bf16 v[68:71], v[196:199], v[182:185], v[68:71]
	v_mfma_f32_16x16x32_bf16 v[64:67], v[214:217], v[182:185], v[64:67]
	s_barrier
	ds_read_b128 v[144:147], v205 offset:16384
	ds_read_b128 v[148:151], v205 offset:17408
	ds_read_b128 v[152:155], v205 offset:18432
	ds_read_b128 v[156:159], v205 offset:19456
	ds_read_b128 v[160:163], v205 offset:20480
	ds_read_b128 v[164:167], v205 offset:21504
	ds_read_b128 v[178:181], v205 offset:22528
	ds_read_b128 v[182:185], v205 offset:23552
	global_load_lds_dwordx4 v168, s[12:13]
	s_mov_b32 m0, s27
	s_nop 0
	global_load_lds_dwordx4 v170, s[12:13]
	s_barrier
	s_waitcnt lgkmcnt(0)
	v_mfma_f32_16x16x32_bf16 v[60:63], v[120:123], v[144:147], 0
	v_mfma_f32_16x16x32_bf16 v[56:59], v[128:131], v[144:147], 0
	v_mfma_f32_16x16x32_bf16 v[44:47], v[120:123], v[152:155], 0
	v_mfma_f32_16x16x32_bf16 v[40:43], v[128:131], v[152:155], 0
	s_add_u32 s14, s14, s52
	s_addc_u32 s15, s15, 0
	v_mfma_f32_16x16x32_bf16 v[28:31], v[120:123], v[160:163], 0
	s_add_i32 s45, s46, s25
	s_mov_b32 m0, s45
	v_mfma_f32_16x16x32_bf16 v[24:27], v[128:131], v[160:163], 0
	v_mfma_f32_16x16x32_bf16 v[12:15], v[120:123], v[178:181], 0
	v_mfma_f32_16x16x32_bf16 v[8:11], v[128:131], v[178:181], 0
	v_mfma_f32_16x16x32_bf16 v[60:63], v[124:127], v[148:151], v[60:63]
	v_mfma_f32_16x16x32_bf16 v[56:59], v[132:135], v[148:151], v[56:59]
	v_mfma_f32_16x16x32_bf16 v[44:47], v[124:127], v[156:159], v[44:47]
	v_mfma_f32_16x16x32_bf16 v[40:43], v[132:135], v[156:159], v[40:43]
	v_mfma_f32_16x16x32_bf16 v[28:31], v[124:127], v[164:167], v[28:31]
	v_mfma_f32_16x16x32_bf16 v[24:27], v[132:135], v[164:167], v[24:27]
	v_mfma_f32_16x16x32_bf16 v[12:15], v[124:127], v[182:185], v[12:15]
	v_mfma_f32_16x16x32_bf16 v[8:11], v[132:135], v[182:185], v[8:11]
	s_barrier
	global_load_lds_dwordx4 v192, s[14:15]
	s_add_i32 m0, s45, 0x2000
	s_nop 0
	global_load_lds_dwordx4 v172, s[14:15]
	s_waitcnt vmcnt(6)
	s_barrier
	v_mfma_f32_16x16x32_bf16 v[52:55], v[186:189], v[144:147], 0
	v_mfma_f32_16x16x32_bf16 v[48:51], v[206:209], v[144:147], 0
	v_mfma_f32_16x16x32_bf16 v[36:39], v[186:189], v[152:155], 0
	v_mfma_f32_16x16x32_bf16 v[32:35], v[206:209], v[152:155], 0
	s_add_i32 s14, 0, 0x18000
	v_mfma_f32_16x16x32_bf16 v[20:23], v[186:189], v[160:163], 0
	s_add_u32 s12, s12, s52
	s_addc_u32 s13, s13, 0
	v_mfma_f32_16x16x32_bf16 v[16:19], v[206:209], v[160:163], 0
	s_mov_b32 m0, s28
	v_mfma_f32_16x16x32_bf16 v[4:7], v[186:189], v[178:181], 0
	v_mfma_f32_16x16x32_bf16 v[0:3], v[206:209], v[178:181], 0
	v_mfma_f32_16x16x32_bf16 v[52:55], v[196:199], v[148:151], v[52:55]
	v_mfma_f32_16x16x32_bf16 v[48:51], v[214:217], v[148:151], v[48:51]
	v_mfma_f32_16x16x32_bf16 v[36:39], v[196:199], v[156:159], v[36:39]
	v_mfma_f32_16x16x32_bf16 v[32:35], v[214:217], v[156:159], v[32:35]
	v_mfma_f32_16x16x32_bf16 v[20:23], v[196:199], v[164:167], v[20:23]
	v_mfma_f32_16x16x32_bf16 v[16:19], v[214:217], v[164:167], v[16:19]
	v_mfma_f32_16x16x32_bf16 v[4:7], v[196:199], v[182:185], v[4:7]
	v_mfma_f32_16x16x32_bf16 v[0:3], v[214:217], v[182:185], v[0:3]
	s_barrier
	ds_read_b128 v[120:123], v218 offset:32768
	ds_read_b128 v[124:127], v218 offset:33792
	ds_read_b128 v[128:131], v218 offset:34816
	ds_read_b128 v[132:135], v218 offset:35840
	ds_read_b128 v[144:147], v205 offset:32768
	ds_read_b128 v[148:151], v205 offset:33792
	ds_read_b128 v[152:155], v205 offset:34816
	ds_read_b128 v[156:159], v205 offset:35840
	ds_read_b128 v[160:163], v205 offset:36864
	ds_read_b128 v[164:167], v205 offset:37888
	ds_read_b128 v[178:181], v205 offset:38912
	ds_read_b128 v[182:185], v205 offset:39936
	global_load_lds_dwordx4 v168, s[12:13]
	s_mov_b32 m0, s29
	s_nop 0
	global_load_lds_dwordx4 v170, s[12:13]
	s_waitcnt lgkmcnt(8)
	s_barrier
	s_waitcnt lgkmcnt(0)
	v_mfma_f32_16x16x32_bf16 v[140:143], v[120:123], v[144:147], v[140:143]
	v_mfma_f32_16x16x32_bf16 v[136:139], v[128:131], v[144:147], v[136:139]
	v_mfma_f32_16x16x32_bf16 v[108:111], v[120:123], v[152:155], v[108:111]
	v_mfma_f32_16x16x32_bf16 v[104:107], v[128:131], v[152:155], v[104:107]
	s_add_i32 s12, 0, 0x1c000
	s_add_i32 s13, s14, s25
	v_mfma_f32_16x16x32_bf16 v[92:95], v[120:123], v[160:163], v[92:95]
	s_mov_b32 m0, s13
	v_mfma_f32_16x16x32_bf16 v[88:91], v[128:131], v[160:163], v[88:91]
	v_mfma_f32_16x16x32_bf16 v[76:79], v[120:123], v[178:181], v[76:79]
	v_mfma_f32_16x16x32_bf16 v[72:75], v[128:131], v[178:181], v[72:75]
	v_mfma_f32_16x16x32_bf16 v[140:143], v[124:127], v[148:151], v[140:143]
	v_mfma_f32_16x16x32_bf16 v[136:139], v[132:135], v[148:151], v[136:139]
	v_mfma_f32_16x16x32_bf16 v[108:111], v[124:127], v[156:159], v[108:111]
	v_mfma_f32_16x16x32_bf16 v[104:107], v[132:135], v[156:159], v[104:107]
	v_mfma_f32_16x16x32_bf16 v[92:95], v[124:127], v[164:167], v[92:95]
	v_mfma_f32_16x16x32_bf16 v[88:91], v[132:135], v[164:167], v[88:91]
	v_mfma_f32_16x16x32_bf16 v[76:79], v[124:127], v[182:185], v[76:79]
	v_mfma_f32_16x16x32_bf16 v[72:75], v[132:135], v[182:185], v[72:75]
	s_barrier
	ds_read_b128 v[186:189], v218 offset:49152
	ds_read_b128 v[196:199], v218 offset:50176
	ds_read_b128 v[206:209], v218 offset:51200
	ds_read_b128 v[214:217], v218 offset:52224
	global_load_lds_dwordx4 v192, s[68:69]
	s_add_i32 m0, s13, 0x2000
	s_nop 0
	global_load_lds_dwordx4 v172, s[68:69]
	s_barrier
	s_waitcnt lgkmcnt(0)
	v_mfma_f32_16x16x32_bf16 v[116:119], v[186:189], v[144:147], v[116:119]
	v_mfma_f32_16x16x32_bf16 v[112:115], v[206:209], v[144:147], v[112:115]
	v_mfma_f32_16x16x32_bf16 v[100:103], v[186:189], v[152:155], v[100:103]
	v_mfma_f32_16x16x32_bf16 v[96:99], v[206:209], v[152:155], v[96:99]
	s_mov_b32 m0, s34
	v_mfma_f32_16x16x32_bf16 v[84:87], v[186:189], v[160:163], v[84:87]
	v_mfma_f32_16x16x32_bf16 v[80:83], v[206:209], v[160:163], v[80:83]
	v_mfma_f32_16x16x32_bf16 v[68:71], v[186:189], v[178:181], v[68:71]
	v_mfma_f32_16x16x32_bf16 v[64:67], v[206:209], v[178:181], v[64:67]
	v_mfma_f32_16x16x32_bf16 v[116:119], v[196:199], v[148:151], v[116:119]
	v_mfma_f32_16x16x32_bf16 v[112:115], v[214:217], v[148:151], v[112:115]
	v_mfma_f32_16x16x32_bf16 v[100:103], v[196:199], v[156:159], v[100:103]
	v_mfma_f32_16x16x32_bf16 v[96:99], v[214:217], v[156:159], v[96:99]
	v_mfma_f32_16x16x32_bf16 v[84:87], v[196:199], v[164:167], v[84:87]
	v_mfma_f32_16x16x32_bf16 v[80:83], v[214:217], v[164:167], v[80:83]
	v_mfma_f32_16x16x32_bf16 v[68:71], v[196:199], v[182:185], v[68:71]
	v_mfma_f32_16x16x32_bf16 v[64:67], v[214:217], v[182:185], v[64:67]
	s_barrier
	ds_read_b128 v[144:147], v205 offset:49152
	ds_read_b128 v[148:151], v205 offset:50176
	ds_read_b128 v[152:155], v205 offset:51200
	ds_read_b128 v[156:159], v205 offset:52224
	ds_read_b128 v[160:163], v205 offset:53248
	ds_read_b128 v[164:167], v205 offset:54272
	ds_read_b128 v[178:181], v205 offset:55296
	ds_read_b128 v[182:185], v205 offset:56320
	global_load_lds_dwordx4 v168, s[70:71]
	s_mov_b32 m0, s35
	s_nop 0
	global_load_lds_dwordx4 v170, s[70:71]
	s_barrier
	s_waitcnt lgkmcnt(0)
	v_mfma_f32_16x16x32_bf16 v[60:63], v[120:123], v[144:147], v[60:63]
	v_mfma_f32_16x16x32_bf16 v[56:59], v[128:131], v[144:147], v[56:59]
	v_mfma_f32_16x16x32_bf16 v[44:47], v[120:123], v[152:155], v[44:47]
	v_mfma_f32_16x16x32_bf16 v[40:43], v[128:131], v[152:155], v[40:43]
	s_add_i32 s12, s12, s25
	v_mfma_f32_16x16x32_bf16 v[28:31], v[120:123], v[160:163], v[28:31]
	s_add_u32 s68, s68, s52
	s_addc_u32 s69, s69, 0
	v_mfma_f32_16x16x32_bf16 v[24:27], v[128:131], v[160:163], v[24:27]
	s_mov_b32 m0, s12
	v_mfma_f32_16x16x32_bf16 v[12:15], v[120:123], v[178:181], v[12:15]
	v_mfma_f32_16x16x32_bf16 v[8:11], v[128:131], v[178:181], v[8:11]
	v_mfma_f32_16x16x32_bf16 v[60:63], v[124:127], v[148:151], v[60:63]
	v_mfma_f32_16x16x32_bf16 v[56:59], v[132:135], v[148:151], v[56:59]
	v_mfma_f32_16x16x32_bf16 v[44:47], v[124:127], v[156:159], v[44:47]
	v_mfma_f32_16x16x32_bf16 v[40:43], v[132:135], v[156:159], v[40:43]
	v_mfma_f32_16x16x32_bf16 v[28:31], v[124:127], v[164:167], v[28:31]
	v_mfma_f32_16x16x32_bf16 v[24:27], v[132:135], v[164:167], v[24:27]
	v_mfma_f32_16x16x32_bf16 v[12:15], v[124:127], v[182:185], v[12:15]
	v_mfma_f32_16x16x32_bf16 v[8:11], v[132:135], v[182:185], v[8:11]
	s_barrier
	global_load_lds_dwordx4 v192, s[68:69]
	s_add_i32 m0, s12, 0x2000
	s_nop 0
	global_load_lds_dwordx4 v172, s[68:69]
	s_waitcnt vmcnt(6)
	s_barrier
	v_mfma_f32_16x16x32_bf16 v[52:55], v[186:189], v[144:147], v[52:55]
	v_mfma_f32_16x16x32_bf16 v[48:51], v[206:209], v[144:147], v[48:51]
	v_mfma_f32_16x16x32_bf16 v[36:39], v[186:189], v[152:155], v[36:39]
	v_mfma_f32_16x16x32_bf16 v[32:35], v[206:209], v[152:155], v[32:35]
	s_add_u32 s10, s10, 0x100
	s_addc_u32 s11, s11, 0
	v_mfma_f32_16x16x32_bf16 v[20:23], v[186:189], v[160:163], v[20:23]
	s_add_u32 s42, s42, 0x100
	s_addc_u32 s43, s43, 0
	v_mfma_f32_16x16x32_bf16 v[16:19], v[206:209], v[160:163], v[16:19]
	s_mov_b32 s12, s44
	v_mfma_f32_16x16x32_bf16 v[4:7], v[186:189], v[178:181], v[4:7]
	v_mfma_f32_16x16x32_bf16 v[0:3], v[206:209], v[178:181], v[0:3]
	v_mfma_f32_16x16x32_bf16 v[52:55], v[196:199], v[148:151], v[52:55]
	v_mfma_f32_16x16x32_bf16 v[48:51], v[214:217], v[148:151], v[48:51]
	v_mfma_f32_16x16x32_bf16 v[36:39], v[196:199], v[156:159], v[36:39]
	v_mfma_f32_16x16x32_bf16 v[32:35], v[214:217], v[156:159], v[32:35]
	v_mfma_f32_16x16x32_bf16 v[20:23], v[196:199], v[164:167], v[20:23]
	v_mfma_f32_16x16x32_bf16 v[16:19], v[214:217], v[164:167], v[16:19]
	v_mfma_f32_16x16x32_bf16 v[4:7], v[196:199], v[182:185], v[4:7]
	v_mfma_f32_16x16x32_bf16 v[0:3], v[214:217], v[182:185], v[0:3]
	s_cmp_ge_u32 s44, s33
	s_barrier
.LBB0_246:
	s_add_i32 s44, s12, 2
	s_add_u32 s14, s10, 0x80
	s_addc_u32 s13, s11, 0
	s_add_i32 s45, 0, 0x10000
	ds_read_b128 v[120:123], v218 offset:0
	ds_read_b128 v[124:127], v218 offset:1024
	ds_read_b128 v[128:131], v218 offset:2048
	ds_read_b128 v[132:135], v218 offset:3072
	s_cmp_eq_u32 s36, s12
	s_cselect_b32 s12, s4, s14
	s_cselect_b32 s13, s5, s13
	s_cselect_b32 s15, s7, s43
	s_cselect_b32 s14, s6, s42
	s_add_i32 m0, s26, 0xc000
	ds_read_b128 v[144:147], v205
	ds_read_b128 v[148:151], v205 offset:1024
	ds_read_b128 v[152:155], v205 offset:2048
	ds_read_b128 v[156:159], v205 offset:3072
	ds_read_b128 v[160:163], v205 offset:4096
	ds_read_b128 v[164:167], v205 offset:5120
	ds_read_b128 v[178:181], v205 offset:6144
	ds_read_b128 v[182:185], v205 offset:7168
	global_load_lds_dwordx4 v174, s[10:11]
	s_add_i32 m0, s26, 0xe000
	s_nop 0
	global_load_lds_dwordx4 v176, s[10:11]
	s_waitcnt lgkmcnt(8)
	s_barrier
	s_waitcnt lgkmcnt(0)
	v_mfma_f32_16x16x32_bf16 v[140:143], v[120:123], v[144:147], v[140:143]
	v_mfma_f32_16x16x32_bf16 v[136:139], v[128:131], v[144:147], v[136:139]
	v_mfma_f32_16x16x32_bf16 v[108:111], v[120:123], v[152:155], v[108:111]
	v_mfma_f32_16x16x32_bf16 v[104:107], v[128:131], v[152:155], v[104:107]
	s_add_i32 s46, 0, 0x14000
	s_add_i32 s45, s45, s25
	v_mfma_f32_16x16x32_bf16 v[92:95], v[120:123], v[160:163], v[92:95]
	s_add_u32 s68, s14, 0x80
	s_addc_u32 s69, s15, 0
	v_mfma_f32_16x16x32_bf16 v[88:91], v[128:131], v[160:163], v[88:91]
	s_mov_b32 m0, s45
	v_mfma_f32_16x16x32_bf16 v[76:79], v[120:123], v[178:181], v[76:79]
	v_mfma_f32_16x16x32_bf16 v[72:75], v[128:131], v[178:181], v[72:75]
	v_mfma_f32_16x16x32_bf16 v[140:143], v[124:127], v[148:151], v[140:143]
	v_mfma_f32_16x16x32_bf16 v[136:139], v[132:135], v[148:151], v[136:139]
	v_mfma_f32_16x16x32_bf16 v[108:111], v[124:127], v[156:159], v[108:111]
	v_mfma_f32_16x16x32_bf16 v[104:107], v[132:135], v[156:159], v[104:107]
	v_mfma_f32_16x16x32_bf16 v[92:95], v[124:127], v[164:167], v[92:95]
	v_mfma_f32_16x16x32_bf16 v[88:91], v[132:135], v[164:167], v[88:91]
	v_mfma_f32_16x16x32_bf16 v[76:79], v[124:127], v[182:185], v[76:79]
	v_mfma_f32_16x16x32_bf16 v[72:75], v[132:135], v[182:185], v[72:75]
	s_barrier
	ds_read_b128 v[186:189], v218 offset:16384
	ds_read_b128 v[196:199], v218 offset:17408
	ds_read_b128 v[206:209], v218 offset:18432
	ds_read_b128 v[214:217], v218 offset:19456
	global_load_lds_dwordx4 v192, s[14:15]
	s_add_i32 m0, s45, 0x2000
	s_nop 0
	global_load_lds_dwordx4 v172, s[14:15]
	s_barrier
	s_waitcnt lgkmcnt(0)
	v_mfma_f32_16x16x32_bf16 v[116:119], v[186:189], v[144:147], v[116:119]
	v_mfma_f32_16x16x32_bf16 v[112:115], v[206:209], v[144:147], v[112:115]
	v_mfma_f32_16x16x32_bf16 v[100:103], v[186:189], v[152:155], v[100:103]
	v_mfma_f32_16x16x32_bf16 v[96:99], v[206:209], v[152:155], v[96:99]
	s_mov_b32 m0, s26
	v_mfma_f32_16x16x32_bf16 v[84:87], v[186:189], v[160:163], v[84:87]
	s_add_u32 s70, s12, 0x80
	s_addc_u32 s71, s13, 0
	v_mfma_f32_16x16x32_bf16 v[80:83], v[206:209], v[160:163], v[80:83]
	v_mfma_f32_16x16x32_bf16 v[68:71], v[186:189], v[178:181], v[68:71]
	v_mfma_f32_16x16x32_bf16 v[64:67], v[206:209], v[178:181], v[64:67]
	v_mfma_f32_16x16x32_bf16 v[116:119], v[196:199], v[148:151], v[116:119]
	v_mfma_f32_16x16x32_bf16 v[112:115], v[214:217], v[148:151], v[112:115]
	v_mfma_f32_16x16x32_bf16 v[100:103], v[196:199], v[156:159], v[100:103]
	v_mfma_f32_16x16x32_bf16 v[96:99], v[214:217], v[156:159], v[96:99]
	v_mfma_f32_16x16x32_bf16 v[84:87], v[196:199], v[164:167], v[84:87]
	v_mfma_f32_16x16x32_bf16 v[80:83], v[214:217], v[164:167], v[80:83]
	v_mfma_f32_16x16x32_bf16 v[68:71], v[196:199], v[182:185], v[68:71]
	v_mfma_f32_16x16x32_bf16 v[64:67], v[214:217], v[182:185], v[64:67]
	s_barrier
	ds_read_b128 v[144:147], v205 offset:16384
	ds_read_b128 v[148:151], v205 offset:17408
	ds_read_b128 v[152:155], v205 offset:18432
	ds_read_b128 v[156:159], v205 offset:19456
	ds_read_b128 v[160:163], v205 offset:20480
	ds_read_b128 v[164:167], v205 offset:21504
	ds_read_b128 v[178:181], v205 offset:22528
	ds_read_b128 v[182:185], v205 offset:23552
	global_load_lds_dwordx4 v168, s[12:13]
	s_mov_b32 m0, s27
	s_nop 0
	global_load_lds_dwordx4 v170, s[12:13]
	s_barrier
	s_waitcnt lgkmcnt(0)
	v_mfma_f32_16x16x32_bf16 v[60:63], v[120:123], v[144:147], v[60:63]
	v_mfma_f32_16x16x32_bf16 v[56:59], v[128:131], v[144:147], v[56:59]
	v_mfma_f32_16x16x32_bf16 v[44:47], v[120:123], v[152:155], v[44:47]
	v_mfma_f32_16x16x32_bf16 v[40:43], v[128:131], v[152:155], v[40:43]
	s_add_u32 s14, s14, s52
	s_addc_u32 s15, s15, 0
	v_mfma_f32_16x16x32_bf16 v[28:31], v[120:123], v[160:163], v[28:31]
	s_add_i32 s45, s46, s25
	s_mov_b32 m0, s45
	v_mfma_f32_16x16x32_bf16 v[24:27], v[128:131], v[160:163], v[24:27]
	v_mfma_f32_16x16x32_bf16 v[12:15], v[120:123], v[178:181], v[12:15]
	v_mfma_f32_16x16x32_bf16 v[8:11], v[128:131], v[178:181], v[8:11]
	v_mfma_f32_16x16x32_bf16 v[60:63], v[124:127], v[148:151], v[60:63]
	v_mfma_f32_16x16x32_bf16 v[56:59], v[132:135], v[148:151], v[56:59]
	v_mfma_f32_16x16x32_bf16 v[44:47], v[124:127], v[156:159], v[44:47]
	v_mfma_f32_16x16x32_bf16 v[40:43], v[132:135], v[156:159], v[40:43]
	v_mfma_f32_16x16x32_bf16 v[28:31], v[124:127], v[164:167], v[28:31]
	v_mfma_f32_16x16x32_bf16 v[24:27], v[132:135], v[164:167], v[24:27]
	v_mfma_f32_16x16x32_bf16 v[12:15], v[124:127], v[182:185], v[12:15]
	v_mfma_f32_16x16x32_bf16 v[8:11], v[132:135], v[182:185], v[8:11]
	s_barrier
	global_load_lds_dwordx4 v192, s[14:15]
	s_add_i32 m0, s45, 0x2000
	s_nop 0
	global_load_lds_dwordx4 v172, s[14:15]
	s_waitcnt vmcnt(6)
	s_barrier
	v_mfma_f32_16x16x32_bf16 v[52:55], v[186:189], v[144:147], v[52:55]
	v_mfma_f32_16x16x32_bf16 v[48:51], v[206:209], v[144:147], v[48:51]
	v_mfma_f32_16x16x32_bf16 v[36:39], v[186:189], v[152:155], v[36:39]
	v_mfma_f32_16x16x32_bf16 v[32:35], v[206:209], v[152:155], v[32:35]
	s_add_i32 s14, 0, 0x18000
	v_mfma_f32_16x16x32_bf16 v[20:23], v[186:189], v[160:163], v[20:23]
	s_add_u32 s12, s12, s52
	s_addc_u32 s13, s13, 0
	v_mfma_f32_16x16x32_bf16 v[16:19], v[206:209], v[160:163], v[16:19]
	s_mov_b32 m0, s28
	v_mfma_f32_16x16x32_bf16 v[4:7], v[186:189], v[178:181], v[4:7]
	v_mfma_f32_16x16x32_bf16 v[0:3], v[206:209], v[178:181], v[0:3]
	v_mfma_f32_16x16x32_bf16 v[52:55], v[196:199], v[148:151], v[52:55]
	v_mfma_f32_16x16x32_bf16 v[48:51], v[214:217], v[148:151], v[48:51]
	v_mfma_f32_16x16x32_bf16 v[36:39], v[196:199], v[156:159], v[36:39]
	v_mfma_f32_16x16x32_bf16 v[32:35], v[214:217], v[156:159], v[32:35]
	v_mfma_f32_16x16x32_bf16 v[20:23], v[196:199], v[164:167], v[20:23]
	v_mfma_f32_16x16x32_bf16 v[16:19], v[214:217], v[164:167], v[16:19]
	v_mfma_f32_16x16x32_bf16 v[4:7], v[196:199], v[182:185], v[4:7]
	v_mfma_f32_16x16x32_bf16 v[0:3], v[214:217], v[182:185], v[0:3]
	s_barrier
	ds_read_b128 v[120:123], v218 offset:32768
	ds_read_b128 v[124:127], v218 offset:33792
	ds_read_b128 v[128:131], v218 offset:34816
	ds_read_b128 v[132:135], v218 offset:35840
	ds_read_b128 v[144:147], v205 offset:32768
	ds_read_b128 v[148:151], v205 offset:33792
	ds_read_b128 v[152:155], v205 offset:34816
	ds_read_b128 v[156:159], v205 offset:35840
	ds_read_b128 v[160:163], v205 offset:36864
	ds_read_b128 v[164:167], v205 offset:37888
	ds_read_b128 v[178:181], v205 offset:38912
	ds_read_b128 v[182:185], v205 offset:39936
	global_load_lds_dwordx4 v168, s[12:13]
	s_mov_b32 m0, s29
	s_nop 0
	global_load_lds_dwordx4 v170, s[12:13]
	s_waitcnt lgkmcnt(8)
	s_barrier
	s_waitcnt lgkmcnt(0)
	v_mfma_f32_16x16x32_bf16 v[140:143], v[120:123], v[144:147], v[140:143]
	v_mfma_f32_16x16x32_bf16 v[136:139], v[128:131], v[144:147], v[136:139]
	v_mfma_f32_16x16x32_bf16 v[108:111], v[120:123], v[152:155], v[108:111]
	v_mfma_f32_16x16x32_bf16 v[104:107], v[128:131], v[152:155], v[104:107]
	s_add_i32 s12, 0, 0x1c000
	s_add_i32 s13, s14, s25
	v_mfma_f32_16x16x32_bf16 v[92:95], v[120:123], v[160:163], v[92:95]
	s_mov_b32 m0, s13
	v_mfma_f32_16x16x32_bf16 v[88:91], v[128:131], v[160:163], v[88:91]
	v_mfma_f32_16x16x32_bf16 v[76:79], v[120:123], v[178:181], v[76:79]
	v_mfma_f32_16x16x32_bf16 v[72:75], v[128:131], v[178:181], v[72:75]
	v_mfma_f32_16x16x32_bf16 v[140:143], v[124:127], v[148:151], v[140:143]
	v_mfma_f32_16x16x32_bf16 v[136:139], v[132:135], v[148:151], v[136:139]
	v_mfma_f32_16x16x32_bf16 v[108:111], v[124:127], v[156:159], v[108:111]
	v_mfma_f32_16x16x32_bf16 v[104:107], v[132:135], v[156:159], v[104:107]
	v_mfma_f32_16x16x32_bf16 v[92:95], v[124:127], v[164:167], v[92:95]
	v_mfma_f32_16x16x32_bf16 v[88:91], v[132:135], v[164:167], v[88:91]
	v_mfma_f32_16x16x32_bf16 v[76:79], v[124:127], v[182:185], v[76:79]
	v_mfma_f32_16x16x32_bf16 v[72:75], v[132:135], v[182:185], v[72:75]
	s_barrier
	ds_read_b128 v[186:189], v218 offset:49152
	ds_read_b128 v[196:199], v218 offset:50176
	ds_read_b128 v[206:209], v218 offset:51200
	ds_read_b128 v[214:217], v218 offset:52224
	global_load_lds_dwordx4 v192, s[68:69]
	s_add_i32 m0, s13, 0x2000
	s_nop 0
	global_load_lds_dwordx4 v172, s[68:69]
	s_barrier
	s_waitcnt lgkmcnt(0)
	v_mfma_f32_16x16x32_bf16 v[116:119], v[186:189], v[144:147], v[116:119]
	v_mfma_f32_16x16x32_bf16 v[112:115], v[206:209], v[144:147], v[112:115]
	v_mfma_f32_16x16x32_bf16 v[100:103], v[186:189], v[152:155], v[100:103]
	v_mfma_f32_16x16x32_bf16 v[96:99], v[206:209], v[152:155], v[96:99]
	s_mov_b32 m0, s34
	v_mfma_f32_16x16x32_bf16 v[84:87], v[186:189], v[160:163], v[84:87]
	v_mfma_f32_16x16x32_bf16 v[80:83], v[206:209], v[160:163], v[80:83]
	v_mfma_f32_16x16x32_bf16 v[68:71], v[186:189], v[178:181], v[68:71]
	v_mfma_f32_16x16x32_bf16 v[64:67], v[206:209], v[178:181], v[64:67]
	v_mfma_f32_16x16x32_bf16 v[116:119], v[196:199], v[148:151], v[116:119]
	v_mfma_f32_16x16x32_bf16 v[112:115], v[214:217], v[148:151], v[112:115]
	v_mfma_f32_16x16x32_bf16 v[100:103], v[196:199], v[156:159], v[100:103]
	v_mfma_f32_16x16x32_bf16 v[96:99], v[214:217], v[156:159], v[96:99]
	v_mfma_f32_16x16x32_bf16 v[84:87], v[196:199], v[164:167], v[84:87]
	v_mfma_f32_16x16x32_bf16 v[80:83], v[214:217], v[164:167], v[80:83]
	v_mfma_f32_16x16x32_bf16 v[68:71], v[196:199], v[182:185], v[68:71]
	v_mfma_f32_16x16x32_bf16 v[64:67], v[214:217], v[182:185], v[64:67]
	s_barrier
	ds_read_b128 v[144:147], v205 offset:49152
	ds_read_b128 v[148:151], v205 offset:50176
	ds_read_b128 v[152:155], v205 offset:51200
	ds_read_b128 v[156:159], v205 offset:52224
	ds_read_b128 v[160:163], v205 offset:53248
	ds_read_b128 v[164:167], v205 offset:54272
	ds_read_b128 v[178:181], v205 offset:55296
	ds_read_b128 v[182:185], v205 offset:56320
	global_load_lds_dwordx4 v168, s[70:71]
	s_mov_b32 m0, s35
	s_nop 0
	global_load_lds_dwordx4 v170, s[70:71]
	s_barrier
	s_waitcnt lgkmcnt(0)
	v_mfma_f32_16x16x32_bf16 v[60:63], v[120:123], v[144:147], v[60:63]
	v_mfma_f32_16x16x32_bf16 v[56:59], v[128:131], v[144:147], v[56:59]
	v_mfma_f32_16x16x32_bf16 v[44:47], v[120:123], v[152:155], v[44:47]
	v_mfma_f32_16x16x32_bf16 v[40:43], v[128:131], v[152:155], v[40:43]
	s_add_i32 s12, s12, s25
	v_mfma_f32_16x16x32_bf16 v[28:31], v[120:123], v[160:163], v[28:31]
	s_add_u32 s68, s68, s52
	s_addc_u32 s69, s69, 0
	v_mfma_f32_16x16x32_bf16 v[24:27], v[128:131], v[160:163], v[24:27]
	s_mov_b32 m0, s12
	v_mfma_f32_16x16x32_bf16 v[12:15], v[120:123], v[178:181], v[12:15]
	v_mfma_f32_16x16x32_bf16 v[8:11], v[128:131], v[178:181], v[8:11]
	v_mfma_f32_16x16x32_bf16 v[60:63], v[124:127], v[148:151], v[60:63]
	v_mfma_f32_16x16x32_bf16 v[56:59], v[132:135], v[148:151], v[56:59]
	v_mfma_f32_16x16x32_bf16 v[44:47], v[124:127], v[156:159], v[44:47]
	v_mfma_f32_16x16x32_bf16 v[40:43], v[132:135], v[156:159], v[40:43]
	v_mfma_f32_16x16x32_bf16 v[28:31], v[124:127], v[164:167], v[28:31]
	v_mfma_f32_16x16x32_bf16 v[24:27], v[132:135], v[164:167], v[24:27]
	v_mfma_f32_16x16x32_bf16 v[12:15], v[124:127], v[182:185], v[12:15]
	v_mfma_f32_16x16x32_bf16 v[8:11], v[132:135], v[182:185], v[8:11]
	s_barrier
	global_load_lds_dwordx4 v192, s[68:69]
	s_add_i32 m0, s12, 0x2000
	s_nop 0
	global_load_lds_dwordx4 v172, s[68:69]
	s_waitcnt vmcnt(6)
	s_barrier
	v_mfma_f32_16x16x32_bf16 v[52:55], v[186:189], v[144:147], v[52:55]
	v_mfma_f32_16x16x32_bf16 v[48:51], v[206:209], v[144:147], v[48:51]
	v_mfma_f32_16x16x32_bf16 v[36:39], v[186:189], v[152:155], v[36:39]
	v_mfma_f32_16x16x32_bf16 v[32:35], v[206:209], v[152:155], v[32:35]
	s_add_u32 s10, s10, 0x100
	s_addc_u32 s11, s11, 0
	v_mfma_f32_16x16x32_bf16 v[20:23], v[186:189], v[160:163], v[20:23]
	s_add_u32 s42, s42, 0x100
	s_addc_u32 s43, s43, 0
	v_mfma_f32_16x16x32_bf16 v[16:19], v[206:209], v[160:163], v[16:19]
	s_mov_b32 s12, s44
	v_mfma_f32_16x16x32_bf16 v[4:7], v[186:189], v[178:181], v[4:7]
	v_mfma_f32_16x16x32_bf16 v[0:3], v[206:209], v[178:181], v[0:3]
	v_mfma_f32_16x16x32_bf16 v[52:55], v[196:199], v[148:151], v[52:55]
	v_mfma_f32_16x16x32_bf16 v[48:51], v[214:217], v[148:151], v[48:51]
	v_mfma_f32_16x16x32_bf16 v[36:39], v[196:199], v[156:159], v[36:39]
	v_mfma_f32_16x16x32_bf16 v[32:35], v[214:217], v[156:159], v[32:35]
	v_mfma_f32_16x16x32_bf16 v[20:23], v[196:199], v[164:167], v[20:23]
	v_mfma_f32_16x16x32_bf16 v[16:19], v[214:217], v[164:167], v[16:19]
	v_mfma_f32_16x16x32_bf16 v[4:7], v[196:199], v[182:185], v[4:7]
	v_mfma_f32_16x16x32_bf16 v[0:3], v[214:217], v[182:185], v[0:3]
	s_cmp_ge_u32 s44, s33
	s_barrier
	s_cbranch_scc0 .LBB0_246
	v_lshl_or_b32 v144, s41, 8, v204
	s_ashr_i32 s10, s40, 4
	s_mul_hi_i32 s11, s10, 0xc000
	s_mul_i32 s10, s10, 0xc000
	v_ashrrev_i32_e32 v145, 31, v144
	v_lshl_add_u32 v146, s40, 8, v190
	s_add_u32 s10, s30, s10
	v_lshlrev_b64 v[178:179], 1, v[144:145]
	v_ashrrev_i32_e32 v147, 31, v146
	s_addc_u32 s11, s31, s11
	v_lshl_add_u64 v[180:181], s[2:3], 0, v[178:179]
	v_lshlrev_b64 v[182:183], 12, v[146:147]
	v_lshl_add_u64 v[124:125], v[144:145], 2, s[10:11]
	v_lshl_add_u64 v[144:145], v[180:181], 0, v[182:183]
	global_load_dwordx4 v[128:131], v[124:125], off offset:16
	global_load_dwordx4 v[132:135], v[124:125], off
	global_load_dwordx4 v[120:123], v[124:125], off offset:528
	s_nop 0
	global_load_dwordx4 v[124:127], v[124:125], off offset:512
	s_nop 0
	global_load_dwordx4 v[196:199], v[144:145], off
	global_load_dwordx4 v[206:209], v[144:145], off offset:256
	v_or_b32_e32 v144, 16, v146
	v_ashrrev_i32_e32 v145, 31, v144
	v_lshlrev_b64 v[188:189], 12, v[144:145]
	v_lshl_add_u64 v[144:145], v[180:181], 0, v[188:189]
	global_load_dwordx4 v[164:167], v[144:145], off
	global_load_dwordx4 v[160:163], v[144:145], off offset:256
	v_or_b32_e32 v144, 32, v146
	v_ashrrev_i32_e32 v145, 31, v144
	v_lshlrev_b64 v[186:187], 12, v[144:145]
	v_lshl_add_u64 v[144:145], v[180:181], 0, v[186:187]
	global_load_dwordx4 v[156:159], v[144:145], off
	global_load_dwordx4 v[152:155], v[144:145], off offset:256
	v_or_b32_e32 v144, 48, v146
	v_ashrrev_i32_e32 v145, 31, v144
	v_lshlrev_b64 v[184:185], 12, v[144:145]
	v_lshl_add_u64 v[144:145], v[180:181], 0, v[184:185]
	global_load_dwordx4 v[148:151], v[144:145], off
	s_nop 0
	global_load_dwordx4 v[144:147], v[144:145], off offset:256
	s_mov_b64 s[10:11], 0x80000
	s_and_b64 vcc, exec, s[0:1]
	s_mov_b32 s41, s38
	s_mov_b32 s40, s39
	s_mov_b64 s[12:13], s[6:7]
	v_readlane_b32 s14, v254, 21
	s_movk_i32 s15, 0x2000
	s_waitcnt vmcnt(0)
	v_lshlrev_b32_e32 v210, 16, v196
	v_and_b32_e32 v211, 0xffff0000, v196
	v_lshlrev_b32_e32 v196, 16, v197
	v_and_b32_e32 v197, 0xffff0000, v197
	v_lshlrev_b32_e32 v214, 16, v198
	v_and_b32_e32 v215, 0xffff0000, v198
	v_lshlrev_b32_e32 v198, 16, v199
	v_and_b32_e32 v199, 0xffff0000, v199
	v_pk_fma_f32 v[140:141], v[140:141], v[132:133], v[210:211]
	v_pk_fma_f32 v[142:143], v[142:143], v[134:135], v[196:197]
	v_pk_fma_f32 v[196:197], v[138:139], v[130:131], v[198:199]
	v_pk_fma_f32 v[138:139], v[136:137], v[128:129], v[214:215]
	v_cvt_pk_bf16_f32 v136, v140, v141
	v_lshl_add_u64 v[140:141], s[8:9], 0, v[182:183]
	v_cvt_pk_bf16_f32 v137, v142, v143
	v_cvt_pk_bf16_f32 v138, v138, v139
	v_cvt_pk_bf16_f32 v139, v196, v197
	v_lshl_add_u64 v[140:141], v[140:141], 0, v[178:179]
	global_store_dwordx4 v[140:141], v[136:139], off
	v_lshlrev_b32_e32 v142, 16, v208
	v_and_b32_e32 v143, 0xffff0000, v208
	v_lshlrev_b32_e32 v136, 16, v206
	v_and_b32_e32 v137, 0xffff0000, v206
	v_lshlrev_b32_e32 v138, 16, v207
	v_and_b32_e32 v139, 0xffff0000, v207
	v_lshlrev_b32_e32 v196, 16, v209
	v_and_b32_e32 v197, 0xffff0000, v209
	v_pk_fma_f32 v[118:119], v[118:119], v[126:127], v[138:139]
	v_pk_fma_f32 v[116:117], v[116:117], v[124:125], v[136:137]
	v_pk_fma_f32 v[136:137], v[114:115], v[122:123], v[196:197]
	v_pk_fma_f32 v[114:115], v[112:113], v[120:121], v[142:143]
	v_cvt_pk_bf16_f32 v112, v116, v117
	v_cvt_pk_bf16_f32 v113, v118, v119
	v_lshlrev_b32_e32 v116, 16, v166
	v_cvt_pk_bf16_f32 v114, v114, v115
	v_cvt_pk_bf16_f32 v115, v136, v137
	global_store_dwordx4 v[140:141], v[112:115], off offset:256
	v_and_b32_e32 v117, 0xffff0000, v166
	v_lshlrev_b32_e32 v118, 16, v167
	v_lshlrev_b32_e32 v112, 16, v164
	v_and_b32_e32 v113, 0xffff0000, v164
	v_and_b32_e32 v119, 0xffff0000, v167
	v_pk_fma_f32 v[108:109], v[108:109], v[132:133], v[112:113]
	v_lshlrev_b32_e32 v114, 16, v165
	v_and_b32_e32 v115, 0xffff0000, v165
	v_pk_fma_f32 v[112:113], v[106:107], v[130:131], v[118:119]
	v_pk_fma_f32 v[106:107], v[104:105], v[128:129], v[116:117]
	v_cvt_pk_bf16_f32 v104, v108, v109
	v_lshl_add_u64 v[108:109], s[8:9], 0, v[188:189]
	v_pk_fma_f32 v[110:111], v[110:111], v[134:135], v[114:115]
	v_lshl_add_u64 v[108:109], v[108:109], 0, v[178:179]
	v_cvt_pk_bf16_f32 v105, v110, v111
	v_cvt_pk_bf16_f32 v106, v106, v107
	v_cvt_pk_bf16_f32 v107, v112, v113
	global_store_dwordx4 v[108:109], v[104:107], off
	v_lshlrev_b32_e32 v110, 16, v162
	v_and_b32_e32 v111, 0xffff0000, v162
	v_lshlrev_b32_e32 v104, 16, v160
	v_and_b32_e32 v105, 0xffff0000, v160
	v_lshlrev_b32_e32 v106, 16, v161
	v_and_b32_e32 v107, 0xffff0000, v161
	v_lshlrev_b32_e32 v112, 16, v163
	v_and_b32_e32 v113, 0xffff0000, v163
	v_pk_fma_f32 v[102:103], v[102:103], v[126:127], v[106:107]
	v_pk_fma_f32 v[100:101], v[100:101], v[124:125], v[104:105]
	v_pk_fma_f32 v[104:105], v[98:99], v[122:123], v[112:113]
	v_pk_fma_f32 v[98:99], v[96:97], v[120:121], v[110:111]
	v_cvt_pk_bf16_f32 v96, v100, v101
	v_cvt_pk_bf16_f32 v97, v102, v103
	v_lshlrev_b32_e32 v100, 16, v158
	v_cvt_pk_bf16_f32 v98, v98, v99
	v_cvt_pk_bf16_f32 v99, v104, v105
	global_store_dwordx4 v[108:109], v[96:99], off offset:256
	v_and_b32_e32 v101, 0xffff0000, v158
	v_lshlrev_b32_e32 v102, 16, v159
	v_lshlrev_b32_e32 v96, 16, v156
	v_and_b32_e32 v97, 0xffff0000, v156
	v_and_b32_e32 v103, 0xffff0000, v159
	v_pk_fma_f32 v[92:93], v[92:93], v[132:133], v[96:97]
	v_lshlrev_b32_e32 v98, 16, v157
	v_and_b32_e32 v99, 0xffff0000, v157
	v_pk_fma_f32 v[96:97], v[90:91], v[130:131], v[102:103]
	v_pk_fma_f32 v[90:91], v[88:89], v[128:129], v[100:101]
	v_cvt_pk_bf16_f32 v88, v92, v93
	v_lshl_add_u64 v[92:93], s[8:9], 0, v[186:187]
	v_pk_fma_f32 v[94:95], v[94:95], v[134:135], v[98:99]
	v_lshl_add_u64 v[92:93], v[92:93], 0, v[178:179]
	v_cvt_pk_bf16_f32 v89, v94, v95
	v_cvt_pk_bf16_f32 v90, v90, v91
	v_cvt_pk_bf16_f32 v91, v96, v97
	global_store_dwordx4 v[92:93], v[88:91], off
	v_lshlrev_b32_e32 v94, 16, v154
	v_and_b32_e32 v95, 0xffff0000, v154
	v_lshlrev_b32_e32 v88, 16, v152
	v_and_b32_e32 v89, 0xffff0000, v152
	v_lshlrev_b32_e32 v90, 16, v153
	v_and_b32_e32 v91, 0xffff0000, v153
	v_lshlrev_b32_e32 v96, 16, v155
	v_and_b32_e32 v97, 0xffff0000, v155
	v_pk_fma_f32 v[86:87], v[86:87], v[126:127], v[90:91]
	v_pk_fma_f32 v[84:85], v[84:85], v[124:125], v[88:89]
	v_pk_fma_f32 v[88:89], v[82:83], v[122:123], v[96:97]
	v_pk_fma_f32 v[82:83], v[80:81], v[120:121], v[94:95]
	v_cvt_pk_bf16_f32 v80, v84, v85
	v_cvt_pk_bf16_f32 v81, v86, v87
	v_lshlrev_b32_e32 v84, 16, v150
	v_cvt_pk_bf16_f32 v82, v82, v83
	v_cvt_pk_bf16_f32 v83, v88, v89
	global_store_dwordx4 v[92:93], v[80:83], off offset:256
	v_and_b32_e32 v85, 0xffff0000, v150
	v_lshlrev_b32_e32 v86, 16, v151
	v_lshlrev_b32_e32 v80, 16, v148
	v_and_b32_e32 v81, 0xffff0000, v148
	v_and_b32_e32 v87, 0xffff0000, v151
	v_pk_fma_f32 v[76:77], v[76:77], v[132:133], v[80:81]
	v_lshlrev_b32_e32 v82, 16, v149
	v_and_b32_e32 v83, 0xffff0000, v149
	v_pk_fma_f32 v[80:81], v[74:75], v[130:131], v[86:87]
	v_pk_fma_f32 v[74:75], v[72:73], v[128:129], v[84:85]
	v_cvt_pk_bf16_f32 v72, v76, v77
	v_lshl_add_u64 v[76:77], s[8:9], 0, v[184:185]
	v_pk_fma_f32 v[78:79], v[78:79], v[134:135], v[82:83]
	v_lshl_add_u64 v[76:77], v[76:77], 0, v[178:179]
	v_cvt_pk_bf16_f32 v73, v78, v79
	v_cvt_pk_bf16_f32 v74, v74, v75
	v_cvt_pk_bf16_f32 v75, v80, v81
	global_store_dwordx4 v[76:77], v[72:75], off
	v_lshlrev_b32_e32 v78, 16, v146
	v_and_b32_e32 v79, 0xffff0000, v146
	v_lshlrev_b32_e32 v72, 16, v144
	v_and_b32_e32 v73, 0xffff0000, v144
	v_lshlrev_b32_e32 v74, 16, v145
	v_and_b32_e32 v75, 0xffff0000, v145
	v_lshlrev_b32_e32 v80, 16, v147
	v_and_b32_e32 v81, 0xffff0000, v147
	v_pk_fma_f32 v[70:71], v[70:71], v[126:127], v[74:75]
	v_pk_fma_f32 v[68:69], v[68:69], v[124:125], v[72:73]
	v_pk_fma_f32 v[72:73], v[66:67], v[122:123], v[80:81]
	v_pk_fma_f32 v[66:67], v[64:65], v[120:121], v[78:79]
	v_cvt_pk_bf16_f32 v64, v68, v69
	v_cvt_pk_bf16_f32 v65, v70, v71
	v_lshl_add_u64 v[98:99], v[182:183], 0, s[10:11]
	v_cvt_pk_bf16_f32 v66, v66, v67
	v_cvt_pk_bf16_f32 v67, v72, v73
	global_store_dwordx4 v[76:77], v[64:67], off offset:256
	s_mov_b64 s[10:11], 0x90000
	v_lshl_add_u64 v[100:101], v[182:183], 0, s[10:11]
	v_lshl_add_u64 v[64:65], v[180:181], 0, v[98:99]
	global_load_dwordx4 v[74:77], v[64:65], off
	global_load_dwordx4 v[78:81], v[64:65], off offset:256
	v_lshl_add_u64 v[64:65], v[180:181], 0, v[100:101]
	global_load_dwordx4 v[82:85], v[64:65], off
	global_load_dwordx4 v[86:89], v[64:65], off offset:256
	s_mov_b64 s[10:11], 0xa0000
	v_lshl_add_u64 v[102:103], v[182:183], 0, s[10:11]
	v_lshl_add_u64 v[64:65], v[180:181], 0, v[102:103]
	global_load_dwordx4 v[90:93], v[64:65], off
	global_load_dwordx4 v[94:97], v[64:65], off offset:256
	s_mov_b64 s[10:11], 0xb0000
	v_lshl_add_u64 v[72:73], v[182:183], 0, s[10:11]
	v_lshl_add_u64 v[64:65], v[180:181], 0, v[72:73]
	global_load_dwordx4 v[68:71], v[64:65], off
	s_nop 0
	global_load_dwordx4 v[64:67], v[64:65], off offset:256
	s_mov_b64 s[10:11], s[4:5]
	s_waitcnt vmcnt(0)
	v_lshlrev_b32_e32 v104, 16, v74
	v_and_b32_e32 v105, 0xffff0000, v74
	v_lshlrev_b32_e32 v74, 16, v75
	v_and_b32_e32 v75, 0xffff0000, v75
	v_lshlrev_b32_e32 v106, 16, v76
	v_and_b32_e32 v107, 0xffff0000, v76
	v_lshlrev_b32_e32 v76, 16, v77
	v_and_b32_e32 v77, 0xffff0000, v77
	v_pk_fma_f32 v[60:61], v[60:61], v[132:133], v[104:105]
	v_pk_fma_f32 v[62:63], v[62:63], v[134:135], v[74:75]
	v_pk_fma_f32 v[74:75], v[58:59], v[130:131], v[76:77]
	v_pk_fma_f32 v[58:59], v[56:57], v[128:129], v[106:107]
	v_cvt_pk_bf16_f32 v56, v60, v61
	v_lshl_add_u64 v[60:61], s[8:9], 0, v[98:99]
	v_cvt_pk_bf16_f32 v57, v62, v63
	v_cvt_pk_bf16_f32 v58, v58, v59
	v_cvt_pk_bf16_f32 v59, v74, v75
	v_lshl_add_u64 v[60:61], v[60:61], 0, v[178:179]
	global_store_dwordx4 v[60:61], v[56:59], off
	v_lshlrev_b32_e32 v62, 16, v80
	v_and_b32_e32 v63, 0xffff0000, v80
	v_lshlrev_b32_e32 v56, 16, v78
	v_and_b32_e32 v57, 0xffff0000, v78
	v_lshlrev_b32_e32 v58, 16, v79
	v_and_b32_e32 v59, 0xffff0000, v79
	v_lshlrev_b32_e32 v74, 16, v81
	v_and_b32_e32 v75, 0xffff0000, v81
	v_pk_fma_f32 v[54:55], v[54:55], v[126:127], v[58:59]
	v_pk_fma_f32 v[52:53], v[52:53], v[124:125], v[56:57]
	v_pk_fma_f32 v[56:57], v[50:51], v[122:123], v[74:75]
	v_pk_fma_f32 v[50:51], v[48:49], v[120:121], v[62:63]
	v_cvt_pk_bf16_f32 v48, v52, v53
	v_cvt_pk_bf16_f32 v49, v54, v55
	v_lshlrev_b32_e32 v52, 16, v84
	v_cvt_pk_bf16_f32 v50, v50, v51
	v_cvt_pk_bf16_f32 v51, v56, v57
	global_store_dwordx4 v[60:61], v[48:51], off offset:256
	v_and_b32_e32 v53, 0xffff0000, v84
	v_lshlrev_b32_e32 v54, 16, v85
	v_lshlrev_b32_e32 v48, 16, v82
	v_and_b32_e32 v49, 0xffff0000, v82
	v_and_b32_e32 v55, 0xffff0000, v85
	v_pk_fma_f32 v[44:45], v[44:45], v[132:133], v[48:49]
	v_lshlrev_b32_e32 v50, 16, v83
	v_and_b32_e32 v51, 0xffff0000, v83
	v_pk_fma_f32 v[48:49], v[42:43], v[130:131], v[54:55]
	v_pk_fma_f32 v[42:43], v[40:41], v[128:129], v[52:53]
	v_cvt_pk_bf16_f32 v40, v44, v45
	v_lshl_add_u64 v[44:45], s[8:9], 0, v[100:101]
	v_pk_fma_f32 v[46:47], v[46:47], v[134:135], v[50:51]
	v_lshl_add_u64 v[44:45], v[44:45], 0, v[178:179]
	v_cvt_pk_bf16_f32 v41, v46, v47
	v_cvt_pk_bf16_f32 v42, v42, v43
	v_cvt_pk_bf16_f32 v43, v48, v49
	global_store_dwordx4 v[44:45], v[40:43], off
	v_lshlrev_b32_e32 v46, 16, v88
	v_and_b32_e32 v47, 0xffff0000, v88
	v_lshlrev_b32_e32 v40, 16, v86
	v_and_b32_e32 v41, 0xffff0000, v86
	v_lshlrev_b32_e32 v42, 16, v87
	v_and_b32_e32 v43, 0xffff0000, v87
	v_lshlrev_b32_e32 v48, 16, v89
	v_and_b32_e32 v49, 0xffff0000, v89
	v_pk_fma_f32 v[38:39], v[38:39], v[126:127], v[42:43]
	v_pk_fma_f32 v[36:37], v[36:37], v[124:125], v[40:41]
	v_pk_fma_f32 v[40:41], v[34:35], v[122:123], v[48:49]
	v_pk_fma_f32 v[34:35], v[32:33], v[120:121], v[46:47]
	v_cvt_pk_bf16_f32 v32, v36, v37
	v_cvt_pk_bf16_f32 v33, v38, v39
	v_lshlrev_b32_e32 v36, 16, v92
	v_cvt_pk_bf16_f32 v34, v34, v35
	v_cvt_pk_bf16_f32 v35, v40, v41
	global_store_dwordx4 v[44:45], v[32:35], off offset:256
	v_and_b32_e32 v37, 0xffff0000, v92
	v_lshlrev_b32_e32 v38, 16, v93
	v_lshlrev_b32_e32 v32, 16, v90
	v_and_b32_e32 v33, 0xffff0000, v90
	v_and_b32_e32 v39, 0xffff0000, v93
	v_pk_fma_f32 v[28:29], v[28:29], v[132:133], v[32:33]
	v_lshlrev_b32_e32 v34, 16, v91
	v_and_b32_e32 v35, 0xffff0000, v91
	v_pk_fma_f32 v[32:33], v[26:27], v[130:131], v[38:39]
	v_pk_fma_f32 v[26:27], v[24:25], v[128:129], v[36:37]
	v_cvt_pk_bf16_f32 v24, v28, v29
	v_lshl_add_u64 v[28:29], s[8:9], 0, v[102:103]
	v_pk_fma_f32 v[30:31], v[30:31], v[134:135], v[34:35]
	v_lshl_add_u64 v[28:29], v[28:29], 0, v[178:179]
	v_cvt_pk_bf16_f32 v25, v30, v31
	v_cvt_pk_bf16_f32 v26, v26, v27
	v_cvt_pk_bf16_f32 v27, v32, v33
	global_store_dwordx4 v[28:29], v[24:27], off
	v_lshlrev_b32_e32 v30, 16, v96
	v_and_b32_e32 v31, 0xffff0000, v96
	v_lshlrev_b32_e32 v24, 16, v94
	v_and_b32_e32 v25, 0xffff0000, v94
	v_lshlrev_b32_e32 v26, 16, v95
	v_and_b32_e32 v27, 0xffff0000, v95
	v_lshlrev_b32_e32 v32, 16, v97
	v_and_b32_e32 v33, 0xffff0000, v97
	v_pk_fma_f32 v[22:23], v[22:23], v[126:127], v[26:27]
	v_pk_fma_f32 v[20:21], v[20:21], v[124:125], v[24:25]
	v_pk_fma_f32 v[24:25], v[18:19], v[122:123], v[32:33]
	v_pk_fma_f32 v[18:19], v[16:17], v[120:121], v[30:31]
	v_cvt_pk_bf16_f32 v16, v20, v21
	v_cvt_pk_bf16_f32 v17, v22, v23
	v_lshlrev_b32_e32 v20, 16, v70
	v_cvt_pk_bf16_f32 v18, v18, v19
	v_cvt_pk_bf16_f32 v19, v24, v25
	global_store_dwordx4 v[28:29], v[16:19], off offset:256
	v_and_b32_e32 v21, 0xffff0000, v70
	v_lshlrev_b32_e32 v22, 16, v71
	v_lshlrev_b32_e32 v16, 16, v68
	v_and_b32_e32 v17, 0xffff0000, v68
	v_and_b32_e32 v23, 0xffff0000, v71
	v_pk_fma_f32 v[12:13], v[12:13], v[132:133], v[16:17]
	v_lshlrev_b32_e32 v18, 16, v69
	v_and_b32_e32 v19, 0xffff0000, v69
	v_pk_fma_f32 v[16:17], v[10:11], v[130:131], v[22:23]
	v_pk_fma_f32 v[10:11], v[8:9], v[128:129], v[20:21]
	v_cvt_pk_bf16_f32 v8, v12, v13
	v_lshl_add_u64 v[12:13], s[8:9], 0, v[72:73]
	v_pk_fma_f32 v[14:15], v[14:15], v[134:135], v[18:19]
	v_lshl_add_u64 v[12:13], v[12:13], 0, v[178:179]
	v_cvt_pk_bf16_f32 v9, v14, v15
	v_cvt_pk_bf16_f32 v10, v10, v11
	v_cvt_pk_bf16_f32 v11, v16, v17
	global_store_dwordx4 v[12:13], v[8:11], off
	v_lshlrev_b32_e32 v14, 16, v66
	v_and_b32_e32 v15, 0xffff0000, v66
	v_lshlrev_b32_e32 v8, 16, v64
	v_and_b32_e32 v9, 0xffff0000, v64
	v_lshlrev_b32_e32 v16, 16, v67
	v_and_b32_e32 v17, 0xffff0000, v67
	v_lshlrev_b32_e32 v10, 16, v65
	v_and_b32_e32 v11, 0xffff0000, v65
	v_pk_fma_f32 v[4:5], v[4:5], v[124:125], v[8:9]
	v_pk_fma_f32 v[8:9], v[2:3], v[122:123], v[16:17]
	v_pk_fma_f32 v[2:3], v[0:1], v[120:121], v[14:15]
	v_pk_fma_f32 v[6:7], v[6:7], v[126:127], v[10:11]
	v_cvt_pk_bf16_f32 v0, v4, v5
	s_nop 0
	v_cvt_pk_bf16_f32 v1, v6, v7
	v_cvt_pk_bf16_f32 v2, v2, v3
	v_cvt_pk_bf16_f32 v3, v8, v9
	global_store_dwordx4 v[12:13], v[0:3], off offset:256
	s_cbranch_vccz .LBB0_235
	s_waitcnt vmcnt(0)
	s_cmpk_gt_u32 s16, 0xff
	s_cbranch_scc1 .LBB0_250
	s_barrier

.LBB0_271:
	s_add_u32 s39, s10, 0x100
	s_addc_u32 s40, s11, 0
	s_mov_b32 s41, -2
	s_mov_b64 s[44:45], 0x80
	v_add_u32_e32 v220, 0x10000, v187
	s_add_u32 s10, s8, 0x100
	s_addc_u32 s11, s9, 0
	s_add_i32 s42, 0, 0x10000
	ds_read_b128 v[108:111], v220 offset:0
	ds_read_b128 v[112:115], v220 offset:1024
	ds_read_b128 v[116:119], v220 offset:2048
	ds_read_b128 v[120:123], v220 offset:3072
	s_cmpk_eq_i32 s41, 0x54
	s_cselect_b32 s15, s5, s11
	s_cselect_b32 s14, s4, s10
	s_cselect_b32 s13, s7, s40
	s_cselect_b32 s12, s6, s39
	s_add_i32 m0, s25, 0xc000
	ds_read_b128 v[144:147], v189
	ds_read_b128 v[148:151], v189 offset:1024
	ds_read_b128 v[152:155], v189 offset:2048
	ds_read_b128 v[156:159], v189 offset:3072
	ds_read_b128 v[160:163], v189 offset:4096
	ds_read_b128 v[174:177], v189 offset:5120
	ds_read_b128 v[178:181], v189 offset:6144
	ds_read_b128 v[182:185], v189 offset:7168
	global_load_lds_dwordx4 v170, s[8:9]
	s_add_i32 m0, s25, 0xe000
	s_nop 0
	global_load_lds_dwordx4 v172, s[8:9]
	s_waitcnt lgkmcnt(8)
	s_barrier
	s_waitcnt lgkmcnt(0)
	v_mfma_f32_16x16x32_bf16 v[140:143], v[108:111], v[144:147], 0
	v_mfma_f32_16x16x32_bf16 v[136:139], v[116:119], v[144:147], 0
	v_mfma_f32_16x16x32_bf16 v[132:135], v[108:111], v[152:155], 0
	v_mfma_f32_16x16x32_bf16 v[104:107], v[116:119], v[152:155], 0
	s_add_i32 s43, 0, 0x14000
	s_add_i32 s8, s42, s19
	v_mfma_f32_16x16x32_bf16 v[96:99], v[108:111], v[160:163], 0
	s_mov_b32 m0, s8
	v_mfma_f32_16x16x32_bf16 v[88:91], v[116:119], v[160:163], 0
	v_mfma_f32_16x16x32_bf16 v[80:83], v[108:111], v[178:181], 0
	v_mfma_f32_16x16x32_bf16 v[72:75], v[116:119], v[178:181], 0
	v_mfma_f32_16x16x32_bf16 v[140:143], v[112:115], v[148:151], v[140:143]
	v_mfma_f32_16x16x32_bf16 v[136:139], v[120:123], v[148:151], v[136:139]
	v_mfma_f32_16x16x32_bf16 v[132:135], v[112:115], v[156:159], v[132:135]
	v_mfma_f32_16x16x32_bf16 v[104:107], v[120:123], v[156:159], v[104:107]
	v_mfma_f32_16x16x32_bf16 v[96:99], v[112:115], v[174:177], v[96:99]
	v_mfma_f32_16x16x32_bf16 v[88:91], v[120:123], v[174:177], v[88:91]
	v_mfma_f32_16x16x32_bf16 v[80:83], v[112:115], v[182:185], v[80:83]
	v_mfma_f32_16x16x32_bf16 v[72:75], v[120:123], v[182:185], v[72:75]
	s_barrier
	ds_read_b128 v[196:199], v220 offset:16384
	ds_read_b128 v[204:207], v220 offset:17408
	ds_read_b128 v[208:211], v220 offset:18432
	ds_read_b128 v[214:217], v220 offset:19456
	global_load_lds_dwordx4 v192, s[12:13]
	s_add_i32 m0, s8, 0x2000
	s_nop 0
	global_load_lds_dwordx4 v168, s[12:13]
	s_barrier
	s_waitcnt lgkmcnt(0)
	v_mfma_f32_16x16x32_bf16 v[128:131], v[196:199], v[144:147], 0
	v_mfma_f32_16x16x32_bf16 v[124:127], v[208:211], v[144:147], 0
	v_mfma_f32_16x16x32_bf16 v[100:103], v[196:199], v[152:155], 0
	v_mfma_f32_16x16x32_bf16 v[92:95], v[208:211], v[152:155], 0
	s_mov_b32 m0, s25
	v_mfma_f32_16x16x32_bf16 v[84:87], v[196:199], v[160:163], 0
	s_add_u32 s44, s14, 0x80
	s_addc_u32 s45, s15, 0
	v_mfma_f32_16x16x32_bf16 v[76:79], v[208:211], v[160:163], 0
	v_mfma_f32_16x16x32_bf16 v[68:71], v[196:199], v[178:181], 0
	v_mfma_f32_16x16x32_bf16 v[64:67], v[208:211], v[178:181], 0
	v_mfma_f32_16x16x32_bf16 v[128:131], v[204:207], v[148:151], v[128:131]
	v_mfma_f32_16x16x32_bf16 v[124:127], v[214:217], v[148:151], v[124:127]
	v_mfma_f32_16x16x32_bf16 v[100:103], v[204:207], v[156:159], v[100:103]
	v_mfma_f32_16x16x32_bf16 v[92:95], v[214:217], v[156:159], v[92:95]
	v_mfma_f32_16x16x32_bf16 v[84:87], v[204:207], v[174:177], v[84:87]
	v_mfma_f32_16x16x32_bf16 v[76:79], v[214:217], v[174:177], v[76:79]
	v_mfma_f32_16x16x32_bf16 v[68:71], v[204:207], v[182:185], v[68:71]
	v_mfma_f32_16x16x32_bf16 v[64:67], v[214:217], v[182:185], v[64:67]
	s_barrier
	ds_read_b128 v[144:147], v189 offset:16384
	ds_read_b128 v[148:151], v189 offset:17408
	ds_read_b128 v[152:155], v189 offset:18432
	ds_read_b128 v[156:159], v189 offset:19456
	ds_read_b128 v[160:163], v189 offset:20480
	ds_read_b128 v[174:177], v189 offset:21504
	ds_read_b128 v[178:181], v189 offset:22528
	ds_read_b128 v[182:185], v189 offset:23552
	global_load_lds_dwordx4 v164, s[14:15]
	s_mov_b32 m0, s26
	s_nop 0
	global_load_lds_dwordx4 v166, s[14:15]
	s_barrier
	s_waitcnt lgkmcnt(0)
	v_mfma_f32_16x16x32_bf16 v[60:63], v[108:111], v[144:147], 0
	v_mfma_f32_16x16x32_bf16 v[56:59], v[116:119], v[144:147], 0
	v_mfma_f32_16x16x32_bf16 v[48:51], v[108:111], v[152:155], 0
	v_mfma_f32_16x16x32_bf16 v[40:43], v[116:119], v[152:155], 0
	s_add_u32 s8, s12, 0x160000
	s_addc_u32 s9, s13, 0
	v_mfma_f32_16x16x32_bf16 v[32:35], v[108:111], v[160:163], 0
	s_add_i32 s42, s43, s19
	s_mov_b32 m0, s42
	v_mfma_f32_16x16x32_bf16 v[24:27], v[116:119], v[160:163], 0
	v_mfma_f32_16x16x32_bf16 v[16:19], v[108:111], v[178:181], 0
	v_mfma_f32_16x16x32_bf16 v[8:11], v[116:119], v[178:181], 0
	v_mfma_f32_16x16x32_bf16 v[60:63], v[112:115], v[148:151], v[60:63]
	v_mfma_f32_16x16x32_bf16 v[56:59], v[120:123], v[148:151], v[56:59]
	v_mfma_f32_16x16x32_bf16 v[48:51], v[112:115], v[156:159], v[48:51]
	v_mfma_f32_16x16x32_bf16 v[40:43], v[120:123], v[156:159], v[40:43]
	v_mfma_f32_16x16x32_bf16 v[32:35], v[112:115], v[174:177], v[32:35]
	v_mfma_f32_16x16x32_bf16 v[24:27], v[120:123], v[174:177], v[24:27]
	v_mfma_f32_16x16x32_bf16 v[16:19], v[112:115], v[182:185], v[16:19]
	v_mfma_f32_16x16x32_bf16 v[8:11], v[120:123], v[182:185], v[8:11]
	s_barrier
	global_load_lds_dwordx4 v192, s[8:9]
	s_add_i32 m0, s42, 0x2000
	s_nop 0
	global_load_lds_dwordx4 v168, s[8:9]
	s_waitcnt vmcnt(6)
	s_barrier
	v_mfma_f32_16x16x32_bf16 v[52:55], v[196:199], v[144:147], 0
	v_mfma_f32_16x16x32_bf16 v[44:47], v[208:211], v[144:147], 0
	v_mfma_f32_16x16x32_bf16 v[36:39], v[196:199], v[152:155], 0
	v_mfma_f32_16x16x32_bf16 v[28:31], v[208:211], v[152:155], 0
	s_add_i32 s42, 0, 0x18000
	v_mfma_f32_16x16x32_bf16 v[20:23], v[196:199], v[160:163], 0
	s_add_u32 s8, s14, 0x160000
	s_addc_u32 s9, s15, 0
	v_mfma_f32_16x16x32_bf16 v[12:15], v[208:211], v[160:163], 0
	s_mov_b32 m0, s27
	v_mfma_f32_16x16x32_bf16 v[4:7], v[196:199], v[178:181], 0
	v_mfma_f32_16x16x32_bf16 v[0:3], v[208:211], v[178:181], 0
	v_mfma_f32_16x16x32_bf16 v[52:55], v[204:207], v[148:151], v[52:55]
	v_mfma_f32_16x16x32_bf16 v[44:47], v[214:217], v[148:151], v[44:47]
	v_mfma_f32_16x16x32_bf16 v[36:39], v[204:207], v[156:159], v[36:39]
	v_mfma_f32_16x16x32_bf16 v[28:31], v[214:217], v[156:159], v[28:31]
	v_mfma_f32_16x16x32_bf16 v[20:23], v[204:207], v[174:177], v[20:23]
	v_mfma_f32_16x16x32_bf16 v[12:15], v[214:217], v[174:177], v[12:15]
	v_mfma_f32_16x16x32_bf16 v[4:7], v[204:207], v[182:185], v[4:7]
	v_mfma_f32_16x16x32_bf16 v[0:3], v[214:217], v[182:185], v[0:3]
	s_barrier
	ds_read_b128 v[108:111], v220 offset:32768
	ds_read_b128 v[112:115], v220 offset:33792
	ds_read_b128 v[116:119], v220 offset:34816
	ds_read_b128 v[120:123], v220 offset:35840
	ds_read_b128 v[144:147], v189 offset:32768
	ds_read_b128 v[148:151], v189 offset:33792
	ds_read_b128 v[152:155], v189 offset:34816
	ds_read_b128 v[156:159], v189 offset:35840
	ds_read_b128 v[160:163], v189 offset:36864
	ds_read_b128 v[174:177], v189 offset:37888
	ds_read_b128 v[178:181], v189 offset:38912
	ds_read_b128 v[182:185], v189 offset:39936
	global_load_lds_dwordx4 v164, s[8:9]
	s_mov_b32 m0, s28
	s_nop 0
	global_load_lds_dwordx4 v166, s[8:9]
	s_waitcnt lgkmcnt(8)
	s_barrier
	s_waitcnt lgkmcnt(0)
	v_mfma_f32_16x16x32_bf16 v[140:143], v[108:111], v[144:147], v[140:143]
	v_mfma_f32_16x16x32_bf16 v[136:139], v[116:119], v[144:147], v[136:139]
	v_mfma_f32_16x16x32_bf16 v[132:135], v[108:111], v[152:155], v[132:135]
	v_mfma_f32_16x16x32_bf16 v[104:107], v[116:119], v[152:155], v[104:107]
	s_add_i32 s14, 0, 0x1c000
	s_add_i32 s8, s42, s19
	v_mfma_f32_16x16x32_bf16 v[96:99], v[108:111], v[160:163], v[96:99]
	s_add_i32 m0, s8, 0xffffff80
	v_mfma_f32_16x16x32_bf16 v[88:91], v[116:119], v[160:163], v[88:91]
	v_mfma_f32_16x16x32_bf16 v[80:83], v[108:111], v[178:181], v[80:83]
	v_mfma_f32_16x16x32_bf16 v[72:75], v[116:119], v[178:181], v[72:75]
	v_mfma_f32_16x16x32_bf16 v[140:143], v[112:115], v[148:151], v[140:143]
	v_mfma_f32_16x16x32_bf16 v[136:139], v[120:123], v[148:151], v[136:139]
	v_mfma_f32_16x16x32_bf16 v[132:135], v[112:115], v[156:159], v[132:135]
	v_mfma_f32_16x16x32_bf16 v[104:107], v[120:123], v[156:159], v[104:107]
	v_mfma_f32_16x16x32_bf16 v[96:99], v[112:115], v[174:177], v[96:99]
	v_mfma_f32_16x16x32_bf16 v[88:91], v[120:123], v[174:177], v[88:91]
	v_mfma_f32_16x16x32_bf16 v[80:83], v[112:115], v[182:185], v[80:83]
	v_mfma_f32_16x16x32_bf16 v[72:75], v[120:123], v[182:185], v[72:75]
	s_barrier
	ds_read_b128 v[196:199], v220 offset:49152
	ds_read_b128 v[204:207], v220 offset:50176
	ds_read_b128 v[208:211], v220 offset:51200
	ds_read_b128 v[214:217], v220 offset:52224
	global_load_lds_dwordx4 v192, s[12:13] offset:128
	s_add_i32 m0, s8, 0x1f80
	s_nop 0
	global_load_lds_dwordx4 v168, s[12:13] offset:128
	s_barrier
	s_waitcnt lgkmcnt(0)
	v_mfma_f32_16x16x32_bf16 v[128:131], v[196:199], v[144:147], v[128:131]
	v_mfma_f32_16x16x32_bf16 v[124:127], v[208:211], v[144:147], v[124:127]
	v_mfma_f32_16x16x32_bf16 v[100:103], v[196:199], v[152:155], v[100:103]
	v_mfma_f32_16x16x32_bf16 v[92:95], v[208:211], v[152:155], v[92:95]
	s_mov_b32 m0, s31
	v_mfma_f32_16x16x32_bf16 v[84:87], v[196:199], v[160:163], v[84:87]
	v_mfma_f32_16x16x32_bf16 v[76:79], v[208:211], v[160:163], v[76:79]
	v_mfma_f32_16x16x32_bf16 v[68:71], v[196:199], v[178:181], v[68:71]
	v_mfma_f32_16x16x32_bf16 v[64:67], v[208:211], v[178:181], v[64:67]
	v_mfma_f32_16x16x32_bf16 v[128:131], v[204:207], v[148:151], v[128:131]
	v_mfma_f32_16x16x32_bf16 v[124:127], v[214:217], v[148:151], v[124:127]
	v_mfma_f32_16x16x32_bf16 v[100:103], v[204:207], v[156:159], v[100:103]
	v_mfma_f32_16x16x32_bf16 v[92:95], v[214:217], v[156:159], v[92:95]
	v_mfma_f32_16x16x32_bf16 v[84:87], v[204:207], v[174:177], v[84:87]
	v_mfma_f32_16x16x32_bf16 v[76:79], v[214:217], v[174:177], v[76:79]
	v_mfma_f32_16x16x32_bf16 v[68:71], v[204:207], v[182:185], v[68:71]
	v_mfma_f32_16x16x32_bf16 v[64:67], v[214:217], v[182:185], v[64:67]
	s_barrier
	ds_read_b128 v[144:147], v189 offset:49152
	ds_read_b128 v[148:151], v189 offset:50176
	ds_read_b128 v[152:155], v189 offset:51200
	ds_read_b128 v[156:159], v189 offset:52224
	ds_read_b128 v[160:163], v189 offset:53248
	ds_read_b128 v[174:177], v189 offset:54272
	ds_read_b128 v[178:181], v189 offset:55296
	ds_read_b128 v[182:185], v189 offset:56320
	global_load_lds_dwordx4 v164, s[44:45]
	s_mov_b32 m0, s33
	s_nop 0
	global_load_lds_dwordx4 v166, s[44:45]
	s_barrier
	s_waitcnt lgkmcnt(0)
	v_mfma_f32_16x16x32_bf16 v[60:63], v[108:111], v[144:147], v[60:63]
	v_mfma_f32_16x16x32_bf16 v[56:59], v[116:119], v[144:147], v[56:59]
	v_mfma_f32_16x16x32_bf16 v[48:51], v[108:111], v[152:155], v[48:51]
	v_mfma_f32_16x16x32_bf16 v[40:43], v[116:119], v[152:155], v[40:43]
	s_add_u32 s8, s12, 0x160080
	s_addc_u32 s9, s13, 0
	v_mfma_f32_16x16x32_bf16 v[32:35], v[108:111], v[160:163], v[32:35]
	s_add_i32 s12, s14, s19
	s_mov_b32 m0, s12
	v_mfma_f32_16x16x32_bf16 v[24:27], v[116:119], v[160:163], v[24:27]
	v_mfma_f32_16x16x32_bf16 v[16:19], v[108:111], v[178:181], v[16:19]
	v_mfma_f32_16x16x32_bf16 v[8:11], v[116:119], v[178:181], v[8:11]
	v_mfma_f32_16x16x32_bf16 v[60:63], v[112:115], v[148:151], v[60:63]
	v_mfma_f32_16x16x32_bf16 v[56:59], v[120:123], v[148:151], v[56:59]
	v_mfma_f32_16x16x32_bf16 v[48:51], v[112:115], v[156:159], v[48:51]
	v_mfma_f32_16x16x32_bf16 v[40:43], v[120:123], v[156:159], v[40:43]
	v_mfma_f32_16x16x32_bf16 v[32:35], v[112:115], v[174:177], v[32:35]
	v_mfma_f32_16x16x32_bf16 v[24:27], v[120:123], v[174:177], v[24:27]
	v_mfma_f32_16x16x32_bf16 v[16:19], v[112:115], v[182:185], v[16:19]
	v_mfma_f32_16x16x32_bf16 v[8:11], v[120:123], v[182:185], v[8:11]
	s_barrier
	global_load_lds_dwordx4 v192, s[8:9]
	s_add_i32 m0, s12, 0x2000
	s_nop 0
	global_load_lds_dwordx4 v168, s[8:9]
	s_waitcnt vmcnt(6)
	s_barrier
	v_mfma_f32_16x16x32_bf16 v[52:55], v[196:199], v[144:147], v[52:55]
	v_mfma_f32_16x16x32_bf16 v[44:47], v[208:211], v[144:147], v[44:47]
	v_mfma_f32_16x16x32_bf16 v[36:39], v[196:199], v[152:155], v[36:39]
	v_mfma_f32_16x16x32_bf16 v[28:31], v[208:211], v[152:155], v[28:31]
	s_add_i32 s41, s41, 2
	v_mfma_f32_16x16x32_bf16 v[20:23], v[196:199], v[160:163], v[20:23]
	s_add_u32 s39, s39, 0x100
	s_addc_u32 s40, s40, 0
	v_mfma_f32_16x16x32_bf16 v[12:15], v[208:211], v[160:163], v[12:15]
	s_mov_b64 s[8:9], s[10:11]
	v_mfma_f32_16x16x32_bf16 v[4:7], v[196:199], v[178:181], v[4:7]
	v_mfma_f32_16x16x32_bf16 v[0:3], v[208:211], v[178:181], v[0:3]
	v_mfma_f32_16x16x32_bf16 v[52:55], v[204:207], v[148:151], v[52:55]
	v_mfma_f32_16x16x32_bf16 v[44:47], v[214:217], v[148:151], v[44:47]
	v_mfma_f32_16x16x32_bf16 v[36:39], v[204:207], v[156:159], v[36:39]
	v_mfma_f32_16x16x32_bf16 v[28:31], v[214:217], v[156:159], v[28:31]
	v_mfma_f32_16x16x32_bf16 v[20:23], v[204:207], v[174:177], v[20:23]
	v_mfma_f32_16x16x32_bf16 v[12:15], v[214:217], v[174:177], v[12:15]
	v_mfma_f32_16x16x32_bf16 v[4:7], v[204:207], v[182:185], v[4:7]
	v_mfma_f32_16x16x32_bf16 v[0:3], v[214:217], v[182:185], v[0:3]
	s_cmpk_gt_u32 s41, 0x55
	s_barrier
.LBB0_272:
	s_add_u32 s10, s8, 0x100
	s_addc_u32 s11, s9, 0
	s_add_i32 s42, 0, 0x10000
	ds_read_b128 v[108:111], v220 offset:0
	ds_read_b128 v[112:115], v220 offset:1024
	ds_read_b128 v[116:119], v220 offset:2048
	ds_read_b128 v[120:123], v220 offset:3072
	s_cmpk_eq_i32 s41, 0x54
	s_cselect_b32 s15, s5, s11
	s_cselect_b32 s14, s4, s10
	s_cselect_b32 s13, s7, s40
	s_cselect_b32 s12, s6, s39
	s_add_i32 m0, s25, 0xc000
	ds_read_b128 v[144:147], v189
	ds_read_b128 v[148:151], v189 offset:1024
	ds_read_b128 v[152:155], v189 offset:2048
	ds_read_b128 v[156:159], v189 offset:3072
	ds_read_b128 v[160:163], v189 offset:4096
	ds_read_b128 v[174:177], v189 offset:5120
	ds_read_b128 v[178:181], v189 offset:6144
	ds_read_b128 v[182:185], v189 offset:7168
	global_load_lds_dwordx4 v170, s[8:9]
	s_add_i32 m0, s25, 0xe000
	s_nop 0
	global_load_lds_dwordx4 v172, s[8:9]
	s_waitcnt lgkmcnt(8)
	s_barrier
	s_waitcnt lgkmcnt(0)
	v_mfma_f32_16x16x32_bf16 v[140:143], v[108:111], v[144:147], v[140:143]
	v_mfma_f32_16x16x32_bf16 v[136:139], v[116:119], v[144:147], v[136:139]
	v_mfma_f32_16x16x32_bf16 v[132:135], v[108:111], v[152:155], v[132:135]
	v_mfma_f32_16x16x32_bf16 v[104:107], v[116:119], v[152:155], v[104:107]
	s_add_i32 s43, 0, 0x14000
	s_add_i32 s8, s42, s19
	v_mfma_f32_16x16x32_bf16 v[96:99], v[108:111], v[160:163], v[96:99]
	s_mov_b32 m0, s8
	v_mfma_f32_16x16x32_bf16 v[88:91], v[116:119], v[160:163], v[88:91]
	v_mfma_f32_16x16x32_bf16 v[80:83], v[108:111], v[178:181], v[80:83]
	v_mfma_f32_16x16x32_bf16 v[72:75], v[116:119], v[178:181], v[72:75]
	v_mfma_f32_16x16x32_bf16 v[140:143], v[112:115], v[148:151], v[140:143]
	v_mfma_f32_16x16x32_bf16 v[136:139], v[120:123], v[148:151], v[136:139]
	v_mfma_f32_16x16x32_bf16 v[132:135], v[112:115], v[156:159], v[132:135]
	v_mfma_f32_16x16x32_bf16 v[104:107], v[120:123], v[156:159], v[104:107]
	v_mfma_f32_16x16x32_bf16 v[96:99], v[112:115], v[174:177], v[96:99]
	v_mfma_f32_16x16x32_bf16 v[88:91], v[120:123], v[174:177], v[88:91]
	v_mfma_f32_16x16x32_bf16 v[80:83], v[112:115], v[182:185], v[80:83]
	v_mfma_f32_16x16x32_bf16 v[72:75], v[120:123], v[182:185], v[72:75]
	s_barrier
	ds_read_b128 v[196:199], v220 offset:16384
	ds_read_b128 v[204:207], v220 offset:17408
	ds_read_b128 v[208:211], v220 offset:18432
	ds_read_b128 v[214:217], v220 offset:19456
	global_load_lds_dwordx4 v192, s[12:13]
	s_add_i32 m0, s8, 0x2000
	s_nop 0
	global_load_lds_dwordx4 v168, s[12:13]
	s_barrier
	s_waitcnt lgkmcnt(0)
	v_mfma_f32_16x16x32_bf16 v[128:131], v[196:199], v[144:147], v[128:131]
	v_mfma_f32_16x16x32_bf16 v[124:127], v[208:211], v[144:147], v[124:127]
	v_mfma_f32_16x16x32_bf16 v[100:103], v[196:199], v[152:155], v[100:103]
	v_mfma_f32_16x16x32_bf16 v[92:95], v[208:211], v[152:155], v[92:95]
	s_mov_b32 m0, s25
	v_mfma_f32_16x16x32_bf16 v[84:87], v[196:199], v[160:163], v[84:87]
	s_add_u32 s44, s14, 0x80
	s_addc_u32 s45, s15, 0
	v_mfma_f32_16x16x32_bf16 v[76:79], v[208:211], v[160:163], v[76:79]
	v_mfma_f32_16x16x32_bf16 v[68:71], v[196:199], v[178:181], v[68:71]
	v_mfma_f32_16x16x32_bf16 v[64:67], v[208:211], v[178:181], v[64:67]
	v_mfma_f32_16x16x32_bf16 v[128:131], v[204:207], v[148:151], v[128:131]
	v_mfma_f32_16x16x32_bf16 v[124:127], v[214:217], v[148:151], v[124:127]
	v_mfma_f32_16x16x32_bf16 v[100:103], v[204:207], v[156:159], v[100:103]
	v_mfma_f32_16x16x32_bf16 v[92:95], v[214:217], v[156:159], v[92:95]
	v_mfma_f32_16x16x32_bf16 v[84:87], v[204:207], v[174:177], v[84:87]
	v_mfma_f32_16x16x32_bf16 v[76:79], v[214:217], v[174:177], v[76:79]
	v_mfma_f32_16x16x32_bf16 v[68:71], v[204:207], v[182:185], v[68:71]
	v_mfma_f32_16x16x32_bf16 v[64:67], v[214:217], v[182:185], v[64:67]
	s_barrier
	ds_read_b128 v[144:147], v189 offset:16384
	ds_read_b128 v[148:151], v189 offset:17408
	ds_read_b128 v[152:155], v189 offset:18432
	ds_read_b128 v[156:159], v189 offset:19456
	ds_read_b128 v[160:163], v189 offset:20480
	ds_read_b128 v[174:177], v189 offset:21504
	ds_read_b128 v[178:181], v189 offset:22528
	ds_read_b128 v[182:185], v189 offset:23552
	global_load_lds_dwordx4 v164, s[14:15]
	s_mov_b32 m0, s26
	s_nop 0
	global_load_lds_dwordx4 v166, s[14:15]
	s_barrier
	s_waitcnt lgkmcnt(0)
	v_mfma_f32_16x16x32_bf16 v[60:63], v[108:111], v[144:147], v[60:63]
	v_mfma_f32_16x16x32_bf16 v[56:59], v[116:119], v[144:147], v[56:59]
	v_mfma_f32_16x16x32_bf16 v[48:51], v[108:111], v[152:155], v[48:51]
	v_mfma_f32_16x16x32_bf16 v[40:43], v[116:119], v[152:155], v[40:43]
	s_add_u32 s8, s12, 0x160000
	s_addc_u32 s9, s13, 0
	v_mfma_f32_16x16x32_bf16 v[32:35], v[108:111], v[160:163], v[32:35]
	s_add_i32 s42, s43, s19
	s_mov_b32 m0, s42
	v_mfma_f32_16x16x32_bf16 v[24:27], v[116:119], v[160:163], v[24:27]
	v_mfma_f32_16x16x32_bf16 v[16:19], v[108:111], v[178:181], v[16:19]
	v_mfma_f32_16x16x32_bf16 v[8:11], v[116:119], v[178:181], v[8:11]
	v_mfma_f32_16x16x32_bf16 v[60:63], v[112:115], v[148:151], v[60:63]
	v_mfma_f32_16x16x32_bf16 v[56:59], v[120:123], v[148:151], v[56:59]
	v_mfma_f32_16x16x32_bf16 v[48:51], v[112:115], v[156:159], v[48:51]
	v_mfma_f32_16x16x32_bf16 v[40:43], v[120:123], v[156:159], v[40:43]
	v_mfma_f32_16x16x32_bf16 v[32:35], v[112:115], v[174:177], v[32:35]
	v_mfma_f32_16x16x32_bf16 v[24:27], v[120:123], v[174:177], v[24:27]
	v_mfma_f32_16x16x32_bf16 v[16:19], v[112:115], v[182:185], v[16:19]
	v_mfma_f32_16x16x32_bf16 v[8:11], v[120:123], v[182:185], v[8:11]
	s_barrier
	global_load_lds_dwordx4 v192, s[8:9]
	s_add_i32 m0, s42, 0x2000
	s_nop 0
	global_load_lds_dwordx4 v168, s[8:9]
	s_waitcnt vmcnt(6)
	s_barrier
	v_mfma_f32_16x16x32_bf16 v[52:55], v[196:199], v[144:147], v[52:55]
	v_mfma_f32_16x16x32_bf16 v[44:47], v[208:211], v[144:147], v[44:47]
	v_mfma_f32_16x16x32_bf16 v[36:39], v[196:199], v[152:155], v[36:39]
	v_mfma_f32_16x16x32_bf16 v[28:31], v[208:211], v[152:155], v[28:31]
	s_add_i32 s42, 0, 0x18000
	v_mfma_f32_16x16x32_bf16 v[20:23], v[196:199], v[160:163], v[20:23]
	s_add_u32 s8, s14, 0x160000
	s_addc_u32 s9, s15, 0
	v_mfma_f32_16x16x32_bf16 v[12:15], v[208:211], v[160:163], v[12:15]
	s_mov_b32 m0, s27
	v_mfma_f32_16x16x32_bf16 v[4:7], v[196:199], v[178:181], v[4:7]
	v_mfma_f32_16x16x32_bf16 v[0:3], v[208:211], v[178:181], v[0:3]
	v_mfma_f32_16x16x32_bf16 v[52:55], v[204:207], v[148:151], v[52:55]
	v_mfma_f32_16x16x32_bf16 v[44:47], v[214:217], v[148:151], v[44:47]
	v_mfma_f32_16x16x32_bf16 v[36:39], v[204:207], v[156:159], v[36:39]
	v_mfma_f32_16x16x32_bf16 v[28:31], v[214:217], v[156:159], v[28:31]
	v_mfma_f32_16x16x32_bf16 v[20:23], v[204:207], v[174:177], v[20:23]
	v_mfma_f32_16x16x32_bf16 v[12:15], v[214:217], v[174:177], v[12:15]
	v_mfma_f32_16x16x32_bf16 v[4:7], v[204:207], v[182:185], v[4:7]
	v_mfma_f32_16x16x32_bf16 v[0:3], v[214:217], v[182:185], v[0:3]
	s_barrier
	ds_read_b128 v[108:111], v220 offset:32768
	ds_read_b128 v[112:115], v220 offset:33792
	ds_read_b128 v[116:119], v220 offset:34816
	ds_read_b128 v[120:123], v220 offset:35840
	ds_read_b128 v[144:147], v189 offset:32768
	ds_read_b128 v[148:151], v189 offset:33792
	ds_read_b128 v[152:155], v189 offset:34816
	ds_read_b128 v[156:159], v189 offset:35840
	ds_read_b128 v[160:163], v189 offset:36864
	ds_read_b128 v[174:177], v189 offset:37888
	ds_read_b128 v[178:181], v189 offset:38912
	ds_read_b128 v[182:185], v189 offset:39936
	global_load_lds_dwordx4 v164, s[8:9]
	s_mov_b32 m0, s28
	s_nop 0
	global_load_lds_dwordx4 v166, s[8:9]
	s_waitcnt lgkmcnt(8)
	s_barrier
	s_waitcnt lgkmcnt(0)
	v_mfma_f32_16x16x32_bf16 v[140:143], v[108:111], v[144:147], v[140:143]
	v_mfma_f32_16x16x32_bf16 v[136:139], v[116:119], v[144:147], v[136:139]
	v_mfma_f32_16x16x32_bf16 v[132:135], v[108:111], v[152:155], v[132:135]
	v_mfma_f32_16x16x32_bf16 v[104:107], v[116:119], v[152:155], v[104:107]
	s_add_i32 s14, 0, 0x1c000
	s_add_i32 s8, s42, s19
	v_mfma_f32_16x16x32_bf16 v[96:99], v[108:111], v[160:163], v[96:99]
	s_add_i32 m0, s8, 0xffffff80
	v_mfma_f32_16x16x32_bf16 v[88:91], v[116:119], v[160:163], v[88:91]
	v_mfma_f32_16x16x32_bf16 v[80:83], v[108:111], v[178:181], v[80:83]
	v_mfma_f32_16x16x32_bf16 v[72:75], v[116:119], v[178:181], v[72:75]
	v_mfma_f32_16x16x32_bf16 v[140:143], v[112:115], v[148:151], v[140:143]
	v_mfma_f32_16x16x32_bf16 v[136:139], v[120:123], v[148:151], v[136:139]
	v_mfma_f32_16x16x32_bf16 v[132:135], v[112:115], v[156:159], v[132:135]
	v_mfma_f32_16x16x32_bf16 v[104:107], v[120:123], v[156:159], v[104:107]
	v_mfma_f32_16x16x32_bf16 v[96:99], v[112:115], v[174:177], v[96:99]
	v_mfma_f32_16x16x32_bf16 v[88:91], v[120:123], v[174:177], v[88:91]
	v_mfma_f32_16x16x32_bf16 v[80:83], v[112:115], v[182:185], v[80:83]
	v_mfma_f32_16x16x32_bf16 v[72:75], v[120:123], v[182:185], v[72:75]
	s_barrier
	ds_read_b128 v[196:199], v220 offset:49152
	ds_read_b128 v[204:207], v220 offset:50176
	ds_read_b128 v[208:211], v220 offset:51200
	ds_read_b128 v[214:217], v220 offset:52224
	global_load_lds_dwordx4 v192, s[12:13] offset:128
	s_add_i32 m0, s8, 0x1f80
	s_nop 0
	global_load_lds_dwordx4 v168, s[12:13] offset:128
	s_barrier
	s_waitcnt lgkmcnt(0)
	v_mfma_f32_16x16x32_bf16 v[128:131], v[196:199], v[144:147], v[128:131]
	v_mfma_f32_16x16x32_bf16 v[124:127], v[208:211], v[144:147], v[124:127]
	v_mfma_f32_16x16x32_bf16 v[100:103], v[196:199], v[152:155], v[100:103]
	v_mfma_f32_16x16x32_bf16 v[92:95], v[208:211], v[152:155], v[92:95]
	s_mov_b32 m0, s31
	v_mfma_f32_16x16x32_bf16 v[84:87], v[196:199], v[160:163], v[84:87]
	v_mfma_f32_16x16x32_bf16 v[76:79], v[208:211], v[160:163], v[76:79]
	v_mfma_f32_16x16x32_bf16 v[68:71], v[196:199], v[178:181], v[68:71]
	v_mfma_f32_16x16x32_bf16 v[64:67], v[208:211], v[178:181], v[64:67]
	v_mfma_f32_16x16x32_bf16 v[128:131], v[204:207], v[148:151], v[128:131]
	v_mfma_f32_16x16x32_bf16 v[124:127], v[214:217], v[148:151], v[124:127]
	v_mfma_f32_16x16x32_bf16 v[100:103], v[204:207], v[156:159], v[100:103]
	v_mfma_f32_16x16x32_bf16 v[92:95], v[214:217], v[156:159], v[92:95]
	v_mfma_f32_16x16x32_bf16 v[84:87], v[204:207], v[174:177], v[84:87]
	v_mfma_f32_16x16x32_bf16 v[76:79], v[214:217], v[174:177], v[76:79]
	v_mfma_f32_16x16x32_bf16 v[68:71], v[204:207], v[182:185], v[68:71]
	v_mfma_f32_16x16x32_bf16 v[64:67], v[214:217], v[182:185], v[64:67]
	s_barrier
	ds_read_b128 v[144:147], v189 offset:49152
	ds_read_b128 v[148:151], v189 offset:50176
	ds_read_b128 v[152:155], v189 offset:51200
	ds_read_b128 v[156:159], v189 offset:52224
	ds_read_b128 v[160:163], v189 offset:53248
	ds_read_b128 v[174:177], v189 offset:54272
	ds_read_b128 v[178:181], v189 offset:55296
	ds_read_b128 v[182:185], v189 offset:56320
	global_load_lds_dwordx4 v164, s[44:45]
	s_mov_b32 m0, s33
	s_nop 0
	global_load_lds_dwordx4 v166, s[44:45]
	s_barrier
	s_waitcnt lgkmcnt(0)
	v_mfma_f32_16x16x32_bf16 v[60:63], v[108:111], v[144:147], v[60:63]
	v_mfma_f32_16x16x32_bf16 v[56:59], v[116:119], v[144:147], v[56:59]
	v_mfma_f32_16x16x32_bf16 v[48:51], v[108:111], v[152:155], v[48:51]
	v_mfma_f32_16x16x32_bf16 v[40:43], v[116:119], v[152:155], v[40:43]
	s_add_u32 s8, s12, 0x160080
	s_addc_u32 s9, s13, 0
	v_mfma_f32_16x16x32_bf16 v[32:35], v[108:111], v[160:163], v[32:35]
	s_add_i32 s12, s14, s19
	s_mov_b32 m0, s12
	v_mfma_f32_16x16x32_bf16 v[24:27], v[116:119], v[160:163], v[24:27]
	v_mfma_f32_16x16x32_bf16 v[16:19], v[108:111], v[178:181], v[16:19]
	v_mfma_f32_16x16x32_bf16 v[8:11], v[116:119], v[178:181], v[8:11]
	v_mfma_f32_16x16x32_bf16 v[60:63], v[112:115], v[148:151], v[60:63]
	v_mfma_f32_16x16x32_bf16 v[56:59], v[120:123], v[148:151], v[56:59]
	v_mfma_f32_16x16x32_bf16 v[48:51], v[112:115], v[156:159], v[48:51]
	v_mfma_f32_16x16x32_bf16 v[40:43], v[120:123], v[156:159], v[40:43]
	v_mfma_f32_16x16x32_bf16 v[32:35], v[112:115], v[174:177], v[32:35]
	v_mfma_f32_16x16x32_bf16 v[24:27], v[120:123], v[174:177], v[24:27]
	v_mfma_f32_16x16x32_bf16 v[16:19], v[112:115], v[182:185], v[16:19]
	v_mfma_f32_16x16x32_bf16 v[8:11], v[120:123], v[182:185], v[8:11]
	s_barrier
	global_load_lds_dwordx4 v192, s[8:9]
	s_add_i32 m0, s12, 0x2000
	s_nop 0
	global_load_lds_dwordx4 v168, s[8:9]
	s_waitcnt vmcnt(6)
	s_barrier
	v_mfma_f32_16x16x32_bf16 v[52:55], v[196:199], v[144:147], v[52:55]
	v_mfma_f32_16x16x32_bf16 v[44:47], v[208:211], v[144:147], v[44:47]
	v_mfma_f32_16x16x32_bf16 v[36:39], v[196:199], v[152:155], v[36:39]
	v_mfma_f32_16x16x32_bf16 v[28:31], v[208:211], v[152:155], v[28:31]
	s_add_i32 s41, s41, 2
	v_mfma_f32_16x16x32_bf16 v[20:23], v[196:199], v[160:163], v[20:23]
	s_add_u32 s39, s39, 0x100
	s_addc_u32 s40, s40, 0
	v_mfma_f32_16x16x32_bf16 v[12:15], v[208:211], v[160:163], v[12:15]
	s_mov_b64 s[8:9], s[10:11]
	v_mfma_f32_16x16x32_bf16 v[4:7], v[196:199], v[178:181], v[4:7]
	v_mfma_f32_16x16x32_bf16 v[0:3], v[208:211], v[178:181], v[0:3]
	v_mfma_f32_16x16x32_bf16 v[52:55], v[204:207], v[148:151], v[52:55]
	v_mfma_f32_16x16x32_bf16 v[44:47], v[214:217], v[148:151], v[44:47]
	v_mfma_f32_16x16x32_bf16 v[36:39], v[204:207], v[156:159], v[36:39]
	v_mfma_f32_16x16x32_bf16 v[28:31], v[214:217], v[156:159], v[28:31]
	v_mfma_f32_16x16x32_bf16 v[20:23], v[204:207], v[174:177], v[20:23]
	v_mfma_f32_16x16x32_bf16 v[12:15], v[214:217], v[174:177], v[12:15]
	v_mfma_f32_16x16x32_bf16 v[4:7], v[204:207], v[182:185], v[4:7]
	v_mfma_f32_16x16x32_bf16 v[0:3], v[214:217], v[182:185], v[0:3]
	s_cmpk_gt_u32 s41, 0x55
	s_barrier
	s_cbranch_scc0 .LBB0_272
	s_ashr_i32 s8, s37, 4
	v_lshl_or_b32 v144, s38, 8, v188
	s_mul_hi_i32 s9, s8, 0xc000
	s_mul_i32 s8, s8, 0xc000
	v_lshl_add_u32 v178, s37, 8, v186
	s_add_u32 s8, s29, s8
	v_ashrrev_i32_e32 v145, 31, v144
	v_ashrrev_i32_e32 v179, 31, v178
	s_addc_u32 s9, s30, s9
	v_lshlrev_b64 v[174:175], 2, v[144:145]
	v_lshl_add_u64 v[176:177], v[144:145], 1, s[2:3]
	v_lshlrev_b64 v[144:145], 12, v[178:179]
	v_lshl_add_u64 v[112:113], s[8:9], 0, v[174:175]
	v_lshl_add_u64 v[144:145], v[176:177], 0, v[144:145]
	global_load_dwordx4 v[116:119], v[112:113], off offset:16
	global_load_dwordx4 v[120:123], v[112:113], off
	global_load_dwordx4 v[108:111], v[112:113], off offset:528
	s_nop 0
	global_load_dwordx4 v[112:115], v[112:113], off offset:512
	s_nop 0
	global_load_dwordx4 v[196:199], v[144:145], off
	global_load_dwordx4 v[204:207], v[144:145], off offset:256
	v_or_b32_e32 v184, 16, v178
	v_ashrrev_i32_e32 v185, 31, v184
	v_lshlrev_b64 v[144:145], 12, v[184:185]
	v_lshl_add_u64 v[144:145], v[176:177], 0, v[144:145]
	global_load_dwordx4 v[208:211], v[144:145], off
	global_load_dwordx4 v[160:163], v[144:145], off offset:256
	v_or_b32_e32 v182, 32, v178
	v_ashrrev_i32_e32 v183, 31, v182
	v_lshlrev_b64 v[144:145], 12, v[182:183]
	v_lshl_add_u64 v[144:145], v[176:177], 0, v[144:145]
	global_load_dwordx4 v[156:159], v[144:145], off
	global_load_dwordx4 v[152:155], v[144:145], off offset:256
	v_or_b32_e32 v180, 48, v178
	v_ashrrev_i32_e32 v181, 31, v180
	v_lshlrev_b64 v[144:145], 12, v[180:181]
	v_lshl_add_u64 v[144:145], v[176:177], 0, v[144:145]
	global_load_dwordx4 v[148:151], v[144:145], off
	s_nop 0
	global_load_dwordx4 v[144:147], v[144:145], off offset:256
	v_readlane_b32 s52, v254, 39
	v_readlane_b32 s66, v254, 53
	v_readlane_b32 s67, v254, 54
	s_and_b64 vcc, exec, s[0:1]
	s_mov_b32 s38, s35
	s_mov_b32 s37, s36
	s_mov_b64 s[10:11], s[6:7]
	s_mov_b64 s[8:9], s[4:5]
	v_readlane_b32 s14, v254, 21
	s_movk_i32 s15, 0x2000
	v_readlane_b32 s53, v254, 40
	v_readlane_b32 s54, v254, 41
	v_readlane_b32 s55, v254, 42
	v_readlane_b32 s56, v254, 43
	v_readlane_b32 s57, v254, 44
	v_readlane_b32 s58, v254, 45
	v_readlane_b32 s59, v254, 46
	v_readlane_b32 s60, v254, 47
	v_readlane_b32 s61, v254, 48
	v_readlane_b32 s62, v254, 49
	v_readlane_b32 s63, v254, 50
	v_readlane_b32 s64, v254, 51
	v_readlane_b32 s65, v254, 52
	s_waitcnt vmcnt(0)
	v_lshlrev_b32_e32 v190, 16, v196
	v_and_b32_e32 v191, 0xffff0000, v196
	v_pk_fma_f32 v[140:141], v[140:141], v[120:121], v[190:191]
	v_lshlrev_b64 v[190:191], 13, v[178:179]
	v_lshlrev_b32_e32 v196, 16, v197
	v_and_b32_e32 v197, 0xffff0000, v197
	v_lshl_add_u64 v[190:191], s[66:67], 0, v[190:191]
	v_pk_fma_f32 v[142:143], v[142:143], v[122:123], v[196:197]
	v_lshl_add_u64 v[190:191], v[190:191], 0, v[174:175]
	global_store_dwordx4 v[190:191], v[140:143], off
	v_lshlrev_b32_e32 v214, 16, v198
	v_and_b32_e32 v215, 0xffff0000, v198
	v_lshlrev_b32_e32 v140, 16, v206
	v_and_b32_e32 v141, 0xffff0000, v206
	v_lshlrev_b32_e32 v142, 16, v207
	v_and_b32_e32 v143, 0xffff0000, v207
	v_pk_fma_f32 v[126:127], v[126:127], v[110:111], v[142:143]
	v_pk_fma_f32 v[124:125], v[124:125], v[108:109], v[140:141]
	global_store_dwordx4 v[190:191], v[124:127], off offset:528
	v_lshlrev_b32_e32 v198, 16, v199
	v_and_b32_e32 v199, 0xffff0000, v199
	v_lshlrev_b32_e32 v124, 16, v208
	v_and_b32_e32 v125, 0xffff0000, v208
	v_pk_fma_f32 v[124:125], v[132:133], v[120:121], v[124:125]
	v_lshlrev_b64 v[132:133], 13, v[184:185]
	v_lshlrev_b32_e32 v126, 16, v209
	v_and_b32_e32 v127, 0xffff0000, v209
	v_lshl_add_u64 v[132:133], s[66:67], 0, v[132:133]
	v_pk_fma_f32 v[126:127], v[134:135], v[122:123], v[126:127]
	v_lshl_add_u64 v[132:133], v[132:133], 0, v[174:175]
	v_pk_fma_f32 v[138:139], v[138:139], v[118:119], v[198:199]
	v_pk_fma_f32 v[136:137], v[136:137], v[116:117], v[214:215]
	global_store_dwordx4 v[132:133], v[124:127], off
	global_store_dwordx4 v[190:191], v[136:139], off offset:16
	s_nop 0
	v_lshlrev_b32_e32 v124, 16, v162
	v_and_b32_e32 v125, 0xffff0000, v162
	v_lshlrev_b32_e32 v126, 16, v163
	v_and_b32_e32 v127, 0xffff0000, v163
	v_lshlrev_b32_e32 v136, 16, v204
	v_and_b32_e32 v137, 0xffff0000, v204
	v_lshlrev_b32_e32 v138, 16, v205
	v_and_b32_e32 v139, 0xffff0000, v205
	v_pk_fma_f32 v[94:95], v[94:95], v[110:111], v[126:127]
	v_pk_fma_f32 v[92:93], v[92:93], v[108:109], v[124:125]
	v_pk_fma_f32 v[130:131], v[130:131], v[114:115], v[138:139]
	v_pk_fma_f32 v[128:129], v[128:129], v[112:113], v[136:137]
	global_store_dwordx4 v[132:133], v[92:95], off offset:528
	global_store_dwordx4 v[190:191], v[128:131], off offset:512
	s_nop 0
	v_lshlrev_b32_e32 v92, 16, v156
	v_and_b32_e32 v93, 0xffff0000, v156
	v_lshlrev_b32_e32 v128, 16, v210
	v_and_b32_e32 v129, 0xffff0000, v210
	v_lshlrev_b32_e32 v130, 16, v211
	v_and_b32_e32 v131, 0xffff0000, v211
	v_pk_fma_f32 v[92:93], v[96:97], v[120:121], v[92:93]
	v_lshlrev_b64 v[96:97], 13, v[182:183]
	v_pk_fma_f32 v[106:107], v[106:107], v[118:119], v[130:131]
	v_pk_fma_f32 v[104:105], v[104:105], v[116:117], v[128:129]
	v_lshlrev_b32_e32 v94, 16, v157
	v_and_b32_e32 v95, 0xffff0000, v157
	v_lshl_add_u64 v[96:97], s[66:67], 0, v[96:97]
	global_store_dwordx4 v[132:133], v[104:107], off offset:16
	v_pk_fma_f32 v[94:95], v[98:99], v[122:123], v[94:95]
	v_lshl_add_u64 v[96:97], v[96:97], 0, v[174:175]
	v_lshlrev_b32_e32 v104, 16, v160
	v_and_b32_e32 v105, 0xffff0000, v160
	v_lshlrev_b32_e32 v106, 16, v161
	v_and_b32_e32 v107, 0xffff0000, v161
	v_pk_fma_f32 v[102:103], v[102:103], v[114:115], v[106:107]
	v_pk_fma_f32 v[100:101], v[100:101], v[112:113], v[104:105]
	global_store_dwordx4 v[96:97], v[92:95], off
	global_store_dwordx4 v[132:133], v[100:103], off offset:512
	v_add_u32_e32 v98, 0x90, v178
	v_lshlrev_b32_e32 v92, 16, v154
	v_and_b32_e32 v93, 0xffff0000, v154
	v_lshlrev_b32_e32 v94, 16, v155
	v_and_b32_e32 v95, 0xffff0000, v155
	v_lshlrev_b32_e32 v100, 16, v158
	v_and_b32_e32 v101, 0xffff0000, v158
	v_lshlrev_b32_e32 v102, 16, v159
	v_and_b32_e32 v103, 0xffff0000, v159
	v_pk_fma_f32 v[78:79], v[78:79], v[110:111], v[94:95]
	v_pk_fma_f32 v[76:77], v[76:77], v[108:109], v[92:93]
	v_pk_fma_f32 v[90:91], v[90:91], v[118:119], v[102:103]
	v_pk_fma_f32 v[88:89], v[88:89], v[116:117], v[100:101]
	global_store_dwordx4 v[96:97], v[76:79], off offset:528
	global_store_dwordx4 v[96:97], v[88:91], off offset:16
	v_ashrrev_i32_e32 v99, 31, v98
	v_lshlrev_b32_e32 v76, 16, v148
	v_and_b32_e32 v77, 0xffff0000, v148
	v_lshlrev_b32_e32 v88, 16, v152
	v_and_b32_e32 v89, 0xffff0000, v152
	v_lshlrev_b32_e32 v90, 16, v153
	v_and_b32_e32 v91, 0xffff0000, v153
	v_pk_fma_f32 v[76:77], v[80:81], v[120:121], v[76:77]
	v_lshlrev_b64 v[80:81], 13, v[180:181]
	v_pk_fma_f32 v[86:87], v[86:87], v[114:115], v[90:91]
	v_pk_fma_f32 v[84:85], v[84:85], v[112:113], v[88:89]
	v_lshlrev_b32_e32 v78, 16, v149
	v_and_b32_e32 v79, 0xffff0000, v149
	v_lshl_add_u64 v[80:81], s[66:67], 0, v[80:81]
	global_store_dwordx4 v[96:97], v[84:87], off offset:512
	v_pk_fma_f32 v[78:79], v[82:83], v[122:123], v[78:79]
	v_lshl_add_u64 v[80:81], v[80:81], 0, v[174:175]
	v_lshlrev_b32_e32 v84, 16, v150
	v_and_b32_e32 v85, 0xffff0000, v150
	v_lshlrev_b32_e32 v86, 16, v151
	v_and_b32_e32 v87, 0xffff0000, v151
	global_store_dwordx4 v[80:81], v[76:79], off
	v_pk_fma_f32 v[74:75], v[74:75], v[118:119], v[86:87]
	v_pk_fma_f32 v[72:73], v[72:73], v[116:117], v[84:85]
	v_lshlrev_b32_e32 v76, 16, v146
	v_and_b32_e32 v77, 0xffff0000, v146
	v_lshlrev_b32_e32 v78, 16, v147
	v_and_b32_e32 v79, 0xffff0000, v147
	v_add_u32_e32 v96, 0x80, v178
	global_store_dwordx4 v[80:81], v[72:75], off offset:16
	v_pk_fma_f32 v[66:67], v[66:67], v[110:111], v[78:79]
	v_pk_fma_f32 v[64:65], v[64:65], v[108:109], v[76:77]
	v_lshlrev_b32_e32 v72, 16, v144
	v_and_b32_e32 v73, 0xffff0000, v144
	v_lshlrev_b32_e32 v74, 16, v145
	v_and_b32_e32 v75, 0xffff0000, v145
	v_ashrrev_i32_e32 v97, 31, v96
	v_pk_fma_f32 v[70:71], v[70:71], v[114:115], v[74:75]
	v_pk_fma_f32 v[68:69], v[68:69], v[112:113], v[72:73]
	global_store_dwordx4 v[80:81], v[64:67], off offset:528
	global_store_dwordx4 v[80:81], v[68:71], off offset:512
	v_add_u32_e32 v100, 0xa0, v178
	v_lshlrev_b64 v[64:65], 12, v[96:97]
	v_lshl_add_u64 v[64:65], v[176:177], 0, v[64:65]
	global_load_dwordx4 v[68:71], v[64:65], off
	global_load_dwordx4 v[72:75], v[64:65], off offset:256
	v_lshlrev_b64 v[64:65], 12, v[98:99]
	v_lshl_add_u64 v[64:65], v[176:177], 0, v[64:65]
	global_load_dwordx4 v[76:79], v[64:65], off
	global_load_dwordx4 v[80:83], v[64:65], off offset:256
	v_ashrrev_i32_e32 v101, 31, v100
	v_lshlrev_b64 v[64:65], 12, v[100:101]
	v_lshl_add_u64 v[64:65], v[176:177], 0, v[64:65]
	global_load_dwordx4 v[84:87], v[64:65], off
	global_load_dwordx4 v[88:91], v[64:65], off offset:256
	v_add_u32_e32 v102, 0xb0, v178
	v_ashrrev_i32_e32 v103, 31, v102
	v_lshlrev_b64 v[64:65], 12, v[102:103]
	v_lshl_add_u64 v[64:65], v[176:177], 0, v[64:65]
	global_load_dwordx4 v[92:95], v[64:65], off
	s_nop 0
	global_load_dwordx4 v[64:67], v[64:65], off offset:256
	s_waitcnt vmcnt(0)
	v_lshlrev_b32_e32 v104, 16, v68
	v_and_b32_e32 v105, 0xffff0000, v68
	v_lshlrev_b32_e32 v68, 16, v69
	v_and_b32_e32 v69, 0xffff0000, v69
	v_pk_fma_f32 v[62:63], v[62:63], v[122:123], v[68:69]
	v_lshlrev_b64 v[68:69], 13, v[96:97]
	v_lshl_add_u64 v[68:69], s[66:67], 0, v[68:69]
	v_pk_fma_f32 v[60:61], v[60:61], v[120:121], v[104:105]
	v_lshl_add_u64 v[68:69], v[68:69], 0, v[174:175]
	global_store_dwordx4 v[68:69], v[60:63], off
	v_lshlrev_b32_e32 v106, 16, v70
	v_and_b32_e32 v107, 0xffff0000, v70
	v_lshlrev_b32_e32 v60, 16, v74
	v_and_b32_e32 v61, 0xffff0000, v74
	v_lshlrev_b32_e32 v62, 16, v75
	v_and_b32_e32 v63, 0xffff0000, v75
	v_pk_fma_f32 v[46:47], v[46:47], v[110:111], v[62:63]
	v_pk_fma_f32 v[44:45], v[44:45], v[108:109], v[60:61]
	global_store_dwordx4 v[68:69], v[44:47], off offset:528
	v_lshlrev_b32_e32 v70, 16, v71
	v_and_b32_e32 v71, 0xffff0000, v71
	v_lshlrev_b32_e32 v44, 16, v76
	v_and_b32_e32 v45, 0xffff0000, v76
	v_pk_fma_f32 v[44:45], v[48:49], v[120:121], v[44:45]
	v_lshlrev_b64 v[48:49], 13, v[98:99]
	v_lshlrev_b32_e32 v46, 16, v77
	v_and_b32_e32 v47, 0xffff0000, v77
	v_lshl_add_u64 v[48:49], s[66:67], 0, v[48:49]
	v_pk_fma_f32 v[58:59], v[58:59], v[118:119], v[70:71]
	v_pk_fma_f32 v[56:57], v[56:57], v[116:117], v[106:107]
	v_pk_fma_f32 v[46:47], v[50:51], v[122:123], v[46:47]
	v_lshl_add_u64 v[48:49], v[48:49], 0, v[174:175]
	global_store_dwordx4 v[68:69], v[56:59], off offset:16
	global_store_dwordx4 v[48:49], v[44:47], off
	s_nop 0
	v_lshlrev_b32_e32 v56, 16, v72
	v_and_b32_e32 v57, 0xffff0000, v72
	v_lshlrev_b32_e32 v58, 16, v73
	v_and_b32_e32 v59, 0xffff0000, v73
	v_lshlrev_b32_e32 v44, 16, v82
	v_and_b32_e32 v45, 0xffff0000, v82
	v_lshlrev_b32_e32 v46, 16, v83
	v_and_b32_e32 v47, 0xffff0000, v83
	v_pk_fma_f32 v[54:55], v[54:55], v[114:115], v[58:59]
	v_pk_fma_f32 v[52:53], v[52:53], v[112:113], v[56:57]
	v_pk_fma_f32 v[30:31], v[30:31], v[110:111], v[46:47]
	v_pk_fma_f32 v[28:29], v[28:29], v[108:109], v[44:45]
	global_store_dwordx4 v[68:69], v[52:55], off offset:512
	global_store_dwordx4 v[48:49], v[28:31], off offset:528
	s_nop 0
	v_lshlrev_b32_e32 v52, 16, v78
	v_and_b32_e32 v53, 0xffff0000, v78
	v_lshlrev_b32_e32 v54, 16, v79
	v_and_b32_e32 v55, 0xffff0000, v79
	v_lshlrev_b32_e32 v28, 16, v84
	v_and_b32_e32 v29, 0xffff0000, v84
	v_pk_fma_f32 v[42:43], v[42:43], v[118:119], v[54:55]
	v_pk_fma_f32 v[40:41], v[40:41], v[116:117], v[52:53]
	v_pk_fma_f32 v[28:29], v[32:33], v[120:121], v[28:29]
	v_lshlrev_b64 v[32:33], 13, v[100:101]
	global_store_dwordx4 v[48:49], v[40:43], off offset:16
	v_lshlrev_b32_e32 v30, 16, v85
	v_and_b32_e32 v31, 0xffff0000, v85
	v_lshlrev_b32_e32 v40, 16, v80
	v_and_b32_e32 v41, 0xffff0000, v80
	v_lshlrev_b32_e32 v42, 16, v81
	v_and_b32_e32 v43, 0xffff0000, v81
	v_lshl_add_u64 v[32:33], s[66:67], 0, v[32:33]
	v_pk_fma_f32 v[38:39], v[38:39], v[114:115], v[42:43]
	v_pk_fma_f32 v[36:37], v[36:37], v[112:113], v[40:41]
	v_pk_fma_f32 v[30:31], v[34:35], v[122:123], v[30:31]
	v_lshl_add_u64 v[32:33], v[32:33], 0, v[174:175]
	global_store_dwordx4 v[48:49], v[36:39], off offset:512
	global_store_dwordx4 v[32:33], v[28:31], off
	s_nop 0
	v_lshlrev_b32_e32 v36, 16, v86
	v_and_b32_e32 v37, 0xffff0000, v86
	v_lshlrev_b32_e32 v38, 16, v87
	v_and_b32_e32 v39, 0xffff0000, v87
	v_lshlrev_b32_e32 v28, 16, v90
	v_and_b32_e32 v29, 0xffff0000, v90
	v_lshlrev_b32_e32 v30, 16, v91
	v_and_b32_e32 v31, 0xffff0000, v91
	v_pk_fma_f32 v[26:27], v[26:27], v[118:119], v[38:39]
	v_pk_fma_f32 v[24:25], v[24:25], v[116:117], v[36:37]
	v_pk_fma_f32 v[14:15], v[14:15], v[110:111], v[30:31]
	v_pk_fma_f32 v[12:13], v[12:13], v[108:109], v[28:29]
	global_store_dwordx4 v[32:33], v[24:27], off offset:16
	global_store_dwordx4 v[32:33], v[12:15], off offset:528
	s_nop 0
	v_lshlrev_b32_e32 v24, 16, v88
	v_and_b32_e32 v25, 0xffff0000, v88
	v_lshlrev_b32_e32 v26, 16, v89
	v_and_b32_e32 v27, 0xffff0000, v89
	v_lshlrev_b32_e32 v12, 16, v92
	v_and_b32_e32 v13, 0xffff0000, v92
	v_pk_fma_f32 v[22:23], v[22:23], v[114:115], v[26:27]
	v_pk_fma_f32 v[20:21], v[20:21], v[112:113], v[24:25]
	v_pk_fma_f32 v[12:13], v[16:17], v[120:121], v[12:13]
	v_lshlrev_b64 v[16:17], 13, v[102:103]
	global_store_dwordx4 v[32:33], v[20:23], off offset:512
	v_lshlrev_b32_e32 v14, 16, v93
	v_and_b32_e32 v15, 0xffff0000, v93
	v_lshlrev_b32_e32 v20, 16, v94
	v_and_b32_e32 v21, 0xffff0000, v94
	v_lshlrev_b32_e32 v22, 16, v95
	v_and_b32_e32 v23, 0xffff0000, v95
	v_lshl_add_u64 v[16:17], s[66:67], 0, v[16:17]
	v_pk_fma_f32 v[14:15], v[18:19], v[122:123], v[14:15]
	v_lshl_add_u64 v[16:17], v[16:17], 0, v[174:175]
	v_pk_fma_f32 v[10:11], v[10:11], v[118:119], v[22:23]
	v_pk_fma_f32 v[8:9], v[8:9], v[116:117], v[20:21]
	global_store_dwordx4 v[16:17], v[12:15], off
	global_store_dwordx4 v[16:17], v[8:11], off offset:16
	s_nop 0
	v_lshlrev_b32_e32 v12, 16, v66
	v_lshlrev_b32_e32 v8, 16, v64
	v_and_b32_e32 v9, 0xffff0000, v64
	v_lshlrev_b32_e32 v10, 16, v65
	v_and_b32_e32 v11, 0xffff0000, v65
	v_and_b32_e32 v13, 0xffff0000, v66
	v_lshlrev_b32_e32 v14, 16, v67
	v_and_b32_e32 v15, 0xffff0000, v67
	v_pk_fma_f32 v[6:7], v[6:7], v[114:115], v[10:11]
	v_pk_fma_f32 v[4:5], v[4:5], v[112:113], v[8:9]
	v_pk_fma_f32 v[2:3], v[2:3], v[110:111], v[14:15]
	v_pk_fma_f32 v[0:1], v[0:1], v[108:109], v[12:13]
	global_store_dwordx4 v[16:17], v[4:7], off offset:512
	global_store_dwordx4 v[16:17], v[0:3], off offset:528
	s_cbranch_vccz .LBB0_261
	s_waitcnt vmcnt(0)
	s_cmpk_gt_u32 s16, 0xff
	s_cbranch_scc1 .LBB0_276
	s_barrier

.LBB0_293:
	v_mov_b64_e32 v[0:1], 0x400
	s_ashr_i32 s7, s6, 31
	v_cmp_lt_i64_e32 vcc, s[8:9], v[0:1]
	s_lshl_b64 s[8:9], s[6:7], 20
	s_add_u32 s8, s20, s8
	s_addc_u32 s9, s21, s9
	s_and_b64 s[10:11], vcc, exec
	s_cselect_b32 s7, s9, s15
	s_cselect_b32 s38, s8, s14
	s_ashr_i32 s5, s4, 31
	s_lshl_b64 s[10:11], s[4:5], 20
	s_add_u32 s10, s22, s10
	s_addc_u32 s11, s23, s11
	s_and_b64 s[18:19], vcc, exec
	s_cselect_b32 s5, s11, s17
	s_cselect_b32 s39, s10, s16
	s_add_u32 s14, s14, 0x80080
	s_addc_u32 s15, s15, 0
	s_add_u32 s40, s16, 0x100
	s_addc_u32 s41, s17, 0
	s_mov_b32 s42, -2
	s_mov_b64 s[48:49], 0x80
	v_add_u32_e32 v220, 0x10000, v159
	s_add_u32 s16, s14, 0xfff80080
	s_addc_u32 s17, s15, -1
	s_add_i32 s43, 0, 0x10000
	ds_read_b128 v[64:67], v220 offset:0
	ds_read_b128 v[68:71], v220 offset:1024
	ds_read_b128 v[72:75], v220 offset:2048
	ds_read_b128 v[76:79], v220 offset:3072
	s_cmp_eq_u32 s42, 28
	s_cselect_b32 s19, s7, s17
	s_cselect_b32 s18, s38, s16
	s_cselect_b32 s17, s5, s41
	s_cselect_b32 s16, s39, s40
	s_add_i32 m0, s13, 0xc000
	ds_read_b128 v[154:157], v161
	ds_read_b128 v[162:165], v161 offset:1024
	ds_read_b128 v[166:169], v161 offset:2048
	ds_read_b128 v[170:173], v161 offset:3072
	ds_read_b128 v[174:177], v161 offset:4096
	ds_read_b128 v[178:181], v161 offset:5120
	ds_read_b128 v[182:185], v161 offset:6144
	ds_read_b128 v[186:189], v161 offset:7168
	global_load_lds_dwordx4 v150, s[14:15]
	s_add_i32 m0, s13, 0xe000
	s_nop 0
	global_load_lds_dwordx4 v152, s[14:15]
	s_waitcnt lgkmcnt(8)
	s_barrier
	s_waitcnt lgkmcnt(0)
	v_mfma_f32_16x16x32_bf16 v[140:143], v[64:67], v[154:157], 0
	v_mfma_f32_16x16x32_bf16 v[136:139], v[72:75], v[154:157], 0
	v_mfma_f32_16x16x32_bf16 v[132:135], v[64:67], v[166:169], 0
	v_mfma_f32_16x16x32_bf16 v[128:131], v[72:75], v[166:169], 0
	s_add_i32 s46, 0, 0x14000
	s_add_i32 s43, s43, s27
	v_mfma_f32_16x16x32_bf16 v[108:111], v[64:67], v[174:177], 0
	s_mov_b32 m0, s43
	v_mfma_f32_16x16x32_bf16 v[104:107], v[72:75], v[174:177], 0
	v_mfma_f32_16x16x32_bf16 v[100:103], v[64:67], v[182:185], 0
	v_mfma_f32_16x16x32_bf16 v[96:99], v[72:75], v[182:185], 0
	v_mfma_f32_16x16x32_bf16 v[140:143], v[68:71], v[162:165], v[140:143]
	v_mfma_f32_16x16x32_bf16 v[136:139], v[76:79], v[162:165], v[136:139]
	v_mfma_f32_16x16x32_bf16 v[132:135], v[68:71], v[170:173], v[132:135]
	v_mfma_f32_16x16x32_bf16 v[128:131], v[76:79], v[170:173], v[128:131]
	v_mfma_f32_16x16x32_bf16 v[108:111], v[68:71], v[178:181], v[108:111]
	v_mfma_f32_16x16x32_bf16 v[104:107], v[76:79], v[178:181], v[104:107]
	v_mfma_f32_16x16x32_bf16 v[100:103], v[68:71], v[186:189], v[100:103]
	v_mfma_f32_16x16x32_bf16 v[96:99], v[76:79], v[186:189], v[96:99]
	s_barrier
	ds_read_b128 v[196:199], v220 offset:16384
	ds_read_b128 v[204:207], v220 offset:17408
	ds_read_b128 v[208:211], v220 offset:18432
	ds_read_b128 v[214:217], v220 offset:19456
	global_load_lds_dwordx4 v192, s[16:17]
	s_add_i32 m0, s43, 0x2000
	s_nop 0
	global_load_lds_dwordx4 v148, s[16:17]
	s_barrier
	s_waitcnt lgkmcnt(0)
	v_mfma_f32_16x16x32_bf16 v[124:127], v[196:199], v[154:157], 0
	v_mfma_f32_16x16x32_bf16 v[120:123], v[208:211], v[154:157], 0
	v_mfma_f32_16x16x32_bf16 v[116:119], v[196:199], v[166:169], 0
	v_mfma_f32_16x16x32_bf16 v[112:115], v[208:211], v[166:169], 0
	s_mov_b32 m0, s13
	v_mfma_f32_16x16x32_bf16 v[92:95], v[196:199], v[174:177], 0
	s_add_u32 s48, s18, 0x80
	s_addc_u32 s49, s19, 0
	v_mfma_f32_16x16x32_bf16 v[88:91], v[208:211], v[174:177], 0
	v_mfma_f32_16x16x32_bf16 v[84:87], v[196:199], v[182:185], 0
	v_mfma_f32_16x16x32_bf16 v[80:83], v[208:211], v[182:185], 0
	v_mfma_f32_16x16x32_bf16 v[124:127], v[204:207], v[162:165], v[124:127]
	v_mfma_f32_16x16x32_bf16 v[120:123], v[214:217], v[162:165], v[120:123]
	v_mfma_f32_16x16x32_bf16 v[116:119], v[204:207], v[170:173], v[116:119]
	v_mfma_f32_16x16x32_bf16 v[112:115], v[214:217], v[170:173], v[112:115]
	v_mfma_f32_16x16x32_bf16 v[92:95], v[204:207], v[178:181], v[92:95]
	v_mfma_f32_16x16x32_bf16 v[88:91], v[214:217], v[178:181], v[88:91]
	v_mfma_f32_16x16x32_bf16 v[84:87], v[204:207], v[186:189], v[84:87]
	v_mfma_f32_16x16x32_bf16 v[80:83], v[214:217], v[186:189], v[80:83]
	s_barrier
	ds_read_b128 v[154:157], v161 offset:16384
	ds_read_b128 v[162:165], v161 offset:17408
	ds_read_b128 v[166:169], v161 offset:18432
	ds_read_b128 v[170:173], v161 offset:19456
	ds_read_b128 v[174:177], v161 offset:20480
	ds_read_b128 v[178:181], v161 offset:21504
	ds_read_b128 v[182:185], v161 offset:22528
	ds_read_b128 v[186:189], v161 offset:23552
	global_load_lds_dwordx4 v144, s[18:19]
	s_mov_b32 m0, s28
	s_nop 0
	global_load_lds_dwordx4 v146, s[18:19]
	s_barrier
	s_waitcnt lgkmcnt(0)
	v_mfma_f32_16x16x32_bf16 v[60:63], v[64:67], v[154:157], 0
	v_mfma_f32_16x16x32_bf16 v[56:59], v[72:75], v[154:157], 0
	v_mfma_f32_16x16x32_bf16 v[52:55], v[64:67], v[166:169], 0
	v_mfma_f32_16x16x32_bf16 v[48:51], v[72:75], v[166:169], 0
	s_add_u32 s44, s16, 0x80000
	s_addc_u32 s45, s17, 0
	v_mfma_f32_16x16x32_bf16 v[28:31], v[64:67], v[174:177], 0
	s_add_i32 s43, s46, s27
	s_mov_b32 m0, s43
	v_mfma_f32_16x16x32_bf16 v[24:27], v[72:75], v[174:177], 0
	v_mfma_f32_16x16x32_bf16 v[20:23], v[64:67], v[182:185], 0
	v_mfma_f32_16x16x32_bf16 v[16:19], v[72:75], v[182:185], 0
	v_mfma_f32_16x16x32_bf16 v[60:63], v[68:71], v[162:165], v[60:63]
	v_mfma_f32_16x16x32_bf16 v[56:59], v[76:79], v[162:165], v[56:59]
	v_mfma_f32_16x16x32_bf16 v[52:55], v[68:71], v[170:173], v[52:55]
	v_mfma_f32_16x16x32_bf16 v[48:51], v[76:79], v[170:173], v[48:51]
	v_mfma_f32_16x16x32_bf16 v[28:31], v[68:71], v[178:181], v[28:31]
	v_mfma_f32_16x16x32_bf16 v[24:27], v[76:79], v[178:181], v[24:27]
	v_mfma_f32_16x16x32_bf16 v[20:23], v[68:71], v[186:189], v[20:23]
	v_mfma_f32_16x16x32_bf16 v[16:19], v[76:79], v[186:189], v[16:19]
	s_barrier
	global_load_lds_dwordx4 v192, s[44:45]
	s_add_i32 m0, s43, 0x2000
	s_nop 0
	global_load_lds_dwordx4 v148, s[44:45]
	s_waitcnt vmcnt(6)
	s_barrier
	v_mfma_f32_16x16x32_bf16 v[44:47], v[196:199], v[154:157], 0
	v_mfma_f32_16x16x32_bf16 v[40:43], v[208:211], v[154:157], 0
	v_mfma_f32_16x16x32_bf16 v[36:39], v[196:199], v[166:169], 0
	v_mfma_f32_16x16x32_bf16 v[32:35], v[208:211], v[166:169], 0
	s_add_i32 s43, 0, 0x18000
	v_mfma_f32_16x16x32_bf16 v[12:15], v[196:199], v[174:177], 0
	s_add_u32 s18, s18, 0x80000
	s_addc_u32 s19, s19, 0
	v_mfma_f32_16x16x32_bf16 v[8:11], v[208:211], v[174:177], 0
	s_mov_b32 m0, s29
	v_mfma_f32_16x16x32_bf16 v[4:7], v[196:199], v[182:185], 0
	v_mfma_f32_16x16x32_bf16 v[0:3], v[208:211], v[182:185], 0
	v_mfma_f32_16x16x32_bf16 v[44:47], v[204:207], v[162:165], v[44:47]
	v_mfma_f32_16x16x32_bf16 v[40:43], v[214:217], v[162:165], v[40:43]
	v_mfma_f32_16x16x32_bf16 v[36:39], v[204:207], v[170:173], v[36:39]
	v_mfma_f32_16x16x32_bf16 v[32:35], v[214:217], v[170:173], v[32:35]
	v_mfma_f32_16x16x32_bf16 v[12:15], v[204:207], v[178:181], v[12:15]
	v_mfma_f32_16x16x32_bf16 v[8:11], v[214:217], v[178:181], v[8:11]
	v_mfma_f32_16x16x32_bf16 v[4:7], v[204:207], v[186:189], v[4:7]
	v_mfma_f32_16x16x32_bf16 v[0:3], v[214:217], v[186:189], v[0:3]
	s_barrier
	ds_read_b128 v[64:67], v220 offset:32768
	ds_read_b128 v[68:71], v220 offset:33792
	ds_read_b128 v[72:75], v220 offset:34816
	ds_read_b128 v[76:79], v220 offset:35840
	ds_read_b128 v[154:157], v161 offset:32768
	ds_read_b128 v[162:165], v161 offset:33792
	ds_read_b128 v[166:169], v161 offset:34816
	ds_read_b128 v[170:173], v161 offset:35840
	ds_read_b128 v[174:177], v161 offset:36864
	ds_read_b128 v[178:181], v161 offset:37888
	ds_read_b128 v[182:185], v161 offset:38912
	ds_read_b128 v[186:189], v161 offset:39936
	global_load_lds_dwordx4 v144, s[18:19]
	s_mov_b32 m0, s30
	s_nop 0
	global_load_lds_dwordx4 v146, s[18:19]
	s_waitcnt lgkmcnt(8)
	s_barrier
	s_waitcnt lgkmcnt(0)
	v_mfma_f32_16x16x32_bf16 v[140:143], v[64:67], v[154:157], v[140:143]
	v_mfma_f32_16x16x32_bf16 v[136:139], v[72:75], v[154:157], v[136:139]
	v_mfma_f32_16x16x32_bf16 v[132:135], v[64:67], v[166:169], v[132:135]
	v_mfma_f32_16x16x32_bf16 v[128:131], v[72:75], v[166:169], v[128:131]
	s_add_i32 s18, 0, 0x1c000
	s_add_i32 s19, s43, s27
	v_mfma_f32_16x16x32_bf16 v[108:111], v[64:67], v[174:177], v[108:111]
	s_add_i32 m0, s19, 0xffffff80
	v_mfma_f32_16x16x32_bf16 v[104:107], v[72:75], v[174:177], v[104:107]
	v_mfma_f32_16x16x32_bf16 v[100:103], v[64:67], v[182:185], v[100:103]
	v_mfma_f32_16x16x32_bf16 v[96:99], v[72:75], v[182:185], v[96:99]
	v_mfma_f32_16x16x32_bf16 v[140:143], v[68:71], v[162:165], v[140:143]
	v_mfma_f32_16x16x32_bf16 v[136:139], v[76:79], v[162:165], v[136:139]
	v_mfma_f32_16x16x32_bf16 v[132:135], v[68:71], v[170:173], v[132:135]
	v_mfma_f32_16x16x32_bf16 v[128:131], v[76:79], v[170:173], v[128:131]
	v_mfma_f32_16x16x32_bf16 v[108:111], v[68:71], v[178:181], v[108:111]
	v_mfma_f32_16x16x32_bf16 v[104:107], v[76:79], v[178:181], v[104:107]
	v_mfma_f32_16x16x32_bf16 v[100:103], v[68:71], v[186:189], v[100:103]
	v_mfma_f32_16x16x32_bf16 v[96:99], v[76:79], v[186:189], v[96:99]
	s_barrier
	ds_read_b128 v[196:199], v220 offset:49152
	ds_read_b128 v[204:207], v220 offset:50176
	ds_read_b128 v[208:211], v220 offset:51200
	ds_read_b128 v[214:217], v220 offset:52224
	global_load_lds_dwordx4 v192, s[16:17] offset:128
	s_add_i32 m0, s19, 0x1f80
	s_nop 0
	global_load_lds_dwordx4 v148, s[16:17] offset:128
	s_barrier
	s_waitcnt lgkmcnt(0)
	v_mfma_f32_16x16x32_bf16 v[124:127], v[196:199], v[154:157], v[124:127]
	v_mfma_f32_16x16x32_bf16 v[120:123], v[208:211], v[154:157], v[120:123]
	v_mfma_f32_16x16x32_bf16 v[116:119], v[196:199], v[166:169], v[116:119]
	v_mfma_f32_16x16x32_bf16 v[112:115], v[208:211], v[166:169], v[112:115]
	s_mov_b32 m0, s34
	v_mfma_f32_16x16x32_bf16 v[92:95], v[196:199], v[174:177], v[92:95]
	v_mfma_f32_16x16x32_bf16 v[88:91], v[208:211], v[174:177], v[88:91]
	v_mfma_f32_16x16x32_bf16 v[84:87], v[196:199], v[182:185], v[84:87]
	v_mfma_f32_16x16x32_bf16 v[80:83], v[208:211], v[182:185], v[80:83]
	v_mfma_f32_16x16x32_bf16 v[124:127], v[204:207], v[162:165], v[124:127]
	v_mfma_f32_16x16x32_bf16 v[120:123], v[214:217], v[162:165], v[120:123]
	v_mfma_f32_16x16x32_bf16 v[116:119], v[204:207], v[170:173], v[116:119]
	v_mfma_f32_16x16x32_bf16 v[112:115], v[214:217], v[170:173], v[112:115]
	v_mfma_f32_16x16x32_bf16 v[92:95], v[204:207], v[178:181], v[92:95]
	v_mfma_f32_16x16x32_bf16 v[88:91], v[214:217], v[178:181], v[88:91]
	v_mfma_f32_16x16x32_bf16 v[84:87], v[204:207], v[186:189], v[84:87]
	v_mfma_f32_16x16x32_bf16 v[80:83], v[214:217], v[186:189], v[80:83]
	s_barrier
	ds_read_b128 v[154:157], v161 offset:49152
	ds_read_b128 v[162:165], v161 offset:50176
	ds_read_b128 v[166:169], v161 offset:51200
	ds_read_b128 v[170:173], v161 offset:52224
	ds_read_b128 v[174:177], v161 offset:53248
	ds_read_b128 v[178:181], v161 offset:54272
	ds_read_b128 v[182:185], v161 offset:55296
	ds_read_b128 v[186:189], v161 offset:56320
	global_load_lds_dwordx4 v144, s[48:49]
	s_mov_b32 m0, s35
	s_nop 0
	global_load_lds_dwordx4 v146, s[48:49]
	s_barrier
	s_waitcnt lgkmcnt(0)
	v_mfma_f32_16x16x32_bf16 v[60:63], v[64:67], v[154:157], v[60:63]
	v_mfma_f32_16x16x32_bf16 v[56:59], v[72:75], v[154:157], v[56:59]
	v_mfma_f32_16x16x32_bf16 v[52:55], v[64:67], v[166:169], v[52:55]
	v_mfma_f32_16x16x32_bf16 v[48:51], v[72:75], v[166:169], v[48:51]
	s_add_u32 s16, s16, 0x80080
	s_addc_u32 s17, s17, 0
	v_mfma_f32_16x16x32_bf16 v[28:31], v[64:67], v[174:177], v[28:31]
	s_add_i32 s18, s18, s27
	s_mov_b32 m0, s18
	v_mfma_f32_16x16x32_bf16 v[24:27], v[72:75], v[174:177], v[24:27]
	v_mfma_f32_16x16x32_bf16 v[20:23], v[64:67], v[182:185], v[20:23]
	v_mfma_f32_16x16x32_bf16 v[16:19], v[72:75], v[182:185], v[16:19]
	v_mfma_f32_16x16x32_bf16 v[60:63], v[68:71], v[162:165], v[60:63]
	v_mfma_f32_16x16x32_bf16 v[56:59], v[76:79], v[162:165], v[56:59]
	v_mfma_f32_16x16x32_bf16 v[52:55], v[68:71], v[170:173], v[52:55]
	v_mfma_f32_16x16x32_bf16 v[48:51], v[76:79], v[170:173], v[48:51]
	v_mfma_f32_16x16x32_bf16 v[28:31], v[68:71], v[178:181], v[28:31]
	v_mfma_f32_16x16x32_bf16 v[24:27], v[76:79], v[178:181], v[24:27]
	v_mfma_f32_16x16x32_bf16 v[20:23], v[68:71], v[186:189], v[20:23]
	v_mfma_f32_16x16x32_bf16 v[16:19], v[76:79], v[186:189], v[16:19]
	s_barrier
	global_load_lds_dwordx4 v192, s[16:17]
	s_add_i32 m0, s18, 0x2000
	s_nop 0
	global_load_lds_dwordx4 v148, s[16:17]
	s_waitcnt vmcnt(6)
	s_barrier
	v_mfma_f32_16x16x32_bf16 v[44:47], v[196:199], v[154:157], v[44:47]
	v_mfma_f32_16x16x32_bf16 v[40:43], v[208:211], v[154:157], v[40:43]
	v_mfma_f32_16x16x32_bf16 v[36:39], v[196:199], v[166:169], v[36:39]
	v_mfma_f32_16x16x32_bf16 v[32:35], v[208:211], v[166:169], v[32:35]
	s_add_i32 s42, s42, 2
	v_mfma_f32_16x16x32_bf16 v[12:15], v[196:199], v[174:177], v[12:15]
	s_add_u32 s14, s14, 0x100
	s_addc_u32 s15, s15, 0
	v_mfma_f32_16x16x32_bf16 v[8:11], v[208:211], v[174:177], v[8:11]
	s_add_u32 s40, s40, 0x100
	s_addc_u32 s41, s41, 0
	v_mfma_f32_16x16x32_bf16 v[4:7], v[196:199], v[182:185], v[4:7]
	v_mfma_f32_16x16x32_bf16 v[0:3], v[208:211], v[182:185], v[0:3]
	v_mfma_f32_16x16x32_bf16 v[44:47], v[204:207], v[162:165], v[44:47]
	v_mfma_f32_16x16x32_bf16 v[40:43], v[214:217], v[162:165], v[40:43]
	v_mfma_f32_16x16x32_bf16 v[36:39], v[204:207], v[170:173], v[36:39]
	v_mfma_f32_16x16x32_bf16 v[32:35], v[214:217], v[170:173], v[32:35]
	v_mfma_f32_16x16x32_bf16 v[12:15], v[204:207], v[178:181], v[12:15]
	v_mfma_f32_16x16x32_bf16 v[8:11], v[214:217], v[178:181], v[8:11]
	v_mfma_f32_16x16x32_bf16 v[4:7], v[204:207], v[186:189], v[4:7]
	v_mfma_f32_16x16x32_bf16 v[0:3], v[214:217], v[186:189], v[0:3]
	s_cmp_gt_u32 s42, 29
	s_barrier
.LBB0_294:
	s_add_u32 s16, s14, 0xfff80080
	s_addc_u32 s17, s15, -1
	s_add_i32 s43, 0, 0x10000
	ds_read_b128 v[64:67], v220 offset:0
	ds_read_b128 v[68:71], v220 offset:1024
	ds_read_b128 v[72:75], v220 offset:2048
	ds_read_b128 v[76:79], v220 offset:3072
	s_cmp_eq_u32 s42, 28
	s_cselect_b32 s19, s7, s17
	s_cselect_b32 s18, s38, s16
	s_cselect_b32 s17, s5, s41
	s_cselect_b32 s16, s39, s40
	s_add_i32 m0, s13, 0xc000
	ds_read_b128 v[154:157], v161
	ds_read_b128 v[162:165], v161 offset:1024
	ds_read_b128 v[166:169], v161 offset:2048
	ds_read_b128 v[170:173], v161 offset:3072
	ds_read_b128 v[174:177], v161 offset:4096
	ds_read_b128 v[178:181], v161 offset:5120
	ds_read_b128 v[182:185], v161 offset:6144
	ds_read_b128 v[186:189], v161 offset:7168
	global_load_lds_dwordx4 v150, s[14:15]
	s_add_i32 m0, s13, 0xe000
	s_nop 0
	global_load_lds_dwordx4 v152, s[14:15]
	s_waitcnt lgkmcnt(8)
	s_barrier
	s_waitcnt lgkmcnt(0)
	v_mfma_f32_16x16x32_bf16 v[140:143], v[64:67], v[154:157], v[140:143]
	v_mfma_f32_16x16x32_bf16 v[136:139], v[72:75], v[154:157], v[136:139]
	v_mfma_f32_16x16x32_bf16 v[132:135], v[64:67], v[166:169], v[132:135]
	v_mfma_f32_16x16x32_bf16 v[128:131], v[72:75], v[166:169], v[128:131]
	s_add_i32 s46, 0, 0x14000
	s_add_i32 s43, s43, s27
	v_mfma_f32_16x16x32_bf16 v[108:111], v[64:67], v[174:177], v[108:111]
	s_mov_b32 m0, s43
	v_mfma_f32_16x16x32_bf16 v[104:107], v[72:75], v[174:177], v[104:107]
	v_mfma_f32_16x16x32_bf16 v[100:103], v[64:67], v[182:185], v[100:103]
	v_mfma_f32_16x16x32_bf16 v[96:99], v[72:75], v[182:185], v[96:99]
	v_mfma_f32_16x16x32_bf16 v[140:143], v[68:71], v[162:165], v[140:143]
	v_mfma_f32_16x16x32_bf16 v[136:139], v[76:79], v[162:165], v[136:139]
	v_mfma_f32_16x16x32_bf16 v[132:135], v[68:71], v[170:173], v[132:135]
	v_mfma_f32_16x16x32_bf16 v[128:131], v[76:79], v[170:173], v[128:131]
	v_mfma_f32_16x16x32_bf16 v[108:111], v[68:71], v[178:181], v[108:111]
	v_mfma_f32_16x16x32_bf16 v[104:107], v[76:79], v[178:181], v[104:107]
	v_mfma_f32_16x16x32_bf16 v[100:103], v[68:71], v[186:189], v[100:103]
	v_mfma_f32_16x16x32_bf16 v[96:99], v[76:79], v[186:189], v[96:99]
	s_barrier
	ds_read_b128 v[196:199], v220 offset:16384
	ds_read_b128 v[204:207], v220 offset:17408
	ds_read_b128 v[208:211], v220 offset:18432
	ds_read_b128 v[214:217], v220 offset:19456
	global_load_lds_dwordx4 v192, s[16:17]
	s_add_i32 m0, s43, 0x2000
	s_nop 0
	global_load_lds_dwordx4 v148, s[16:17]
	s_barrier
	s_waitcnt lgkmcnt(0)
	v_mfma_f32_16x16x32_bf16 v[124:127], v[196:199], v[154:157], v[124:127]
	v_mfma_f32_16x16x32_bf16 v[120:123], v[208:211], v[154:157], v[120:123]
	v_mfma_f32_16x16x32_bf16 v[116:119], v[196:199], v[166:169], v[116:119]
	v_mfma_f32_16x16x32_bf16 v[112:115], v[208:211], v[166:169], v[112:115]
	s_mov_b32 m0, s13
	v_mfma_f32_16x16x32_bf16 v[92:95], v[196:199], v[174:177], v[92:95]
	s_add_u32 s48, s18, 0x80
	s_addc_u32 s49, s19, 0
	v_mfma_f32_16x16x32_bf16 v[88:91], v[208:211], v[174:177], v[88:91]
	v_mfma_f32_16x16x32_bf16 v[84:87], v[196:199], v[182:185], v[84:87]
	v_mfma_f32_16x16x32_bf16 v[80:83], v[208:211], v[182:185], v[80:83]
	v_mfma_f32_16x16x32_bf16 v[124:127], v[204:207], v[162:165], v[124:127]
	v_mfma_f32_16x16x32_bf16 v[120:123], v[214:217], v[162:165], v[120:123]
	v_mfma_f32_16x16x32_bf16 v[116:119], v[204:207], v[170:173], v[116:119]
	v_mfma_f32_16x16x32_bf16 v[112:115], v[214:217], v[170:173], v[112:115]
	v_mfma_f32_16x16x32_bf16 v[92:95], v[204:207], v[178:181], v[92:95]
	v_mfma_f32_16x16x32_bf16 v[88:91], v[214:217], v[178:181], v[88:91]
	v_mfma_f32_16x16x32_bf16 v[84:87], v[204:207], v[186:189], v[84:87]
	v_mfma_f32_16x16x32_bf16 v[80:83], v[214:217], v[186:189], v[80:83]
	s_barrier
	ds_read_b128 v[154:157], v161 offset:16384
	ds_read_b128 v[162:165], v161 offset:17408
	ds_read_b128 v[166:169], v161 offset:18432
	ds_read_b128 v[170:173], v161 offset:19456
	ds_read_b128 v[174:177], v161 offset:20480
	ds_read_b128 v[178:181], v161 offset:21504
	ds_read_b128 v[182:185], v161 offset:22528
	ds_read_b128 v[186:189], v161 offset:23552
	global_load_lds_dwordx4 v144, s[18:19]
	s_mov_b32 m0, s28
	s_nop 0
	global_load_lds_dwordx4 v146, s[18:19]
	s_barrier
	s_waitcnt lgkmcnt(0)
	v_mfma_f32_16x16x32_bf16 v[60:63], v[64:67], v[154:157], v[60:63]
	v_mfma_f32_16x16x32_bf16 v[56:59], v[72:75], v[154:157], v[56:59]
	v_mfma_f32_16x16x32_bf16 v[52:55], v[64:67], v[166:169], v[52:55]
	v_mfma_f32_16x16x32_bf16 v[48:51], v[72:75], v[166:169], v[48:51]
	s_add_u32 s44, s16, 0x80000
	s_addc_u32 s45, s17, 0
	v_mfma_f32_16x16x32_bf16 v[28:31], v[64:67], v[174:177], v[28:31]
	s_add_i32 s43, s46, s27
	s_mov_b32 m0, s43
	v_mfma_f32_16x16x32_bf16 v[24:27], v[72:75], v[174:177], v[24:27]
	v_mfma_f32_16x16x32_bf16 v[20:23], v[64:67], v[182:185], v[20:23]
	v_mfma_f32_16x16x32_bf16 v[16:19], v[72:75], v[182:185], v[16:19]
	v_mfma_f32_16x16x32_bf16 v[60:63], v[68:71], v[162:165], v[60:63]
	v_mfma_f32_16x16x32_bf16 v[56:59], v[76:79], v[162:165], v[56:59]
	v_mfma_f32_16x16x32_bf16 v[52:55], v[68:71], v[170:173], v[52:55]
	v_mfma_f32_16x16x32_bf16 v[48:51], v[76:79], v[170:173], v[48:51]
	v_mfma_f32_16x16x32_bf16 v[28:31], v[68:71], v[178:181], v[28:31]
	v_mfma_f32_16x16x32_bf16 v[24:27], v[76:79], v[178:181], v[24:27]
	v_mfma_f32_16x16x32_bf16 v[20:23], v[68:71], v[186:189], v[20:23]
	v_mfma_f32_16x16x32_bf16 v[16:19], v[76:79], v[186:189], v[16:19]
	s_barrier
	global_load_lds_dwordx4 v192, s[44:45]
	s_add_i32 m0, s43, 0x2000
	s_nop 0
	global_load_lds_dwordx4 v148, s[44:45]
	s_waitcnt vmcnt(6)
	s_barrier
	v_mfma_f32_16x16x32_bf16 v[44:47], v[196:199], v[154:157], v[44:47]
	v_mfma_f32_16x16x32_bf16 v[40:43], v[208:211], v[154:157], v[40:43]
	v_mfma_f32_16x16x32_bf16 v[36:39], v[196:199], v[166:169], v[36:39]
	v_mfma_f32_16x16x32_bf16 v[32:35], v[208:211], v[166:169], v[32:35]
	s_add_i32 s43, 0, 0x18000
	v_mfma_f32_16x16x32_bf16 v[12:15], v[196:199], v[174:177], v[12:15]
	s_add_u32 s18, s18, 0x80000
	s_addc_u32 s19, s19, 0
	v_mfma_f32_16x16x32_bf16 v[8:11], v[208:211], v[174:177], v[8:11]
	s_mov_b32 m0, s29
	v_mfma_f32_16x16x32_bf16 v[4:7], v[196:199], v[182:185], v[4:7]
	v_mfma_f32_16x16x32_bf16 v[0:3], v[208:211], v[182:185], v[0:3]
	v_mfma_f32_16x16x32_bf16 v[44:47], v[204:207], v[162:165], v[44:47]
	v_mfma_f32_16x16x32_bf16 v[40:43], v[214:217], v[162:165], v[40:43]
	v_mfma_f32_16x16x32_bf16 v[36:39], v[204:207], v[170:173], v[36:39]
	v_mfma_f32_16x16x32_bf16 v[32:35], v[214:217], v[170:173], v[32:35]
	v_mfma_f32_16x16x32_bf16 v[12:15], v[204:207], v[178:181], v[12:15]
	v_mfma_f32_16x16x32_bf16 v[8:11], v[214:217], v[178:181], v[8:11]
	v_mfma_f32_16x16x32_bf16 v[4:7], v[204:207], v[186:189], v[4:7]
	v_mfma_f32_16x16x32_bf16 v[0:3], v[214:217], v[186:189], v[0:3]
	s_barrier
	ds_read_b128 v[64:67], v220 offset:32768
	ds_read_b128 v[68:71], v220 offset:33792
	ds_read_b128 v[72:75], v220 offset:34816
	ds_read_b128 v[76:79], v220 offset:35840
	ds_read_b128 v[154:157], v161 offset:32768
	ds_read_b128 v[162:165], v161 offset:33792
	ds_read_b128 v[166:169], v161 offset:34816
	ds_read_b128 v[170:173], v161 offset:35840
	ds_read_b128 v[174:177], v161 offset:36864
	ds_read_b128 v[178:181], v161 offset:37888
	ds_read_b128 v[182:185], v161 offset:38912
	ds_read_b128 v[186:189], v161 offset:39936
	global_load_lds_dwordx4 v144, s[18:19]
	s_mov_b32 m0, s30
	s_nop 0
	global_load_lds_dwordx4 v146, s[18:19]
	s_waitcnt lgkmcnt(8)
	s_barrier
	s_waitcnt lgkmcnt(0)
	v_mfma_f32_16x16x32_bf16 v[140:143], v[64:67], v[154:157], v[140:143]
	v_mfma_f32_16x16x32_bf16 v[136:139], v[72:75], v[154:157], v[136:139]
	v_mfma_f32_16x16x32_bf16 v[132:135], v[64:67], v[166:169], v[132:135]
	v_mfma_f32_16x16x32_bf16 v[128:131], v[72:75], v[166:169], v[128:131]
	s_add_i32 s18, 0, 0x1c000
	s_add_i32 s19, s43, s27
	v_mfma_f32_16x16x32_bf16 v[108:111], v[64:67], v[174:177], v[108:111]
	s_add_i32 m0, s19, 0xffffff80
	v_mfma_f32_16x16x32_bf16 v[104:107], v[72:75], v[174:177], v[104:107]
	v_mfma_f32_16x16x32_bf16 v[100:103], v[64:67], v[182:185], v[100:103]
	v_mfma_f32_16x16x32_bf16 v[96:99], v[72:75], v[182:185], v[96:99]
	v_mfma_f32_16x16x32_bf16 v[140:143], v[68:71], v[162:165], v[140:143]
	v_mfma_f32_16x16x32_bf16 v[136:139], v[76:79], v[162:165], v[136:139]
	v_mfma_f32_16x16x32_bf16 v[132:135], v[68:71], v[170:173], v[132:135]
	v_mfma_f32_16x16x32_bf16 v[128:131], v[76:79], v[170:173], v[128:131]
	v_mfma_f32_16x16x32_bf16 v[108:111], v[68:71], v[178:181], v[108:111]
	v_mfma_f32_16x16x32_bf16 v[104:107], v[76:79], v[178:181], v[104:107]
	v_mfma_f32_16x16x32_bf16 v[100:103], v[68:71], v[186:189], v[100:103]
	v_mfma_f32_16x16x32_bf16 v[96:99], v[76:79], v[186:189], v[96:99]
	s_barrier
	ds_read_b128 v[196:199], v220 offset:49152
	ds_read_b128 v[204:207], v220 offset:50176
	ds_read_b128 v[208:211], v220 offset:51200
	ds_read_b128 v[214:217], v220 offset:52224
	global_load_lds_dwordx4 v192, s[16:17] offset:128
	s_add_i32 m0, s19, 0x1f80
	s_nop 0
	global_load_lds_dwordx4 v148, s[16:17] offset:128
	s_barrier
	s_waitcnt lgkmcnt(0)
	v_mfma_f32_16x16x32_bf16 v[124:127], v[196:199], v[154:157], v[124:127]
	v_mfma_f32_16x16x32_bf16 v[120:123], v[208:211], v[154:157], v[120:123]
	v_mfma_f32_16x16x32_bf16 v[116:119], v[196:199], v[166:169], v[116:119]
	v_mfma_f32_16x16x32_bf16 v[112:115], v[208:211], v[166:169], v[112:115]
	s_mov_b32 m0, s34
	v_mfma_f32_16x16x32_bf16 v[92:95], v[196:199], v[174:177], v[92:95]
	v_mfma_f32_16x16x32_bf16 v[88:91], v[208:211], v[174:177], v[88:91]
	v_mfma_f32_16x16x32_bf16 v[84:87], v[196:199], v[182:185], v[84:87]
	v_mfma_f32_16x16x32_bf16 v[80:83], v[208:211], v[182:185], v[80:83]
	v_mfma_f32_16x16x32_bf16 v[124:127], v[204:207], v[162:165], v[124:127]
	v_mfma_f32_16x16x32_bf16 v[120:123], v[214:217], v[162:165], v[120:123]
	v_mfma_f32_16x16x32_bf16 v[116:119], v[204:207], v[170:173], v[116:119]
	v_mfma_f32_16x16x32_bf16 v[112:115], v[214:217], v[170:173], v[112:115]
	v_mfma_f32_16x16x32_bf16 v[92:95], v[204:207], v[178:181], v[92:95]
	v_mfma_f32_16x16x32_bf16 v[88:91], v[214:217], v[178:181], v[88:91]
	v_mfma_f32_16x16x32_bf16 v[84:87], v[204:207], v[186:189], v[84:87]
	v_mfma_f32_16x16x32_bf16 v[80:83], v[214:217], v[186:189], v[80:83]
	s_barrier
	ds_read_b128 v[154:157], v161 offset:49152
	ds_read_b128 v[162:165], v161 offset:50176
	ds_read_b128 v[166:169], v161 offset:51200
	ds_read_b128 v[170:173], v161 offset:52224
	ds_read_b128 v[174:177], v161 offset:53248
	ds_read_b128 v[178:181], v161 offset:54272
	ds_read_b128 v[182:185], v161 offset:55296
	ds_read_b128 v[186:189], v161 offset:56320
	global_load_lds_dwordx4 v144, s[48:49]
	s_mov_b32 m0, s35
	s_nop 0
	global_load_lds_dwordx4 v146, s[48:49]
	s_barrier
	s_waitcnt lgkmcnt(0)
	v_mfma_f32_16x16x32_bf16 v[60:63], v[64:67], v[154:157], v[60:63]
	v_mfma_f32_16x16x32_bf16 v[56:59], v[72:75], v[154:157], v[56:59]
	v_mfma_f32_16x16x32_bf16 v[52:55], v[64:67], v[166:169], v[52:55]
	v_mfma_f32_16x16x32_bf16 v[48:51], v[72:75], v[166:169], v[48:51]
	s_add_u32 s16, s16, 0x80080
	s_addc_u32 s17, s17, 0
	v_mfma_f32_16x16x32_bf16 v[28:31], v[64:67], v[174:177], v[28:31]
	s_add_i32 s18, s18, s27
	s_mov_b32 m0, s18
	v_mfma_f32_16x16x32_bf16 v[24:27], v[72:75], v[174:177], v[24:27]
	v_mfma_f32_16x16x32_bf16 v[20:23], v[64:67], v[182:185], v[20:23]
	v_mfma_f32_16x16x32_bf16 v[16:19], v[72:75], v[182:185], v[16:19]
	v_mfma_f32_16x16x32_bf16 v[60:63], v[68:71], v[162:165], v[60:63]
	v_mfma_f32_16x16x32_bf16 v[56:59], v[76:79], v[162:165], v[56:59]
	v_mfma_f32_16x16x32_bf16 v[52:55], v[68:71], v[170:173], v[52:55]
	v_mfma_f32_16x16x32_bf16 v[48:51], v[76:79], v[170:173], v[48:51]
	v_mfma_f32_16x16x32_bf16 v[28:31], v[68:71], v[178:181], v[28:31]
	v_mfma_f32_16x16x32_bf16 v[24:27], v[76:79], v[178:181], v[24:27]
	v_mfma_f32_16x16x32_bf16 v[20:23], v[68:71], v[186:189], v[20:23]
	v_mfma_f32_16x16x32_bf16 v[16:19], v[76:79], v[186:189], v[16:19]
	s_barrier
	global_load_lds_dwordx4 v192, s[16:17]
	s_add_i32 m0, s18, 0x2000
	s_nop 0
	global_load_lds_dwordx4 v148, s[16:17]
	s_waitcnt vmcnt(6)
	s_barrier
	v_mfma_f32_16x16x32_bf16 v[44:47], v[196:199], v[154:157], v[44:47]
	v_mfma_f32_16x16x32_bf16 v[40:43], v[208:211], v[154:157], v[40:43]
	v_mfma_f32_16x16x32_bf16 v[36:39], v[196:199], v[166:169], v[36:39]
	v_mfma_f32_16x16x32_bf16 v[32:35], v[208:211], v[166:169], v[32:35]
	s_add_i32 s42, s42, 2
	v_mfma_f32_16x16x32_bf16 v[12:15], v[196:199], v[174:177], v[12:15]
	s_add_u32 s14, s14, 0x100
	s_addc_u32 s15, s15, 0
	v_mfma_f32_16x16x32_bf16 v[8:11], v[208:211], v[174:177], v[8:11]
	s_add_u32 s40, s40, 0x100
	s_addc_u32 s41, s41, 0
	v_mfma_f32_16x16x32_bf16 v[4:7], v[196:199], v[182:185], v[4:7]
	v_mfma_f32_16x16x32_bf16 v[0:3], v[208:211], v[182:185], v[0:3]
	v_mfma_f32_16x16x32_bf16 v[44:47], v[204:207], v[162:165], v[44:47]
	v_mfma_f32_16x16x32_bf16 v[40:43], v[214:217], v[162:165], v[40:43]
	v_mfma_f32_16x16x32_bf16 v[36:39], v[204:207], v[170:173], v[36:39]
	v_mfma_f32_16x16x32_bf16 v[32:35], v[214:217], v[170:173], v[32:35]
	v_mfma_f32_16x16x32_bf16 v[12:15], v[204:207], v[178:181], v[12:15]
	v_mfma_f32_16x16x32_bf16 v[8:11], v[214:217], v[178:181], v[8:11]
	v_mfma_f32_16x16x32_bf16 v[4:7], v[204:207], v[186:189], v[4:7]
	v_mfma_f32_16x16x32_bf16 v[0:3], v[214:217], v[186:189], v[0:3]
	s_cmp_gt_u32 s42, 29
	s_barrier
	s_cbranch_scc0 .LBB0_294
	s_ashr_i32 s5, s12, 4
	v_lshl_or_b32 v190, s37, 8, v160
	s_mul_hi_i32 s7, s5, 0xc000
	s_mul_i32 s5, s5, 0xc000
	s_add_u32 s14, s31, s5
	v_ashrrev_i32_e32 v191, 31, v190
	v_lshl_add_u32 v154, s12, 8, v158
	v_readlane_b32 s52, v254, 23
	s_addc_u32 s15, s33, s7
	v_lshlrev_b64 v[156:157], 2, v[190:191]
	v_readlane_b32 s53, v254, 24
	v_ashrrev_i32_e32 v155, 31, v154
	v_lshl_add_u64 v[68:69], s[14:15], 0, v[156:157]
	v_lshl_add_u64 v[156:157], s[52:53], 0, v[156:157]
	v_lshlrev_b64 v[162:163], 13, v[154:155]
	v_lshl_add_u64 v[174:175], v[156:157], 0, v[162:163]
	global_load_dwordx4 v[72:75], v[68:69], off offset:16
	global_load_dwordx4 v[76:79], v[68:69], off
	global_load_dwordx4 v[64:67], v[68:69], off offset:528
	s_nop 0
	global_load_dwordx4 v[68:71], v[68:69], off offset:512
	s_nop 0
	global_load_dwordx4 v[162:165], v[174:175], off offset:16
	global_load_dwordx4 v[166:169], v[174:175], off
	global_load_dwordx4 v[170:173], v[174:175], off offset:528
	s_nop 0
	global_load_dwordx4 v[174:177], v[174:175], off offset:512
	v_or_b32_e32 v204, 16, v154
	v_ashrrev_i32_e32 v205, 31, v204
	v_lshlrev_b64 v[178:179], 13, v[204:205]
	v_lshl_add_u64 v[196:197], v[156:157], 0, v[178:179]
	global_load_dwordx4 v[178:181], v[196:197], off offset:16
	global_load_dwordx4 v[182:185], v[196:197], off
	global_load_dwordx4 v[186:189], v[196:197], off offset:528
	s_nop 0
	global_load_dwordx4 v[196:199], v[196:197], off offset:512
	v_lshlrev_b64 v[206:207], 12, v[154:155]
	s_and_b64 vcc, exec, s[0:1]
	s_mov_b32 s37, s4
	s_mov_b32 s12, s6
	s_mov_b64 s[16:17], s[10:11]
	s_mov_b64 s[14:15], s[8:9]
	s_mov_b32 s11, 0xc000
	v_readlane_b32 s54, v254, 25
	v_readlane_b32 s55, v254, 26
	v_readlane_b32 s56, v254, 27
	v_readlane_b32 s57, v254, 28
	v_readlane_b32 s58, v254, 29
	v_readlane_b32 s59, v254, 30
	v_readlane_b32 s60, v254, 31
	v_readlane_b32 s61, v254, 32
	v_readlane_b32 s62, v254, 33
	v_readlane_b32 s63, v254, 34
	v_readlane_b32 s64, v254, 35
	v_readlane_b32 s65, v254, 36
	v_readlane_b32 s66, v254, 37
	v_readlane_b32 s67, v254, 38
	s_waitcnt vmcnt(0)
	v_pk_fma_f32 v[136:137], v[136:137], v[72:73], v[162:163]
	v_pk_fma_f32 v[142:143], v[142:143], v[78:79], v[168:169]
	v_pk_fma_f32 v[140:141], v[140:141], v[76:77], v[166:167]
	v_pk_fma_f32 v[164:165], v[138:139], v[74:75], v[164:165]
	v_cvt_pk_bf16_f32 v138, v140, v141
	v_cvt_pk_bf16_f32 v139, v142, v143
	v_cvt_pk_bf16_f32 v140, v136, v137
	v_lshl_add_u64 v[142:143], s[2:3], 0, v[206:207]
	v_lshlrev_b64 v[136:137], 1, v[190:191]
	v_lshl_add_u64 v[142:143], v[142:143], 0, v[136:137]
	v_pk_fma_f32 v[124:125], v[124:125], v[68:69], v[174:175]
	v_cvt_pk_bf16_f32 v141, v164, v165
	global_store_dwordx4 v[142:143], v[138:141], off
	v_pk_fma_f32 v[126:127], v[126:127], v[70:71], v[176:177]
	v_pk_fma_f32 v[128:129], v[128:129], v[72:73], v[178:179]
	v_pk_fma_f32 v[138:139], v[122:123], v[66:67], v[172:173]
	v_pk_fma_f32 v[122:123], v[120:121], v[64:65], v[170:171]
	v_cvt_pk_bf16_f32 v120, v124, v125
	v_cvt_pk_bf16_f32 v121, v126, v127
	v_lshlrev_b64 v[124:125], 12, v[204:205]
	v_cvt_pk_bf16_f32 v122, v122, v123
	v_cvt_pk_bf16_f32 v123, v138, v139
	global_store_dwordx4 v[142:143], v[120:123], off offset:256
	v_lshl_add_u64 v[124:125], s[2:3], 0, v[124:125]
	v_lshl_add_u64 v[124:125], v[124:125], 0, v[136:137]
	v_pk_fma_f32 v[120:121], v[132:133], v[76:77], v[182:183]
	v_pk_fma_f32 v[122:123], v[134:135], v[78:79], v[184:185]
	v_cvt_pk_bf16_f32 v120, v120, v121
	v_or_b32_e32 v142, 32, v154
	v_cvt_pk_bf16_f32 v121, v122, v123
	v_pk_fma_f32 v[126:127], v[130:131], v[74:75], v[180:181]
	v_cvt_pk_bf16_f32 v122, v128, v129
	v_pk_fma_f32 v[118:119], v[118:119], v[70:71], v[198:199]
	v_cvt_pk_bf16_f32 v123, v126, v127
	global_store_dwordx4 v[124:125], v[120:123], off
	v_pk_fma_f32 v[116:117], v[116:117], v[68:69], v[196:197]
	v_ashrrev_i32_e32 v143, 31, v142
	v_pk_fma_f32 v[120:121], v[114:115], v[66:67], v[188:189]
	v_pk_fma_f32 v[114:115], v[112:113], v[64:65], v[186:187]
	v_cvt_pk_bf16_f32 v112, v116, v117
	v_cvt_pk_bf16_f32 v113, v118, v119
	v_or_b32_e32 v166, 48, v154
	v_cvt_pk_bf16_f32 v114, v114, v115
	v_cvt_pk_bf16_f32 v115, v120, v121
	global_store_dwordx4 v[124:125], v[112:115], off offset:256
	v_ashrrev_i32_e32 v167, 31, v166
	v_lshlrev_b64 v[128:129], 13, v[166:167]
	v_lshlrev_b64 v[112:113], 13, v[142:143]
	v_lshl_add_u64 v[124:125], v[156:157], 0, v[112:113]
	global_load_dwordx4 v[112:115], v[124:125], off offset:16
	global_load_dwordx4 v[116:119], v[124:125], off
	global_load_dwordx4 v[120:123], v[124:125], off offset:528
	s_nop 0
	global_load_dwordx4 v[124:127], v[124:125], off offset:512
	v_lshl_add_u64 v[162:163], v[156:157], 0, v[128:129]
	global_load_dwordx4 v[128:131], v[162:163], off offset:16
	global_load_dwordx4 v[132:135], v[162:163], off
	global_load_dwordx4 v[138:141], v[162:163], off offset:528
	s_nop 0
	global_load_dwordx4 v[162:165], v[162:163], off offset:512
	v_lshlrev_b64 v[142:143], 12, v[142:143]
	s_waitcnt vmcnt(0)
	v_pk_fma_f32 v[114:115], v[106:107], v[74:75], v[114:115]
	v_pk_fma_f32 v[108:109], v[108:109], v[76:77], v[116:117]
	v_pk_fma_f32 v[106:107], v[104:105], v[72:73], v[112:113]
	v_cvt_pk_bf16_f32 v104, v108, v109
	v_lshl_add_u64 v[108:109], s[2:3], 0, v[142:143]
	v_pk_fma_f32 v[110:111], v[110:111], v[78:79], v[118:119]
	v_lshl_add_u64 v[108:109], v[108:109], 0, v[136:137]
	v_cvt_pk_bf16_f32 v105, v110, v111
	v_pk_fma_f32 v[92:93], v[92:93], v[68:69], v[124:125]
	v_cvt_pk_bf16_f32 v106, v106, v107
	v_cvt_pk_bf16_f32 v107, v114, v115
	global_store_dwordx4 v[108:109], v[104:107], off
	v_pk_fma_f32 v[94:95], v[94:95], v[70:71], v[126:127]
	v_add_u32_e32 v112, 0x80, v154
	v_pk_fma_f32 v[104:105], v[90:91], v[66:67], v[122:123]
	v_pk_fma_f32 v[90:91], v[88:89], v[64:65], v[120:121]
	v_cvt_pk_bf16_f32 v88, v92, v93
	v_cvt_pk_bf16_f32 v89, v94, v95
	v_lshlrev_b64 v[92:93], 12, v[166:167]
	v_cvt_pk_bf16_f32 v90, v90, v91
	v_cvt_pk_bf16_f32 v91, v104, v105
	global_store_dwordx4 v[108:109], v[88:91], off offset:256
	v_lshl_add_u64 v[92:93], s[2:3], 0, v[92:93]
	v_lshl_add_u64 v[92:93], v[92:93], 0, v[136:137]
	v_pk_fma_f32 v[88:89], v[100:101], v[76:77], v[132:133]
	v_pk_fma_f32 v[90:91], v[102:103], v[78:79], v[134:135]
	v_cvt_pk_bf16_f32 v88, v88, v89
	v_pk_fma_f32 v[94:95], v[98:99], v[74:75], v[130:131]
	v_cvt_pk_bf16_f32 v89, v90, v91
	v_pk_fma_f32 v[96:97], v[96:97], v[72:73], v[128:129]
	v_pk_fma_f32 v[86:87], v[86:87], v[70:71], v[164:165]
	v_cvt_pk_bf16_f32 v90, v96, v97
	v_cvt_pk_bf16_f32 v91, v94, v95
	global_store_dwordx4 v[92:93], v[88:91], off
	v_pk_fma_f32 v[84:85], v[84:85], v[68:69], v[162:163]
	v_ashrrev_i32_e32 v113, 31, v112
	v_pk_fma_f32 v[88:89], v[82:83], v[66:67], v[140:141]
	v_pk_fma_f32 v[82:83], v[80:81], v[64:65], v[138:139]
	v_cvt_pk_bf16_f32 v80, v84, v85
	v_cvt_pk_bf16_f32 v81, v86, v87
	v_add_u32_e32 v114, 0x90, v154
	v_cvt_pk_bf16_f32 v82, v82, v83
	v_cvt_pk_bf16_f32 v83, v88, v89
	global_store_dwordx4 v[92:93], v[80:83], off offset:256
	v_ashrrev_i32_e32 v115, 31, v114
	v_lshlrev_b64 v[96:97], 13, v[114:115]
	v_lshlrev_b64 v[80:81], 13, v[112:113]
	v_lshl_add_u64 v[92:93], v[156:157], 0, v[80:81]
	global_load_dwordx4 v[80:83], v[92:93], off offset:16
	global_load_dwordx4 v[84:87], v[92:93], off
	global_load_dwordx4 v[88:91], v[92:93], off offset:528
	s_nop 0
	global_load_dwordx4 v[92:95], v[92:93], off offset:512
	v_lshl_add_u64 v[108:109], v[156:157], 0, v[96:97]
	global_load_dwordx4 v[96:99], v[108:109], off offset:16
	global_load_dwordx4 v[100:103], v[108:109], off
	global_load_dwordx4 v[104:107], v[108:109], off offset:528
	s_nop 0
	global_load_dwordx4 v[108:111], v[108:109], off offset:512
	v_lshlrev_b64 v[112:113], 12, v[112:113]
	s_waitcnt vmcnt(0)
	v_pk_fma_f32 v[82:83], v[58:59], v[74:75], v[82:83]
	v_pk_fma_f32 v[60:61], v[60:61], v[76:77], v[84:85]
	v_pk_fma_f32 v[58:59], v[56:57], v[72:73], v[80:81]
	v_cvt_pk_bf16_f32 v56, v60, v61
	v_lshl_add_u64 v[60:61], s[2:3], 0, v[112:113]
	v_pk_fma_f32 v[62:63], v[62:63], v[78:79], v[86:87]
	v_lshl_add_u64 v[60:61], v[60:61], 0, v[136:137]
	v_cvt_pk_bf16_f32 v57, v62, v63
	v_pk_fma_f32 v[44:45], v[44:45], v[68:69], v[92:93]
	v_cvt_pk_bf16_f32 v58, v58, v59
	v_cvt_pk_bf16_f32 v59, v82, v83
	global_store_dwordx4 v[60:61], v[56:59], off
	v_pk_fma_f32 v[46:47], v[46:47], v[70:71], v[94:95]
	v_add_u32_e32 v80, 0xa0, v154
	v_pk_fma_f32 v[56:57], v[42:43], v[66:67], v[90:91]
	v_pk_fma_f32 v[42:43], v[40:41], v[64:65], v[88:89]
	v_cvt_pk_bf16_f32 v40, v44, v45
	v_cvt_pk_bf16_f32 v41, v46, v47
	v_lshlrev_b64 v[44:45], 12, v[114:115]
	v_cvt_pk_bf16_f32 v42, v42, v43
	v_cvt_pk_bf16_f32 v43, v56, v57
	global_store_dwordx4 v[60:61], v[40:43], off offset:256
	v_lshl_add_u64 v[44:45], s[2:3], 0, v[44:45]
	v_lshl_add_u64 v[44:45], v[44:45], 0, v[136:137]
	v_pk_fma_f32 v[40:41], v[52:53], v[76:77], v[100:101]
	v_pk_fma_f32 v[42:43], v[54:55], v[78:79], v[102:103]
	v_cvt_pk_bf16_f32 v40, v40, v41
	v_pk_fma_f32 v[46:47], v[50:51], v[74:75], v[98:99]
	v_cvt_pk_bf16_f32 v41, v42, v43
	v_pk_fma_f32 v[48:49], v[48:49], v[72:73], v[96:97]
	v_pk_fma_f32 v[38:39], v[38:39], v[70:71], v[110:111]
	v_cvt_pk_bf16_f32 v42, v48, v49
	v_cvt_pk_bf16_f32 v43, v46, v47
	global_store_dwordx4 v[44:45], v[40:43], off
	v_pk_fma_f32 v[36:37], v[36:37], v[68:69], v[108:109]
	v_ashrrev_i32_e32 v81, 31, v80
	v_pk_fma_f32 v[40:41], v[34:35], v[66:67], v[106:107]
	v_pk_fma_f32 v[34:35], v[32:33], v[64:65], v[104:105]
	v_cvt_pk_bf16_f32 v32, v36, v37
	v_cvt_pk_bf16_f32 v33, v38, v39
	v_add_u32_e32 v82, 0xb0, v154
	v_cvt_pk_bf16_f32 v34, v34, v35
	v_cvt_pk_bf16_f32 v35, v40, v41
	global_store_dwordx4 v[44:45], v[32:35], off offset:256
	v_ashrrev_i32_e32 v83, 31, v82
	v_lshlrev_b64 v[48:49], 13, v[82:83]
	v_lshlrev_b64 v[32:33], 13, v[80:81]
	v_lshl_add_u64 v[44:45], v[156:157], 0, v[32:33]
	global_load_dwordx4 v[32:35], v[44:45], off offset:16
	global_load_dwordx4 v[36:39], v[44:45], off
	global_load_dwordx4 v[40:43], v[44:45], off offset:528
	s_nop 0
	global_load_dwordx4 v[44:47], v[44:45], off offset:512
	v_lshl_add_u64 v[60:61], v[156:157], 0, v[48:49]
	global_load_dwordx4 v[48:51], v[60:61], off offset:16
	global_load_dwordx4 v[52:55], v[60:61], off
	global_load_dwordx4 v[56:59], v[60:61], off offset:528
	s_nop 0
	global_load_dwordx4 v[60:63], v[60:61], off offset:512
	v_lshlrev_b64 v[80:81], 12, v[80:81]
	s_waitcnt vmcnt(0)
	v_pk_fma_f32 v[34:35], v[26:27], v[74:75], v[34:35]
	v_pk_fma_f32 v[28:29], v[28:29], v[76:77], v[36:37]
	v_pk_fma_f32 v[26:27], v[24:25], v[72:73], v[32:33]
	v_cvt_pk_bf16_f32 v24, v28, v29
	v_lshl_add_u64 v[28:29], s[2:3], 0, v[80:81]
	v_pk_fma_f32 v[30:31], v[30:31], v[78:79], v[38:39]
	v_lshl_add_u64 v[28:29], v[28:29], 0, v[136:137]
	v_cvt_pk_bf16_f32 v25, v30, v31
	v_pk_fma_f32 v[12:13], v[12:13], v[68:69], v[44:45]
	v_cvt_pk_bf16_f32 v26, v26, v27
	v_cvt_pk_bf16_f32 v27, v34, v35
	global_store_dwordx4 v[28:29], v[24:27], off
	v_pk_fma_f32 v[14:15], v[14:15], v[70:71], v[46:47]
	v_pk_fma_f32 v[16:17], v[16:17], v[72:73], v[48:49]
	v_pk_fma_f32 v[24:25], v[10:11], v[66:67], v[42:43]
	v_pk_fma_f32 v[10:11], v[8:9], v[64:65], v[40:41]
	v_cvt_pk_bf16_f32 v8, v12, v13
	v_cvt_pk_bf16_f32 v9, v14, v15
	v_lshlrev_b64 v[12:13], 12, v[82:83]
	v_cvt_pk_bf16_f32 v10, v10, v11
	v_cvt_pk_bf16_f32 v11, v24, v25
	global_store_dwordx4 v[28:29], v[8:11], off offset:256
	v_lshl_add_u64 v[12:13], s[2:3], 0, v[12:13]
	v_lshl_add_u64 v[12:13], v[12:13], 0, v[136:137]
	v_pk_fma_f32 v[8:9], v[20:21], v[76:77], v[52:53]
	v_pk_fma_f32 v[10:11], v[22:23], v[78:79], v[54:55]
	v_cvt_pk_bf16_f32 v8, v8, v9
	v_pk_fma_f32 v[14:15], v[18:19], v[74:75], v[50:51]
	v_cvt_pk_bf16_f32 v9, v10, v11
	v_cvt_pk_bf16_f32 v10, v16, v17
	v_pk_fma_f32 v[6:7], v[6:7], v[70:71], v[62:63]
	v_cvt_pk_bf16_f32 v11, v14, v15
	global_store_dwordx4 v[12:13], v[8:11], off
	v_pk_fma_f32 v[4:5], v[4:5], v[68:69], v[60:61]
	s_nop 0
	v_pk_fma_f32 v[8:9], v[2:3], v[66:67], v[58:59]
	v_pk_fma_f32 v[2:3], v[0:1], v[64:65], v[56:57]
	v_cvt_pk_bf16_f32 v0, v4, v5
	v_cvt_pk_bf16_f32 v1, v6, v7
	s_nop 0
	v_cvt_pk_bf16_f32 v2, v2, v3
	v_cvt_pk_bf16_f32 v3, v8, v9
	global_store_dwordx4 v[12:13], v[0:3], off offset:256
	s_cbranch_vccz .LBB0_287
	s_waitcnt vmcnt(0)
	s_cmpk_gt_u32 s25, 0xff
	s_cbranch_scc1 .LBB0_298
	s_barrier

.LBB0_414:
	s_ashr_i32 s9, s8, 31
	v_cmp_lt_i64_e32 vcc, s[10:11], v[202:203]
	s_lshl_b64 s[10:11], s[8:9], 20
	s_add_u32 s10, s24, s10
	s_addc_u32 s11, s25, s11
	s_and_b64 s[12:13], vcc, exec
	s_cselect_b32 s9, s11, s17
	s_cselect_b32 s38, s10, s16
	s_ashr_i32 s7, s6, 31
	s_lshl_b64 s[12:13], s[6:7], 20
	s_add_u32 s12, s26, s12
	s_addc_u32 s13, s27, s13
	s_and_b64 s[20:21], vcc, exec
	s_cselect_b32 s7, s13, s19
	s_cselect_b32 s39, s12, s18
	s_add_u32 s16, s16, 0x80080
	s_addc_u32 s17, s17, 0
	s_add_u32 s40, s18, 0x100
	s_addc_u32 s41, s19, 0
	s_mov_b32 s42, -2
	s_mov_b64 s[48:49], 0x80
	v_add_u32_e32 v196, 0x10000, v143
	s_add_u32 s18, s16, 0xfff80080
	s_addc_u32 s19, s17, -1
	s_add_i32 s43, 0, 0x10000
	ds_read_b128 v[146:149], v196 offset:0
	ds_read_b128 v[150:153], v196 offset:1024
	ds_read_b128 v[154:157], v196 offset:2048
	ds_read_b128 v[158:161], v196 offset:3072
	s_cmp_eq_u32 s42, 28
	s_cselect_b32 s21, s9, s19
	s_cselect_b32 s20, s38, s18
	s_cselect_b32 s19, s7, s41
	s_cselect_b32 s18, s39, s40
	s_add_i32 m0, s30, 0xc000
	ds_read_b128 v[162:165], v145
	ds_read_b128 v[166:169], v145 offset:1024
	ds_read_b128 v[170:173], v145 offset:2048
	ds_read_b128 v[174:177], v145 offset:3072
	ds_read_b128 v[178:181], v145 offset:4096
	ds_read_b128 v[182:185], v145 offset:5120
	ds_read_b128 v[186:189], v145 offset:6144
	ds_read_b128 v[204:207], v145 offset:7168
	global_load_lds_dwordx4 v136, s[16:17]
	s_add_i32 m0, s30, 0xe000
	s_nop 0
	global_load_lds_dwordx4 v138, s[16:17]
	s_waitcnt lgkmcnt(8)
	s_barrier
	s_waitcnt lgkmcnt(0)
	v_mfma_f32_16x16x32_bf16 v[124:127], v[146:149], v[162:165], 0
	v_mfma_f32_16x16x32_bf16 v[120:123], v[154:157], v[162:165], 0
	v_mfma_f32_16x16x32_bf16 v[116:119], v[146:149], v[170:173], 0
	v_mfma_f32_16x16x32_bf16 v[108:111], v[154:157], v[170:173], 0
	s_add_i32 s46, 0, 0x14000
	s_add_i32 s43, s43, s28
	v_mfma_f32_16x16x32_bf16 v[100:103], v[146:149], v[178:181], 0
	s_mov_b32 m0, s43
	v_mfma_f32_16x16x32_bf16 v[92:95], v[154:157], v[178:181], 0
	v_mfma_f32_16x16x32_bf16 v[84:87], v[146:149], v[186:189], 0
	v_mfma_f32_16x16x32_bf16 v[76:79], v[154:157], v[186:189], 0
	v_mfma_f32_16x16x32_bf16 v[124:127], v[150:153], v[166:169], v[124:127]
	v_mfma_f32_16x16x32_bf16 v[120:123], v[158:161], v[166:169], v[120:123]
	v_mfma_f32_16x16x32_bf16 v[116:119], v[150:153], v[174:177], v[116:119]
	v_mfma_f32_16x16x32_bf16 v[108:111], v[158:161], v[174:177], v[108:111]
	v_mfma_f32_16x16x32_bf16 v[100:103], v[150:153], v[182:185], v[100:103]
	v_mfma_f32_16x16x32_bf16 v[92:95], v[158:161], v[182:185], v[92:95]
	v_mfma_f32_16x16x32_bf16 v[84:87], v[150:153], v[204:207], v[84:87]
	v_mfma_f32_16x16x32_bf16 v[76:79], v[158:161], v[204:207], v[76:79]
	s_barrier
	ds_read_b128 v[208:211], v196 offset:16384
	ds_read_b128 v[214:217], v196 offset:17408
	ds_read_b128 v[218:221], v196 offset:18432
	ds_read_b128 v[222:225], v196 offset:19456
	global_load_lds_dwordx4 v192, s[18:19]
	s_add_i32 m0, s43, 0x2000
	s_nop 0
	global_load_lds_dwordx4 v128, s[18:19]
	s_barrier
	s_waitcnt lgkmcnt(0)
	v_mfma_f32_16x16x32_bf16 v[112:115], v[208:211], v[162:165], 0
	v_mfma_f32_16x16x32_bf16 v[104:107], v[218:221], v[162:165], 0
	v_mfma_f32_16x16x32_bf16 v[96:99], v[208:211], v[170:173], 0
	v_mfma_f32_16x16x32_bf16 v[88:91], v[218:221], v[170:173], 0
	s_mov_b32 m0, s30
	v_mfma_f32_16x16x32_bf16 v[80:83], v[208:211], v[178:181], 0
	s_add_u32 s48, s20, 0x80
	s_addc_u32 s49, s21, 0
	v_mfma_f32_16x16x32_bf16 v[72:75], v[218:221], v[178:181], 0
	v_mfma_f32_16x16x32_bf16 v[68:71], v[208:211], v[186:189], 0
	v_mfma_f32_16x16x32_bf16 v[64:67], v[218:221], v[186:189], 0
	v_mfma_f32_16x16x32_bf16 v[112:115], v[214:217], v[166:169], v[112:115]
	v_mfma_f32_16x16x32_bf16 v[104:107], v[222:225], v[166:169], v[104:107]
	v_mfma_f32_16x16x32_bf16 v[96:99], v[214:217], v[174:177], v[96:99]
	v_mfma_f32_16x16x32_bf16 v[88:91], v[222:225], v[174:177], v[88:91]
	v_mfma_f32_16x16x32_bf16 v[80:83], v[214:217], v[182:185], v[80:83]
	v_mfma_f32_16x16x32_bf16 v[72:75], v[222:225], v[182:185], v[72:75]
	v_mfma_f32_16x16x32_bf16 v[68:71], v[214:217], v[204:207], v[68:71]
	v_mfma_f32_16x16x32_bf16 v[64:67], v[222:225], v[204:207], v[64:67]
	s_barrier
	ds_read_b128 v[162:165], v145 offset:16384
	ds_read_b128 v[166:169], v145 offset:17408
	ds_read_b128 v[170:173], v145 offset:18432
	ds_read_b128 v[174:177], v145 offset:19456
	ds_read_b128 v[178:181], v145 offset:20480
	ds_read_b128 v[182:185], v145 offset:21504
	ds_read_b128 v[186:189], v145 offset:22528
	ds_read_b128 v[204:207], v145 offset:23552
	global_load_lds_dwordx4 v132, s[20:21]
	s_mov_b32 m0, s31
	s_nop 0
	global_load_lds_dwordx4 v130, s[20:21]
	s_barrier
	s_waitcnt lgkmcnt(0)
	v_mfma_f32_16x16x32_bf16 v[60:63], v[146:149], v[162:165], 0
	v_mfma_f32_16x16x32_bf16 v[56:59], v[154:157], v[162:165], 0
	v_mfma_f32_16x16x32_bf16 v[52:55], v[146:149], v[170:173], 0
	v_mfma_f32_16x16x32_bf16 v[44:47], v[154:157], v[170:173], 0
	s_add_u32 s44, s18, 0x80000
	s_addc_u32 s45, s19, 0
	v_mfma_f32_16x16x32_bf16 v[36:39], v[146:149], v[178:181], 0
	s_add_i32 s43, s46, s28
	s_mov_b32 m0, s43
	v_mfma_f32_16x16x32_bf16 v[28:31], v[154:157], v[178:181], 0
	v_mfma_f32_16x16x32_bf16 v[20:23], v[146:149], v[186:189], 0
	v_mfma_f32_16x16x32_bf16 v[12:15], v[154:157], v[186:189], 0
	v_mfma_f32_16x16x32_bf16 v[60:63], v[150:153], v[166:169], v[60:63]
	v_mfma_f32_16x16x32_bf16 v[56:59], v[158:161], v[166:169], v[56:59]
	v_mfma_f32_16x16x32_bf16 v[52:55], v[150:153], v[174:177], v[52:55]
	v_mfma_f32_16x16x32_bf16 v[44:47], v[158:161], v[174:177], v[44:47]
	v_mfma_f32_16x16x32_bf16 v[36:39], v[150:153], v[182:185], v[36:39]
	v_mfma_f32_16x16x32_bf16 v[28:31], v[158:161], v[182:185], v[28:31]
	v_mfma_f32_16x16x32_bf16 v[20:23], v[150:153], v[204:207], v[20:23]
	v_mfma_f32_16x16x32_bf16 v[12:15], v[158:161], v[204:207], v[12:15]
	s_barrier
	global_load_lds_dwordx4 v192, s[44:45]
	s_add_i32 m0, s43, 0x2000
	s_nop 0
	global_load_lds_dwordx4 v128, s[44:45]
	s_waitcnt vmcnt(6)
	s_barrier
	v_mfma_f32_16x16x32_bf16 v[48:51], v[208:211], v[162:165], 0
	v_mfma_f32_16x16x32_bf16 v[40:43], v[218:221], v[162:165], 0
	v_mfma_f32_16x16x32_bf16 v[32:35], v[208:211], v[170:173], 0
	v_mfma_f32_16x16x32_bf16 v[24:27], v[218:221], v[170:173], 0
	s_add_i32 s43, 0, 0x18000
	v_mfma_f32_16x16x32_bf16 v[16:19], v[208:211], v[178:181], 0
	s_add_u32 s20, s20, 0x80000
	s_addc_u32 s21, s21, 0
	v_mfma_f32_16x16x32_bf16 v[8:11], v[218:221], v[178:181], 0
	s_mov_b32 m0, s33
	v_mfma_f32_16x16x32_bf16 v[4:7], v[208:211], v[186:189], 0
	v_mfma_f32_16x16x32_bf16 v[0:3], v[218:221], v[186:189], 0
	v_mfma_f32_16x16x32_bf16 v[48:51], v[214:217], v[166:169], v[48:51]
	v_mfma_f32_16x16x32_bf16 v[40:43], v[222:225], v[166:169], v[40:43]
	v_mfma_f32_16x16x32_bf16 v[32:35], v[214:217], v[174:177], v[32:35]
	v_mfma_f32_16x16x32_bf16 v[24:27], v[222:225], v[174:177], v[24:27]
	v_mfma_f32_16x16x32_bf16 v[16:19], v[214:217], v[182:185], v[16:19]
	v_mfma_f32_16x16x32_bf16 v[8:11], v[222:225], v[182:185], v[8:11]
	v_mfma_f32_16x16x32_bf16 v[4:7], v[214:217], v[204:207], v[4:7]
	v_mfma_f32_16x16x32_bf16 v[0:3], v[222:225], v[204:207], v[0:3]
	s_barrier
	ds_read_b128 v[146:149], v196 offset:32768
	ds_read_b128 v[150:153], v196 offset:33792
	ds_read_b128 v[154:157], v196 offset:34816
	ds_read_b128 v[158:161], v196 offset:35840
	ds_read_b128 v[162:165], v145 offset:32768
	ds_read_b128 v[166:169], v145 offset:33792
	ds_read_b128 v[170:173], v145 offset:34816
	ds_read_b128 v[174:177], v145 offset:35840
	ds_read_b128 v[178:181], v145 offset:36864
	ds_read_b128 v[182:185], v145 offset:37888
	ds_read_b128 v[186:189], v145 offset:38912
	ds_read_b128 v[204:207], v145 offset:39936
	global_load_lds_dwordx4 v132, s[20:21]
	s_mov_b32 m0, s34
	s_nop 0
	global_load_lds_dwordx4 v130, s[20:21]
	s_waitcnt lgkmcnt(8)
	s_barrier
	s_waitcnt lgkmcnt(0)
	v_mfma_f32_16x16x32_bf16 v[124:127], v[146:149], v[162:165], v[124:127]
	v_mfma_f32_16x16x32_bf16 v[120:123], v[154:157], v[162:165], v[120:123]
	v_mfma_f32_16x16x32_bf16 v[116:119], v[146:149], v[170:173], v[116:119]
	v_mfma_f32_16x16x32_bf16 v[108:111], v[154:157], v[170:173], v[108:111]
	s_add_i32 s20, 0, 0x1c000
	s_add_i32 s21, s43, s28
	v_mfma_f32_16x16x32_bf16 v[100:103], v[146:149], v[178:181], v[100:103]
	s_add_i32 m0, s21, 0xffffff80
	v_mfma_f32_16x16x32_bf16 v[92:95], v[154:157], v[178:181], v[92:95]
	v_mfma_f32_16x16x32_bf16 v[84:87], v[146:149], v[186:189], v[84:87]
	v_mfma_f32_16x16x32_bf16 v[76:79], v[154:157], v[186:189], v[76:79]
	v_mfma_f32_16x16x32_bf16 v[124:127], v[150:153], v[166:169], v[124:127]
	v_mfma_f32_16x16x32_bf16 v[120:123], v[158:161], v[166:169], v[120:123]
	v_mfma_f32_16x16x32_bf16 v[116:119], v[150:153], v[174:177], v[116:119]
	v_mfma_f32_16x16x32_bf16 v[108:111], v[158:161], v[174:177], v[108:111]
	v_mfma_f32_16x16x32_bf16 v[100:103], v[150:153], v[182:185], v[100:103]
	v_mfma_f32_16x16x32_bf16 v[92:95], v[158:161], v[182:185], v[92:95]
	v_mfma_f32_16x16x32_bf16 v[84:87], v[150:153], v[204:207], v[84:87]
	v_mfma_f32_16x16x32_bf16 v[76:79], v[158:161], v[204:207], v[76:79]
	s_barrier
	ds_read_b128 v[208:211], v196 offset:49152
	ds_read_b128 v[214:217], v196 offset:50176
	ds_read_b128 v[218:221], v196 offset:51200
	ds_read_b128 v[222:225], v196 offset:52224
	global_load_lds_dwordx4 v192, s[18:19] offset:128
	s_add_i32 m0, s21, 0x1f80
	s_nop 0
	global_load_lds_dwordx4 v128, s[18:19] offset:128
	s_barrier
	s_waitcnt lgkmcnt(0)
	v_mfma_f32_16x16x32_bf16 v[112:115], v[208:211], v[162:165], v[112:115]
	v_mfma_f32_16x16x32_bf16 v[104:107], v[218:221], v[162:165], v[104:107]
	v_mfma_f32_16x16x32_bf16 v[96:99], v[208:211], v[170:173], v[96:99]
	v_mfma_f32_16x16x32_bf16 v[88:91], v[218:221], v[170:173], v[88:91]
	s_mov_b32 m0, s35
	v_mfma_f32_16x16x32_bf16 v[80:83], v[208:211], v[178:181], v[80:83]
	v_mfma_f32_16x16x32_bf16 v[72:75], v[218:221], v[178:181], v[72:75]
	v_mfma_f32_16x16x32_bf16 v[68:71], v[208:211], v[186:189], v[68:71]
	v_mfma_f32_16x16x32_bf16 v[64:67], v[218:221], v[186:189], v[64:67]
	v_mfma_f32_16x16x32_bf16 v[112:115], v[214:217], v[166:169], v[112:115]
	v_mfma_f32_16x16x32_bf16 v[104:107], v[222:225], v[166:169], v[104:107]
	v_mfma_f32_16x16x32_bf16 v[96:99], v[214:217], v[174:177], v[96:99]
	v_mfma_f32_16x16x32_bf16 v[88:91], v[222:225], v[174:177], v[88:91]
	v_mfma_f32_16x16x32_bf16 v[80:83], v[214:217], v[182:185], v[80:83]
	v_mfma_f32_16x16x32_bf16 v[72:75], v[222:225], v[182:185], v[72:75]
	v_mfma_f32_16x16x32_bf16 v[68:71], v[214:217], v[204:207], v[68:71]
	v_mfma_f32_16x16x32_bf16 v[64:67], v[222:225], v[204:207], v[64:67]
	s_barrier
	ds_read_b128 v[162:165], v145 offset:49152
	ds_read_b128 v[166:169], v145 offset:50176
	ds_read_b128 v[170:173], v145 offset:51200
	ds_read_b128 v[174:177], v145 offset:52224
	ds_read_b128 v[178:181], v145 offset:53248
	ds_read_b128 v[182:185], v145 offset:54272
	ds_read_b128 v[186:189], v145 offset:55296
	ds_read_b128 v[204:207], v145 offset:56320
	global_load_lds_dwordx4 v132, s[48:49]
	s_mov_b32 m0, s36
	s_nop 0
	global_load_lds_dwordx4 v130, s[48:49]
	s_barrier
	s_waitcnt lgkmcnt(0)
	v_mfma_f32_16x16x32_bf16 v[60:63], v[146:149], v[162:165], v[60:63]
	v_mfma_f32_16x16x32_bf16 v[56:59], v[154:157], v[162:165], v[56:59]
	v_mfma_f32_16x16x32_bf16 v[52:55], v[146:149], v[170:173], v[52:55]
	v_mfma_f32_16x16x32_bf16 v[44:47], v[154:157], v[170:173], v[44:47]
	s_add_u32 s18, s18, 0x80080
	s_addc_u32 s19, s19, 0
	v_mfma_f32_16x16x32_bf16 v[36:39], v[146:149], v[178:181], v[36:39]
	s_add_i32 s20, s20, s28
	s_mov_b32 m0, s20
	v_mfma_f32_16x16x32_bf16 v[28:31], v[154:157], v[178:181], v[28:31]
	v_mfma_f32_16x16x32_bf16 v[20:23], v[146:149], v[186:189], v[20:23]
	v_mfma_f32_16x16x32_bf16 v[12:15], v[154:157], v[186:189], v[12:15]
	v_mfma_f32_16x16x32_bf16 v[60:63], v[150:153], v[166:169], v[60:63]
	v_mfma_f32_16x16x32_bf16 v[56:59], v[158:161], v[166:169], v[56:59]
	v_mfma_f32_16x16x32_bf16 v[52:55], v[150:153], v[174:177], v[52:55]
	v_mfma_f32_16x16x32_bf16 v[44:47], v[158:161], v[174:177], v[44:47]
	v_mfma_f32_16x16x32_bf16 v[36:39], v[150:153], v[182:185], v[36:39]
	v_mfma_f32_16x16x32_bf16 v[28:31], v[158:161], v[182:185], v[28:31]
	v_mfma_f32_16x16x32_bf16 v[20:23], v[150:153], v[204:207], v[20:23]
	v_mfma_f32_16x16x32_bf16 v[12:15], v[158:161], v[204:207], v[12:15]
	s_barrier
	global_load_lds_dwordx4 v192, s[18:19]
	s_add_i32 m0, s20, 0x2000
	s_nop 0
	global_load_lds_dwordx4 v128, s[18:19]
	s_waitcnt vmcnt(6)
	s_barrier
	v_mfma_f32_16x16x32_bf16 v[48:51], v[208:211], v[162:165], v[48:51]
	v_mfma_f32_16x16x32_bf16 v[40:43], v[218:221], v[162:165], v[40:43]
	v_mfma_f32_16x16x32_bf16 v[32:35], v[208:211], v[170:173], v[32:35]
	v_mfma_f32_16x16x32_bf16 v[24:27], v[218:221], v[170:173], v[24:27]
	s_add_i32 s42, s42, 2
	v_mfma_f32_16x16x32_bf16 v[16:19], v[208:211], v[178:181], v[16:19]
	s_add_u32 s16, s16, 0x100
	s_addc_u32 s17, s17, 0
	v_mfma_f32_16x16x32_bf16 v[8:11], v[218:221], v[178:181], v[8:11]
	s_add_u32 s40, s40, 0x100
	s_addc_u32 s41, s41, 0
	v_mfma_f32_16x16x32_bf16 v[4:7], v[208:211], v[186:189], v[4:7]
	v_mfma_f32_16x16x32_bf16 v[0:3], v[218:221], v[186:189], v[0:3]
	v_mfma_f32_16x16x32_bf16 v[48:51], v[214:217], v[166:169], v[48:51]
	v_mfma_f32_16x16x32_bf16 v[40:43], v[222:225], v[166:169], v[40:43]
	v_mfma_f32_16x16x32_bf16 v[32:35], v[214:217], v[174:177], v[32:35]
	v_mfma_f32_16x16x32_bf16 v[24:27], v[222:225], v[174:177], v[24:27]
	v_mfma_f32_16x16x32_bf16 v[16:19], v[214:217], v[182:185], v[16:19]
	v_mfma_f32_16x16x32_bf16 v[8:11], v[222:225], v[182:185], v[8:11]
	v_mfma_f32_16x16x32_bf16 v[4:7], v[214:217], v[204:207], v[4:7]
	v_mfma_f32_16x16x32_bf16 v[0:3], v[222:225], v[204:207], v[0:3]
	s_cmp_gt_u32 s42, 29
	s_barrier
.LBB0_415:
	s_add_u32 s18, s16, 0xfff80080
	s_addc_u32 s19, s17, -1
	s_add_i32 s43, 0, 0x10000
	ds_read_b128 v[146:149], v196 offset:0
	ds_read_b128 v[150:153], v196 offset:1024
	ds_read_b128 v[154:157], v196 offset:2048
	ds_read_b128 v[158:161], v196 offset:3072
	s_cmp_eq_u32 s42, 28
	s_cselect_b32 s21, s9, s19
	s_cselect_b32 s20, s38, s18
	s_cselect_b32 s19, s7, s41
	s_cselect_b32 s18, s39, s40
	s_add_i32 m0, s30, 0xc000
	ds_read_b128 v[162:165], v145
	ds_read_b128 v[166:169], v145 offset:1024
	ds_read_b128 v[170:173], v145 offset:2048
	ds_read_b128 v[174:177], v145 offset:3072
	ds_read_b128 v[178:181], v145 offset:4096
	ds_read_b128 v[182:185], v145 offset:5120
	ds_read_b128 v[186:189], v145 offset:6144
	ds_read_b128 v[204:207], v145 offset:7168
	global_load_lds_dwordx4 v136, s[16:17]
	s_add_i32 m0, s30, 0xe000
	s_nop 0
	global_load_lds_dwordx4 v138, s[16:17]
	s_waitcnt lgkmcnt(8)
	s_barrier
	s_waitcnt lgkmcnt(0)
	v_mfma_f32_16x16x32_bf16 v[124:127], v[146:149], v[162:165], v[124:127]
	v_mfma_f32_16x16x32_bf16 v[120:123], v[154:157], v[162:165], v[120:123]
	v_mfma_f32_16x16x32_bf16 v[116:119], v[146:149], v[170:173], v[116:119]
	v_mfma_f32_16x16x32_bf16 v[108:111], v[154:157], v[170:173], v[108:111]
	s_add_i32 s46, 0, 0x14000
	s_add_i32 s43, s43, s28
	v_mfma_f32_16x16x32_bf16 v[100:103], v[146:149], v[178:181], v[100:103]
	s_mov_b32 m0, s43
	v_mfma_f32_16x16x32_bf16 v[92:95], v[154:157], v[178:181], v[92:95]
	v_mfma_f32_16x16x32_bf16 v[84:87], v[146:149], v[186:189], v[84:87]
	v_mfma_f32_16x16x32_bf16 v[76:79], v[154:157], v[186:189], v[76:79]
	v_mfma_f32_16x16x32_bf16 v[124:127], v[150:153], v[166:169], v[124:127]
	v_mfma_f32_16x16x32_bf16 v[120:123], v[158:161], v[166:169], v[120:123]
	v_mfma_f32_16x16x32_bf16 v[116:119], v[150:153], v[174:177], v[116:119]
	v_mfma_f32_16x16x32_bf16 v[108:111], v[158:161], v[174:177], v[108:111]
	v_mfma_f32_16x16x32_bf16 v[100:103], v[150:153], v[182:185], v[100:103]
	v_mfma_f32_16x16x32_bf16 v[92:95], v[158:161], v[182:185], v[92:95]
	v_mfma_f32_16x16x32_bf16 v[84:87], v[150:153], v[204:207], v[84:87]
	v_mfma_f32_16x16x32_bf16 v[76:79], v[158:161], v[204:207], v[76:79]
	s_barrier
	ds_read_b128 v[208:211], v196 offset:16384
	ds_read_b128 v[214:217], v196 offset:17408
	ds_read_b128 v[218:221], v196 offset:18432
	ds_read_b128 v[222:225], v196 offset:19456
	global_load_lds_dwordx4 v192, s[18:19]
	s_add_i32 m0, s43, 0x2000
	s_nop 0
	global_load_lds_dwordx4 v128, s[18:19]
	s_barrier
	s_waitcnt lgkmcnt(0)
	v_mfma_f32_16x16x32_bf16 v[112:115], v[208:211], v[162:165], v[112:115]
	v_mfma_f32_16x16x32_bf16 v[104:107], v[218:221], v[162:165], v[104:107]
	v_mfma_f32_16x16x32_bf16 v[96:99], v[208:211], v[170:173], v[96:99]
	v_mfma_f32_16x16x32_bf16 v[88:91], v[218:221], v[170:173], v[88:91]
	s_mov_b32 m0, s30
	v_mfma_f32_16x16x32_bf16 v[80:83], v[208:211], v[178:181], v[80:83]
	s_add_u32 s48, s20, 0x80
	s_addc_u32 s49, s21, 0
	v_mfma_f32_16x16x32_bf16 v[72:75], v[218:221], v[178:181], v[72:75]
	v_mfma_f32_16x16x32_bf16 v[68:71], v[208:211], v[186:189], v[68:71]
	v_mfma_f32_16x16x32_bf16 v[64:67], v[218:221], v[186:189], v[64:67]
	v_mfma_f32_16x16x32_bf16 v[112:115], v[214:217], v[166:169], v[112:115]
	v_mfma_f32_16x16x32_bf16 v[104:107], v[222:225], v[166:169], v[104:107]
	v_mfma_f32_16x16x32_bf16 v[96:99], v[214:217], v[174:177], v[96:99]
	v_mfma_f32_16x16x32_bf16 v[88:91], v[222:225], v[174:177], v[88:91]
	v_mfma_f32_16x16x32_bf16 v[80:83], v[214:217], v[182:185], v[80:83]
	v_mfma_f32_16x16x32_bf16 v[72:75], v[222:225], v[182:185], v[72:75]
	v_mfma_f32_16x16x32_bf16 v[68:71], v[214:217], v[204:207], v[68:71]
	v_mfma_f32_16x16x32_bf16 v[64:67], v[222:225], v[204:207], v[64:67]
	s_barrier
	ds_read_b128 v[162:165], v145 offset:16384
	ds_read_b128 v[166:169], v145 offset:17408
	ds_read_b128 v[170:173], v145 offset:18432
	ds_read_b128 v[174:177], v145 offset:19456
	ds_read_b128 v[178:181], v145 offset:20480
	ds_read_b128 v[182:185], v145 offset:21504
	ds_read_b128 v[186:189], v145 offset:22528
	ds_read_b128 v[204:207], v145 offset:23552
	global_load_lds_dwordx4 v132, s[20:21]
	s_mov_b32 m0, s31
	s_nop 0
	global_load_lds_dwordx4 v130, s[20:21]
	s_barrier
	s_waitcnt lgkmcnt(0)
	v_mfma_f32_16x16x32_bf16 v[60:63], v[146:149], v[162:165], v[60:63]
	v_mfma_f32_16x16x32_bf16 v[56:59], v[154:157], v[162:165], v[56:59]
	v_mfma_f32_16x16x32_bf16 v[52:55], v[146:149], v[170:173], v[52:55]
	v_mfma_f32_16x16x32_bf16 v[44:47], v[154:157], v[170:173], v[44:47]
	s_add_u32 s44, s18, 0x80000
	s_addc_u32 s45, s19, 0
	v_mfma_f32_16x16x32_bf16 v[36:39], v[146:149], v[178:181], v[36:39]
	s_add_i32 s43, s46, s28
	s_mov_b32 m0, s43
	v_mfma_f32_16x16x32_bf16 v[28:31], v[154:157], v[178:181], v[28:31]
	v_mfma_f32_16x16x32_bf16 v[20:23], v[146:149], v[186:189], v[20:23]
	v_mfma_f32_16x16x32_bf16 v[12:15], v[154:157], v[186:189], v[12:15]
	v_mfma_f32_16x16x32_bf16 v[60:63], v[150:153], v[166:169], v[60:63]
	v_mfma_f32_16x16x32_bf16 v[56:59], v[158:161], v[166:169], v[56:59]
	v_mfma_f32_16x16x32_bf16 v[52:55], v[150:153], v[174:177], v[52:55]
	v_mfma_f32_16x16x32_bf16 v[44:47], v[158:161], v[174:177], v[44:47]
	v_mfma_f32_16x16x32_bf16 v[36:39], v[150:153], v[182:185], v[36:39]
	v_mfma_f32_16x16x32_bf16 v[28:31], v[158:161], v[182:185], v[28:31]
	v_mfma_f32_16x16x32_bf16 v[20:23], v[150:153], v[204:207], v[20:23]
	v_mfma_f32_16x16x32_bf16 v[12:15], v[158:161], v[204:207], v[12:15]
	s_barrier
	global_load_lds_dwordx4 v192, s[44:45]
	s_add_i32 m0, s43, 0x2000
	s_nop 0
	global_load_lds_dwordx4 v128, s[44:45]
	s_waitcnt vmcnt(6)
	s_barrier
	v_mfma_f32_16x16x32_bf16 v[48:51], v[208:211], v[162:165], v[48:51]
	v_mfma_f32_16x16x32_bf16 v[40:43], v[218:221], v[162:165], v[40:43]
	v_mfma_f32_16x16x32_bf16 v[32:35], v[208:211], v[170:173], v[32:35]
	v_mfma_f32_16x16x32_bf16 v[24:27], v[218:221], v[170:173], v[24:27]
	s_add_i32 s43, 0, 0x18000
	v_mfma_f32_16x16x32_bf16 v[16:19], v[208:211], v[178:181], v[16:19]
	s_add_u32 s20, s20, 0x80000
	s_addc_u32 s21, s21, 0
	v_mfma_f32_16x16x32_bf16 v[8:11], v[218:221], v[178:181], v[8:11]
	s_mov_b32 m0, s33
	v_mfma_f32_16x16x32_bf16 v[4:7], v[208:211], v[186:189], v[4:7]
	v_mfma_f32_16x16x32_bf16 v[0:3], v[218:221], v[186:189], v[0:3]
	v_mfma_f32_16x16x32_bf16 v[48:51], v[214:217], v[166:169], v[48:51]
	v_mfma_f32_16x16x32_bf16 v[40:43], v[222:225], v[166:169], v[40:43]
	v_mfma_f32_16x16x32_bf16 v[32:35], v[214:217], v[174:177], v[32:35]
	v_mfma_f32_16x16x32_bf16 v[24:27], v[222:225], v[174:177], v[24:27]
	v_mfma_f32_16x16x32_bf16 v[16:19], v[214:217], v[182:185], v[16:19]
	v_mfma_f32_16x16x32_bf16 v[8:11], v[222:225], v[182:185], v[8:11]
	v_mfma_f32_16x16x32_bf16 v[4:7], v[214:217], v[204:207], v[4:7]
	v_mfma_f32_16x16x32_bf16 v[0:3], v[222:225], v[204:207], v[0:3]
	s_barrier
	ds_read_b128 v[146:149], v196 offset:32768
	ds_read_b128 v[150:153], v196 offset:33792
	ds_read_b128 v[154:157], v196 offset:34816
	ds_read_b128 v[158:161], v196 offset:35840
	ds_read_b128 v[162:165], v145 offset:32768
	ds_read_b128 v[166:169], v145 offset:33792
	ds_read_b128 v[170:173], v145 offset:34816
	ds_read_b128 v[174:177], v145 offset:35840
	ds_read_b128 v[178:181], v145 offset:36864
	ds_read_b128 v[182:185], v145 offset:37888
	ds_read_b128 v[186:189], v145 offset:38912
	ds_read_b128 v[204:207], v145 offset:39936
	global_load_lds_dwordx4 v132, s[20:21]
	s_mov_b32 m0, s34
	s_nop 0
	global_load_lds_dwordx4 v130, s[20:21]
	s_waitcnt lgkmcnt(8)
	s_barrier
	s_waitcnt lgkmcnt(0)
	v_mfma_f32_16x16x32_bf16 v[124:127], v[146:149], v[162:165], v[124:127]
	v_mfma_f32_16x16x32_bf16 v[120:123], v[154:157], v[162:165], v[120:123]
	v_mfma_f32_16x16x32_bf16 v[116:119], v[146:149], v[170:173], v[116:119]
	v_mfma_f32_16x16x32_bf16 v[108:111], v[154:157], v[170:173], v[108:111]
	s_add_i32 s20, 0, 0x1c000
	s_add_i32 s21, s43, s28
	v_mfma_f32_16x16x32_bf16 v[100:103], v[146:149], v[178:181], v[100:103]
	s_add_i32 m0, s21, 0xffffff80
	v_mfma_f32_16x16x32_bf16 v[92:95], v[154:157], v[178:181], v[92:95]
	v_mfma_f32_16x16x32_bf16 v[84:87], v[146:149], v[186:189], v[84:87]
	v_mfma_f32_16x16x32_bf16 v[76:79], v[154:157], v[186:189], v[76:79]
	v_mfma_f32_16x16x32_bf16 v[124:127], v[150:153], v[166:169], v[124:127]
	v_mfma_f32_16x16x32_bf16 v[120:123], v[158:161], v[166:169], v[120:123]
	v_mfma_f32_16x16x32_bf16 v[116:119], v[150:153], v[174:177], v[116:119]
	v_mfma_f32_16x16x32_bf16 v[108:111], v[158:161], v[174:177], v[108:111]
	v_mfma_f32_16x16x32_bf16 v[100:103], v[150:153], v[182:185], v[100:103]
	v_mfma_f32_16x16x32_bf16 v[92:95], v[158:161], v[182:185], v[92:95]
	v_mfma_f32_16x16x32_bf16 v[84:87], v[150:153], v[204:207], v[84:87]
	v_mfma_f32_16x16x32_bf16 v[76:79], v[158:161], v[204:207], v[76:79]
	s_barrier
	ds_read_b128 v[208:211], v196 offset:49152
	ds_read_b128 v[214:217], v196 offset:50176
	ds_read_b128 v[218:221], v196 offset:51200
	ds_read_b128 v[222:225], v196 offset:52224
	global_load_lds_dwordx4 v192, s[18:19] offset:128
	s_add_i32 m0, s21, 0x1f80
	s_nop 0
	global_load_lds_dwordx4 v128, s[18:19] offset:128
	s_barrier
	s_waitcnt lgkmcnt(0)
	v_mfma_f32_16x16x32_bf16 v[112:115], v[208:211], v[162:165], v[112:115]
	v_mfma_f32_16x16x32_bf16 v[104:107], v[218:221], v[162:165], v[104:107]
	v_mfma_f32_16x16x32_bf16 v[96:99], v[208:211], v[170:173], v[96:99]
	v_mfma_f32_16x16x32_bf16 v[88:91], v[218:221], v[170:173], v[88:91]
	s_mov_b32 m0, s35
	v_mfma_f32_16x16x32_bf16 v[80:83], v[208:211], v[178:181], v[80:83]
	v_mfma_f32_16x16x32_bf16 v[72:75], v[218:221], v[178:181], v[72:75]
	v_mfma_f32_16x16x32_bf16 v[68:71], v[208:211], v[186:189], v[68:71]
	v_mfma_f32_16x16x32_bf16 v[64:67], v[218:221], v[186:189], v[64:67]
	v_mfma_f32_16x16x32_bf16 v[112:115], v[214:217], v[166:169], v[112:115]
	v_mfma_f32_16x16x32_bf16 v[104:107], v[222:225], v[166:169], v[104:107]
	v_mfma_f32_16x16x32_bf16 v[96:99], v[214:217], v[174:177], v[96:99]
	v_mfma_f32_16x16x32_bf16 v[88:91], v[222:225], v[174:177], v[88:91]
	v_mfma_f32_16x16x32_bf16 v[80:83], v[214:217], v[182:185], v[80:83]
	v_mfma_f32_16x16x32_bf16 v[72:75], v[222:225], v[182:185], v[72:75]
	v_mfma_f32_16x16x32_bf16 v[68:71], v[214:217], v[204:207], v[68:71]
	v_mfma_f32_16x16x32_bf16 v[64:67], v[222:225], v[204:207], v[64:67]
	s_barrier
	ds_read_b128 v[162:165], v145 offset:49152
	ds_read_b128 v[166:169], v145 offset:50176
	ds_read_b128 v[170:173], v145 offset:51200
	ds_read_b128 v[174:177], v145 offset:52224
	ds_read_b128 v[178:181], v145 offset:53248
	ds_read_b128 v[182:185], v145 offset:54272
	ds_read_b128 v[186:189], v145 offset:55296
	ds_read_b128 v[204:207], v145 offset:56320
	global_load_lds_dwordx4 v132, s[48:49]
	s_mov_b32 m0, s36
	s_nop 0
	global_load_lds_dwordx4 v130, s[48:49]
	s_barrier
	s_waitcnt lgkmcnt(0)
	v_mfma_f32_16x16x32_bf16 v[60:63], v[146:149], v[162:165], v[60:63]
	v_mfma_f32_16x16x32_bf16 v[56:59], v[154:157], v[162:165], v[56:59]
	v_mfma_f32_16x16x32_bf16 v[52:55], v[146:149], v[170:173], v[52:55]
	v_mfma_f32_16x16x32_bf16 v[44:47], v[154:157], v[170:173], v[44:47]
	s_add_u32 s18, s18, 0x80080
	s_addc_u32 s19, s19, 0
	v_mfma_f32_16x16x32_bf16 v[36:39], v[146:149], v[178:181], v[36:39]
	s_add_i32 s20, s20, s28
	s_mov_b32 m0, s20
	v_mfma_f32_16x16x32_bf16 v[28:31], v[154:157], v[178:181], v[28:31]
	v_mfma_f32_16x16x32_bf16 v[20:23], v[146:149], v[186:189], v[20:23]
	v_mfma_f32_16x16x32_bf16 v[12:15], v[154:157], v[186:189], v[12:15]
	v_mfma_f32_16x16x32_bf16 v[60:63], v[150:153], v[166:169], v[60:63]
	v_mfma_f32_16x16x32_bf16 v[56:59], v[158:161], v[166:169], v[56:59]
	v_mfma_f32_16x16x32_bf16 v[52:55], v[150:153], v[174:177], v[52:55]
	v_mfma_f32_16x16x32_bf16 v[44:47], v[158:161], v[174:177], v[44:47]
	v_mfma_f32_16x16x32_bf16 v[36:39], v[150:153], v[182:185], v[36:39]
	v_mfma_f32_16x16x32_bf16 v[28:31], v[158:161], v[182:185], v[28:31]
	v_mfma_f32_16x16x32_bf16 v[20:23], v[150:153], v[204:207], v[20:23]
	v_mfma_f32_16x16x32_bf16 v[12:15], v[158:161], v[204:207], v[12:15]
	s_barrier
	global_load_lds_dwordx4 v192, s[18:19]
	s_add_i32 m0, s20, 0x2000
	s_nop 0
	global_load_lds_dwordx4 v128, s[18:19]
	s_waitcnt vmcnt(6)
	s_barrier
	v_mfma_f32_16x16x32_bf16 v[48:51], v[208:211], v[162:165], v[48:51]
	v_mfma_f32_16x16x32_bf16 v[40:43], v[218:221], v[162:165], v[40:43]
	v_mfma_f32_16x16x32_bf16 v[32:35], v[208:211], v[170:173], v[32:35]
	v_mfma_f32_16x16x32_bf16 v[24:27], v[218:221], v[170:173], v[24:27]
	s_add_i32 s42, s42, 2
	v_mfma_f32_16x16x32_bf16 v[16:19], v[208:211], v[178:181], v[16:19]
	s_add_u32 s16, s16, 0x100
	s_addc_u32 s17, s17, 0
	v_mfma_f32_16x16x32_bf16 v[8:11], v[218:221], v[178:181], v[8:11]
	s_add_u32 s40, s40, 0x100
	s_addc_u32 s41, s41, 0
	v_mfma_f32_16x16x32_bf16 v[4:7], v[208:211], v[186:189], v[4:7]
	v_mfma_f32_16x16x32_bf16 v[0:3], v[218:221], v[186:189], v[0:3]
	v_mfma_f32_16x16x32_bf16 v[48:51], v[214:217], v[166:169], v[48:51]
	v_mfma_f32_16x16x32_bf16 v[40:43], v[222:225], v[166:169], v[40:43]
	v_mfma_f32_16x16x32_bf16 v[32:35], v[214:217], v[174:177], v[32:35]
	v_mfma_f32_16x16x32_bf16 v[24:27], v[222:225], v[174:177], v[24:27]
	v_mfma_f32_16x16x32_bf16 v[16:19], v[214:217], v[182:185], v[16:19]
	v_mfma_f32_16x16x32_bf16 v[8:11], v[222:225], v[182:185], v[8:11]
	v_mfma_f32_16x16x32_bf16 v[4:7], v[214:217], v[204:207], v[4:7]
	v_mfma_f32_16x16x32_bf16 v[0:3], v[222:225], v[204:207], v[0:3]
	s_cmp_gt_u32 s42, 29
	s_barrier
	s_cbranch_scc0 .LBB0_415
	s_mul_hi_i32 s9, s15, 0x2aaaaaab
	v_lshl_add_u32 v153, s14, 8, v142
	s_lshr_b32 s14, s9, 31
	s_lshr_b32 s9, s9, 2
	s_add_i32 s9, s9, s14
	s_lshl_b32 s7, s15, 8
	s_mul_i32 s16, s9, 0x1800
	v_readlane_b32 s40, v254, 14
	v_readlane_b32 s41, v254, 15
	s_sub_i32 s40, s7, s16
	s_mov_b64 s[20:21], s[40:41]
	v_readlane_b32 s42, v254, 16
	v_readlane_b32 s43, v254, 17
	v_writelane_b32 v254, s20, 14
	s_mov_b64 s[14:15], -1
	s_cmpk_gt_i32 s40, 0xfff
	v_writelane_b32 v254, s21, 15
	v_writelane_b32 v254, s22, 16
	v_writelane_b32 v254, s23, 17
	v_or_b32_e32 v152, 16, v153
	v_or_b32_e32 v151, 32, v153
	v_or_b32_e32 v150, 48, v153
	v_add_u32_e32 v149, 0x80, v153
	v_add_u32_e32 v148, 0x90, v153
	v_add_u32_e32 v147, 0xa0, v153
	v_add_u32_e32 v146, 0xb0, v153
	s_cbranch_scc0 .LBB0_418
	v_mov_b32_e32 v156, v193
	v_mov_b32_e32 v157, v193
	s_ashr_i32 s17, s16, 31
	v_mov_b64_e32 v[140:141], s[2:3]
	s_mov_b32 s9, 0x9000
	v_cvt_pk_fp8_f32 v156, v124, v125
	v_cvt_pk_fp8_f32 v157, v120, v121
	s_lshl_b64 s[14:15], s[16:17], 1
	v_mad_i64_i32 v[154:155], s[16:17], v153, s9, v[140:141]
	s_add_u32 s14, s14, 0x2000
	v_readlane_b32 s16, v254, 14
	s_addc_u32 s15, s15, 0
	v_readlane_b32 s17, v254, 15
	v_lshl_add_u64 v[154:155], v[154:155], 0, s[14:15]
	s_mov_b64 s[20:21], s[16:17]
	v_cvt_pk_fp8_f32 v156, v126, v127 op_sel:[0,0,1]
	v_cvt_pk_fp8_f32 v157, v122, v123 op_sel:[0,0,1]
	v_lshl_add_u64 v[154:155], v[154:155], 0, s[20:21]
	v_lshl_add_u64 v[154:155], v[154:155], 0, s[4:5]
	v_lshl_add_u64 v[154:155], v[154:155], 0, v[134:135]
	global_store_dwordx2 v[154:155], v[156:157], off offset:-4096
	v_mov_b32_e32 v156, v193
	v_mov_b32_e32 v157, v193
	v_cvt_pk_fp8_f32 v156, v112, v113
	v_cvt_pk_fp8_f32 v157, v104, v105
	v_readlane_b32 s18, v254, 16
	v_readlane_b32 s19, v254, 17
	v_cvt_pk_fp8_f32 v156, v114, v115 op_sel:[0,0,1]
	v_cvt_pk_fp8_f32 v157, v106, v107 op_sel:[0,0,1]
	global_store_dwordx2 v[154:155], v[156:157], off offset:-3968
	v_mov_b32_e32 v156, v193
	v_mov_b32_e32 v157, v193
	v_cvt_pk_fp8_f32 v156, v116, v117
	v_cvt_pk_fp8_f32 v157, v108, v109
	v_mad_i64_i32 v[154:155], s[16:17], v152, s9, v[140:141]
	v_lshl_add_u64 v[154:155], v[154:155], 0, s[14:15]
	v_cvt_pk_fp8_f32 v156, v118, v119 op_sel:[0,0,1]
	v_cvt_pk_fp8_f32 v157, v110, v111 op_sel:[0,0,1]
	v_lshl_add_u64 v[154:155], v[154:155], 0, s[20:21]
	v_lshl_add_u64 v[154:155], v[154:155], 0, s[4:5]
	v_lshl_add_u64 v[154:155], v[154:155], 0, v[134:135]
	global_store_dwordx2 v[154:155], v[156:157], off offset:-4096
	v_mov_b32_e32 v156, v193
	v_mov_b32_e32 v157, v193
	v_cvt_pk_fp8_f32 v156, v96, v97
	v_cvt_pk_fp8_f32 v157, v88, v89
	v_cvt_pk_fp8_f32 v156, v98, v99 op_sel:[0,0,1]
	v_cvt_pk_fp8_f32 v157, v90, v91 op_sel:[0,0,1]
	global_store_dwordx2 v[154:155], v[156:157], off offset:-3968
	v_mov_b32_e32 v156, v193
	v_mov_b32_e32 v157, v193
	v_cvt_pk_fp8_f32 v156, v100, v101
	v_cvt_pk_fp8_f32 v157, v92, v93
	v_mad_i64_i32 v[154:155], s[16:17], v151, s9, v[140:141]
	v_lshl_add_u64 v[154:155], v[154:155], 0, s[14:15]
	v_cvt_pk_fp8_f32 v156, v102, v103 op_sel:[0,0,1]
	v_cvt_pk_fp8_f32 v157, v94, v95 op_sel:[0,0,1]
	v_lshl_add_u64 v[154:155], v[154:155], 0, s[20:21]
	v_lshl_add_u64 v[154:155], v[154:155], 0, s[4:5]
	v_lshl_add_u64 v[154:155], v[154:155], 0, v[134:135]
	global_store_dwordx2 v[154:155], v[156:157], off offset:-4096
	v_mov_b32_e32 v156, v193
	v_mov_b32_e32 v157, v193
	v_cvt_pk_fp8_f32 v156, v80, v81
	v_cvt_pk_fp8_f32 v157, v72, v73
	v_cvt_pk_fp8_f32 v156, v82, v83 op_sel:[0,0,1]
	v_cvt_pk_fp8_f32 v157, v74, v75 op_sel:[0,0,1]
	global_store_dwordx2 v[154:155], v[156:157], off offset:-3968
	v_mov_b32_e32 v156, v193
	v_mov_b32_e32 v157, v193
	v_cvt_pk_fp8_f32 v156, v84, v85
	v_cvt_pk_fp8_f32 v157, v76, v77
	v_mad_i64_i32 v[154:155], s[16:17], v150, s9, v[140:141]
	v_lshl_add_u64 v[154:155], v[154:155], 0, s[14:15]
	v_cvt_pk_fp8_f32 v156, v86, v87 op_sel:[0,0,1]
	v_cvt_pk_fp8_f32 v157, v78, v79 op_sel:[0,0,1]
	v_lshl_add_u64 v[154:155], v[154:155], 0, s[20:21]
	v_lshl_add_u64 v[154:155], v[154:155], 0, s[4:5]
	v_lshl_add_u64 v[154:155], v[154:155], 0, v[134:135]
	global_store_dwordx2 v[154:155], v[156:157], off offset:-4096
	v_mov_b32_e32 v156, v193
	v_mov_b32_e32 v157, v193
	v_cvt_pk_fp8_f32 v156, v68, v69
	v_cvt_pk_fp8_f32 v157, v64, v65
	v_cvt_pk_fp8_f32 v156, v70, v71 op_sel:[0,0,1]
	v_cvt_pk_fp8_f32 v157, v66, v67 op_sel:[0,0,1]
	global_store_dwordx2 v[154:155], v[156:157], off offset:-3968
	v_mov_b32_e32 v156, v193
	v_mov_b32_e32 v157, v193
	v_cvt_pk_fp8_f32 v156, v60, v61
	v_cvt_pk_fp8_f32 v157, v56, v57
	v_mad_i64_i32 v[154:155], s[16:17], v149, s9, v[140:141]
	v_lshl_add_u64 v[154:155], v[154:155], 0, s[14:15]
	v_cvt_pk_fp8_f32 v156, v62, v63 op_sel:[0,0,1]
	v_cvt_pk_fp8_f32 v157, v58, v59 op_sel:[0,0,1]
	v_lshl_add_u64 v[154:155], v[154:155], 0, s[20:21]
	v_lshl_add_u64 v[154:155], v[154:155], 0, s[4:5]
	v_lshl_add_u64 v[154:155], v[154:155], 0, v[134:135]
	global_store_dwordx2 v[154:155], v[156:157], off offset:-4096
	v_mov_b32_e32 v156, v193
	v_mov_b32_e32 v157, v193
	v_cvt_pk_fp8_f32 v156, v48, v49
	v_cvt_pk_fp8_f32 v157, v40, v41
	v_cvt_pk_fp8_f32 v156, v50, v51 op_sel:[0,0,1]
	v_cvt_pk_fp8_f32 v157, v42, v43 op_sel:[0,0,1]
	global_store_dwordx2 v[154:155], v[156:157], off offset:-3968
	v_mov_b32_e32 v156, v193
	v_mov_b32_e32 v157, v193
	v_cvt_pk_fp8_f32 v156, v52, v53
	v_cvt_pk_fp8_f32 v157, v44, v45
	v_mad_i64_i32 v[154:155], s[16:17], v148, s9, v[140:141]
	v_lshl_add_u64 v[154:155], v[154:155], 0, s[14:15]
	v_cvt_pk_fp8_f32 v156, v54, v55 op_sel:[0,0,1]
	v_cvt_pk_fp8_f32 v157, v46, v47 op_sel:[0,0,1]
	v_lshl_add_u64 v[154:155], v[154:155], 0, s[20:21]
	v_lshl_add_u64 v[154:155], v[154:155], 0, s[4:5]
	v_lshl_add_u64 v[154:155], v[154:155], 0, v[134:135]
	global_store_dwordx2 v[154:155], v[156:157], off offset:-4096
	v_mov_b32_e32 v156, v193
	v_mov_b32_e32 v157, v193
	v_cvt_pk_fp8_f32 v156, v32, v33
	v_cvt_pk_fp8_f32 v157, v24, v25
	v_cvt_pk_fp8_f32 v156, v34, v35 op_sel:[0,0,1]
	v_cvt_pk_fp8_f32 v157, v26, v27 op_sel:[0,0,1]
	global_store_dwordx2 v[154:155], v[156:157], off offset:-3968
	v_mov_b32_e32 v156, v193
	v_mov_b32_e32 v157, v193
	v_cvt_pk_fp8_f32 v156, v36, v37
	v_cvt_pk_fp8_f32 v157, v28, v29
	v_mad_i64_i32 v[154:155], s[16:17], v147, s9, v[140:141]
	v_lshl_add_u64 v[154:155], v[154:155], 0, s[14:15]
	v_cvt_pk_fp8_f32 v156, v38, v39 op_sel:[0,0,1]
	v_cvt_pk_fp8_f32 v157, v30, v31 op_sel:[0,0,1]
	v_lshl_add_u64 v[154:155], v[154:155], 0, s[20:21]
	v_lshl_add_u64 v[154:155], v[154:155], 0, s[4:5]
	v_lshl_add_u64 v[154:155], v[154:155], 0, v[134:135]
	global_store_dwordx2 v[154:155], v[156:157], off offset:-4096
	v_mov_b32_e32 v156, v193
	v_mov_b32_e32 v157, v193
	v_cvt_pk_fp8_f32 v156, v16, v17
	v_cvt_pk_fp8_f32 v157, v8, v9
	v_mad_i64_i32 v[140:141], s[16:17], v146, s9, v[140:141]
	v_cvt_pk_fp8_f32 v156, v18, v19 op_sel:[0,0,1]
	v_cvt_pk_fp8_f32 v157, v10, v11 op_sel:[0,0,1]
	v_lshl_add_u64 v[140:141], v[140:141], 0, s[14:15]
	v_lshl_add_u64 v[140:141], v[140:141], 0, s[20:21]
	v_lshl_add_u64 v[140:141], v[140:141], 0, s[4:5]
	global_store_dwordx2 v[154:155], v[156:157], off offset:-3968
	v_mov_b32_e32 v154, v193
	v_mov_b32_e32 v155, v193
	v_cvt_pk_fp8_f32 v154, v20, v21
	v_cvt_pk_fp8_f32 v155, v12, v13
	v_lshl_add_u64 v[140:141], v[140:141], 0, v[134:135]
	s_mov_b64 s[14:15], 0
	v_cvt_pk_fp8_f32 v154, v22, v23 op_sel:[0,0,1]
	v_cvt_pk_fp8_f32 v155, v14, v15 op_sel:[0,0,1]
	global_store_dwordx2 v[140:141], v[154:155], off offset:-4096
	v_mov_b32_e32 v154, v193
	v_mov_b32_e32 v155, v193
	v_cvt_pk_fp8_f32 v154, v4, v5
	v_cvt_pk_fp8_f32 v155, v0, v1
	v_cvt_pk_fp8_f32 v154, v6, v7 op_sel:[0,0,1]
	v_cvt_pk_fp8_f32 v155, v2, v3 op_sel:[0,0,1]
	global_store_dwordx2 v[140:141], v[154:155], off offset:-3968
